# DMA address adds of K-loop segments 2 and 4 hoisted into the preceding MFMA blocks (segment 4 adds done in place)
# baseline (speedup 1.0000x reference)
.Llbb_0:
	s_add_i32 s47, s44, 2
	s_add_u32 s4, s42, 0x80
	s_addc_u32 s5, s43, 0
	s_add_i32 s54, 0, 0x10000
	s_cmp_eq_u32 s69, s44
	s_cselect_b32 s45, s13, s5
	s_cselect_b32 s44, s12, s4
	s_cselect_b32 vcc_hi, s1, s11
	s_cselect_b32 vcc_lo, s0, s10
	s_add_i32 s4, 0, 0x14000
	v_add_u32_e32 v140, s54, v223
	v_add_u32_e32 v156, s4, v223
	s_waitcnt lgkmcnt(0)
	ds_read_b128 v[128:131], v140
	ds_read_b128 v[132:135], v140 offset:1024
	ds_read_b128 v[136:139], v140 offset:2048
	ds_read_b128 v[140:143], v140 offset:3072
	ds_read_b128 v[144:147], v156
	ds_read_b128 v[148:151], v156 offset:1024
	ds_read_b128 v[152:155], v156 offset:2048
	ds_read_b128 v[156:159], v156 offset:3072
	v_lshl_add_u64 v[214:215], s[42:43], 0, v[194:195]
	s_add_i32 m0, s59, 0xc000
	ds_read_b128 v[160:163], v228
	ds_read_b128 v[164:167], v228 offset:1024
	ds_read_b128 v[168:171], v228 offset:2048
	ds_read_b128 v[172:175], v228 offset:3072
	ds_read_b128 v[198:201], v228 offset:4096
	ds_read_b128 v[202:205], v228 offset:5120
	ds_read_b128 v[206:209], v228 offset:6144
	ds_read_b128 v[210:213], v228 offset:7168
	global_load_lds_dwordx4 v[214:215], off
	v_lshl_add_u64 v[214:215], s[42:43], 0, v[196:197]
	s_add_i32 m0, s59, 0xe000
	s_nop 0
	global_load_lds_dwordx4 v[214:215], off
	s_waitcnt vmcnt(8)
	s_waitcnt lgkmcnt(0)
	s_barrier
	s_waitcnt lgkmcnt(0)
	v_mfma_f32_16x16x32_bf16 v[120:123], v[128:131], v[160:163], 0
	v_mfma_f32_16x16x32_bf16 v[116:119], v[136:139], v[160:163], 0
	v_lshl_add_u64 v[214:215], vcc, 0, v[190:191]
	v_mfma_f32_16x16x32_bf16 v[108:111], v[128:131], v[168:171], 0
	v_lshl_add_u64 v[216:217], vcc, 0, v[186:187]
	v_mfma_f32_16x16x32_bf16 v[100:103], v[136:139], v[168:171], 0
	s_add_u32 vcc_lo, vcc_lo, s24
	v_mfma_f32_16x16x32_bf16 v[92:95], v[128:131], v[198:201], 0
	s_addc_u32 vcc_hi, vcc_hi, s25
	v_mfma_f32_16x16x32_bf16 v[84:87], v[136:139], v[198:201], 0
	v_lshl_add_u64 v[230:231], vcc, 0, v[190:191]
	v_mfma_f32_16x16x32_bf16 v[76:79], v[128:131], v[206:209], 0
	v_lshl_add_u64 v[232:233], vcc, 0, v[186:187]
	v_mfma_f32_16x16x32_bf16 v[68:71], v[136:139], v[206:209], 0
	v_lshl_add_u64 v[234:235], s[44:45], 0, v[192:193]
	v_mfma_f32_16x16x32_bf16 v[120:123], v[132:135], v[164:167], v[120:123]
	v_lshl_add_u64 v[236:237], s[44:45], 0, v[188:189]
	v_mfma_f32_16x16x32_bf16 v[116:119], v[140:143], v[164:167], v[116:119]
	v_mfma_f32_16x16x32_bf16 v[108:111], v[132:135], v[172:175], v[108:111]
	v_mfma_f32_16x16x32_bf16 v[100:103], v[140:143], v[172:175], v[100:103]
	v_mfma_f32_16x16x32_bf16 v[92:95], v[132:135], v[202:205], v[92:95]
	v_mfma_f32_16x16x32_bf16 v[84:87], v[140:143], v[202:205], v[84:87]
	v_mfma_f32_16x16x32_bf16 v[76:79], v[132:135], v[210:213], v[76:79]
	v_mfma_f32_16x16x32_bf16 v[68:71], v[140:143], v[210:213], v[68:71]
	v_mfma_f32_16x16x32_bf16 v[124:127], v[144:147], v[160:163], 0
	v_mfma_f32_16x16x32_bf16 v[112:115], v[152:155], v[160:163], 0
	v_mfma_f32_16x16x32_bf16 v[104:107], v[144:147], v[168:171], 0
	v_mfma_f32_16x16x32_bf16 v[96:99], v[152:155], v[168:171], 0
	v_mfma_f32_16x16x32_bf16 v[88:91], v[144:147], v[198:201], 0
	v_mfma_f32_16x16x32_bf16 v[80:83], v[152:155], v[198:201], 0
	v_mfma_f32_16x16x32_bf16 v[72:75], v[144:147], v[206:209], 0
	v_mfma_f32_16x16x32_bf16 v[64:67], v[152:155], v[206:209], 0
	v_mfma_f32_16x16x32_bf16 v[124:127], v[148:151], v[164:167], v[124:127]
	v_mfma_f32_16x16x32_bf16 v[112:115], v[156:159], v[164:167], v[112:115]
	v_mfma_f32_16x16x32_bf16 v[104:107], v[148:151], v[172:175], v[104:107]
	v_mfma_f32_16x16x32_bf16 v[96:99], v[156:159], v[172:175], v[96:99]
	v_mfma_f32_16x16x32_bf16 v[88:91], v[148:151], v[202:205], v[88:91]
	v_mfma_f32_16x16x32_bf16 v[80:83], v[156:159], v[202:205], v[80:83]
	v_mfma_f32_16x16x32_bf16 v[72:75], v[148:151], v[210:213], v[72:75]
	v_mfma_f32_16x16x32_bf16 v[64:67], v[156:159], v[210:213], v[64:67]
	s_barrier
	s_add_i32 s5, s54, s58
	s_mov_b32 m0, s5
	ds_read_b128 v[160:163], v228 offset:16384
	ds_read_b128 v[164:167], v228 offset:17408
	ds_read_b128 v[168:171], v228 offset:18432
	ds_read_b128 v[172:175], v228 offset:19456
	ds_read_b128 v[198:201], v228 offset:20480
	ds_read_b128 v[202:205], v228 offset:21504
	ds_read_b128 v[206:209], v228 offset:22528
	ds_read_b128 v[210:213], v228 offset:23552
	global_load_lds_dwordx4 v[214:215], off
	s_add_i32 m0, s5, 0x2000
	s_add_i32 s4, s4, s58
	global_load_lds_dwordx4 v[216:217], off
	s_mov_b32 m0, s4
	s_nop 0
	global_load_lds_dwordx4 v[230:231], off
	s_add_i32 m0, s4, 0x2000
	s_nop 0
	global_load_lds_dwordx4 v[232:233], off
	s_mov_b32 m0, s59
	s_nop 0
	global_load_lds_dwordx4 v[234:235], off
	s_mov_b32 m0, s60
	s_nop 0
	global_load_lds_dwordx4 v[236:237], off
	s_waitcnt vmcnt(8)
	s_waitcnt lgkmcnt(0)
	s_barrier
	s_waitcnt lgkmcnt(0)
	v_mfma_f32_16x16x32_bf16 v[60:63], v[128:131], v[160:163], 0
	v_mfma_f32_16x16x32_bf16 v[52:55], v[136:139], v[160:163], 0
	v_mfma_f32_16x16x32_bf16 v[44:47], v[128:131], v[168:171], 0
	v_mfma_f32_16x16x32_bf16 v[36:39], v[136:139], v[168:171], 0
	v_mfma_f32_16x16x32_bf16 v[28:31], v[128:131], v[198:201], 0
	v_mfma_f32_16x16x32_bf16 v[20:23], v[136:139], v[198:201], 0
	v_mfma_f32_16x16x32_bf16 v[12:15], v[128:131], v[206:209], 0
	v_mfma_f32_16x16x32_bf16 v[4:7], v[136:139], v[206:209], 0
	v_mfma_f32_16x16x32_bf16 v[60:63], v[132:135], v[164:167], v[60:63]
	v_mfma_f32_16x16x32_bf16 v[52:55], v[140:143], v[164:167], v[52:55]
	v_mfma_f32_16x16x32_bf16 v[44:47], v[132:135], v[172:175], v[44:47]
	v_mfma_f32_16x16x32_bf16 v[36:39], v[140:143], v[172:175], v[36:39]
	v_mfma_f32_16x16x32_bf16 v[28:31], v[132:135], v[202:205], v[28:31]
	v_mfma_f32_16x16x32_bf16 v[20:23], v[140:143], v[202:205], v[20:23]
	v_mfma_f32_16x16x32_bf16 v[12:15], v[132:135], v[210:213], v[12:15]
	v_mfma_f32_16x16x32_bf16 v[4:7], v[140:143], v[210:213], v[4:7]
	v_mfma_f32_16x16x32_bf16 v[56:59], v[144:147], v[160:163], 0
	v_mfma_f32_16x16x32_bf16 v[48:51], v[152:155], v[160:163], 0
	v_mfma_f32_16x16x32_bf16 v[40:43], v[144:147], v[168:171], 0
	v_mfma_f32_16x16x32_bf16 v[32:35], v[152:155], v[168:171], 0
	v_mfma_f32_16x16x32_bf16 v[24:27], v[144:147], v[198:201], 0
	v_mfma_f32_16x16x32_bf16 v[16:19], v[152:155], v[198:201], 0
	v_mfma_f32_16x16x32_bf16 v[8:11], v[144:147], v[206:209], 0
	v_mfma_f32_16x16x32_bf16 v[0:3], v[152:155], v[206:209], 0
	v_mfma_f32_16x16x32_bf16 v[56:59], v[148:151], v[164:167], v[56:59]
	v_mfma_f32_16x16x32_bf16 v[48:51], v[156:159], v[164:167], v[48:51]
	v_mfma_f32_16x16x32_bf16 v[40:43], v[148:151], v[172:175], v[40:43]
	v_mfma_f32_16x16x32_bf16 v[32:35], v[156:159], v[172:175], v[32:35]
	v_mfma_f32_16x16x32_bf16 v[24:27], v[148:151], v[202:205], v[24:27]
	v_mfma_f32_16x16x32_bf16 v[16:19], v[156:159], v[202:205], v[16:19]
	v_mfma_f32_16x16x32_bf16 v[8:11], v[148:151], v[210:213], v[8:11]
	v_mfma_f32_16x16x32_bf16 v[0:3], v[156:159], v[210:213], v[0:3]
	s_barrier
	s_add_i32 s4, 0, 0x18000
	s_add_i32 s5, 0, 0x1c000
	v_add_u32_e32 v140, s4, v223
	v_add_u32_e32 v156, s5, v223
	ds_read_b128 v[128:131], v140
	ds_read_b128 v[132:135], v140 offset:1024
	ds_read_b128 v[136:139], v140 offset:2048
	ds_read_b128 v[140:143], v140 offset:3072
	ds_read_b128 v[144:147], v156
	ds_read_b128 v[148:151], v156 offset:1024
	ds_read_b128 v[152:155], v156 offset:2048
	ds_read_b128 v[156:159], v156 offset:3072
	s_add_u32 s44, s44, s24
	s_addc_u32 s45, s45, s25
	s_mov_b32 m0, s61
	v_lshl_add_u64 v[238:239], s[44:45], 0, v[192:193]
	ds_read_b128 v[160:163], v228 offset:32768
	ds_read_b128 v[164:167], v228 offset:33792
	ds_read_b128 v[168:171], v228 offset:34816
	ds_read_b128 v[172:175], v228 offset:35840
	ds_read_b128 v[198:201], v228 offset:36864
	ds_read_b128 v[202:205], v228 offset:37888
	ds_read_b128 v[206:209], v228 offset:38912
	ds_read_b128 v[210:213], v228 offset:39936
	global_load_lds_dwordx4 v[238:239], off
	v_lshl_add_u64 v[238:239], s[44:45], 0, v[188:189]
	s_mov_b32 m0, s62
	s_nop 0
	global_load_lds_dwordx4 v[238:239], off
	s_waitcnt vmcnt(8)
	s_waitcnt lgkmcnt(0)
	s_barrier
	s_waitcnt lgkmcnt(0)
	v_mfma_f32_16x16x32_bf16 v[120:123], v[128:131], v[160:163], v[120:123]
	v_mfma_f32_16x16x32_bf16 v[116:119], v[136:139], v[160:163], v[116:119]
	v_lshl_add_u64 v[214:215], v[214:215], 0, s[14:15]
	v_mfma_f32_16x16x32_bf16 v[108:111], v[128:131], v[168:171], v[108:111]
	v_lshl_add_u64 v[216:217], v[216:217], 0, s[14:15]
	v_mfma_f32_16x16x32_bf16 v[100:103], v[136:139], v[168:171], v[100:103]
	v_lshl_add_u64 v[230:231], v[230:231], 0, s[14:15]
	v_mfma_f32_16x16x32_bf16 v[92:95], v[128:131], v[198:201], v[92:95]
	v_lshl_add_u64 v[232:233], v[232:233], 0, s[14:15]
	v_mfma_f32_16x16x32_bf16 v[84:87], v[136:139], v[198:201], v[84:87]
	v_lshl_add_u64 v[234:235], v[234:235], 0, s[14:15]
	v_mfma_f32_16x16x32_bf16 v[76:79], v[128:131], v[206:209], v[76:79]
	v_lshl_add_u64 v[236:237], v[236:237], 0, s[14:15]
	v_mfma_f32_16x16x32_bf16 v[68:71], v[136:139], v[206:209], v[68:71]
	v_mfma_f32_16x16x32_bf16 v[120:123], v[132:135], v[164:167], v[120:123]
	v_mfma_f32_16x16x32_bf16 v[116:119], v[140:143], v[164:167], v[116:119]
	v_mfma_f32_16x16x32_bf16 v[108:111], v[132:135], v[172:175], v[108:111]
	v_mfma_f32_16x16x32_bf16 v[100:103], v[140:143], v[172:175], v[100:103]
	v_mfma_f32_16x16x32_bf16 v[92:95], v[132:135], v[202:205], v[92:95]
	v_mfma_f32_16x16x32_bf16 v[84:87], v[140:143], v[202:205], v[84:87]
	v_mfma_f32_16x16x32_bf16 v[76:79], v[132:135], v[210:213], v[76:79]
	v_mfma_f32_16x16x32_bf16 v[68:71], v[140:143], v[210:213], v[68:71]
	v_mfma_f32_16x16x32_bf16 v[124:127], v[144:147], v[160:163], v[124:127]
	v_mfma_f32_16x16x32_bf16 v[112:115], v[152:155], v[160:163], v[112:115]
	v_mfma_f32_16x16x32_bf16 v[104:107], v[144:147], v[168:171], v[104:107]
	v_mfma_f32_16x16x32_bf16 v[96:99], v[152:155], v[168:171], v[96:99]
	v_mfma_f32_16x16x32_bf16 v[88:91], v[144:147], v[198:201], v[88:91]
	v_mfma_f32_16x16x32_bf16 v[80:83], v[152:155], v[198:201], v[80:83]
	v_mfma_f32_16x16x32_bf16 v[72:75], v[144:147], v[206:209], v[72:75]
	v_mfma_f32_16x16x32_bf16 v[64:67], v[152:155], v[206:209], v[64:67]
	v_mfma_f32_16x16x32_bf16 v[124:127], v[148:151], v[164:167], v[124:127]
	v_mfma_f32_16x16x32_bf16 v[112:115], v[156:159], v[164:167], v[112:115]
	v_mfma_f32_16x16x32_bf16 v[104:107], v[148:151], v[172:175], v[104:107]
	v_mfma_f32_16x16x32_bf16 v[96:99], v[156:159], v[172:175], v[96:99]
	v_mfma_f32_16x16x32_bf16 v[88:91], v[148:151], v[202:205], v[88:91]
	v_mfma_f32_16x16x32_bf16 v[80:83], v[156:159], v[202:205], v[80:83]
	v_mfma_f32_16x16x32_bf16 v[72:75], v[148:151], v[210:213], v[72:75]
	v_mfma_f32_16x16x32_bf16 v[64:67], v[156:159], v[210:213], v[64:67]
	s_barrier
	s_add_i32 s4, s4, s58
	s_mov_b32 m0, s4
	ds_read_b128 v[160:163], v228 offset:49152
	ds_read_b128 v[164:167], v228 offset:50176
	ds_read_b128 v[168:171], v228 offset:51200
	ds_read_b128 v[172:175], v228 offset:52224
	ds_read_b128 v[198:201], v228 offset:53248
	ds_read_b128 v[202:205], v228 offset:54272
	ds_read_b128 v[206:209], v228 offset:55296
	ds_read_b128 v[210:213], v228 offset:56320
	global_load_lds_dwordx4 v[214:215], off
	s_add_i32 m0, s4, 0x2000
	s_add_i32 s4, s5, s58
	global_load_lds_dwordx4 v[216:217], off
	s_mov_b32 m0, s4
	s_nop 0
	global_load_lds_dwordx4 v[230:231], off
	s_add_i32 m0, s4, 0x2000
	s_nop 0
	global_load_lds_dwordx4 v[232:233], off
	s_mov_b32 m0, s63
	s_nop 0
	global_load_lds_dwordx4 v[234:235], off
	s_mov_b32 m0, s66
	s_nop 0
	global_load_lds_dwordx4 v[236:237], off
	s_waitcnt vmcnt(8)
	s_waitcnt lgkmcnt(0)
	s_barrier
	s_waitcnt lgkmcnt(0)
	v_mfma_f32_16x16x32_bf16 v[60:63], v[128:131], v[160:163], v[60:63]
	s_add_u32 s42, s42, 0x100
	v_mfma_f32_16x16x32_bf16 v[52:55], v[136:139], v[160:163], v[52:55]
	s_addc_u32 s43, s43, 0
	v_mfma_f32_16x16x32_bf16 v[44:47], v[128:131], v[168:171], v[44:47]
	s_add_u32 s10, s10, 0x100
	v_mfma_f32_16x16x32_bf16 v[36:39], v[136:139], v[168:171], v[36:39]
	s_addc_u32 s11, s11, 0
	v_mfma_f32_16x16x32_bf16 v[28:31], v[128:131], v[198:201], v[28:31]
	s_mov_b32 s44, s47
	v_mfma_f32_16x16x32_bf16 v[20:23], v[136:139], v[198:201], v[20:23]
	s_cmp_ge_i32 s47, s67
	v_mfma_f32_16x16x32_bf16 v[12:15], v[128:131], v[206:209], v[12:15]
	s_cselect_b32 s99, 1, 0
	v_mfma_f32_16x16x32_bf16 v[4:7], v[136:139], v[206:209], v[4:7]
	s_add_i32 s47, s44, 2
	v_mfma_f32_16x16x32_bf16 v[60:63], v[132:135], v[164:167], v[60:63]
	s_add_u32 s4, s42, 0x80
	v_mfma_f32_16x16x32_bf16 v[52:55], v[140:143], v[164:167], v[52:55]
	s_addc_u32 s5, s43, 0
	v_mfma_f32_16x16x32_bf16 v[44:47], v[132:135], v[172:175], v[44:47]
	s_add_i32 s54, 0, 0x10000
	v_mfma_f32_16x16x32_bf16 v[36:39], v[140:143], v[172:175], v[36:39]
	s_cmp_eq_u32 s69, s44
	v_mfma_f32_16x16x32_bf16 v[28:31], v[132:135], v[202:205], v[28:31]
	s_cselect_b32 s45, s13, s5
	v_mfma_f32_16x16x32_bf16 v[20:23], v[140:143], v[202:205], v[20:23]
	s_cselect_b32 s44, s12, s4
	v_mfma_f32_16x16x32_bf16 v[12:15], v[132:135], v[210:213], v[12:15]
	s_cselect_b32 vcc_hi, s1, s11
	v_mfma_f32_16x16x32_bf16 v[4:7], v[140:143], v[210:213], v[4:7]
	s_cselect_b32 vcc_lo, s0, s10
	v_mfma_f32_16x16x32_bf16 v[56:59], v[144:147], v[160:163], v[56:59]
	s_add_i32 s4, 0, 0x14000
	v_mfma_f32_16x16x32_bf16 v[48:51], v[152:155], v[160:163], v[48:51]
	v_mfma_f32_16x16x32_bf16 v[40:43], v[144:147], v[168:171], v[40:43]
	v_mfma_f32_16x16x32_bf16 v[32:35], v[152:155], v[168:171], v[32:35]
	v_mfma_f32_16x16x32_bf16 v[24:27], v[144:147], v[198:201], v[24:27]
	v_mfma_f32_16x16x32_bf16 v[16:19], v[152:155], v[198:201], v[16:19]
	v_mfma_f32_16x16x32_bf16 v[8:11], v[144:147], v[206:209], v[8:11]
	v_mfma_f32_16x16x32_bf16 v[0:3], v[152:155], v[206:209], v[0:3]
	v_mfma_f32_16x16x32_bf16 v[56:59], v[148:151], v[164:167], v[56:59]
	v_mfma_f32_16x16x32_bf16 v[48:51], v[156:159], v[164:167], v[48:51]
	v_mfma_f32_16x16x32_bf16 v[40:43], v[148:151], v[172:175], v[40:43]
	v_mfma_f32_16x16x32_bf16 v[32:35], v[156:159], v[172:175], v[32:35]
	v_mfma_f32_16x16x32_bf16 v[24:27], v[148:151], v[202:205], v[24:27]
	v_mfma_f32_16x16x32_bf16 v[16:19], v[156:159], v[202:205], v[16:19]
	v_mfma_f32_16x16x32_bf16 v[8:11], v[148:151], v[210:213], v[8:11]
	v_mfma_f32_16x16x32_bf16 v[0:3], v[156:159], v[210:213], v[0:3]
	s_barrier
	s_cmp_lg_u32 s99, 0
	s_cbranch_scc1 .Lpeelx_4
.LBB0_155:
	v_add_u32_e32 v140, s54, v223
	v_add_u32_e32 v156, s4, v223
	s_waitcnt lgkmcnt(0)
	ds_read_b128 v[128:131], v140
	ds_read_b128 v[132:135], v140 offset:1024
	ds_read_b128 v[136:139], v140 offset:2048
	ds_read_b128 v[140:143], v140 offset:3072
	ds_read_b128 v[144:147], v156
	ds_read_b128 v[148:151], v156 offset:1024
	ds_read_b128 v[152:155], v156 offset:2048
	ds_read_b128 v[156:159], v156 offset:3072
	v_lshl_add_u64 v[214:215], s[42:43], 0, v[194:195]
	s_add_i32 m0, s59, 0xc000
	ds_read_b128 v[160:163], v228
	ds_read_b128 v[164:167], v228 offset:1024
	ds_read_b128 v[168:171], v228 offset:2048
	ds_read_b128 v[172:175], v228 offset:3072
	ds_read_b128 v[198:201], v228 offset:4096
	ds_read_b128 v[202:205], v228 offset:5120
	ds_read_b128 v[206:209], v228 offset:6144
	ds_read_b128 v[210:213], v228 offset:7168
	global_load_lds_dwordx4 v[214:215], off
	v_lshl_add_u64 v[214:215], s[42:43], 0, v[196:197]
	s_add_i32 m0, s59, 0xe000
	s_nop 0
	global_load_lds_dwordx4 v[214:215], off
	s_waitcnt vmcnt(8)
	s_waitcnt lgkmcnt(0)
	s_barrier
	s_waitcnt lgkmcnt(0)
	v_mfma_f32_16x16x32_bf16 v[120:123], v[128:131], v[160:163], v[120:123]
	v_mfma_f32_16x16x32_bf16 v[116:119], v[136:139], v[160:163], v[116:119]
	v_lshl_add_u64 v[214:215], vcc, 0, v[190:191]
	v_mfma_f32_16x16x32_bf16 v[108:111], v[128:131], v[168:171], v[108:111]
	v_lshl_add_u64 v[216:217], vcc, 0, v[186:187]
	v_mfma_f32_16x16x32_bf16 v[100:103], v[136:139], v[168:171], v[100:103]
	s_add_u32 vcc_lo, vcc_lo, s24
	v_mfma_f32_16x16x32_bf16 v[92:95], v[128:131], v[198:201], v[92:95]
	s_addc_u32 vcc_hi, vcc_hi, s25
	v_mfma_f32_16x16x32_bf16 v[84:87], v[136:139], v[198:201], v[84:87]
	v_lshl_add_u64 v[230:231], vcc, 0, v[190:191]
	v_mfma_f32_16x16x32_bf16 v[76:79], v[128:131], v[206:209], v[76:79]
	v_lshl_add_u64 v[232:233], vcc, 0, v[186:187]
	v_mfma_f32_16x16x32_bf16 v[68:71], v[136:139], v[206:209], v[68:71]
	v_lshl_add_u64 v[234:235], s[44:45], 0, v[192:193]
	v_mfma_f32_16x16x32_bf16 v[120:123], v[132:135], v[164:167], v[120:123]
	v_lshl_add_u64 v[236:237], s[44:45], 0, v[188:189]
	v_mfma_f32_16x16x32_bf16 v[116:119], v[140:143], v[164:167], v[116:119]
	v_mfma_f32_16x16x32_bf16 v[108:111], v[132:135], v[172:175], v[108:111]
	v_mfma_f32_16x16x32_bf16 v[100:103], v[140:143], v[172:175], v[100:103]
	v_mfma_f32_16x16x32_bf16 v[92:95], v[132:135], v[202:205], v[92:95]
	v_mfma_f32_16x16x32_bf16 v[84:87], v[140:143], v[202:205], v[84:87]
	v_mfma_f32_16x16x32_bf16 v[76:79], v[132:135], v[210:213], v[76:79]
	v_mfma_f32_16x16x32_bf16 v[68:71], v[140:143], v[210:213], v[68:71]
	v_mfma_f32_16x16x32_bf16 v[124:127], v[144:147], v[160:163], v[124:127]
	v_mfma_f32_16x16x32_bf16 v[112:115], v[152:155], v[160:163], v[112:115]
	v_mfma_f32_16x16x32_bf16 v[104:107], v[144:147], v[168:171], v[104:107]
	v_mfma_f32_16x16x32_bf16 v[96:99], v[152:155], v[168:171], v[96:99]
	v_mfma_f32_16x16x32_bf16 v[88:91], v[144:147], v[198:201], v[88:91]
	v_mfma_f32_16x16x32_bf16 v[80:83], v[152:155], v[198:201], v[80:83]
	v_mfma_f32_16x16x32_bf16 v[72:75], v[144:147], v[206:209], v[72:75]
	v_mfma_f32_16x16x32_bf16 v[64:67], v[152:155], v[206:209], v[64:67]
	v_mfma_f32_16x16x32_bf16 v[124:127], v[148:151], v[164:167], v[124:127]
	v_mfma_f32_16x16x32_bf16 v[112:115], v[156:159], v[164:167], v[112:115]
	v_mfma_f32_16x16x32_bf16 v[104:107], v[148:151], v[172:175], v[104:107]
	v_mfma_f32_16x16x32_bf16 v[96:99], v[156:159], v[172:175], v[96:99]
	v_mfma_f32_16x16x32_bf16 v[88:91], v[148:151], v[202:205], v[88:91]
	v_mfma_f32_16x16x32_bf16 v[80:83], v[156:159], v[202:205], v[80:83]
	v_mfma_f32_16x16x32_bf16 v[72:75], v[148:151], v[210:213], v[72:75]
	v_mfma_f32_16x16x32_bf16 v[64:67], v[156:159], v[210:213], v[64:67]
	s_barrier
	s_add_i32 s5, s54, s58
	s_mov_b32 m0, s5
	ds_read_b128 v[160:163], v228 offset:16384
	ds_read_b128 v[164:167], v228 offset:17408
	ds_read_b128 v[168:171], v228 offset:18432
	ds_read_b128 v[172:175], v228 offset:19456
	ds_read_b128 v[198:201], v228 offset:20480
	ds_read_b128 v[202:205], v228 offset:21504
	ds_read_b128 v[206:209], v228 offset:22528
	ds_read_b128 v[210:213], v228 offset:23552
	global_load_lds_dwordx4 v[214:215], off
	s_add_i32 m0, s5, 0x2000
	s_add_i32 s4, s4, s58
	global_load_lds_dwordx4 v[216:217], off
	s_mov_b32 m0, s4
	s_nop 0
	global_load_lds_dwordx4 v[230:231], off
	s_add_i32 m0, s4, 0x2000
	s_nop 0
	global_load_lds_dwordx4 v[232:233], off
	s_mov_b32 m0, s59
	s_nop 0
	global_load_lds_dwordx4 v[234:235], off
	s_mov_b32 m0, s60
	s_nop 0
	global_load_lds_dwordx4 v[236:237], off
	s_waitcnt vmcnt(8)
	s_waitcnt lgkmcnt(0)
	s_barrier
	s_waitcnt lgkmcnt(0)
	v_mfma_f32_16x16x32_bf16 v[60:63], v[128:131], v[160:163], v[60:63]
	v_mfma_f32_16x16x32_bf16 v[52:55], v[136:139], v[160:163], v[52:55]
	v_mfma_f32_16x16x32_bf16 v[44:47], v[128:131], v[168:171], v[44:47]
	v_mfma_f32_16x16x32_bf16 v[36:39], v[136:139], v[168:171], v[36:39]
	v_mfma_f32_16x16x32_bf16 v[28:31], v[128:131], v[198:201], v[28:31]
	v_mfma_f32_16x16x32_bf16 v[20:23], v[136:139], v[198:201], v[20:23]
	v_mfma_f32_16x16x32_bf16 v[12:15], v[128:131], v[206:209], v[12:15]
	v_mfma_f32_16x16x32_bf16 v[4:7], v[136:139], v[206:209], v[4:7]
	v_mfma_f32_16x16x32_bf16 v[60:63], v[132:135], v[164:167], v[60:63]
	v_mfma_f32_16x16x32_bf16 v[52:55], v[140:143], v[164:167], v[52:55]
	v_mfma_f32_16x16x32_bf16 v[44:47], v[132:135], v[172:175], v[44:47]
	v_mfma_f32_16x16x32_bf16 v[36:39], v[140:143], v[172:175], v[36:39]
	v_mfma_f32_16x16x32_bf16 v[28:31], v[132:135], v[202:205], v[28:31]
	v_mfma_f32_16x16x32_bf16 v[20:23], v[140:143], v[202:205], v[20:23]
	v_mfma_f32_16x16x32_bf16 v[12:15], v[132:135], v[210:213], v[12:15]
	v_mfma_f32_16x16x32_bf16 v[4:7], v[140:143], v[210:213], v[4:7]
	v_mfma_f32_16x16x32_bf16 v[56:59], v[144:147], v[160:163], v[56:59]
	v_mfma_f32_16x16x32_bf16 v[48:51], v[152:155], v[160:163], v[48:51]
	v_mfma_f32_16x16x32_bf16 v[40:43], v[144:147], v[168:171], v[40:43]
	v_mfma_f32_16x16x32_bf16 v[32:35], v[152:155], v[168:171], v[32:35]
	v_mfma_f32_16x16x32_bf16 v[24:27], v[144:147], v[198:201], v[24:27]
	v_mfma_f32_16x16x32_bf16 v[16:19], v[152:155], v[198:201], v[16:19]
	v_mfma_f32_16x16x32_bf16 v[8:11], v[144:147], v[206:209], v[8:11]
	v_mfma_f32_16x16x32_bf16 v[0:3], v[152:155], v[206:209], v[0:3]
	v_mfma_f32_16x16x32_bf16 v[56:59], v[148:151], v[164:167], v[56:59]
	v_mfma_f32_16x16x32_bf16 v[48:51], v[156:159], v[164:167], v[48:51]
	v_mfma_f32_16x16x32_bf16 v[40:43], v[148:151], v[172:175], v[40:43]
	v_mfma_f32_16x16x32_bf16 v[32:35], v[156:159], v[172:175], v[32:35]
	v_mfma_f32_16x16x32_bf16 v[24:27], v[148:151], v[202:205], v[24:27]
	v_mfma_f32_16x16x32_bf16 v[16:19], v[156:159], v[202:205], v[16:19]
	v_mfma_f32_16x16x32_bf16 v[8:11], v[148:151], v[210:213], v[8:11]
	v_mfma_f32_16x16x32_bf16 v[0:3], v[156:159], v[210:213], v[0:3]
	s_barrier
	s_add_i32 s4, 0, 0x18000
	s_add_i32 s5, 0, 0x1c000
	v_add_u32_e32 v140, s4, v223
	v_add_u32_e32 v156, s5, v223
	ds_read_b128 v[128:131], v140
	ds_read_b128 v[132:135], v140 offset:1024
	ds_read_b128 v[136:139], v140 offset:2048
	ds_read_b128 v[140:143], v140 offset:3072
	ds_read_b128 v[144:147], v156
	ds_read_b128 v[148:151], v156 offset:1024
	ds_read_b128 v[152:155], v156 offset:2048
	ds_read_b128 v[156:159], v156 offset:3072
	s_add_u32 s44, s44, s24
	s_addc_u32 s45, s45, s25
	s_mov_b32 m0, s61
	v_lshl_add_u64 v[238:239], s[44:45], 0, v[192:193]
	ds_read_b128 v[160:163], v228 offset:32768
	ds_read_b128 v[164:167], v228 offset:33792
	ds_read_b128 v[168:171], v228 offset:34816
	ds_read_b128 v[172:175], v228 offset:35840
	ds_read_b128 v[198:201], v228 offset:36864
	ds_read_b128 v[202:205], v228 offset:37888
	ds_read_b128 v[206:209], v228 offset:38912
	ds_read_b128 v[210:213], v228 offset:39936
	global_load_lds_dwordx4 v[238:239], off
	v_lshl_add_u64 v[238:239], s[44:45], 0, v[188:189]
	s_mov_b32 m0, s62
	s_nop 0
	global_load_lds_dwordx4 v[238:239], off
	s_waitcnt vmcnt(8)
	s_waitcnt lgkmcnt(0)
	s_barrier
	s_waitcnt lgkmcnt(0)
	v_mfma_f32_16x16x32_bf16 v[120:123], v[128:131], v[160:163], v[120:123]
	v_mfma_f32_16x16x32_bf16 v[116:119], v[136:139], v[160:163], v[116:119]
	v_lshl_add_u64 v[214:215], v[214:215], 0, s[14:15]
	v_mfma_f32_16x16x32_bf16 v[108:111], v[128:131], v[168:171], v[108:111]
	v_lshl_add_u64 v[216:217], v[216:217], 0, s[14:15]
	v_mfma_f32_16x16x32_bf16 v[100:103], v[136:139], v[168:171], v[100:103]
	v_lshl_add_u64 v[230:231], v[230:231], 0, s[14:15]
	v_mfma_f32_16x16x32_bf16 v[92:95], v[128:131], v[198:201], v[92:95]
	v_lshl_add_u64 v[232:233], v[232:233], 0, s[14:15]
	v_mfma_f32_16x16x32_bf16 v[84:87], v[136:139], v[198:201], v[84:87]
	v_lshl_add_u64 v[234:235], v[234:235], 0, s[14:15]
	v_mfma_f32_16x16x32_bf16 v[76:79], v[128:131], v[206:209], v[76:79]
	v_lshl_add_u64 v[236:237], v[236:237], 0, s[14:15]
	v_mfma_f32_16x16x32_bf16 v[68:71], v[136:139], v[206:209], v[68:71]
	v_mfma_f32_16x16x32_bf16 v[120:123], v[132:135], v[164:167], v[120:123]
	v_mfma_f32_16x16x32_bf16 v[116:119], v[140:143], v[164:167], v[116:119]
	v_mfma_f32_16x16x32_bf16 v[108:111], v[132:135], v[172:175], v[108:111]
	v_mfma_f32_16x16x32_bf16 v[100:103], v[140:143], v[172:175], v[100:103]
	v_mfma_f32_16x16x32_bf16 v[92:95], v[132:135], v[202:205], v[92:95]
	v_mfma_f32_16x16x32_bf16 v[84:87], v[140:143], v[202:205], v[84:87]
	v_mfma_f32_16x16x32_bf16 v[76:79], v[132:135], v[210:213], v[76:79]
	v_mfma_f32_16x16x32_bf16 v[68:71], v[140:143], v[210:213], v[68:71]
	v_mfma_f32_16x16x32_bf16 v[124:127], v[144:147], v[160:163], v[124:127]
	v_mfma_f32_16x16x32_bf16 v[112:115], v[152:155], v[160:163], v[112:115]
	v_mfma_f32_16x16x32_bf16 v[104:107], v[144:147], v[168:171], v[104:107]
	v_mfma_f32_16x16x32_bf16 v[96:99], v[152:155], v[168:171], v[96:99]
	v_mfma_f32_16x16x32_bf16 v[88:91], v[144:147], v[198:201], v[88:91]
	v_mfma_f32_16x16x32_bf16 v[80:83], v[152:155], v[198:201], v[80:83]
	v_mfma_f32_16x16x32_bf16 v[72:75], v[144:147], v[206:209], v[72:75]
	v_mfma_f32_16x16x32_bf16 v[64:67], v[152:155], v[206:209], v[64:67]
	v_mfma_f32_16x16x32_bf16 v[124:127], v[148:151], v[164:167], v[124:127]
	v_mfma_f32_16x16x32_bf16 v[112:115], v[156:159], v[164:167], v[112:115]
	v_mfma_f32_16x16x32_bf16 v[104:107], v[148:151], v[172:175], v[104:107]
	v_mfma_f32_16x16x32_bf16 v[96:99], v[156:159], v[172:175], v[96:99]
	v_mfma_f32_16x16x32_bf16 v[88:91], v[148:151], v[202:205], v[88:91]
	v_mfma_f32_16x16x32_bf16 v[80:83], v[156:159], v[202:205], v[80:83]
	v_mfma_f32_16x16x32_bf16 v[72:75], v[148:151], v[210:213], v[72:75]
	v_mfma_f32_16x16x32_bf16 v[64:67], v[156:159], v[210:213], v[64:67]
	s_barrier
	s_add_i32 s4, s4, s58
	s_mov_b32 m0, s4
	ds_read_b128 v[160:163], v228 offset:49152
	ds_read_b128 v[164:167], v228 offset:50176
	ds_read_b128 v[168:171], v228 offset:51200
	ds_read_b128 v[172:175], v228 offset:52224
	ds_read_b128 v[198:201], v228 offset:53248
	ds_read_b128 v[202:205], v228 offset:54272
	ds_read_b128 v[206:209], v228 offset:55296
	ds_read_b128 v[210:213], v228 offset:56320
	global_load_lds_dwordx4 v[214:215], off
	s_add_i32 m0, s4, 0x2000
	s_add_i32 s4, s5, s58
	global_load_lds_dwordx4 v[216:217], off
	s_mov_b32 m0, s4
	s_nop 0
	global_load_lds_dwordx4 v[230:231], off
	s_add_i32 m0, s4, 0x2000
	s_nop 0
	global_load_lds_dwordx4 v[232:233], off
	s_mov_b32 m0, s63
	s_nop 0
	global_load_lds_dwordx4 v[234:235], off
	s_mov_b32 m0, s66
	s_nop 0
	global_load_lds_dwordx4 v[236:237], off
	s_waitcnt vmcnt(8)
	s_waitcnt lgkmcnt(0)
	s_barrier
	s_waitcnt lgkmcnt(0)
	v_mfma_f32_16x16x32_bf16 v[60:63], v[128:131], v[160:163], v[60:63]
	s_add_u32 s42, s42, 0x100
	v_mfma_f32_16x16x32_bf16 v[52:55], v[136:139], v[160:163], v[52:55]
	s_addc_u32 s43, s43, 0
	v_mfma_f32_16x16x32_bf16 v[44:47], v[128:131], v[168:171], v[44:47]
	s_add_u32 s10, s10, 0x100
	v_mfma_f32_16x16x32_bf16 v[36:39], v[136:139], v[168:171], v[36:39]
	s_addc_u32 s11, s11, 0
	v_mfma_f32_16x16x32_bf16 v[28:31], v[128:131], v[198:201], v[28:31]
	s_mov_b32 s44, s47
	v_mfma_f32_16x16x32_bf16 v[20:23], v[136:139], v[198:201], v[20:23]
	s_cmp_ge_i32 s47, s67
	v_mfma_f32_16x16x32_bf16 v[12:15], v[128:131], v[206:209], v[12:15]
	s_cselect_b32 s99, 1, 0
	v_mfma_f32_16x16x32_bf16 v[4:7], v[136:139], v[206:209], v[4:7]
	s_add_i32 s47, s44, 2
	v_mfma_f32_16x16x32_bf16 v[60:63], v[132:135], v[164:167], v[60:63]
	s_add_u32 s4, s42, 0x80
	v_mfma_f32_16x16x32_bf16 v[52:55], v[140:143], v[164:167], v[52:55]
	s_addc_u32 s5, s43, 0
	v_mfma_f32_16x16x32_bf16 v[44:47], v[132:135], v[172:175], v[44:47]
	s_add_i32 s54, 0, 0x10000
	v_mfma_f32_16x16x32_bf16 v[36:39], v[140:143], v[172:175], v[36:39]
	s_cmp_eq_u32 s69, s44
	v_mfma_f32_16x16x32_bf16 v[28:31], v[132:135], v[202:205], v[28:31]
	s_cselect_b32 s45, s13, s5
	v_mfma_f32_16x16x32_bf16 v[20:23], v[140:143], v[202:205], v[20:23]
	s_cselect_b32 s44, s12, s4
	v_mfma_f32_16x16x32_bf16 v[12:15], v[132:135], v[210:213], v[12:15]
	s_cselect_b32 vcc_hi, s1, s11
	v_mfma_f32_16x16x32_bf16 v[4:7], v[140:143], v[210:213], v[4:7]
	s_cselect_b32 vcc_lo, s0, s10
	v_mfma_f32_16x16x32_bf16 v[56:59], v[144:147], v[160:163], v[56:59]
	s_add_i32 s4, 0, 0x14000
	v_mfma_f32_16x16x32_bf16 v[48:51], v[152:155], v[160:163], v[48:51]
	v_mfma_f32_16x16x32_bf16 v[40:43], v[144:147], v[168:171], v[40:43]
	v_mfma_f32_16x16x32_bf16 v[32:35], v[152:155], v[168:171], v[32:35]
	v_mfma_f32_16x16x32_bf16 v[24:27], v[144:147], v[198:201], v[24:27]
	v_mfma_f32_16x16x32_bf16 v[16:19], v[152:155], v[198:201], v[16:19]
	v_mfma_f32_16x16x32_bf16 v[8:11], v[144:147], v[206:209], v[8:11]
	v_mfma_f32_16x16x32_bf16 v[0:3], v[152:155], v[206:209], v[0:3]
	v_mfma_f32_16x16x32_bf16 v[56:59], v[148:151], v[164:167], v[56:59]
	v_mfma_f32_16x16x32_bf16 v[48:51], v[156:159], v[164:167], v[48:51]
	v_mfma_f32_16x16x32_bf16 v[40:43], v[148:151], v[172:175], v[40:43]
	v_mfma_f32_16x16x32_bf16 v[32:35], v[156:159], v[172:175], v[32:35]
	v_mfma_f32_16x16x32_bf16 v[24:27], v[148:151], v[202:205], v[24:27]
	v_mfma_f32_16x16x32_bf16 v[16:19], v[156:159], v[202:205], v[16:19]
	v_mfma_f32_16x16x32_bf16 v[8:11], v[148:151], v[210:213], v[8:11]
	v_mfma_f32_16x16x32_bf16 v[0:3], v[156:159], v[210:213], v[0:3]
	s_barrier
	s_cmp_lg_u32 s99, 0
	s_cbranch_scc0 .LBB0_155

.Llbb_1:
	s_add_i32 s44, s34, 2
	s_add_u32 s4, s30, 0x80
	s_addc_u32 s5, s31, 0
	s_add_i32 s45, 0, 0x10000
	s_cmp_eq_u32 s62, s34
	s_cselect_b32 s35, s27, s5
	s_cselect_b32 s34, s26, s4
	s_cselect_b32 s5, s29, s11
	s_cselect_b32 s4, s28, s10
	s_add_i32 s54, 0, 0x14000
	v_add_u32_e32 v140, s45, v195
	v_add_u32_e32 v166, s54, v195
	ds_read_b128 v[128:131], v140
	ds_read_b128 v[132:135], v140 offset:1024
	ds_read_b128 v[136:139], v140 offset:2048
	ds_read_b128 v[140:143], v140 offset:3072
	ds_read_b128 v[144:147], v166
	ds_read_b128 v[148:151], v166 offset:1024
	ds_read_b128 v[152:155], v166 offset:2048
	ds_read_b128 v[166:169], v166 offset:3072
	v_lshl_add_u64 v[174:175], s[30:31], 0, v[162:163]
	s_add_i32 m0, s38, 0xc000
	ds_read_b128 v[170:173], v197
	ds_read_b128 v[186:189], v197 offset:1024
	ds_read_b128 v[190:193], v197 offset:2048
	ds_read_b128 v[198:201], v197 offset:3072
	ds_read_b128 v[202:205], v197 offset:4096
	ds_read_b128 v[206:209], v197 offset:5120
	ds_read_b128 v[210:213], v197 offset:6144
	ds_read_b128 v[214:217], v197 offset:7168
	global_load_lds_dwordx4 v[174:175], off
	v_lshl_add_u64 v[174:175], s[30:31], 0, v[164:165]
	s_add_i32 m0, s38, 0xe000
	s_nop 0
	global_load_lds_dwordx4 v[174:175], off
	s_waitcnt vmcnt(8)
	s_waitcnt lgkmcnt(0)
	s_barrier
	s_waitcnt lgkmcnt(0)
	v_mfma_f32_16x16x32_bf16 v[120:123], v[128:131], v[170:173], 0
	v_mfma_f32_16x16x32_bf16 v[124:127], v[136:139], v[170:173], 0
	v_lshl_add_u64 v[174:175], s[4:5], 0, v[176:177]
	v_mfma_f32_16x16x32_bf16 v[108:111], v[128:131], v[190:193], 0
	v_lshl_add_u64 v[222:223], s[4:5], 0, v[156:157]
	v_mfma_f32_16x16x32_bf16 v[104:107], v[136:139], v[190:193], 0
	s_add_u32 s4, s4, s0
	v_mfma_f32_16x16x32_bf16 v[92:95], v[128:131], v[202:205], 0
	s_addc_u32 s5, s5, s1
	v_mfma_f32_16x16x32_bf16 v[88:91], v[136:139], v[202:205], 0
	v_lshl_add_u64 v[224:225], s[4:5], 0, v[176:177]
	v_mfma_f32_16x16x32_bf16 v[76:79], v[128:131], v[210:213], 0
	v_lshl_add_u64 v[226:227], s[4:5], 0, v[156:157]
	v_mfma_f32_16x16x32_bf16 v[72:75], v[136:139], v[210:213], 0
	v_lshl_add_u64 v[228:229], s[34:35], 0, v[160:161]
	v_mfma_f32_16x16x32_bf16 v[120:123], v[132:135], v[186:189], v[120:123]
	v_lshl_add_u64 v[230:231], s[34:35], 0, v[158:159]
	v_mfma_f32_16x16x32_bf16 v[124:127], v[140:143], v[186:189], v[124:127]
	v_mfma_f32_16x16x32_bf16 v[108:111], v[132:135], v[198:201], v[108:111]
	v_mfma_f32_16x16x32_bf16 v[104:107], v[140:143], v[198:201], v[104:107]
	v_mfma_f32_16x16x32_bf16 v[92:95], v[132:135], v[206:209], v[92:95]
	v_mfma_f32_16x16x32_bf16 v[88:91], v[140:143], v[206:209], v[88:91]
	v_mfma_f32_16x16x32_bf16 v[76:79], v[132:135], v[214:217], v[76:79]
	v_mfma_f32_16x16x32_bf16 v[72:75], v[140:143], v[214:217], v[72:75]
	v_mfma_f32_16x16x32_bf16 v[116:119], v[144:147], v[170:173], 0
	v_mfma_f32_16x16x32_bf16 v[112:115], v[152:155], v[170:173], 0
	v_mfma_f32_16x16x32_bf16 v[100:103], v[144:147], v[190:193], 0
	v_mfma_f32_16x16x32_bf16 v[96:99], v[152:155], v[190:193], 0
	v_mfma_f32_16x16x32_bf16 v[84:87], v[144:147], v[202:205], 0
	v_mfma_f32_16x16x32_bf16 v[80:83], v[152:155], v[202:205], 0
	v_mfma_f32_16x16x32_bf16 v[68:71], v[144:147], v[210:213], 0
	v_mfma_f32_16x16x32_bf16 v[64:67], v[152:155], v[210:213], 0
	v_mfma_f32_16x16x32_bf16 v[116:119], v[148:151], v[186:189], v[116:119]
	v_mfma_f32_16x16x32_bf16 v[112:115], v[166:169], v[186:189], v[112:115]
	v_mfma_f32_16x16x32_bf16 v[100:103], v[148:151], v[198:201], v[100:103]
	v_mfma_f32_16x16x32_bf16 v[96:99], v[166:169], v[198:201], v[96:99]
	v_mfma_f32_16x16x32_bf16 v[84:87], v[148:151], v[206:209], v[84:87]
	v_mfma_f32_16x16x32_bf16 v[80:83], v[166:169], v[206:209], v[80:83]
	v_mfma_f32_16x16x32_bf16 v[68:71], v[148:151], v[214:217], v[68:71]
	v_mfma_f32_16x16x32_bf16 v[64:67], v[166:169], v[214:217], v[64:67]
	s_barrier
	s_add_i32 s45, s45, s37
	s_mov_b32 m0, s45
	ds_read_b128 v[170:173], v197 offset:16384
	ds_read_b128 v[186:189], v197 offset:17408
	ds_read_b128 v[190:193], v197 offset:18432
	ds_read_b128 v[198:201], v197 offset:19456
	ds_read_b128 v[202:205], v197 offset:20480
	ds_read_b128 v[206:209], v197 offset:21504
	ds_read_b128 v[210:213], v197 offset:22528
	ds_read_b128 v[214:217], v197 offset:23552
	global_load_lds_dwordx4 v[174:175], off
	s_add_i32 m0, s45, 0x2000
	s_add_i32 s45, s54, s37
	global_load_lds_dwordx4 v[222:223], off
	s_mov_b32 m0, s45
	s_nop 0
	global_load_lds_dwordx4 v[224:225], off
	s_add_i32 m0, s45, 0x2000
	s_nop 0
	global_load_lds_dwordx4 v[226:227], off
	s_mov_b32 m0, s38
	s_nop 0
	global_load_lds_dwordx4 v[228:229], off
	s_mov_b32 m0, s39
	s_nop 0
	global_load_lds_dwordx4 v[230:231], off
	s_waitcnt vmcnt(8)
	s_waitcnt lgkmcnt(0)
	s_barrier
	s_waitcnt lgkmcnt(0)
	v_mfma_f32_16x16x32_bf16 v[60:63], v[128:131], v[170:173], 0
	v_mfma_f32_16x16x32_bf16 v[56:59], v[136:139], v[170:173], 0
	v_mfma_f32_16x16x32_bf16 v[44:47], v[128:131], v[190:193], 0
	v_mfma_f32_16x16x32_bf16 v[40:43], v[136:139], v[190:193], 0
	v_mfma_f32_16x16x32_bf16 v[28:31], v[128:131], v[202:205], 0
	v_mfma_f32_16x16x32_bf16 v[24:27], v[136:139], v[202:205], 0
	v_mfma_f32_16x16x32_bf16 v[12:15], v[128:131], v[210:213], 0
	v_mfma_f32_16x16x32_bf16 v[8:11], v[136:139], v[210:213], 0
	v_mfma_f32_16x16x32_bf16 v[60:63], v[132:135], v[186:189], v[60:63]
	v_mfma_f32_16x16x32_bf16 v[56:59], v[140:143], v[186:189], v[56:59]
	v_mfma_f32_16x16x32_bf16 v[44:47], v[132:135], v[198:201], v[44:47]
	v_mfma_f32_16x16x32_bf16 v[40:43], v[140:143], v[198:201], v[40:43]
	v_mfma_f32_16x16x32_bf16 v[28:31], v[132:135], v[206:209], v[28:31]
	v_mfma_f32_16x16x32_bf16 v[24:27], v[140:143], v[206:209], v[24:27]
	v_mfma_f32_16x16x32_bf16 v[12:15], v[132:135], v[214:217], v[12:15]
	v_mfma_f32_16x16x32_bf16 v[8:11], v[140:143], v[214:217], v[8:11]
	v_mfma_f32_16x16x32_bf16 v[52:55], v[144:147], v[170:173], 0
	v_mfma_f32_16x16x32_bf16 v[48:51], v[152:155], v[170:173], 0
	v_mfma_f32_16x16x32_bf16 v[36:39], v[144:147], v[190:193], 0
	v_mfma_f32_16x16x32_bf16 v[32:35], v[152:155], v[190:193], 0
	v_mfma_f32_16x16x32_bf16 v[20:23], v[144:147], v[202:205], 0
	v_mfma_f32_16x16x32_bf16 v[16:19], v[152:155], v[202:205], 0
	v_mfma_f32_16x16x32_bf16 v[4:7], v[144:147], v[210:213], 0
	v_mfma_f32_16x16x32_bf16 v[0:3], v[152:155], v[210:213], 0
	v_mfma_f32_16x16x32_bf16 v[52:55], v[148:151], v[186:189], v[52:55]
	v_mfma_f32_16x16x32_bf16 v[48:51], v[166:169], v[186:189], v[48:51]
	v_mfma_f32_16x16x32_bf16 v[36:39], v[148:151], v[198:201], v[36:39]
	v_mfma_f32_16x16x32_bf16 v[32:35], v[166:169], v[198:201], v[32:35]
	v_mfma_f32_16x16x32_bf16 v[20:23], v[148:151], v[206:209], v[20:23]
	v_mfma_f32_16x16x32_bf16 v[16:19], v[166:169], v[206:209], v[16:19]
	v_mfma_f32_16x16x32_bf16 v[4:7], v[148:151], v[214:217], v[4:7]
	v_mfma_f32_16x16x32_bf16 v[0:3], v[166:169], v[214:217], v[0:3]
	s_barrier
	s_add_i32 s45, 0, 0x18000
	s_add_i32 s54, 0, 0x1c000
	v_add_u32_e32 v140, s45, v195
	v_add_u32_e32 v166, s54, v195
	ds_read_b128 v[128:131], v140
	ds_read_b128 v[132:135], v140 offset:1024
	ds_read_b128 v[136:139], v140 offset:2048
	ds_read_b128 v[140:143], v140 offset:3072
	ds_read_b128 v[144:147], v166
	ds_read_b128 v[148:151], v166 offset:1024
	ds_read_b128 v[152:155], v166 offset:2048
	ds_read_b128 v[166:169], v166 offset:3072
	s_add_u32 s4, s34, s0
	s_addc_u32 s5, s35, s1
	s_mov_b32 m0, s48
	v_lshl_add_u64 v[232:233], s[4:5], 0, v[160:161]
	ds_read_b128 v[170:173], v197 offset:32768
	ds_read_b128 v[186:189], v197 offset:33792
	ds_read_b128 v[190:193], v197 offset:34816
	ds_read_b128 v[198:201], v197 offset:35840
	ds_read_b128 v[202:205], v197 offset:36864
	ds_read_b128 v[206:209], v197 offset:37888
	ds_read_b128 v[210:213], v197 offset:38912
	ds_read_b128 v[214:217], v197 offset:39936
	global_load_lds_dwordx4 v[232:233], off
	v_lshl_add_u64 v[232:233], s[4:5], 0, v[158:159]
	s_mov_b32 m0, s49
	s_nop 0
	global_load_lds_dwordx4 v[232:233], off
	s_waitcnt vmcnt(8)
	s_waitcnt lgkmcnt(0)
	s_barrier
	s_waitcnt lgkmcnt(0)
	v_mfma_f32_16x16x32_bf16 v[120:123], v[128:131], v[170:173], v[120:123]
	v_mfma_f32_16x16x32_bf16 v[124:127], v[136:139], v[170:173], v[124:127]
	v_lshl_add_u64 v[174:175], v[174:175], 0, s[14:15]
	v_mfma_f32_16x16x32_bf16 v[108:111], v[128:131], v[190:193], v[108:111]
	v_lshl_add_u64 v[222:223], v[222:223], 0, s[14:15]
	v_mfma_f32_16x16x32_bf16 v[104:107], v[136:139], v[190:193], v[104:107]
	v_lshl_add_u64 v[224:225], v[224:225], 0, s[14:15]
	v_mfma_f32_16x16x32_bf16 v[92:95], v[128:131], v[202:205], v[92:95]
	v_lshl_add_u64 v[226:227], v[226:227], 0, s[14:15]
	v_mfma_f32_16x16x32_bf16 v[88:91], v[136:139], v[202:205], v[88:91]
	v_lshl_add_u64 v[228:229], v[228:229], 0, s[14:15]
	v_mfma_f32_16x16x32_bf16 v[76:79], v[128:131], v[210:213], v[76:79]
	v_lshl_add_u64 v[230:231], v[230:231], 0, s[14:15]
	v_mfma_f32_16x16x32_bf16 v[72:75], v[136:139], v[210:213], v[72:75]
	v_mfma_f32_16x16x32_bf16 v[120:123], v[132:135], v[186:189], v[120:123]
	v_mfma_f32_16x16x32_bf16 v[124:127], v[140:143], v[186:189], v[124:127]
	v_mfma_f32_16x16x32_bf16 v[108:111], v[132:135], v[198:201], v[108:111]
	v_mfma_f32_16x16x32_bf16 v[104:107], v[140:143], v[198:201], v[104:107]
	v_mfma_f32_16x16x32_bf16 v[92:95], v[132:135], v[206:209], v[92:95]
	v_mfma_f32_16x16x32_bf16 v[88:91], v[140:143], v[206:209], v[88:91]
	v_mfma_f32_16x16x32_bf16 v[76:79], v[132:135], v[214:217], v[76:79]
	v_mfma_f32_16x16x32_bf16 v[72:75], v[140:143], v[214:217], v[72:75]
	v_mfma_f32_16x16x32_bf16 v[116:119], v[144:147], v[170:173], v[116:119]
	v_mfma_f32_16x16x32_bf16 v[112:115], v[152:155], v[170:173], v[112:115]
	v_mfma_f32_16x16x32_bf16 v[100:103], v[144:147], v[190:193], v[100:103]
	v_mfma_f32_16x16x32_bf16 v[96:99], v[152:155], v[190:193], v[96:99]
	v_mfma_f32_16x16x32_bf16 v[84:87], v[144:147], v[202:205], v[84:87]
	v_mfma_f32_16x16x32_bf16 v[80:83], v[152:155], v[202:205], v[80:83]
	v_mfma_f32_16x16x32_bf16 v[68:71], v[144:147], v[210:213], v[68:71]
	v_mfma_f32_16x16x32_bf16 v[64:67], v[152:155], v[210:213], v[64:67]
	v_mfma_f32_16x16x32_bf16 v[116:119], v[148:151], v[186:189], v[116:119]
	v_mfma_f32_16x16x32_bf16 v[112:115], v[166:169], v[186:189], v[112:115]
	v_mfma_f32_16x16x32_bf16 v[100:103], v[148:151], v[198:201], v[100:103]
	v_mfma_f32_16x16x32_bf16 v[96:99], v[166:169], v[198:201], v[96:99]
	v_mfma_f32_16x16x32_bf16 v[84:87], v[148:151], v[206:209], v[84:87]
	v_mfma_f32_16x16x32_bf16 v[80:83], v[166:169], v[206:209], v[80:83]
	v_mfma_f32_16x16x32_bf16 v[68:71], v[148:151], v[214:217], v[68:71]
	v_mfma_f32_16x16x32_bf16 v[64:67], v[166:169], v[214:217], v[64:67]
	s_barrier
	s_add_i32 s4, s45, s37
	s_mov_b32 m0, s4
	ds_read_b128 v[170:173], v197 offset:49152
	ds_read_b128 v[186:189], v197 offset:50176
	ds_read_b128 v[190:193], v197 offset:51200
	ds_read_b128 v[198:201], v197 offset:52224
	ds_read_b128 v[202:205], v197 offset:53248
	ds_read_b128 v[206:209], v197 offset:54272
	ds_read_b128 v[210:213], v197 offset:55296
	ds_read_b128 v[214:217], v197 offset:56320
	global_load_lds_dwordx4 v[174:175], off
	s_add_i32 m0, s4, 0x2000
	s_add_i32 s4, s54, s37
	global_load_lds_dwordx4 v[222:223], off
	s_mov_b32 m0, s4
	s_nop 0
	global_load_lds_dwordx4 v[224:225], off
	s_add_i32 m0, s4, 0x2000
	s_nop 0
	global_load_lds_dwordx4 v[226:227], off
	s_mov_b32 m0, s60
	s_nop 0
	global_load_lds_dwordx4 v[228:229], off
	s_mov_b32 m0, s61
	s_nop 0
	global_load_lds_dwordx4 v[230:231], off
	s_waitcnt vmcnt(8)
	s_waitcnt lgkmcnt(0)
	s_barrier
	s_waitcnt lgkmcnt(0)
	v_mfma_f32_16x16x32_bf16 v[60:63], v[128:131], v[170:173], v[60:63]
	s_add_u32 s30, s30, 0x100
	v_mfma_f32_16x16x32_bf16 v[56:59], v[136:139], v[170:173], v[56:59]
	s_addc_u32 s31, s31, 0
	v_mfma_f32_16x16x32_bf16 v[44:47], v[128:131], v[190:193], v[44:47]
	s_add_u32 s10, s10, 0x100
	v_mfma_f32_16x16x32_bf16 v[40:43], v[136:139], v[190:193], v[40:43]
	s_addc_u32 s11, s11, 0
	v_mfma_f32_16x16x32_bf16 v[28:31], v[128:131], v[202:205], v[28:31]
	s_mov_b32 s34, s44
	v_mfma_f32_16x16x32_bf16 v[24:27], v[136:139], v[202:205], v[24:27]
	s_cmp_ge_i32 s44, s59
	v_mfma_f32_16x16x32_bf16 v[12:15], v[128:131], v[210:213], v[12:15]
	s_cselect_b32 s99, 1, 0
	v_mfma_f32_16x16x32_bf16 v[8:11], v[136:139], v[210:213], v[8:11]
	s_add_i32 s44, s34, 2
	v_mfma_f32_16x16x32_bf16 v[60:63], v[132:135], v[186:189], v[60:63]
	s_add_u32 s4, s30, 0x80
	v_mfma_f32_16x16x32_bf16 v[56:59], v[140:143], v[186:189], v[56:59]
	s_addc_u32 s5, s31, 0
	v_mfma_f32_16x16x32_bf16 v[44:47], v[132:135], v[198:201], v[44:47]
	s_add_i32 s45, 0, 0x10000
	v_mfma_f32_16x16x32_bf16 v[40:43], v[140:143], v[198:201], v[40:43]
	s_cmp_eq_u32 s62, s34
	v_mfma_f32_16x16x32_bf16 v[28:31], v[132:135], v[206:209], v[28:31]
	s_cselect_b32 s35, s27, s5
	v_mfma_f32_16x16x32_bf16 v[24:27], v[140:143], v[206:209], v[24:27]
	s_cselect_b32 s34, s26, s4
	v_mfma_f32_16x16x32_bf16 v[12:15], v[132:135], v[214:217], v[12:15]
	s_cselect_b32 s5, s29, s11
	v_mfma_f32_16x16x32_bf16 v[8:11], v[140:143], v[214:217], v[8:11]
	s_cselect_b32 s4, s28, s10
	v_mfma_f32_16x16x32_bf16 v[52:55], v[144:147], v[170:173], v[52:55]
	s_add_i32 s54, 0, 0x14000
	v_mfma_f32_16x16x32_bf16 v[48:51], v[152:155], v[170:173], v[48:51]
	v_mfma_f32_16x16x32_bf16 v[36:39], v[144:147], v[190:193], v[36:39]
	v_mfma_f32_16x16x32_bf16 v[32:35], v[152:155], v[190:193], v[32:35]
	v_mfma_f32_16x16x32_bf16 v[20:23], v[144:147], v[202:205], v[20:23]
	v_mfma_f32_16x16x32_bf16 v[16:19], v[152:155], v[202:205], v[16:19]
	v_mfma_f32_16x16x32_bf16 v[4:7], v[144:147], v[210:213], v[4:7]
	v_mfma_f32_16x16x32_bf16 v[0:3], v[152:155], v[210:213], v[0:3]
	v_mfma_f32_16x16x32_bf16 v[52:55], v[148:151], v[186:189], v[52:55]
	v_mfma_f32_16x16x32_bf16 v[48:51], v[166:169], v[186:189], v[48:51]
	v_mfma_f32_16x16x32_bf16 v[36:39], v[148:151], v[198:201], v[36:39]
	v_mfma_f32_16x16x32_bf16 v[32:35], v[166:169], v[198:201], v[32:35]
	v_mfma_f32_16x16x32_bf16 v[20:23], v[148:151], v[206:209], v[20:23]
	v_mfma_f32_16x16x32_bf16 v[16:19], v[166:169], v[206:209], v[16:19]
	v_mfma_f32_16x16x32_bf16 v[4:7], v[148:151], v[214:217], v[4:7]
	v_mfma_f32_16x16x32_bf16 v[0:3], v[166:169], v[214:217], v[0:3]
	s_barrier
	s_cmp_lg_u32 s99, 0
	s_cbranch_scc1 .Lpeelx_5
.LBB0_262:
	v_add_u32_e32 v140, s45, v195
	v_add_u32_e32 v166, s54, v195
	ds_read_b128 v[128:131], v140
	ds_read_b128 v[132:135], v140 offset:1024
	ds_read_b128 v[136:139], v140 offset:2048
	ds_read_b128 v[140:143], v140 offset:3072
	ds_read_b128 v[144:147], v166
	ds_read_b128 v[148:151], v166 offset:1024
	ds_read_b128 v[152:155], v166 offset:2048
	ds_read_b128 v[166:169], v166 offset:3072
	v_lshl_add_u64 v[174:175], s[30:31], 0, v[162:163]
	s_add_i32 m0, s38, 0xc000
	ds_read_b128 v[170:173], v197
	ds_read_b128 v[186:189], v197 offset:1024
	ds_read_b128 v[190:193], v197 offset:2048
	ds_read_b128 v[198:201], v197 offset:3072
	ds_read_b128 v[202:205], v197 offset:4096
	ds_read_b128 v[206:209], v197 offset:5120
	ds_read_b128 v[210:213], v197 offset:6144
	ds_read_b128 v[214:217], v197 offset:7168
	global_load_lds_dwordx4 v[174:175], off
	v_lshl_add_u64 v[174:175], s[30:31], 0, v[164:165]
	s_add_i32 m0, s38, 0xe000
	s_nop 0
	global_load_lds_dwordx4 v[174:175], off
	s_waitcnt vmcnt(8)
	s_waitcnt lgkmcnt(0)
	s_barrier
	s_waitcnt lgkmcnt(0)
	v_mfma_f32_16x16x32_bf16 v[120:123], v[128:131], v[170:173], v[120:123]
	v_mfma_f32_16x16x32_bf16 v[124:127], v[136:139], v[170:173], v[124:127]
	v_lshl_add_u64 v[174:175], s[4:5], 0, v[176:177]
	v_mfma_f32_16x16x32_bf16 v[108:111], v[128:131], v[190:193], v[108:111]
	v_lshl_add_u64 v[222:223], s[4:5], 0, v[156:157]
	v_mfma_f32_16x16x32_bf16 v[104:107], v[136:139], v[190:193], v[104:107]
	s_add_u32 s4, s4, s0
	v_mfma_f32_16x16x32_bf16 v[92:95], v[128:131], v[202:205], v[92:95]
	s_addc_u32 s5, s5, s1
	v_mfma_f32_16x16x32_bf16 v[88:91], v[136:139], v[202:205], v[88:91]
	v_lshl_add_u64 v[224:225], s[4:5], 0, v[176:177]
	v_mfma_f32_16x16x32_bf16 v[76:79], v[128:131], v[210:213], v[76:79]
	v_lshl_add_u64 v[226:227], s[4:5], 0, v[156:157]
	v_mfma_f32_16x16x32_bf16 v[72:75], v[136:139], v[210:213], v[72:75]
	v_lshl_add_u64 v[228:229], s[34:35], 0, v[160:161]
	v_mfma_f32_16x16x32_bf16 v[120:123], v[132:135], v[186:189], v[120:123]
	v_lshl_add_u64 v[230:231], s[34:35], 0, v[158:159]
	v_mfma_f32_16x16x32_bf16 v[124:127], v[140:143], v[186:189], v[124:127]
	v_mfma_f32_16x16x32_bf16 v[108:111], v[132:135], v[198:201], v[108:111]
	v_mfma_f32_16x16x32_bf16 v[104:107], v[140:143], v[198:201], v[104:107]
	v_mfma_f32_16x16x32_bf16 v[92:95], v[132:135], v[206:209], v[92:95]
	v_mfma_f32_16x16x32_bf16 v[88:91], v[140:143], v[206:209], v[88:91]
	v_mfma_f32_16x16x32_bf16 v[76:79], v[132:135], v[214:217], v[76:79]
	v_mfma_f32_16x16x32_bf16 v[72:75], v[140:143], v[214:217], v[72:75]
	v_mfma_f32_16x16x32_bf16 v[116:119], v[144:147], v[170:173], v[116:119]
	v_mfma_f32_16x16x32_bf16 v[112:115], v[152:155], v[170:173], v[112:115]
	v_mfma_f32_16x16x32_bf16 v[100:103], v[144:147], v[190:193], v[100:103]
	v_mfma_f32_16x16x32_bf16 v[96:99], v[152:155], v[190:193], v[96:99]
	v_mfma_f32_16x16x32_bf16 v[84:87], v[144:147], v[202:205], v[84:87]
	v_mfma_f32_16x16x32_bf16 v[80:83], v[152:155], v[202:205], v[80:83]
	v_mfma_f32_16x16x32_bf16 v[68:71], v[144:147], v[210:213], v[68:71]
	v_mfma_f32_16x16x32_bf16 v[64:67], v[152:155], v[210:213], v[64:67]
	v_mfma_f32_16x16x32_bf16 v[116:119], v[148:151], v[186:189], v[116:119]
	v_mfma_f32_16x16x32_bf16 v[112:115], v[166:169], v[186:189], v[112:115]
	v_mfma_f32_16x16x32_bf16 v[100:103], v[148:151], v[198:201], v[100:103]
	v_mfma_f32_16x16x32_bf16 v[96:99], v[166:169], v[198:201], v[96:99]
	v_mfma_f32_16x16x32_bf16 v[84:87], v[148:151], v[206:209], v[84:87]
	v_mfma_f32_16x16x32_bf16 v[80:83], v[166:169], v[206:209], v[80:83]
	v_mfma_f32_16x16x32_bf16 v[68:71], v[148:151], v[214:217], v[68:71]
	v_mfma_f32_16x16x32_bf16 v[64:67], v[166:169], v[214:217], v[64:67]
	s_barrier
	s_add_i32 s45, s45, s37
	s_mov_b32 m0, s45
	ds_read_b128 v[170:173], v197 offset:16384
	ds_read_b128 v[186:189], v197 offset:17408
	ds_read_b128 v[190:193], v197 offset:18432
	ds_read_b128 v[198:201], v197 offset:19456
	ds_read_b128 v[202:205], v197 offset:20480
	ds_read_b128 v[206:209], v197 offset:21504
	ds_read_b128 v[210:213], v197 offset:22528
	ds_read_b128 v[214:217], v197 offset:23552
	global_load_lds_dwordx4 v[174:175], off
	s_add_i32 m0, s45, 0x2000
	s_add_i32 s45, s54, s37
	global_load_lds_dwordx4 v[222:223], off
	s_mov_b32 m0, s45
	s_nop 0
	global_load_lds_dwordx4 v[224:225], off
	s_add_i32 m0, s45, 0x2000
	s_nop 0
	global_load_lds_dwordx4 v[226:227], off
	s_mov_b32 m0, s38
	s_nop 0
	global_load_lds_dwordx4 v[228:229], off
	s_mov_b32 m0, s39
	s_nop 0
	global_load_lds_dwordx4 v[230:231], off
	s_waitcnt vmcnt(8)
	s_waitcnt lgkmcnt(0)
	s_barrier
	s_waitcnt lgkmcnt(0)
	v_mfma_f32_16x16x32_bf16 v[60:63], v[128:131], v[170:173], v[60:63]
	v_mfma_f32_16x16x32_bf16 v[56:59], v[136:139], v[170:173], v[56:59]
	v_mfma_f32_16x16x32_bf16 v[44:47], v[128:131], v[190:193], v[44:47]
	v_mfma_f32_16x16x32_bf16 v[40:43], v[136:139], v[190:193], v[40:43]
	v_mfma_f32_16x16x32_bf16 v[28:31], v[128:131], v[202:205], v[28:31]
	v_mfma_f32_16x16x32_bf16 v[24:27], v[136:139], v[202:205], v[24:27]
	v_mfma_f32_16x16x32_bf16 v[12:15], v[128:131], v[210:213], v[12:15]
	v_mfma_f32_16x16x32_bf16 v[8:11], v[136:139], v[210:213], v[8:11]
	v_mfma_f32_16x16x32_bf16 v[60:63], v[132:135], v[186:189], v[60:63]
	v_mfma_f32_16x16x32_bf16 v[56:59], v[140:143], v[186:189], v[56:59]
	v_mfma_f32_16x16x32_bf16 v[44:47], v[132:135], v[198:201], v[44:47]
	v_mfma_f32_16x16x32_bf16 v[40:43], v[140:143], v[198:201], v[40:43]
	v_mfma_f32_16x16x32_bf16 v[28:31], v[132:135], v[206:209], v[28:31]
	v_mfma_f32_16x16x32_bf16 v[24:27], v[140:143], v[206:209], v[24:27]
	v_mfma_f32_16x16x32_bf16 v[12:15], v[132:135], v[214:217], v[12:15]
	v_mfma_f32_16x16x32_bf16 v[8:11], v[140:143], v[214:217], v[8:11]
	v_mfma_f32_16x16x32_bf16 v[52:55], v[144:147], v[170:173], v[52:55]
	v_mfma_f32_16x16x32_bf16 v[48:51], v[152:155], v[170:173], v[48:51]
	v_mfma_f32_16x16x32_bf16 v[36:39], v[144:147], v[190:193], v[36:39]
	v_mfma_f32_16x16x32_bf16 v[32:35], v[152:155], v[190:193], v[32:35]
	v_mfma_f32_16x16x32_bf16 v[20:23], v[144:147], v[202:205], v[20:23]
	v_mfma_f32_16x16x32_bf16 v[16:19], v[152:155], v[202:205], v[16:19]
	v_mfma_f32_16x16x32_bf16 v[4:7], v[144:147], v[210:213], v[4:7]
	v_mfma_f32_16x16x32_bf16 v[0:3], v[152:155], v[210:213], v[0:3]
	v_mfma_f32_16x16x32_bf16 v[52:55], v[148:151], v[186:189], v[52:55]
	v_mfma_f32_16x16x32_bf16 v[48:51], v[166:169], v[186:189], v[48:51]
	v_mfma_f32_16x16x32_bf16 v[36:39], v[148:151], v[198:201], v[36:39]
	v_mfma_f32_16x16x32_bf16 v[32:35], v[166:169], v[198:201], v[32:35]
	v_mfma_f32_16x16x32_bf16 v[20:23], v[148:151], v[206:209], v[20:23]
	v_mfma_f32_16x16x32_bf16 v[16:19], v[166:169], v[206:209], v[16:19]
	v_mfma_f32_16x16x32_bf16 v[4:7], v[148:151], v[214:217], v[4:7]
	v_mfma_f32_16x16x32_bf16 v[0:3], v[166:169], v[214:217], v[0:3]
	s_barrier
	s_add_i32 s45, 0, 0x18000
	s_add_i32 s54, 0, 0x1c000
	v_add_u32_e32 v140, s45, v195
	v_add_u32_e32 v166, s54, v195
	ds_read_b128 v[128:131], v140
	ds_read_b128 v[132:135], v140 offset:1024
	ds_read_b128 v[136:139], v140 offset:2048
	ds_read_b128 v[140:143], v140 offset:3072
	ds_read_b128 v[144:147], v166
	ds_read_b128 v[148:151], v166 offset:1024
	ds_read_b128 v[152:155], v166 offset:2048
	ds_read_b128 v[166:169], v166 offset:3072
	s_add_u32 s4, s34, s0
	s_addc_u32 s5, s35, s1
	s_mov_b32 m0, s48
	v_lshl_add_u64 v[232:233], s[4:5], 0, v[160:161]
	ds_read_b128 v[170:173], v197 offset:32768
	ds_read_b128 v[186:189], v197 offset:33792
	ds_read_b128 v[190:193], v197 offset:34816
	ds_read_b128 v[198:201], v197 offset:35840
	ds_read_b128 v[202:205], v197 offset:36864
	ds_read_b128 v[206:209], v197 offset:37888
	ds_read_b128 v[210:213], v197 offset:38912
	ds_read_b128 v[214:217], v197 offset:39936
	global_load_lds_dwordx4 v[232:233], off
	v_lshl_add_u64 v[232:233], s[4:5], 0, v[158:159]
	s_mov_b32 m0, s49
	s_nop 0
	global_load_lds_dwordx4 v[232:233], off
	s_waitcnt vmcnt(8)
	s_waitcnt lgkmcnt(0)
	s_barrier
	s_waitcnt lgkmcnt(0)
	v_mfma_f32_16x16x32_bf16 v[120:123], v[128:131], v[170:173], v[120:123]
	v_mfma_f32_16x16x32_bf16 v[124:127], v[136:139], v[170:173], v[124:127]
	v_lshl_add_u64 v[174:175], v[174:175], 0, s[14:15]
	v_mfma_f32_16x16x32_bf16 v[108:111], v[128:131], v[190:193], v[108:111]
	v_lshl_add_u64 v[222:223], v[222:223], 0, s[14:15]
	v_mfma_f32_16x16x32_bf16 v[104:107], v[136:139], v[190:193], v[104:107]
	v_lshl_add_u64 v[224:225], v[224:225], 0, s[14:15]
	v_mfma_f32_16x16x32_bf16 v[92:95], v[128:131], v[202:205], v[92:95]
	v_lshl_add_u64 v[226:227], v[226:227], 0, s[14:15]
	v_mfma_f32_16x16x32_bf16 v[88:91], v[136:139], v[202:205], v[88:91]
	v_lshl_add_u64 v[228:229], v[228:229], 0, s[14:15]
	v_mfma_f32_16x16x32_bf16 v[76:79], v[128:131], v[210:213], v[76:79]
	v_lshl_add_u64 v[230:231], v[230:231], 0, s[14:15]
	v_mfma_f32_16x16x32_bf16 v[72:75], v[136:139], v[210:213], v[72:75]
	v_mfma_f32_16x16x32_bf16 v[120:123], v[132:135], v[186:189], v[120:123]
	v_mfma_f32_16x16x32_bf16 v[124:127], v[140:143], v[186:189], v[124:127]
	v_mfma_f32_16x16x32_bf16 v[108:111], v[132:135], v[198:201], v[108:111]
	v_mfma_f32_16x16x32_bf16 v[104:107], v[140:143], v[198:201], v[104:107]
	v_mfma_f32_16x16x32_bf16 v[92:95], v[132:135], v[206:209], v[92:95]
	v_mfma_f32_16x16x32_bf16 v[88:91], v[140:143], v[206:209], v[88:91]
	v_mfma_f32_16x16x32_bf16 v[76:79], v[132:135], v[214:217], v[76:79]
	v_mfma_f32_16x16x32_bf16 v[72:75], v[140:143], v[214:217], v[72:75]
	v_mfma_f32_16x16x32_bf16 v[116:119], v[144:147], v[170:173], v[116:119]
	v_mfma_f32_16x16x32_bf16 v[112:115], v[152:155], v[170:173], v[112:115]
	v_mfma_f32_16x16x32_bf16 v[100:103], v[144:147], v[190:193], v[100:103]
	v_mfma_f32_16x16x32_bf16 v[96:99], v[152:155], v[190:193], v[96:99]
	v_mfma_f32_16x16x32_bf16 v[84:87], v[144:147], v[202:205], v[84:87]
	v_mfma_f32_16x16x32_bf16 v[80:83], v[152:155], v[202:205], v[80:83]
	v_mfma_f32_16x16x32_bf16 v[68:71], v[144:147], v[210:213], v[68:71]
	v_mfma_f32_16x16x32_bf16 v[64:67], v[152:155], v[210:213], v[64:67]
	v_mfma_f32_16x16x32_bf16 v[116:119], v[148:151], v[186:189], v[116:119]
	v_mfma_f32_16x16x32_bf16 v[112:115], v[166:169], v[186:189], v[112:115]
	v_mfma_f32_16x16x32_bf16 v[100:103], v[148:151], v[198:201], v[100:103]
	v_mfma_f32_16x16x32_bf16 v[96:99], v[166:169], v[198:201], v[96:99]
	v_mfma_f32_16x16x32_bf16 v[84:87], v[148:151], v[206:209], v[84:87]
	v_mfma_f32_16x16x32_bf16 v[80:83], v[166:169], v[206:209], v[80:83]
	v_mfma_f32_16x16x32_bf16 v[68:71], v[148:151], v[214:217], v[68:71]
	v_mfma_f32_16x16x32_bf16 v[64:67], v[166:169], v[214:217], v[64:67]
	s_barrier
	s_add_i32 s4, s45, s37
	s_mov_b32 m0, s4
	ds_read_b128 v[170:173], v197 offset:49152
	ds_read_b128 v[186:189], v197 offset:50176
	ds_read_b128 v[190:193], v197 offset:51200
	ds_read_b128 v[198:201], v197 offset:52224
	ds_read_b128 v[202:205], v197 offset:53248
	ds_read_b128 v[206:209], v197 offset:54272
	ds_read_b128 v[210:213], v197 offset:55296
	ds_read_b128 v[214:217], v197 offset:56320
	global_load_lds_dwordx4 v[174:175], off
	s_add_i32 m0, s4, 0x2000
	s_add_i32 s4, s54, s37
	global_load_lds_dwordx4 v[222:223], off
	s_mov_b32 m0, s4
	s_nop 0
	global_load_lds_dwordx4 v[224:225], off
	s_add_i32 m0, s4, 0x2000
	s_nop 0
	global_load_lds_dwordx4 v[226:227], off
	s_mov_b32 m0, s60
	s_nop 0
	global_load_lds_dwordx4 v[228:229], off
	s_mov_b32 m0, s61
	s_nop 0
	global_load_lds_dwordx4 v[230:231], off
	s_waitcnt vmcnt(8)
	s_waitcnt lgkmcnt(0)
	s_barrier
	s_waitcnt lgkmcnt(0)
	v_mfma_f32_16x16x32_bf16 v[60:63], v[128:131], v[170:173], v[60:63]
	s_add_u32 s30, s30, 0x100
	v_mfma_f32_16x16x32_bf16 v[56:59], v[136:139], v[170:173], v[56:59]
	s_addc_u32 s31, s31, 0
	v_mfma_f32_16x16x32_bf16 v[44:47], v[128:131], v[190:193], v[44:47]
	s_add_u32 s10, s10, 0x100
	v_mfma_f32_16x16x32_bf16 v[40:43], v[136:139], v[190:193], v[40:43]
	s_addc_u32 s11, s11, 0
	v_mfma_f32_16x16x32_bf16 v[28:31], v[128:131], v[202:205], v[28:31]
	s_mov_b32 s34, s44
	v_mfma_f32_16x16x32_bf16 v[24:27], v[136:139], v[202:205], v[24:27]
	s_cmp_ge_i32 s44, s59
	v_mfma_f32_16x16x32_bf16 v[12:15], v[128:131], v[210:213], v[12:15]
	s_cselect_b32 s99, 1, 0
	v_mfma_f32_16x16x32_bf16 v[8:11], v[136:139], v[210:213], v[8:11]
	s_add_i32 s44, s34, 2
	v_mfma_f32_16x16x32_bf16 v[60:63], v[132:135], v[186:189], v[60:63]
	s_add_u32 s4, s30, 0x80
	v_mfma_f32_16x16x32_bf16 v[56:59], v[140:143], v[186:189], v[56:59]
	s_addc_u32 s5, s31, 0
	v_mfma_f32_16x16x32_bf16 v[44:47], v[132:135], v[198:201], v[44:47]
	s_add_i32 s45, 0, 0x10000
	v_mfma_f32_16x16x32_bf16 v[40:43], v[140:143], v[198:201], v[40:43]
	s_cmp_eq_u32 s62, s34
	v_mfma_f32_16x16x32_bf16 v[28:31], v[132:135], v[206:209], v[28:31]
	s_cselect_b32 s35, s27, s5
	v_mfma_f32_16x16x32_bf16 v[24:27], v[140:143], v[206:209], v[24:27]
	s_cselect_b32 s34, s26, s4
	v_mfma_f32_16x16x32_bf16 v[12:15], v[132:135], v[214:217], v[12:15]
	s_cselect_b32 s5, s29, s11
	v_mfma_f32_16x16x32_bf16 v[8:11], v[140:143], v[214:217], v[8:11]
	s_cselect_b32 s4, s28, s10
	v_mfma_f32_16x16x32_bf16 v[52:55], v[144:147], v[170:173], v[52:55]
	s_add_i32 s54, 0, 0x14000
	v_mfma_f32_16x16x32_bf16 v[48:51], v[152:155], v[170:173], v[48:51]
	v_mfma_f32_16x16x32_bf16 v[36:39], v[144:147], v[190:193], v[36:39]
	v_mfma_f32_16x16x32_bf16 v[32:35], v[152:155], v[190:193], v[32:35]
	v_mfma_f32_16x16x32_bf16 v[20:23], v[144:147], v[202:205], v[20:23]
	v_mfma_f32_16x16x32_bf16 v[16:19], v[152:155], v[202:205], v[16:19]
	v_mfma_f32_16x16x32_bf16 v[4:7], v[144:147], v[210:213], v[4:7]
	v_mfma_f32_16x16x32_bf16 v[0:3], v[152:155], v[210:213], v[0:3]
	v_mfma_f32_16x16x32_bf16 v[52:55], v[148:151], v[186:189], v[52:55]
	v_mfma_f32_16x16x32_bf16 v[48:51], v[166:169], v[186:189], v[48:51]
	v_mfma_f32_16x16x32_bf16 v[36:39], v[148:151], v[198:201], v[36:39]
	v_mfma_f32_16x16x32_bf16 v[32:35], v[166:169], v[198:201], v[32:35]
	v_mfma_f32_16x16x32_bf16 v[20:23], v[148:151], v[206:209], v[20:23]
	v_mfma_f32_16x16x32_bf16 v[16:19], v[166:169], v[206:209], v[16:19]
	v_mfma_f32_16x16x32_bf16 v[4:7], v[148:151], v[214:217], v[4:7]
	v_mfma_f32_16x16x32_bf16 v[0:3], v[166:169], v[214:217], v[0:3]
	s_barrier
	s_cmp_lg_u32 s99, 0
	s_cbranch_scc0 .LBB0_262

.Llbb_2:
	s_add_i32 s44, s34, 2
	s_add_u32 s4, s30, 0x80
	s_addc_u32 s5, s31, 0
	s_add_i32 s45, 0, 0x10000
	s_cmp_eq_u32 s62, s34
	s_cselect_b32 s35, s27, s5
	s_cselect_b32 s34, s26, s4
	s_cselect_b32 s5, s29, s11
	s_cselect_b32 s4, s28, s10
	s_add_i32 s54, 0, 0x14000
	v_add_u32_e32 v140, s45, v163
	v_add_u32_e32 v170, s54, v163
	ds_read_b128 v[128:131], v140
	ds_read_b128 v[132:135], v140 offset:1024
	ds_read_b128 v[136:139], v140 offset:2048
	ds_read_b128 v[140:143], v140 offset:3072
	ds_read_b128 v[154:157], v170
	ds_read_b128 v[158:161], v170 offset:1024
	ds_read_b128 v[166:169], v170 offset:2048
	ds_read_b128 v[170:173], v170 offset:3072
	v_lshl_add_u64 v[174:175], s[30:31], 0, v[150:151]
	s_add_i32 m0, s38, 0xc000
	ds_read_b128 v[186:189], v165
	ds_read_b128 v[190:193], v165 offset:1024
	ds_read_b128 v[194:197], v165 offset:2048
	ds_read_b128 v[198:201], v165 offset:3072
	ds_read_b128 v[202:205], v165 offset:4096
	ds_read_b128 v[206:209], v165 offset:5120
	ds_read_b128 v[210:213], v165 offset:6144
	ds_read_b128 v[214:217], v165 offset:7168
	global_load_lds_dwordx4 v[174:175], off
	v_lshl_add_u64 v[174:175], s[30:31], 0, v[152:153]
	s_add_i32 m0, s38, 0xe000
	s_nop 0
	global_load_lds_dwordx4 v[174:175], off
	s_waitcnt vmcnt(8)
	s_waitcnt lgkmcnt(0)
	s_barrier
	s_waitcnt lgkmcnt(0)
	v_mfma_f32_16x16x32_bf16 v[124:127], v[128:131], v[186:189], 0
	v_mfma_f32_16x16x32_bf16 v[120:123], v[136:139], v[186:189], 0
	v_lshl_add_u64 v[174:175], s[4:5], 0, v[176:177]
	v_mfma_f32_16x16x32_bf16 v[108:111], v[128:131], v[194:197], 0
	v_lshl_add_u64 v[222:223], s[4:5], 0, v[144:145]
	v_mfma_f32_16x16x32_bf16 v[104:107], v[136:139], v[194:197], 0
	s_add_u32 s4, s4, s0
	v_mfma_f32_16x16x32_bf16 v[92:95], v[128:131], v[202:205], 0
	s_addc_u32 s5, s5, s1
	v_mfma_f32_16x16x32_bf16 v[88:91], v[136:139], v[202:205], 0
	v_lshl_add_u64 v[224:225], s[4:5], 0, v[176:177]
	v_mfma_f32_16x16x32_bf16 v[76:79], v[128:131], v[210:213], 0
	v_lshl_add_u64 v[226:227], s[4:5], 0, v[144:145]
	v_mfma_f32_16x16x32_bf16 v[72:75], v[136:139], v[210:213], 0
	v_lshl_add_u64 v[228:229], s[34:35], 0, v[148:149]
	v_mfma_f32_16x16x32_bf16 v[124:127], v[132:135], v[190:193], v[124:127]
	v_lshl_add_u64 v[230:231], s[34:35], 0, v[146:147]
	v_mfma_f32_16x16x32_bf16 v[120:123], v[140:143], v[190:193], v[120:123]
	v_mfma_f32_16x16x32_bf16 v[108:111], v[132:135], v[198:201], v[108:111]
	v_mfma_f32_16x16x32_bf16 v[104:107], v[140:143], v[198:201], v[104:107]
	v_mfma_f32_16x16x32_bf16 v[92:95], v[132:135], v[206:209], v[92:95]
	v_mfma_f32_16x16x32_bf16 v[88:91], v[140:143], v[206:209], v[88:91]
	v_mfma_f32_16x16x32_bf16 v[76:79], v[132:135], v[214:217], v[76:79]
	v_mfma_f32_16x16x32_bf16 v[72:75], v[140:143], v[214:217], v[72:75]
	v_mfma_f32_16x16x32_bf16 v[116:119], v[154:157], v[186:189], 0
	v_mfma_f32_16x16x32_bf16 v[112:115], v[166:169], v[186:189], 0
	v_mfma_f32_16x16x32_bf16 v[100:103], v[154:157], v[194:197], 0
	v_mfma_f32_16x16x32_bf16 v[96:99], v[166:169], v[194:197], 0
	v_mfma_f32_16x16x32_bf16 v[84:87], v[154:157], v[202:205], 0
	v_mfma_f32_16x16x32_bf16 v[80:83], v[166:169], v[202:205], 0
	v_mfma_f32_16x16x32_bf16 v[68:71], v[154:157], v[210:213], 0
	v_mfma_f32_16x16x32_bf16 v[64:67], v[166:169], v[210:213], 0
	v_mfma_f32_16x16x32_bf16 v[116:119], v[158:161], v[190:193], v[116:119]
	v_mfma_f32_16x16x32_bf16 v[112:115], v[170:173], v[190:193], v[112:115]
	v_mfma_f32_16x16x32_bf16 v[100:103], v[158:161], v[198:201], v[100:103]
	v_mfma_f32_16x16x32_bf16 v[96:99], v[170:173], v[198:201], v[96:99]
	v_mfma_f32_16x16x32_bf16 v[84:87], v[158:161], v[206:209], v[84:87]
	v_mfma_f32_16x16x32_bf16 v[80:83], v[170:173], v[206:209], v[80:83]
	v_mfma_f32_16x16x32_bf16 v[68:71], v[158:161], v[214:217], v[68:71]
	v_mfma_f32_16x16x32_bf16 v[64:67], v[170:173], v[214:217], v[64:67]
	s_barrier
	s_add_i32 s45, s45, s37
	s_mov_b32 m0, s45
	ds_read_b128 v[186:189], v165 offset:16384
	ds_read_b128 v[190:193], v165 offset:17408
	ds_read_b128 v[194:197], v165 offset:18432
	ds_read_b128 v[198:201], v165 offset:19456
	ds_read_b128 v[202:205], v165 offset:20480
	ds_read_b128 v[206:209], v165 offset:21504
	ds_read_b128 v[210:213], v165 offset:22528
	ds_read_b128 v[214:217], v165 offset:23552
	global_load_lds_dwordx4 v[174:175], off
	s_add_i32 m0, s45, 0x2000
	s_add_i32 s45, s54, s37
	global_load_lds_dwordx4 v[222:223], off
	s_mov_b32 m0, s45
	s_nop 0
	global_load_lds_dwordx4 v[224:225], off
	s_add_i32 m0, s45, 0x2000
	s_nop 0
	global_load_lds_dwordx4 v[226:227], off
	s_mov_b32 m0, s38
	s_nop 0
	global_load_lds_dwordx4 v[228:229], off
	s_mov_b32 m0, s39
	s_nop 0
	global_load_lds_dwordx4 v[230:231], off
	s_waitcnt vmcnt(8)
	s_waitcnt lgkmcnt(0)
	s_barrier
	s_waitcnt lgkmcnt(0)
	v_mfma_f32_16x16x32_bf16 v[60:63], v[128:131], v[186:189], 0
	v_mfma_f32_16x16x32_bf16 v[56:59], v[136:139], v[186:189], 0
	v_mfma_f32_16x16x32_bf16 v[44:47], v[128:131], v[194:197], 0
	v_mfma_f32_16x16x32_bf16 v[40:43], v[136:139], v[194:197], 0
	v_mfma_f32_16x16x32_bf16 v[28:31], v[128:131], v[202:205], 0
	v_mfma_f32_16x16x32_bf16 v[24:27], v[136:139], v[202:205], 0
	v_mfma_f32_16x16x32_bf16 v[12:15], v[128:131], v[210:213], 0
	v_mfma_f32_16x16x32_bf16 v[8:11], v[136:139], v[210:213], 0
	v_mfma_f32_16x16x32_bf16 v[60:63], v[132:135], v[190:193], v[60:63]
	v_mfma_f32_16x16x32_bf16 v[56:59], v[140:143], v[190:193], v[56:59]
	v_mfma_f32_16x16x32_bf16 v[44:47], v[132:135], v[198:201], v[44:47]
	v_mfma_f32_16x16x32_bf16 v[40:43], v[140:143], v[198:201], v[40:43]
	v_mfma_f32_16x16x32_bf16 v[28:31], v[132:135], v[206:209], v[28:31]
	v_mfma_f32_16x16x32_bf16 v[24:27], v[140:143], v[206:209], v[24:27]
	v_mfma_f32_16x16x32_bf16 v[12:15], v[132:135], v[214:217], v[12:15]
	v_mfma_f32_16x16x32_bf16 v[8:11], v[140:143], v[214:217], v[8:11]
	v_mfma_f32_16x16x32_bf16 v[52:55], v[154:157], v[186:189], 0
	v_mfma_f32_16x16x32_bf16 v[48:51], v[166:169], v[186:189], 0
	v_mfma_f32_16x16x32_bf16 v[36:39], v[154:157], v[194:197], 0
	v_mfma_f32_16x16x32_bf16 v[32:35], v[166:169], v[194:197], 0
	v_mfma_f32_16x16x32_bf16 v[20:23], v[154:157], v[202:205], 0
	v_mfma_f32_16x16x32_bf16 v[16:19], v[166:169], v[202:205], 0
	v_mfma_f32_16x16x32_bf16 v[4:7], v[154:157], v[210:213], 0
	v_mfma_f32_16x16x32_bf16 v[0:3], v[166:169], v[210:213], 0
	v_mfma_f32_16x16x32_bf16 v[52:55], v[158:161], v[190:193], v[52:55]
	v_mfma_f32_16x16x32_bf16 v[48:51], v[170:173], v[190:193], v[48:51]
	v_mfma_f32_16x16x32_bf16 v[36:39], v[158:161], v[198:201], v[36:39]
	v_mfma_f32_16x16x32_bf16 v[32:35], v[170:173], v[198:201], v[32:35]
	v_mfma_f32_16x16x32_bf16 v[20:23], v[158:161], v[206:209], v[20:23]
	v_mfma_f32_16x16x32_bf16 v[16:19], v[170:173], v[206:209], v[16:19]
	v_mfma_f32_16x16x32_bf16 v[4:7], v[158:161], v[214:217], v[4:7]
	v_mfma_f32_16x16x32_bf16 v[0:3], v[170:173], v[214:217], v[0:3]
	s_barrier
	s_add_i32 s45, 0, 0x18000
	s_add_i32 s54, 0, 0x1c000
	v_add_u32_e32 v140, s45, v163
	v_add_u32_e32 v170, s54, v163
	ds_read_b128 v[128:131], v140
	ds_read_b128 v[132:135], v140 offset:1024
	ds_read_b128 v[136:139], v140 offset:2048
	ds_read_b128 v[140:143], v140 offset:3072
	ds_read_b128 v[154:157], v170
	ds_read_b128 v[158:161], v170 offset:1024
	ds_read_b128 v[166:169], v170 offset:2048
	ds_read_b128 v[170:173], v170 offset:3072
	s_add_u32 s4, s34, s0
	s_addc_u32 s5, s35, s1
	s_mov_b32 m0, s48
	v_lshl_add_u64 v[232:233], s[4:5], 0, v[148:149]
	ds_read_b128 v[186:189], v165 offset:32768
	ds_read_b128 v[190:193], v165 offset:33792
	ds_read_b128 v[194:197], v165 offset:34816
	ds_read_b128 v[198:201], v165 offset:35840
	ds_read_b128 v[202:205], v165 offset:36864
	ds_read_b128 v[206:209], v165 offset:37888
	ds_read_b128 v[210:213], v165 offset:38912
	ds_read_b128 v[214:217], v165 offset:39936
	global_load_lds_dwordx4 v[232:233], off
	v_lshl_add_u64 v[232:233], s[4:5], 0, v[146:147]
	s_mov_b32 m0, s49
	s_nop 0
	global_load_lds_dwordx4 v[232:233], off
	s_waitcnt vmcnt(8)
	s_waitcnt lgkmcnt(0)
	s_barrier
	s_waitcnt lgkmcnt(0)
	v_mfma_f32_16x16x32_bf16 v[124:127], v[128:131], v[186:189], v[124:127]
	v_mfma_f32_16x16x32_bf16 v[120:123], v[136:139], v[186:189], v[120:123]
	v_lshl_add_u64 v[174:175], v[174:175], 0, s[14:15]
	v_mfma_f32_16x16x32_bf16 v[108:111], v[128:131], v[194:197], v[108:111]
	v_lshl_add_u64 v[222:223], v[222:223], 0, s[14:15]
	v_mfma_f32_16x16x32_bf16 v[104:107], v[136:139], v[194:197], v[104:107]
	v_lshl_add_u64 v[224:225], v[224:225], 0, s[14:15]
	v_mfma_f32_16x16x32_bf16 v[92:95], v[128:131], v[202:205], v[92:95]
	v_lshl_add_u64 v[226:227], v[226:227], 0, s[14:15]
	v_mfma_f32_16x16x32_bf16 v[88:91], v[136:139], v[202:205], v[88:91]
	v_lshl_add_u64 v[228:229], v[228:229], 0, s[14:15]
	v_mfma_f32_16x16x32_bf16 v[76:79], v[128:131], v[210:213], v[76:79]
	v_lshl_add_u64 v[230:231], v[230:231], 0, s[14:15]
	v_mfma_f32_16x16x32_bf16 v[72:75], v[136:139], v[210:213], v[72:75]
	v_mfma_f32_16x16x32_bf16 v[124:127], v[132:135], v[190:193], v[124:127]
	v_mfma_f32_16x16x32_bf16 v[120:123], v[140:143], v[190:193], v[120:123]
	v_mfma_f32_16x16x32_bf16 v[108:111], v[132:135], v[198:201], v[108:111]
	v_mfma_f32_16x16x32_bf16 v[104:107], v[140:143], v[198:201], v[104:107]
	v_mfma_f32_16x16x32_bf16 v[92:95], v[132:135], v[206:209], v[92:95]
	v_mfma_f32_16x16x32_bf16 v[88:91], v[140:143], v[206:209], v[88:91]
	v_mfma_f32_16x16x32_bf16 v[76:79], v[132:135], v[214:217], v[76:79]
	v_mfma_f32_16x16x32_bf16 v[72:75], v[140:143], v[214:217], v[72:75]
	v_mfma_f32_16x16x32_bf16 v[116:119], v[154:157], v[186:189], v[116:119]
	v_mfma_f32_16x16x32_bf16 v[112:115], v[166:169], v[186:189], v[112:115]
	v_mfma_f32_16x16x32_bf16 v[100:103], v[154:157], v[194:197], v[100:103]
	v_mfma_f32_16x16x32_bf16 v[96:99], v[166:169], v[194:197], v[96:99]
	v_mfma_f32_16x16x32_bf16 v[84:87], v[154:157], v[202:205], v[84:87]
	v_mfma_f32_16x16x32_bf16 v[80:83], v[166:169], v[202:205], v[80:83]
	v_mfma_f32_16x16x32_bf16 v[68:71], v[154:157], v[210:213], v[68:71]
	v_mfma_f32_16x16x32_bf16 v[64:67], v[166:169], v[210:213], v[64:67]
	v_mfma_f32_16x16x32_bf16 v[116:119], v[158:161], v[190:193], v[116:119]
	v_mfma_f32_16x16x32_bf16 v[112:115], v[170:173], v[190:193], v[112:115]
	v_mfma_f32_16x16x32_bf16 v[100:103], v[158:161], v[198:201], v[100:103]
	v_mfma_f32_16x16x32_bf16 v[96:99], v[170:173], v[198:201], v[96:99]
	v_mfma_f32_16x16x32_bf16 v[84:87], v[158:161], v[206:209], v[84:87]
	v_mfma_f32_16x16x32_bf16 v[80:83], v[170:173], v[206:209], v[80:83]
	v_mfma_f32_16x16x32_bf16 v[68:71], v[158:161], v[214:217], v[68:71]
	v_mfma_f32_16x16x32_bf16 v[64:67], v[170:173], v[214:217], v[64:67]
	s_barrier
	s_add_i32 s4, s45, s37
	s_mov_b32 m0, s4
	ds_read_b128 v[186:189], v165 offset:49152
	ds_read_b128 v[190:193], v165 offset:50176
	ds_read_b128 v[194:197], v165 offset:51200
	ds_read_b128 v[198:201], v165 offset:52224
	ds_read_b128 v[202:205], v165 offset:53248
	ds_read_b128 v[206:209], v165 offset:54272
	ds_read_b128 v[210:213], v165 offset:55296
	ds_read_b128 v[214:217], v165 offset:56320
	global_load_lds_dwordx4 v[174:175], off
	s_add_i32 m0, s4, 0x2000
	s_add_i32 s4, s54, s37
	global_load_lds_dwordx4 v[222:223], off
	s_mov_b32 m0, s4
	s_nop 0
	global_load_lds_dwordx4 v[224:225], off
	s_add_i32 m0, s4, 0x2000
	s_nop 0
	global_load_lds_dwordx4 v[226:227], off
	s_mov_b32 m0, s60
	s_nop 0
	global_load_lds_dwordx4 v[228:229], off
	s_mov_b32 m0, s61
	s_nop 0
	global_load_lds_dwordx4 v[230:231], off
	s_waitcnt vmcnt(8)
	s_waitcnt lgkmcnt(0)
	s_barrier
	s_waitcnt lgkmcnt(0)
	v_mfma_f32_16x16x32_bf16 v[60:63], v[128:131], v[186:189], v[60:63]
	s_add_u32 s30, s30, 0x100
	v_mfma_f32_16x16x32_bf16 v[56:59], v[136:139], v[186:189], v[56:59]
	s_addc_u32 s31, s31, 0
	v_mfma_f32_16x16x32_bf16 v[44:47], v[128:131], v[194:197], v[44:47]
	s_add_u32 s10, s10, 0x100
	v_mfma_f32_16x16x32_bf16 v[40:43], v[136:139], v[194:197], v[40:43]
	s_addc_u32 s11, s11, 0
	v_mfma_f32_16x16x32_bf16 v[28:31], v[128:131], v[202:205], v[28:31]
	s_mov_b32 s34, s44
	v_mfma_f32_16x16x32_bf16 v[24:27], v[136:139], v[202:205], v[24:27]
	s_cmp_ge_i32 s44, s59
	v_mfma_f32_16x16x32_bf16 v[12:15], v[128:131], v[210:213], v[12:15]
	s_cselect_b32 s99, 1, 0
	v_mfma_f32_16x16x32_bf16 v[8:11], v[136:139], v[210:213], v[8:11]
	s_add_i32 s44, s34, 2
	v_mfma_f32_16x16x32_bf16 v[60:63], v[132:135], v[190:193], v[60:63]
	s_add_u32 s4, s30, 0x80
	v_mfma_f32_16x16x32_bf16 v[56:59], v[140:143], v[190:193], v[56:59]
	s_addc_u32 s5, s31, 0
	v_mfma_f32_16x16x32_bf16 v[44:47], v[132:135], v[198:201], v[44:47]
	s_add_i32 s45, 0, 0x10000
	v_mfma_f32_16x16x32_bf16 v[40:43], v[140:143], v[198:201], v[40:43]
	s_cmp_eq_u32 s62, s34
	v_mfma_f32_16x16x32_bf16 v[28:31], v[132:135], v[206:209], v[28:31]
	s_cselect_b32 s35, s27, s5
	v_mfma_f32_16x16x32_bf16 v[24:27], v[140:143], v[206:209], v[24:27]
	s_cselect_b32 s34, s26, s4
	v_mfma_f32_16x16x32_bf16 v[12:15], v[132:135], v[214:217], v[12:15]
	s_cselect_b32 s5, s29, s11
	v_mfma_f32_16x16x32_bf16 v[8:11], v[140:143], v[214:217], v[8:11]
	s_cselect_b32 s4, s28, s10
	v_mfma_f32_16x16x32_bf16 v[52:55], v[154:157], v[186:189], v[52:55]
	s_add_i32 s54, 0, 0x14000
	v_mfma_f32_16x16x32_bf16 v[48:51], v[166:169], v[186:189], v[48:51]
	v_mfma_f32_16x16x32_bf16 v[36:39], v[154:157], v[194:197], v[36:39]
	v_mfma_f32_16x16x32_bf16 v[32:35], v[166:169], v[194:197], v[32:35]
	v_mfma_f32_16x16x32_bf16 v[20:23], v[154:157], v[202:205], v[20:23]
	v_mfma_f32_16x16x32_bf16 v[16:19], v[166:169], v[202:205], v[16:19]
	v_mfma_f32_16x16x32_bf16 v[4:7], v[154:157], v[210:213], v[4:7]
	v_mfma_f32_16x16x32_bf16 v[0:3], v[166:169], v[210:213], v[0:3]
	v_mfma_f32_16x16x32_bf16 v[52:55], v[158:161], v[190:193], v[52:55]
	v_mfma_f32_16x16x32_bf16 v[48:51], v[170:173], v[190:193], v[48:51]
	v_mfma_f32_16x16x32_bf16 v[36:39], v[158:161], v[198:201], v[36:39]
	v_mfma_f32_16x16x32_bf16 v[32:35], v[170:173], v[198:201], v[32:35]
	v_mfma_f32_16x16x32_bf16 v[20:23], v[158:161], v[206:209], v[20:23]
	v_mfma_f32_16x16x32_bf16 v[16:19], v[170:173], v[206:209], v[16:19]
	v_mfma_f32_16x16x32_bf16 v[4:7], v[158:161], v[214:217], v[4:7]
	v_mfma_f32_16x16x32_bf16 v[0:3], v[170:173], v[214:217], v[0:3]
	s_barrier
	s_cmp_lg_u32 s99, 0
	s_cbranch_scc1 .Lpeelx_6
.LBB0_305:
	v_add_u32_e32 v140, s45, v163
	v_add_u32_e32 v170, s54, v163
	ds_read_b128 v[128:131], v140
	ds_read_b128 v[132:135], v140 offset:1024
	ds_read_b128 v[136:139], v140 offset:2048
	ds_read_b128 v[140:143], v140 offset:3072
	ds_read_b128 v[154:157], v170
	ds_read_b128 v[158:161], v170 offset:1024
	ds_read_b128 v[166:169], v170 offset:2048
	ds_read_b128 v[170:173], v170 offset:3072
	v_lshl_add_u64 v[174:175], s[30:31], 0, v[150:151]
	s_add_i32 m0, s38, 0xc000
	ds_read_b128 v[186:189], v165
	ds_read_b128 v[190:193], v165 offset:1024
	ds_read_b128 v[194:197], v165 offset:2048
	ds_read_b128 v[198:201], v165 offset:3072
	ds_read_b128 v[202:205], v165 offset:4096
	ds_read_b128 v[206:209], v165 offset:5120
	ds_read_b128 v[210:213], v165 offset:6144
	ds_read_b128 v[214:217], v165 offset:7168
	global_load_lds_dwordx4 v[174:175], off
	v_lshl_add_u64 v[174:175], s[30:31], 0, v[152:153]
	s_add_i32 m0, s38, 0xe000
	s_nop 0
	global_load_lds_dwordx4 v[174:175], off
	s_waitcnt vmcnt(8)
	s_waitcnt lgkmcnt(0)
	s_barrier
	s_waitcnt lgkmcnt(0)
	v_mfma_f32_16x16x32_bf16 v[124:127], v[128:131], v[186:189], v[124:127]
	v_mfma_f32_16x16x32_bf16 v[120:123], v[136:139], v[186:189], v[120:123]
	v_lshl_add_u64 v[174:175], s[4:5], 0, v[176:177]
	v_mfma_f32_16x16x32_bf16 v[108:111], v[128:131], v[194:197], v[108:111]
	v_lshl_add_u64 v[222:223], s[4:5], 0, v[144:145]
	v_mfma_f32_16x16x32_bf16 v[104:107], v[136:139], v[194:197], v[104:107]
	s_add_u32 s4, s4, s0
	v_mfma_f32_16x16x32_bf16 v[92:95], v[128:131], v[202:205], v[92:95]
	s_addc_u32 s5, s5, s1
	v_mfma_f32_16x16x32_bf16 v[88:91], v[136:139], v[202:205], v[88:91]
	v_lshl_add_u64 v[224:225], s[4:5], 0, v[176:177]
	v_mfma_f32_16x16x32_bf16 v[76:79], v[128:131], v[210:213], v[76:79]
	v_lshl_add_u64 v[226:227], s[4:5], 0, v[144:145]
	v_mfma_f32_16x16x32_bf16 v[72:75], v[136:139], v[210:213], v[72:75]
	v_lshl_add_u64 v[228:229], s[34:35], 0, v[148:149]
	v_mfma_f32_16x16x32_bf16 v[124:127], v[132:135], v[190:193], v[124:127]
	v_lshl_add_u64 v[230:231], s[34:35], 0, v[146:147]
	v_mfma_f32_16x16x32_bf16 v[120:123], v[140:143], v[190:193], v[120:123]
	v_mfma_f32_16x16x32_bf16 v[108:111], v[132:135], v[198:201], v[108:111]
	v_mfma_f32_16x16x32_bf16 v[104:107], v[140:143], v[198:201], v[104:107]
	v_mfma_f32_16x16x32_bf16 v[92:95], v[132:135], v[206:209], v[92:95]
	v_mfma_f32_16x16x32_bf16 v[88:91], v[140:143], v[206:209], v[88:91]
	v_mfma_f32_16x16x32_bf16 v[76:79], v[132:135], v[214:217], v[76:79]
	v_mfma_f32_16x16x32_bf16 v[72:75], v[140:143], v[214:217], v[72:75]
	v_mfma_f32_16x16x32_bf16 v[116:119], v[154:157], v[186:189], v[116:119]
	v_mfma_f32_16x16x32_bf16 v[112:115], v[166:169], v[186:189], v[112:115]
	v_mfma_f32_16x16x32_bf16 v[100:103], v[154:157], v[194:197], v[100:103]
	v_mfma_f32_16x16x32_bf16 v[96:99], v[166:169], v[194:197], v[96:99]
	v_mfma_f32_16x16x32_bf16 v[84:87], v[154:157], v[202:205], v[84:87]
	v_mfma_f32_16x16x32_bf16 v[80:83], v[166:169], v[202:205], v[80:83]
	v_mfma_f32_16x16x32_bf16 v[68:71], v[154:157], v[210:213], v[68:71]
	v_mfma_f32_16x16x32_bf16 v[64:67], v[166:169], v[210:213], v[64:67]
	v_mfma_f32_16x16x32_bf16 v[116:119], v[158:161], v[190:193], v[116:119]
	v_mfma_f32_16x16x32_bf16 v[112:115], v[170:173], v[190:193], v[112:115]
	v_mfma_f32_16x16x32_bf16 v[100:103], v[158:161], v[198:201], v[100:103]
	v_mfma_f32_16x16x32_bf16 v[96:99], v[170:173], v[198:201], v[96:99]
	v_mfma_f32_16x16x32_bf16 v[84:87], v[158:161], v[206:209], v[84:87]
	v_mfma_f32_16x16x32_bf16 v[80:83], v[170:173], v[206:209], v[80:83]
	v_mfma_f32_16x16x32_bf16 v[68:71], v[158:161], v[214:217], v[68:71]
	v_mfma_f32_16x16x32_bf16 v[64:67], v[170:173], v[214:217], v[64:67]
	s_barrier
	s_add_i32 s45, s45, s37
	s_mov_b32 m0, s45
	ds_read_b128 v[186:189], v165 offset:16384
	ds_read_b128 v[190:193], v165 offset:17408
	ds_read_b128 v[194:197], v165 offset:18432
	ds_read_b128 v[198:201], v165 offset:19456
	ds_read_b128 v[202:205], v165 offset:20480
	ds_read_b128 v[206:209], v165 offset:21504
	ds_read_b128 v[210:213], v165 offset:22528
	ds_read_b128 v[214:217], v165 offset:23552
	global_load_lds_dwordx4 v[174:175], off
	s_add_i32 m0, s45, 0x2000
	s_add_i32 s45, s54, s37
	global_load_lds_dwordx4 v[222:223], off
	s_mov_b32 m0, s45
	s_nop 0
	global_load_lds_dwordx4 v[224:225], off
	s_add_i32 m0, s45, 0x2000
	s_nop 0
	global_load_lds_dwordx4 v[226:227], off
	s_mov_b32 m0, s38
	s_nop 0
	global_load_lds_dwordx4 v[228:229], off
	s_mov_b32 m0, s39
	s_nop 0
	global_load_lds_dwordx4 v[230:231], off
	s_waitcnt vmcnt(8)
	s_waitcnt lgkmcnt(0)
	s_barrier
	s_waitcnt lgkmcnt(0)
	v_mfma_f32_16x16x32_bf16 v[60:63], v[128:131], v[186:189], v[60:63]
	v_mfma_f32_16x16x32_bf16 v[56:59], v[136:139], v[186:189], v[56:59]
	v_mfma_f32_16x16x32_bf16 v[44:47], v[128:131], v[194:197], v[44:47]
	v_mfma_f32_16x16x32_bf16 v[40:43], v[136:139], v[194:197], v[40:43]
	v_mfma_f32_16x16x32_bf16 v[28:31], v[128:131], v[202:205], v[28:31]
	v_mfma_f32_16x16x32_bf16 v[24:27], v[136:139], v[202:205], v[24:27]
	v_mfma_f32_16x16x32_bf16 v[12:15], v[128:131], v[210:213], v[12:15]
	v_mfma_f32_16x16x32_bf16 v[8:11], v[136:139], v[210:213], v[8:11]
	v_mfma_f32_16x16x32_bf16 v[60:63], v[132:135], v[190:193], v[60:63]
	v_mfma_f32_16x16x32_bf16 v[56:59], v[140:143], v[190:193], v[56:59]
	v_mfma_f32_16x16x32_bf16 v[44:47], v[132:135], v[198:201], v[44:47]
	v_mfma_f32_16x16x32_bf16 v[40:43], v[140:143], v[198:201], v[40:43]
	v_mfma_f32_16x16x32_bf16 v[28:31], v[132:135], v[206:209], v[28:31]
	v_mfma_f32_16x16x32_bf16 v[24:27], v[140:143], v[206:209], v[24:27]
	v_mfma_f32_16x16x32_bf16 v[12:15], v[132:135], v[214:217], v[12:15]
	v_mfma_f32_16x16x32_bf16 v[8:11], v[140:143], v[214:217], v[8:11]
	v_mfma_f32_16x16x32_bf16 v[52:55], v[154:157], v[186:189], v[52:55]
	v_mfma_f32_16x16x32_bf16 v[48:51], v[166:169], v[186:189], v[48:51]
	v_mfma_f32_16x16x32_bf16 v[36:39], v[154:157], v[194:197], v[36:39]
	v_mfma_f32_16x16x32_bf16 v[32:35], v[166:169], v[194:197], v[32:35]
	v_mfma_f32_16x16x32_bf16 v[20:23], v[154:157], v[202:205], v[20:23]
	v_mfma_f32_16x16x32_bf16 v[16:19], v[166:169], v[202:205], v[16:19]
	v_mfma_f32_16x16x32_bf16 v[4:7], v[154:157], v[210:213], v[4:7]
	v_mfma_f32_16x16x32_bf16 v[0:3], v[166:169], v[210:213], v[0:3]
	v_mfma_f32_16x16x32_bf16 v[52:55], v[158:161], v[190:193], v[52:55]
	v_mfma_f32_16x16x32_bf16 v[48:51], v[170:173], v[190:193], v[48:51]
	v_mfma_f32_16x16x32_bf16 v[36:39], v[158:161], v[198:201], v[36:39]
	v_mfma_f32_16x16x32_bf16 v[32:35], v[170:173], v[198:201], v[32:35]
	v_mfma_f32_16x16x32_bf16 v[20:23], v[158:161], v[206:209], v[20:23]
	v_mfma_f32_16x16x32_bf16 v[16:19], v[170:173], v[206:209], v[16:19]
	v_mfma_f32_16x16x32_bf16 v[4:7], v[158:161], v[214:217], v[4:7]
	v_mfma_f32_16x16x32_bf16 v[0:3], v[170:173], v[214:217], v[0:3]
	s_barrier
	s_add_i32 s45, 0, 0x18000
	s_add_i32 s54, 0, 0x1c000
	v_add_u32_e32 v140, s45, v163
	v_add_u32_e32 v170, s54, v163
	ds_read_b128 v[128:131], v140
	ds_read_b128 v[132:135], v140 offset:1024
	ds_read_b128 v[136:139], v140 offset:2048
	ds_read_b128 v[140:143], v140 offset:3072
	ds_read_b128 v[154:157], v170
	ds_read_b128 v[158:161], v170 offset:1024
	ds_read_b128 v[166:169], v170 offset:2048
	ds_read_b128 v[170:173], v170 offset:3072
	s_add_u32 s4, s34, s0
	s_addc_u32 s5, s35, s1
	s_mov_b32 m0, s48
	v_lshl_add_u64 v[232:233], s[4:5], 0, v[148:149]
	ds_read_b128 v[186:189], v165 offset:32768
	ds_read_b128 v[190:193], v165 offset:33792
	ds_read_b128 v[194:197], v165 offset:34816
	ds_read_b128 v[198:201], v165 offset:35840
	ds_read_b128 v[202:205], v165 offset:36864
	ds_read_b128 v[206:209], v165 offset:37888
	ds_read_b128 v[210:213], v165 offset:38912
	ds_read_b128 v[214:217], v165 offset:39936
	global_load_lds_dwordx4 v[232:233], off
	v_lshl_add_u64 v[232:233], s[4:5], 0, v[146:147]
	s_mov_b32 m0, s49
	s_nop 0
	global_load_lds_dwordx4 v[232:233], off
	s_waitcnt vmcnt(8)
	s_waitcnt lgkmcnt(0)
	s_barrier
	s_waitcnt lgkmcnt(0)
	v_mfma_f32_16x16x32_bf16 v[124:127], v[128:131], v[186:189], v[124:127]
	v_mfma_f32_16x16x32_bf16 v[120:123], v[136:139], v[186:189], v[120:123]
	v_lshl_add_u64 v[174:175], v[174:175], 0, s[14:15]
	v_mfma_f32_16x16x32_bf16 v[108:111], v[128:131], v[194:197], v[108:111]
	v_lshl_add_u64 v[222:223], v[222:223], 0, s[14:15]
	v_mfma_f32_16x16x32_bf16 v[104:107], v[136:139], v[194:197], v[104:107]
	v_lshl_add_u64 v[224:225], v[224:225], 0, s[14:15]
	v_mfma_f32_16x16x32_bf16 v[92:95], v[128:131], v[202:205], v[92:95]
	v_lshl_add_u64 v[226:227], v[226:227], 0, s[14:15]
	v_mfma_f32_16x16x32_bf16 v[88:91], v[136:139], v[202:205], v[88:91]
	v_lshl_add_u64 v[228:229], v[228:229], 0, s[14:15]
	v_mfma_f32_16x16x32_bf16 v[76:79], v[128:131], v[210:213], v[76:79]
	v_lshl_add_u64 v[230:231], v[230:231], 0, s[14:15]
	v_mfma_f32_16x16x32_bf16 v[72:75], v[136:139], v[210:213], v[72:75]
	v_mfma_f32_16x16x32_bf16 v[124:127], v[132:135], v[190:193], v[124:127]
	v_mfma_f32_16x16x32_bf16 v[120:123], v[140:143], v[190:193], v[120:123]
	v_mfma_f32_16x16x32_bf16 v[108:111], v[132:135], v[198:201], v[108:111]
	v_mfma_f32_16x16x32_bf16 v[104:107], v[140:143], v[198:201], v[104:107]
	v_mfma_f32_16x16x32_bf16 v[92:95], v[132:135], v[206:209], v[92:95]
	v_mfma_f32_16x16x32_bf16 v[88:91], v[140:143], v[206:209], v[88:91]
	v_mfma_f32_16x16x32_bf16 v[76:79], v[132:135], v[214:217], v[76:79]
	v_mfma_f32_16x16x32_bf16 v[72:75], v[140:143], v[214:217], v[72:75]
	v_mfma_f32_16x16x32_bf16 v[116:119], v[154:157], v[186:189], v[116:119]
	v_mfma_f32_16x16x32_bf16 v[112:115], v[166:169], v[186:189], v[112:115]
	v_mfma_f32_16x16x32_bf16 v[100:103], v[154:157], v[194:197], v[100:103]
	v_mfma_f32_16x16x32_bf16 v[96:99], v[166:169], v[194:197], v[96:99]
	v_mfma_f32_16x16x32_bf16 v[84:87], v[154:157], v[202:205], v[84:87]
	v_mfma_f32_16x16x32_bf16 v[80:83], v[166:169], v[202:205], v[80:83]
	v_mfma_f32_16x16x32_bf16 v[68:71], v[154:157], v[210:213], v[68:71]
	v_mfma_f32_16x16x32_bf16 v[64:67], v[166:169], v[210:213], v[64:67]
	v_mfma_f32_16x16x32_bf16 v[116:119], v[158:161], v[190:193], v[116:119]
	v_mfma_f32_16x16x32_bf16 v[112:115], v[170:173], v[190:193], v[112:115]
	v_mfma_f32_16x16x32_bf16 v[100:103], v[158:161], v[198:201], v[100:103]
	v_mfma_f32_16x16x32_bf16 v[96:99], v[170:173], v[198:201], v[96:99]
	v_mfma_f32_16x16x32_bf16 v[84:87], v[158:161], v[206:209], v[84:87]
	v_mfma_f32_16x16x32_bf16 v[80:83], v[170:173], v[206:209], v[80:83]
	v_mfma_f32_16x16x32_bf16 v[68:71], v[158:161], v[214:217], v[68:71]
	v_mfma_f32_16x16x32_bf16 v[64:67], v[170:173], v[214:217], v[64:67]
	s_barrier
	s_add_i32 s4, s45, s37
	s_mov_b32 m0, s4
	ds_read_b128 v[186:189], v165 offset:49152
	ds_read_b128 v[190:193], v165 offset:50176
	ds_read_b128 v[194:197], v165 offset:51200
	ds_read_b128 v[198:201], v165 offset:52224
	ds_read_b128 v[202:205], v165 offset:53248
	ds_read_b128 v[206:209], v165 offset:54272
	ds_read_b128 v[210:213], v165 offset:55296
	ds_read_b128 v[214:217], v165 offset:56320
	global_load_lds_dwordx4 v[174:175], off
	s_add_i32 m0, s4, 0x2000
	s_add_i32 s4, s54, s37
	global_load_lds_dwordx4 v[222:223], off
	s_mov_b32 m0, s4
	s_nop 0
	global_load_lds_dwordx4 v[224:225], off
	s_add_i32 m0, s4, 0x2000
	s_nop 0
	global_load_lds_dwordx4 v[226:227], off
	s_mov_b32 m0, s60
	s_nop 0
	global_load_lds_dwordx4 v[228:229], off
	s_mov_b32 m0, s61
	s_nop 0
	global_load_lds_dwordx4 v[230:231], off
	s_waitcnt vmcnt(8)
	s_waitcnt lgkmcnt(0)
	s_barrier
	s_waitcnt lgkmcnt(0)
	v_mfma_f32_16x16x32_bf16 v[60:63], v[128:131], v[186:189], v[60:63]
	s_add_u32 s30, s30, 0x100
	v_mfma_f32_16x16x32_bf16 v[56:59], v[136:139], v[186:189], v[56:59]
	s_addc_u32 s31, s31, 0
	v_mfma_f32_16x16x32_bf16 v[44:47], v[128:131], v[194:197], v[44:47]
	s_add_u32 s10, s10, 0x100
	v_mfma_f32_16x16x32_bf16 v[40:43], v[136:139], v[194:197], v[40:43]
	s_addc_u32 s11, s11, 0
	v_mfma_f32_16x16x32_bf16 v[28:31], v[128:131], v[202:205], v[28:31]
	s_mov_b32 s34, s44
	v_mfma_f32_16x16x32_bf16 v[24:27], v[136:139], v[202:205], v[24:27]
	s_cmp_ge_i32 s44, s59
	v_mfma_f32_16x16x32_bf16 v[12:15], v[128:131], v[210:213], v[12:15]
	s_cselect_b32 s99, 1, 0
	v_mfma_f32_16x16x32_bf16 v[8:11], v[136:139], v[210:213], v[8:11]
	s_add_i32 s44, s34, 2
	v_mfma_f32_16x16x32_bf16 v[60:63], v[132:135], v[190:193], v[60:63]
	s_add_u32 s4, s30, 0x80
	v_mfma_f32_16x16x32_bf16 v[56:59], v[140:143], v[190:193], v[56:59]
	s_addc_u32 s5, s31, 0
	v_mfma_f32_16x16x32_bf16 v[44:47], v[132:135], v[198:201], v[44:47]
	s_add_i32 s45, 0, 0x10000
	v_mfma_f32_16x16x32_bf16 v[40:43], v[140:143], v[198:201], v[40:43]
	s_cmp_eq_u32 s62, s34
	v_mfma_f32_16x16x32_bf16 v[28:31], v[132:135], v[206:209], v[28:31]
	s_cselect_b32 s35, s27, s5
	v_mfma_f32_16x16x32_bf16 v[24:27], v[140:143], v[206:209], v[24:27]
	s_cselect_b32 s34, s26, s4
	v_mfma_f32_16x16x32_bf16 v[12:15], v[132:135], v[214:217], v[12:15]
	s_cselect_b32 s5, s29, s11
	v_mfma_f32_16x16x32_bf16 v[8:11], v[140:143], v[214:217], v[8:11]
	s_cselect_b32 s4, s28, s10
	v_mfma_f32_16x16x32_bf16 v[52:55], v[154:157], v[186:189], v[52:55]
	s_add_i32 s54, 0, 0x14000
	v_mfma_f32_16x16x32_bf16 v[48:51], v[166:169], v[186:189], v[48:51]
	v_mfma_f32_16x16x32_bf16 v[36:39], v[154:157], v[194:197], v[36:39]
	v_mfma_f32_16x16x32_bf16 v[32:35], v[166:169], v[194:197], v[32:35]
	v_mfma_f32_16x16x32_bf16 v[20:23], v[154:157], v[202:205], v[20:23]
	v_mfma_f32_16x16x32_bf16 v[16:19], v[166:169], v[202:205], v[16:19]
	v_mfma_f32_16x16x32_bf16 v[4:7], v[154:157], v[210:213], v[4:7]
	v_mfma_f32_16x16x32_bf16 v[0:3], v[166:169], v[210:213], v[0:3]
	v_mfma_f32_16x16x32_bf16 v[52:55], v[158:161], v[190:193], v[52:55]
	v_mfma_f32_16x16x32_bf16 v[48:51], v[170:173], v[190:193], v[48:51]
	v_mfma_f32_16x16x32_bf16 v[36:39], v[158:161], v[198:201], v[36:39]
	v_mfma_f32_16x16x32_bf16 v[32:35], v[170:173], v[198:201], v[32:35]
	v_mfma_f32_16x16x32_bf16 v[20:23], v[158:161], v[206:209], v[20:23]
	v_mfma_f32_16x16x32_bf16 v[16:19], v[170:173], v[206:209], v[16:19]
	v_mfma_f32_16x16x32_bf16 v[4:7], v[158:161], v[214:217], v[4:7]
	v_mfma_f32_16x16x32_bf16 v[0:3], v[170:173], v[214:217], v[0:3]
	s_barrier
	s_cmp_lg_u32 s99, 0
	s_cbranch_scc0 .LBB0_305

.Llbb_3:
	s_add_i32 s44, s30, 2
	s_add_u32 s4, s28, 0x80
	s_addc_u32 s5, s29, 0
	s_add_i32 s45, 0, 0x10000
	s_cmp_eq_u32 s61, s30
	s_cselect_b32 s31, s25, s5
	s_cselect_b32 s30, s24, s4
	s_cselect_b32 s5, s27, s11
	s_cselect_b32 s4, s26, s10
	s_add_i32 s54, 0, 0x14000
	v_add_u32_e32 v156, s45, v151
	v_add_u32_e32 v172, s54, v151
	ds_read_b128 v[128:131], v156
	ds_read_b128 v[142:145], v156 offset:1024
	ds_read_b128 v[146:149], v156 offset:2048
	ds_read_b128 v[156:159], v156 offset:3072
	ds_read_b128 v[160:163], v172
	ds_read_b128 v[164:167], v172 offset:1024
	ds_read_b128 v[168:171], v172 offset:2048
	ds_read_b128 v[172:175], v172 offset:3072
	v_lshl_add_u64 v[222:223], s[28:29], 0, v[138:139]
	s_add_i32 m0, s37, 0xc000
	ds_read_b128 v[186:189], v155
	ds_read_b128 v[190:193], v155 offset:1024
	ds_read_b128 v[194:197], v155 offset:2048
	ds_read_b128 v[198:201], v155 offset:3072
	ds_read_b128 v[202:205], v155 offset:4096
	ds_read_b128 v[206:209], v155 offset:5120
	ds_read_b128 v[210:213], v155 offset:6144
	ds_read_b128 v[214:217], v155 offset:7168
	global_load_lds_dwordx4 v[222:223], off
	v_lshl_add_u64 v[222:223], s[28:29], 0, v[140:141]
	s_add_i32 m0, s37, 0xe000
	s_nop 0
	global_load_lds_dwordx4 v[222:223], off
	s_waitcnt vmcnt(8)
	s_waitcnt lgkmcnt(0)
	s_barrier
	s_waitcnt lgkmcnt(0)
	v_mfma_f32_16x16x32_bf16 v[120:123], v[128:131], v[186:189], 0
	v_mfma_f32_16x16x32_bf16 v[116:119], v[146:149], v[186:189], 0
	v_lshl_add_u64 v[222:223], s[4:5], 0, v[176:177]
	v_mfma_f32_16x16x32_bf16 v[108:111], v[128:131], v[194:197], 0
	v_lshl_add_u64 v[224:225], s[4:5], 0, v[132:133]
	v_mfma_f32_16x16x32_bf16 v[100:103], v[146:149], v[194:197], 0
	s_add_u32 s4, s4, s6
	v_mfma_f32_16x16x32_bf16 v[92:95], v[128:131], v[202:205], 0
	s_addc_u32 s5, s5, s7
	v_mfma_f32_16x16x32_bf16 v[84:87], v[146:149], v[202:205], 0
	v_lshl_add_u64 v[226:227], s[4:5], 0, v[176:177]
	v_mfma_f32_16x16x32_bf16 v[76:79], v[128:131], v[210:213], 0
	v_lshl_add_u64 v[228:229], s[4:5], 0, v[132:133]
	v_mfma_f32_16x16x32_bf16 v[68:71], v[146:149], v[210:213], 0
	v_lshl_add_u64 v[230:231], s[30:31], 0, v[136:137]
	v_mfma_f32_16x16x32_bf16 v[120:123], v[142:145], v[190:193], v[120:123]
	v_lshl_add_u64 v[232:233], s[30:31], 0, v[134:135]
	v_mfma_f32_16x16x32_bf16 v[116:119], v[156:159], v[190:193], v[116:119]
	v_mfma_f32_16x16x32_bf16 v[108:111], v[142:145], v[198:201], v[108:111]
	v_mfma_f32_16x16x32_bf16 v[100:103], v[156:159], v[198:201], v[100:103]
	v_mfma_f32_16x16x32_bf16 v[92:95], v[142:145], v[206:209], v[92:95]
	v_mfma_f32_16x16x32_bf16 v[84:87], v[156:159], v[206:209], v[84:87]
	v_mfma_f32_16x16x32_bf16 v[76:79], v[142:145], v[214:217], v[76:79]
	v_mfma_f32_16x16x32_bf16 v[68:71], v[156:159], v[214:217], v[68:71]
	v_mfma_f32_16x16x32_bf16 v[124:127], v[160:163], v[186:189], 0
	v_mfma_f32_16x16x32_bf16 v[112:115], v[168:171], v[186:189], 0
	v_mfma_f32_16x16x32_bf16 v[104:107], v[160:163], v[194:197], 0
	v_mfma_f32_16x16x32_bf16 v[96:99], v[168:171], v[194:197], 0
	v_mfma_f32_16x16x32_bf16 v[88:91], v[160:163], v[202:205], 0
	v_mfma_f32_16x16x32_bf16 v[80:83], v[168:171], v[202:205], 0
	v_mfma_f32_16x16x32_bf16 v[72:75], v[160:163], v[210:213], 0
	v_mfma_f32_16x16x32_bf16 v[64:67], v[168:171], v[210:213], 0
	v_mfma_f32_16x16x32_bf16 v[124:127], v[164:167], v[190:193], v[124:127]
	v_mfma_f32_16x16x32_bf16 v[112:115], v[172:175], v[190:193], v[112:115]
	v_mfma_f32_16x16x32_bf16 v[104:107], v[164:167], v[198:201], v[104:107]
	v_mfma_f32_16x16x32_bf16 v[96:99], v[172:175], v[198:201], v[96:99]
	v_mfma_f32_16x16x32_bf16 v[88:91], v[164:167], v[206:209], v[88:91]
	v_mfma_f32_16x16x32_bf16 v[80:83], v[172:175], v[206:209], v[80:83]
	v_mfma_f32_16x16x32_bf16 v[72:75], v[164:167], v[214:217], v[72:75]
	v_mfma_f32_16x16x32_bf16 v[64:67], v[172:175], v[214:217], v[64:67]
	s_barrier
	s_add_i32 s45, s45, s36
	s_mov_b32 m0, s45
	ds_read_b128 v[186:189], v155 offset:16384
	ds_read_b128 v[190:193], v155 offset:17408
	ds_read_b128 v[194:197], v155 offset:18432
	ds_read_b128 v[198:201], v155 offset:19456
	ds_read_b128 v[202:205], v155 offset:20480
	ds_read_b128 v[206:209], v155 offset:21504
	ds_read_b128 v[210:213], v155 offset:22528
	ds_read_b128 v[214:217], v155 offset:23552
	global_load_lds_dwordx4 v[222:223], off
	s_add_i32 m0, s45, 0x2000
	s_add_i32 s45, s54, s36
	global_load_lds_dwordx4 v[224:225], off
	s_mov_b32 m0, s45
	s_nop 0
	global_load_lds_dwordx4 v[226:227], off
	s_add_i32 m0, s45, 0x2000
	s_nop 0
	global_load_lds_dwordx4 v[228:229], off
	s_mov_b32 m0, s37
	s_nop 0
	global_load_lds_dwordx4 v[230:231], off
	s_mov_b32 m0, s38
	s_nop 0
	global_load_lds_dwordx4 v[232:233], off
	s_waitcnt vmcnt(8)
	s_waitcnt lgkmcnt(0)
	s_barrier
	s_waitcnt lgkmcnt(0)
	v_mfma_f32_16x16x32_bf16 v[60:63], v[128:131], v[186:189], 0
	v_mfma_f32_16x16x32_bf16 v[52:55], v[146:149], v[186:189], 0
	v_mfma_f32_16x16x32_bf16 v[44:47], v[128:131], v[194:197], 0
	v_mfma_f32_16x16x32_bf16 v[36:39], v[146:149], v[194:197], 0
	v_mfma_f32_16x16x32_bf16 v[28:31], v[128:131], v[202:205], 0
	v_mfma_f32_16x16x32_bf16 v[20:23], v[146:149], v[202:205], 0
	v_mfma_f32_16x16x32_bf16 v[12:15], v[128:131], v[210:213], 0
	v_mfma_f32_16x16x32_bf16 v[4:7], v[146:149], v[210:213], 0
	v_mfma_f32_16x16x32_bf16 v[60:63], v[142:145], v[190:193], v[60:63]
	v_mfma_f32_16x16x32_bf16 v[52:55], v[156:159], v[190:193], v[52:55]
	v_mfma_f32_16x16x32_bf16 v[44:47], v[142:145], v[198:201], v[44:47]
	v_mfma_f32_16x16x32_bf16 v[36:39], v[156:159], v[198:201], v[36:39]
	v_mfma_f32_16x16x32_bf16 v[28:31], v[142:145], v[206:209], v[28:31]
	v_mfma_f32_16x16x32_bf16 v[20:23], v[156:159], v[206:209], v[20:23]
	v_mfma_f32_16x16x32_bf16 v[12:15], v[142:145], v[214:217], v[12:15]
	v_mfma_f32_16x16x32_bf16 v[4:7], v[156:159], v[214:217], v[4:7]
	v_mfma_f32_16x16x32_bf16 v[56:59], v[160:163], v[186:189], 0
	v_mfma_f32_16x16x32_bf16 v[48:51], v[168:171], v[186:189], 0
	v_mfma_f32_16x16x32_bf16 v[40:43], v[160:163], v[194:197], 0
	v_mfma_f32_16x16x32_bf16 v[32:35], v[168:171], v[194:197], 0
	v_mfma_f32_16x16x32_bf16 v[24:27], v[160:163], v[202:205], 0
	v_mfma_f32_16x16x32_bf16 v[16:19], v[168:171], v[202:205], 0
	v_mfma_f32_16x16x32_bf16 v[8:11], v[160:163], v[210:213], 0
	v_mfma_f32_16x16x32_bf16 v[0:3], v[168:171], v[210:213], 0
	v_mfma_f32_16x16x32_bf16 v[56:59], v[164:167], v[190:193], v[56:59]
	v_mfma_f32_16x16x32_bf16 v[48:51], v[172:175], v[190:193], v[48:51]
	v_mfma_f32_16x16x32_bf16 v[40:43], v[164:167], v[198:201], v[40:43]
	v_mfma_f32_16x16x32_bf16 v[32:35], v[172:175], v[198:201], v[32:35]
	v_mfma_f32_16x16x32_bf16 v[24:27], v[164:167], v[206:209], v[24:27]
	v_mfma_f32_16x16x32_bf16 v[16:19], v[172:175], v[206:209], v[16:19]
	v_mfma_f32_16x16x32_bf16 v[8:11], v[164:167], v[214:217], v[8:11]
	v_mfma_f32_16x16x32_bf16 v[0:3], v[172:175], v[214:217], v[0:3]
	s_barrier
	s_add_i32 s45, 0, 0x18000
	s_add_i32 s54, 0, 0x1c000
	v_add_u32_e32 v156, s45, v151
	v_add_u32_e32 v172, s54, v151
	ds_read_b128 v[128:131], v156
	ds_read_b128 v[142:145], v156 offset:1024
	ds_read_b128 v[146:149], v156 offset:2048
	ds_read_b128 v[156:159], v156 offset:3072
	ds_read_b128 v[160:163], v172
	ds_read_b128 v[164:167], v172 offset:1024
	ds_read_b128 v[168:171], v172 offset:2048
	ds_read_b128 v[172:175], v172 offset:3072
	s_add_u32 s4, s30, s6
	s_addc_u32 s5, s31, s7
	s_mov_b32 m0, s39
	v_lshl_add_u64 v[234:235], s[4:5], 0, v[136:137]
	ds_read_b128 v[186:189], v155 offset:32768
	ds_read_b128 v[190:193], v155 offset:33792
	ds_read_b128 v[194:197], v155 offset:34816
	ds_read_b128 v[198:201], v155 offset:35840
	ds_read_b128 v[202:205], v155 offset:36864
	ds_read_b128 v[206:209], v155 offset:37888
	ds_read_b128 v[210:213], v155 offset:38912
	ds_read_b128 v[214:217], v155 offset:39936
	global_load_lds_dwordx4 v[234:235], off
	v_lshl_add_u64 v[234:235], s[4:5], 0, v[134:135]
	s_mov_b32 m0, s48
	s_nop 0
	global_load_lds_dwordx4 v[234:235], off
	s_waitcnt vmcnt(8)
	s_waitcnt lgkmcnt(0)
	s_barrier
	s_waitcnt lgkmcnt(0)
	v_mfma_f32_16x16x32_bf16 v[120:123], v[128:131], v[186:189], v[120:123]
	v_mfma_f32_16x16x32_bf16 v[116:119], v[146:149], v[186:189], v[116:119]
	v_lshl_add_u64 v[222:223], v[222:223], 0, s[14:15]
	v_mfma_f32_16x16x32_bf16 v[108:111], v[128:131], v[194:197], v[108:111]
	v_lshl_add_u64 v[224:225], v[224:225], 0, s[14:15]
	v_mfma_f32_16x16x32_bf16 v[100:103], v[146:149], v[194:197], v[100:103]
	v_lshl_add_u64 v[226:227], v[226:227], 0, s[14:15]
	v_mfma_f32_16x16x32_bf16 v[92:95], v[128:131], v[202:205], v[92:95]
	v_lshl_add_u64 v[228:229], v[228:229], 0, s[14:15]
	v_mfma_f32_16x16x32_bf16 v[84:87], v[146:149], v[202:205], v[84:87]
	v_lshl_add_u64 v[230:231], v[230:231], 0, s[14:15]
	v_mfma_f32_16x16x32_bf16 v[76:79], v[128:131], v[210:213], v[76:79]
	v_lshl_add_u64 v[232:233], v[232:233], 0, s[14:15]
	v_mfma_f32_16x16x32_bf16 v[68:71], v[146:149], v[210:213], v[68:71]
	v_mfma_f32_16x16x32_bf16 v[120:123], v[142:145], v[190:193], v[120:123]
	v_mfma_f32_16x16x32_bf16 v[116:119], v[156:159], v[190:193], v[116:119]
	v_mfma_f32_16x16x32_bf16 v[108:111], v[142:145], v[198:201], v[108:111]
	v_mfma_f32_16x16x32_bf16 v[100:103], v[156:159], v[198:201], v[100:103]
	v_mfma_f32_16x16x32_bf16 v[92:95], v[142:145], v[206:209], v[92:95]
	v_mfma_f32_16x16x32_bf16 v[84:87], v[156:159], v[206:209], v[84:87]
	v_mfma_f32_16x16x32_bf16 v[76:79], v[142:145], v[214:217], v[76:79]
	v_mfma_f32_16x16x32_bf16 v[68:71], v[156:159], v[214:217], v[68:71]
	v_mfma_f32_16x16x32_bf16 v[124:127], v[160:163], v[186:189], v[124:127]
	v_mfma_f32_16x16x32_bf16 v[112:115], v[168:171], v[186:189], v[112:115]
	v_mfma_f32_16x16x32_bf16 v[104:107], v[160:163], v[194:197], v[104:107]
	v_mfma_f32_16x16x32_bf16 v[96:99], v[168:171], v[194:197], v[96:99]
	v_mfma_f32_16x16x32_bf16 v[88:91], v[160:163], v[202:205], v[88:91]
	v_mfma_f32_16x16x32_bf16 v[80:83], v[168:171], v[202:205], v[80:83]
	v_mfma_f32_16x16x32_bf16 v[72:75], v[160:163], v[210:213], v[72:75]
	v_mfma_f32_16x16x32_bf16 v[64:67], v[168:171], v[210:213], v[64:67]
	v_mfma_f32_16x16x32_bf16 v[124:127], v[164:167], v[190:193], v[124:127]
	v_mfma_f32_16x16x32_bf16 v[112:115], v[172:175], v[190:193], v[112:115]
	v_mfma_f32_16x16x32_bf16 v[104:107], v[164:167], v[198:201], v[104:107]
	v_mfma_f32_16x16x32_bf16 v[96:99], v[172:175], v[198:201], v[96:99]
	v_mfma_f32_16x16x32_bf16 v[88:91], v[164:167], v[206:209], v[88:91]
	v_mfma_f32_16x16x32_bf16 v[80:83], v[172:175], v[206:209], v[80:83]
	v_mfma_f32_16x16x32_bf16 v[72:75], v[164:167], v[214:217], v[72:75]
	v_mfma_f32_16x16x32_bf16 v[64:67], v[172:175], v[214:217], v[64:67]
	s_barrier
	s_add_i32 s4, s45, s36
	s_mov_b32 m0, s4
	ds_read_b128 v[186:189], v155 offset:49152
	ds_read_b128 v[190:193], v155 offset:50176
	ds_read_b128 v[194:197], v155 offset:51200
	ds_read_b128 v[198:201], v155 offset:52224
	ds_read_b128 v[202:205], v155 offset:53248
	ds_read_b128 v[206:209], v155 offset:54272
	ds_read_b128 v[210:213], v155 offset:55296
	ds_read_b128 v[214:217], v155 offset:56320
	global_load_lds_dwordx4 v[222:223], off
	s_add_i32 m0, s4, 0x2000
	s_add_i32 s4, s54, s36
	global_load_lds_dwordx4 v[224:225], off
	s_mov_b32 m0, s4
	s_nop 0
	global_load_lds_dwordx4 v[226:227], off
	s_add_i32 m0, s4, 0x2000
	s_nop 0
	global_load_lds_dwordx4 v[228:229], off
	s_mov_b32 m0, s59
	s_nop 0
	global_load_lds_dwordx4 v[230:231], off
	s_mov_b32 m0, s60
	s_nop 0
	global_load_lds_dwordx4 v[232:233], off
	s_waitcnt vmcnt(8)
	s_waitcnt lgkmcnt(0)
	s_barrier
	s_waitcnt lgkmcnt(0)
	v_mfma_f32_16x16x32_bf16 v[60:63], v[128:131], v[186:189], v[60:63]
	s_add_u32 s28, s28, 0x100
	v_mfma_f32_16x16x32_bf16 v[52:55], v[146:149], v[186:189], v[52:55]
	s_addc_u32 s29, s29, 0
	v_mfma_f32_16x16x32_bf16 v[44:47], v[128:131], v[194:197], v[44:47]
	s_add_u32 s10, s10, 0x100
	v_mfma_f32_16x16x32_bf16 v[36:39], v[146:149], v[194:197], v[36:39]
	s_addc_u32 s11, s11, 0
	v_mfma_f32_16x16x32_bf16 v[28:31], v[128:131], v[202:205], v[28:31]
	s_mov_b32 s30, s44
	v_mfma_f32_16x16x32_bf16 v[20:23], v[146:149], v[202:205], v[20:23]
	s_cmp_ge_i32 s44, s49
	v_mfma_f32_16x16x32_bf16 v[12:15], v[128:131], v[210:213], v[12:15]
	s_cselect_b32 s99, 1, 0
	v_mfma_f32_16x16x32_bf16 v[4:7], v[146:149], v[210:213], v[4:7]
	s_add_i32 s44, s30, 2
	v_mfma_f32_16x16x32_bf16 v[60:63], v[142:145], v[190:193], v[60:63]
	s_add_u32 s4, s28, 0x80
	v_mfma_f32_16x16x32_bf16 v[52:55], v[156:159], v[190:193], v[52:55]
	s_addc_u32 s5, s29, 0
	v_mfma_f32_16x16x32_bf16 v[44:47], v[142:145], v[198:201], v[44:47]
	s_add_i32 s45, 0, 0x10000
	v_mfma_f32_16x16x32_bf16 v[36:39], v[156:159], v[198:201], v[36:39]
	s_cmp_eq_u32 s61, s30
	v_mfma_f32_16x16x32_bf16 v[28:31], v[142:145], v[206:209], v[28:31]
	s_cselect_b32 s31, s25, s5
	v_mfma_f32_16x16x32_bf16 v[20:23], v[156:159], v[206:209], v[20:23]
	s_cselect_b32 s30, s24, s4
	v_mfma_f32_16x16x32_bf16 v[12:15], v[142:145], v[214:217], v[12:15]
	s_cselect_b32 s5, s27, s11
	v_mfma_f32_16x16x32_bf16 v[4:7], v[156:159], v[214:217], v[4:7]
	s_cselect_b32 s4, s26, s10
	v_mfma_f32_16x16x32_bf16 v[56:59], v[160:163], v[186:189], v[56:59]
	s_add_i32 s54, 0, 0x14000
	v_mfma_f32_16x16x32_bf16 v[48:51], v[168:171], v[186:189], v[48:51]
	v_mfma_f32_16x16x32_bf16 v[40:43], v[160:163], v[194:197], v[40:43]
	v_mfma_f32_16x16x32_bf16 v[32:35], v[168:171], v[194:197], v[32:35]
	v_mfma_f32_16x16x32_bf16 v[24:27], v[160:163], v[202:205], v[24:27]
	v_mfma_f32_16x16x32_bf16 v[16:19], v[168:171], v[202:205], v[16:19]
	v_mfma_f32_16x16x32_bf16 v[8:11], v[160:163], v[210:213], v[8:11]
	v_mfma_f32_16x16x32_bf16 v[0:3], v[168:171], v[210:213], v[0:3]
	v_mfma_f32_16x16x32_bf16 v[56:59], v[164:167], v[190:193], v[56:59]
	v_mfma_f32_16x16x32_bf16 v[48:51], v[172:175], v[190:193], v[48:51]
	v_mfma_f32_16x16x32_bf16 v[40:43], v[164:167], v[198:201], v[40:43]
	v_mfma_f32_16x16x32_bf16 v[32:35], v[172:175], v[198:201], v[32:35]
	v_mfma_f32_16x16x32_bf16 v[24:27], v[164:167], v[206:209], v[24:27]
	v_mfma_f32_16x16x32_bf16 v[16:19], v[172:175], v[206:209], v[16:19]
	v_mfma_f32_16x16x32_bf16 v[8:11], v[164:167], v[214:217], v[8:11]
	v_mfma_f32_16x16x32_bf16 v[0:3], v[172:175], v[214:217], v[0:3]
	s_barrier
	s_cmp_lg_u32 s99, 0
	s_cbranch_scc1 .Lpeelx_7
.LBB0_394:
	v_add_u32_e32 v156, s45, v151
	v_add_u32_e32 v172, s54, v151
	ds_read_b128 v[128:131], v156
	ds_read_b128 v[142:145], v156 offset:1024
	ds_read_b128 v[146:149], v156 offset:2048
	ds_read_b128 v[156:159], v156 offset:3072
	ds_read_b128 v[160:163], v172
	ds_read_b128 v[164:167], v172 offset:1024
	ds_read_b128 v[168:171], v172 offset:2048
	ds_read_b128 v[172:175], v172 offset:3072
	v_lshl_add_u64 v[222:223], s[28:29], 0, v[138:139]
	s_add_i32 m0, s37, 0xc000
	ds_read_b128 v[186:189], v155
	ds_read_b128 v[190:193], v155 offset:1024
	ds_read_b128 v[194:197], v155 offset:2048
	ds_read_b128 v[198:201], v155 offset:3072
	ds_read_b128 v[202:205], v155 offset:4096
	ds_read_b128 v[206:209], v155 offset:5120
	ds_read_b128 v[210:213], v155 offset:6144
	ds_read_b128 v[214:217], v155 offset:7168
	global_load_lds_dwordx4 v[222:223], off
	v_lshl_add_u64 v[222:223], s[28:29], 0, v[140:141]
	s_add_i32 m0, s37, 0xe000
	s_nop 0
	global_load_lds_dwordx4 v[222:223], off
	s_waitcnt vmcnt(8)
	s_waitcnt lgkmcnt(0)
	s_barrier
	s_waitcnt lgkmcnt(0)
	v_mfma_f32_16x16x32_bf16 v[120:123], v[128:131], v[186:189], v[120:123]
	v_mfma_f32_16x16x32_bf16 v[116:119], v[146:149], v[186:189], v[116:119]
	v_lshl_add_u64 v[222:223], s[4:5], 0, v[176:177]
	v_mfma_f32_16x16x32_bf16 v[108:111], v[128:131], v[194:197], v[108:111]
	v_lshl_add_u64 v[224:225], s[4:5], 0, v[132:133]
	v_mfma_f32_16x16x32_bf16 v[100:103], v[146:149], v[194:197], v[100:103]
	s_add_u32 s4, s4, s6
	v_mfma_f32_16x16x32_bf16 v[92:95], v[128:131], v[202:205], v[92:95]
	s_addc_u32 s5, s5, s7
	v_mfma_f32_16x16x32_bf16 v[84:87], v[146:149], v[202:205], v[84:87]
	v_lshl_add_u64 v[226:227], s[4:5], 0, v[176:177]
	v_mfma_f32_16x16x32_bf16 v[76:79], v[128:131], v[210:213], v[76:79]
	v_lshl_add_u64 v[228:229], s[4:5], 0, v[132:133]
	v_mfma_f32_16x16x32_bf16 v[68:71], v[146:149], v[210:213], v[68:71]
	v_lshl_add_u64 v[230:231], s[30:31], 0, v[136:137]
	v_mfma_f32_16x16x32_bf16 v[120:123], v[142:145], v[190:193], v[120:123]
	v_lshl_add_u64 v[232:233], s[30:31], 0, v[134:135]
	v_mfma_f32_16x16x32_bf16 v[116:119], v[156:159], v[190:193], v[116:119]
	v_mfma_f32_16x16x32_bf16 v[108:111], v[142:145], v[198:201], v[108:111]
	v_mfma_f32_16x16x32_bf16 v[100:103], v[156:159], v[198:201], v[100:103]
	v_mfma_f32_16x16x32_bf16 v[92:95], v[142:145], v[206:209], v[92:95]
	v_mfma_f32_16x16x32_bf16 v[84:87], v[156:159], v[206:209], v[84:87]
	v_mfma_f32_16x16x32_bf16 v[76:79], v[142:145], v[214:217], v[76:79]
	v_mfma_f32_16x16x32_bf16 v[68:71], v[156:159], v[214:217], v[68:71]
	v_mfma_f32_16x16x32_bf16 v[124:127], v[160:163], v[186:189], v[124:127]
	v_mfma_f32_16x16x32_bf16 v[112:115], v[168:171], v[186:189], v[112:115]
	v_mfma_f32_16x16x32_bf16 v[104:107], v[160:163], v[194:197], v[104:107]
	v_mfma_f32_16x16x32_bf16 v[96:99], v[168:171], v[194:197], v[96:99]
	v_mfma_f32_16x16x32_bf16 v[88:91], v[160:163], v[202:205], v[88:91]
	v_mfma_f32_16x16x32_bf16 v[80:83], v[168:171], v[202:205], v[80:83]
	v_mfma_f32_16x16x32_bf16 v[72:75], v[160:163], v[210:213], v[72:75]
	v_mfma_f32_16x16x32_bf16 v[64:67], v[168:171], v[210:213], v[64:67]
	v_mfma_f32_16x16x32_bf16 v[124:127], v[164:167], v[190:193], v[124:127]
	v_mfma_f32_16x16x32_bf16 v[112:115], v[172:175], v[190:193], v[112:115]
	v_mfma_f32_16x16x32_bf16 v[104:107], v[164:167], v[198:201], v[104:107]
	v_mfma_f32_16x16x32_bf16 v[96:99], v[172:175], v[198:201], v[96:99]
	v_mfma_f32_16x16x32_bf16 v[88:91], v[164:167], v[206:209], v[88:91]
	v_mfma_f32_16x16x32_bf16 v[80:83], v[172:175], v[206:209], v[80:83]
	v_mfma_f32_16x16x32_bf16 v[72:75], v[164:167], v[214:217], v[72:75]
	v_mfma_f32_16x16x32_bf16 v[64:67], v[172:175], v[214:217], v[64:67]
	s_barrier
	s_add_i32 s45, s45, s36
	s_mov_b32 m0, s45
	ds_read_b128 v[186:189], v155 offset:16384
	ds_read_b128 v[190:193], v155 offset:17408
	ds_read_b128 v[194:197], v155 offset:18432
	ds_read_b128 v[198:201], v155 offset:19456
	ds_read_b128 v[202:205], v155 offset:20480
	ds_read_b128 v[206:209], v155 offset:21504
	ds_read_b128 v[210:213], v155 offset:22528
	ds_read_b128 v[214:217], v155 offset:23552
	global_load_lds_dwordx4 v[222:223], off
	s_add_i32 m0, s45, 0x2000
	s_add_i32 s45, s54, s36
	global_load_lds_dwordx4 v[224:225], off
	s_mov_b32 m0, s45
	s_nop 0
	global_load_lds_dwordx4 v[226:227], off
	s_add_i32 m0, s45, 0x2000
	s_nop 0
	global_load_lds_dwordx4 v[228:229], off
	s_mov_b32 m0, s37
	s_nop 0
	global_load_lds_dwordx4 v[230:231], off
	s_mov_b32 m0, s38
	s_nop 0
	global_load_lds_dwordx4 v[232:233], off
	s_waitcnt vmcnt(8)
	s_waitcnt lgkmcnt(0)
	s_barrier
	s_waitcnt lgkmcnt(0)
	v_mfma_f32_16x16x32_bf16 v[60:63], v[128:131], v[186:189], v[60:63]
	v_mfma_f32_16x16x32_bf16 v[52:55], v[146:149], v[186:189], v[52:55]
	v_mfma_f32_16x16x32_bf16 v[44:47], v[128:131], v[194:197], v[44:47]
	v_mfma_f32_16x16x32_bf16 v[36:39], v[146:149], v[194:197], v[36:39]
	v_mfma_f32_16x16x32_bf16 v[28:31], v[128:131], v[202:205], v[28:31]
	v_mfma_f32_16x16x32_bf16 v[20:23], v[146:149], v[202:205], v[20:23]
	v_mfma_f32_16x16x32_bf16 v[12:15], v[128:131], v[210:213], v[12:15]
	v_mfma_f32_16x16x32_bf16 v[4:7], v[146:149], v[210:213], v[4:7]
	v_mfma_f32_16x16x32_bf16 v[60:63], v[142:145], v[190:193], v[60:63]
	v_mfma_f32_16x16x32_bf16 v[52:55], v[156:159], v[190:193], v[52:55]
	v_mfma_f32_16x16x32_bf16 v[44:47], v[142:145], v[198:201], v[44:47]
	v_mfma_f32_16x16x32_bf16 v[36:39], v[156:159], v[198:201], v[36:39]
	v_mfma_f32_16x16x32_bf16 v[28:31], v[142:145], v[206:209], v[28:31]
	v_mfma_f32_16x16x32_bf16 v[20:23], v[156:159], v[206:209], v[20:23]
	v_mfma_f32_16x16x32_bf16 v[12:15], v[142:145], v[214:217], v[12:15]
	v_mfma_f32_16x16x32_bf16 v[4:7], v[156:159], v[214:217], v[4:7]
	v_mfma_f32_16x16x32_bf16 v[56:59], v[160:163], v[186:189], v[56:59]
	v_mfma_f32_16x16x32_bf16 v[48:51], v[168:171], v[186:189], v[48:51]
	v_mfma_f32_16x16x32_bf16 v[40:43], v[160:163], v[194:197], v[40:43]
	v_mfma_f32_16x16x32_bf16 v[32:35], v[168:171], v[194:197], v[32:35]
	v_mfma_f32_16x16x32_bf16 v[24:27], v[160:163], v[202:205], v[24:27]
	v_mfma_f32_16x16x32_bf16 v[16:19], v[168:171], v[202:205], v[16:19]
	v_mfma_f32_16x16x32_bf16 v[8:11], v[160:163], v[210:213], v[8:11]
	v_mfma_f32_16x16x32_bf16 v[0:3], v[168:171], v[210:213], v[0:3]
	v_mfma_f32_16x16x32_bf16 v[56:59], v[164:167], v[190:193], v[56:59]
	v_mfma_f32_16x16x32_bf16 v[48:51], v[172:175], v[190:193], v[48:51]
	v_mfma_f32_16x16x32_bf16 v[40:43], v[164:167], v[198:201], v[40:43]
	v_mfma_f32_16x16x32_bf16 v[32:35], v[172:175], v[198:201], v[32:35]
	v_mfma_f32_16x16x32_bf16 v[24:27], v[164:167], v[206:209], v[24:27]
	v_mfma_f32_16x16x32_bf16 v[16:19], v[172:175], v[206:209], v[16:19]
	v_mfma_f32_16x16x32_bf16 v[8:11], v[164:167], v[214:217], v[8:11]
	v_mfma_f32_16x16x32_bf16 v[0:3], v[172:175], v[214:217], v[0:3]
	s_barrier
	s_add_i32 s45, 0, 0x18000
	s_add_i32 s54, 0, 0x1c000
	v_add_u32_e32 v156, s45, v151
	v_add_u32_e32 v172, s54, v151
	ds_read_b128 v[128:131], v156
	ds_read_b128 v[142:145], v156 offset:1024
	ds_read_b128 v[146:149], v156 offset:2048
	ds_read_b128 v[156:159], v156 offset:3072
	ds_read_b128 v[160:163], v172
	ds_read_b128 v[164:167], v172 offset:1024
	ds_read_b128 v[168:171], v172 offset:2048
	ds_read_b128 v[172:175], v172 offset:3072
	s_add_u32 s4, s30, s6
	s_addc_u32 s5, s31, s7
	s_mov_b32 m0, s39
	v_lshl_add_u64 v[234:235], s[4:5], 0, v[136:137]
	ds_read_b128 v[186:189], v155 offset:32768
	ds_read_b128 v[190:193], v155 offset:33792
	ds_read_b128 v[194:197], v155 offset:34816
	ds_read_b128 v[198:201], v155 offset:35840
	ds_read_b128 v[202:205], v155 offset:36864
	ds_read_b128 v[206:209], v155 offset:37888
	ds_read_b128 v[210:213], v155 offset:38912
	ds_read_b128 v[214:217], v155 offset:39936
	global_load_lds_dwordx4 v[234:235], off
	v_lshl_add_u64 v[234:235], s[4:5], 0, v[134:135]
	s_mov_b32 m0, s48
	s_nop 0
	global_load_lds_dwordx4 v[234:235], off
	s_waitcnt vmcnt(8)
	s_waitcnt lgkmcnt(0)
	s_barrier
	s_waitcnt lgkmcnt(0)
	v_mfma_f32_16x16x32_bf16 v[120:123], v[128:131], v[186:189], v[120:123]
	v_mfma_f32_16x16x32_bf16 v[116:119], v[146:149], v[186:189], v[116:119]
	v_lshl_add_u64 v[222:223], v[222:223], 0, s[14:15]
	v_mfma_f32_16x16x32_bf16 v[108:111], v[128:131], v[194:197], v[108:111]
	v_lshl_add_u64 v[224:225], v[224:225], 0, s[14:15]
	v_mfma_f32_16x16x32_bf16 v[100:103], v[146:149], v[194:197], v[100:103]
	v_lshl_add_u64 v[226:227], v[226:227], 0, s[14:15]
	v_mfma_f32_16x16x32_bf16 v[92:95], v[128:131], v[202:205], v[92:95]
	v_lshl_add_u64 v[228:229], v[228:229], 0, s[14:15]
	v_mfma_f32_16x16x32_bf16 v[84:87], v[146:149], v[202:205], v[84:87]
	v_lshl_add_u64 v[230:231], v[230:231], 0, s[14:15]
	v_mfma_f32_16x16x32_bf16 v[76:79], v[128:131], v[210:213], v[76:79]
	v_lshl_add_u64 v[232:233], v[232:233], 0, s[14:15]
	v_mfma_f32_16x16x32_bf16 v[68:71], v[146:149], v[210:213], v[68:71]
	v_mfma_f32_16x16x32_bf16 v[120:123], v[142:145], v[190:193], v[120:123]
	v_mfma_f32_16x16x32_bf16 v[116:119], v[156:159], v[190:193], v[116:119]
	v_mfma_f32_16x16x32_bf16 v[108:111], v[142:145], v[198:201], v[108:111]
	v_mfma_f32_16x16x32_bf16 v[100:103], v[156:159], v[198:201], v[100:103]
	v_mfma_f32_16x16x32_bf16 v[92:95], v[142:145], v[206:209], v[92:95]
	v_mfma_f32_16x16x32_bf16 v[84:87], v[156:159], v[206:209], v[84:87]
	v_mfma_f32_16x16x32_bf16 v[76:79], v[142:145], v[214:217], v[76:79]
	v_mfma_f32_16x16x32_bf16 v[68:71], v[156:159], v[214:217], v[68:71]
	v_mfma_f32_16x16x32_bf16 v[124:127], v[160:163], v[186:189], v[124:127]
	v_mfma_f32_16x16x32_bf16 v[112:115], v[168:171], v[186:189], v[112:115]
	v_mfma_f32_16x16x32_bf16 v[104:107], v[160:163], v[194:197], v[104:107]
	v_mfma_f32_16x16x32_bf16 v[96:99], v[168:171], v[194:197], v[96:99]
	v_mfma_f32_16x16x32_bf16 v[88:91], v[160:163], v[202:205], v[88:91]
	v_mfma_f32_16x16x32_bf16 v[80:83], v[168:171], v[202:205], v[80:83]
	v_mfma_f32_16x16x32_bf16 v[72:75], v[160:163], v[210:213], v[72:75]
	v_mfma_f32_16x16x32_bf16 v[64:67], v[168:171], v[210:213], v[64:67]
	v_mfma_f32_16x16x32_bf16 v[124:127], v[164:167], v[190:193], v[124:127]
	v_mfma_f32_16x16x32_bf16 v[112:115], v[172:175], v[190:193], v[112:115]
	v_mfma_f32_16x16x32_bf16 v[104:107], v[164:167], v[198:201], v[104:107]
	v_mfma_f32_16x16x32_bf16 v[96:99], v[172:175], v[198:201], v[96:99]
	v_mfma_f32_16x16x32_bf16 v[88:91], v[164:167], v[206:209], v[88:91]
	v_mfma_f32_16x16x32_bf16 v[80:83], v[172:175], v[206:209], v[80:83]
	v_mfma_f32_16x16x32_bf16 v[72:75], v[164:167], v[214:217], v[72:75]
	v_mfma_f32_16x16x32_bf16 v[64:67], v[172:175], v[214:217], v[64:67]
	s_barrier
	s_add_i32 s4, s45, s36
	s_mov_b32 m0, s4
	ds_read_b128 v[186:189], v155 offset:49152
	ds_read_b128 v[190:193], v155 offset:50176
	ds_read_b128 v[194:197], v155 offset:51200
	ds_read_b128 v[198:201], v155 offset:52224
	ds_read_b128 v[202:205], v155 offset:53248
	ds_read_b128 v[206:209], v155 offset:54272
	ds_read_b128 v[210:213], v155 offset:55296
	ds_read_b128 v[214:217], v155 offset:56320
	global_load_lds_dwordx4 v[222:223], off
	s_add_i32 m0, s4, 0x2000
	s_add_i32 s4, s54, s36
	global_load_lds_dwordx4 v[224:225], off
	s_mov_b32 m0, s4
	s_nop 0
	global_load_lds_dwordx4 v[226:227], off
	s_add_i32 m0, s4, 0x2000
	s_nop 0
	global_load_lds_dwordx4 v[228:229], off
	s_mov_b32 m0, s59
	s_nop 0
	global_load_lds_dwordx4 v[230:231], off
	s_mov_b32 m0, s60
	s_nop 0
	global_load_lds_dwordx4 v[232:233], off
	s_waitcnt vmcnt(8)
	s_waitcnt lgkmcnt(0)
	s_barrier
	s_waitcnt lgkmcnt(0)
	v_mfma_f32_16x16x32_bf16 v[60:63], v[128:131], v[186:189], v[60:63]
	s_add_u32 s28, s28, 0x100
	v_mfma_f32_16x16x32_bf16 v[52:55], v[146:149], v[186:189], v[52:55]
	s_addc_u32 s29, s29, 0
	v_mfma_f32_16x16x32_bf16 v[44:47], v[128:131], v[194:197], v[44:47]
	s_add_u32 s10, s10, 0x100
	v_mfma_f32_16x16x32_bf16 v[36:39], v[146:149], v[194:197], v[36:39]
	s_addc_u32 s11, s11, 0
	v_mfma_f32_16x16x32_bf16 v[28:31], v[128:131], v[202:205], v[28:31]
	s_mov_b32 s30, s44
	v_mfma_f32_16x16x32_bf16 v[20:23], v[146:149], v[202:205], v[20:23]
	s_cmp_ge_i32 s44, s49
	v_mfma_f32_16x16x32_bf16 v[12:15], v[128:131], v[210:213], v[12:15]
	s_cselect_b32 s99, 1, 0
	v_mfma_f32_16x16x32_bf16 v[4:7], v[146:149], v[210:213], v[4:7]
	s_add_i32 s44, s30, 2
	v_mfma_f32_16x16x32_bf16 v[60:63], v[142:145], v[190:193], v[60:63]
	s_add_u32 s4, s28, 0x80
	v_mfma_f32_16x16x32_bf16 v[52:55], v[156:159], v[190:193], v[52:55]
	s_addc_u32 s5, s29, 0
	v_mfma_f32_16x16x32_bf16 v[44:47], v[142:145], v[198:201], v[44:47]
	s_add_i32 s45, 0, 0x10000
	v_mfma_f32_16x16x32_bf16 v[36:39], v[156:159], v[198:201], v[36:39]
	s_cmp_eq_u32 s61, s30
	v_mfma_f32_16x16x32_bf16 v[28:31], v[142:145], v[206:209], v[28:31]
	s_cselect_b32 s31, s25, s5
	v_mfma_f32_16x16x32_bf16 v[20:23], v[156:159], v[206:209], v[20:23]
	s_cselect_b32 s30, s24, s4
	v_mfma_f32_16x16x32_bf16 v[12:15], v[142:145], v[214:217], v[12:15]
	s_cselect_b32 s5, s27, s11
	v_mfma_f32_16x16x32_bf16 v[4:7], v[156:159], v[214:217], v[4:7]
	s_cselect_b32 s4, s26, s10
	v_mfma_f32_16x16x32_bf16 v[56:59], v[160:163], v[186:189], v[56:59]
	s_add_i32 s54, 0, 0x14000
	v_mfma_f32_16x16x32_bf16 v[48:51], v[168:171], v[186:189], v[48:51]
	v_mfma_f32_16x16x32_bf16 v[40:43], v[160:163], v[194:197], v[40:43]
	v_mfma_f32_16x16x32_bf16 v[32:35], v[168:171], v[194:197], v[32:35]
	v_mfma_f32_16x16x32_bf16 v[24:27], v[160:163], v[202:205], v[24:27]
	v_mfma_f32_16x16x32_bf16 v[16:19], v[168:171], v[202:205], v[16:19]
	v_mfma_f32_16x16x32_bf16 v[8:11], v[160:163], v[210:213], v[8:11]
	v_mfma_f32_16x16x32_bf16 v[0:3], v[168:171], v[210:213], v[0:3]
	v_mfma_f32_16x16x32_bf16 v[56:59], v[164:167], v[190:193], v[56:59]
	v_mfma_f32_16x16x32_bf16 v[48:51], v[172:175], v[190:193], v[48:51]
	v_mfma_f32_16x16x32_bf16 v[40:43], v[164:167], v[198:201], v[40:43]
	v_mfma_f32_16x16x32_bf16 v[32:35], v[172:175], v[198:201], v[32:35]
	v_mfma_f32_16x16x32_bf16 v[24:27], v[164:167], v[206:209], v[24:27]
	v_mfma_f32_16x16x32_bf16 v[16:19], v[172:175], v[206:209], v[16:19]
	v_mfma_f32_16x16x32_bf16 v[8:11], v[164:167], v[214:217], v[8:11]
	v_mfma_f32_16x16x32_bf16 v[0:3], v[172:175], v[214:217], v[0:3]
	s_barrier
	s_cmp_lg_u32 s99, 0
	s_cbranch_scc0 .LBB0_394

.Llbb_4:
	s_add_i32 s44, s30, 2
	s_add_u32 s4, s28, 0x80
	s_addc_u32 s5, s29, 0
	s_add_i32 s45, 0, 0x10000
	s_cmp_eq_u32 s61, s30
	s_cselect_b32 s31, s25, s5
	s_cselect_b32 s30, s24, s4
	s_cselect_b32 s5, s27, s11
	s_cselect_b32 s4, s26, s10
	s_add_i32 s54, 0, 0x14000
	v_add_u32_e32 v140, s45, v195
	v_add_u32_e32 v166, s54, v195
	ds_read_b128 v[128:131], v140
	ds_read_b128 v[132:135], v140 offset:1024
	ds_read_b128 v[136:139], v140 offset:2048
	ds_read_b128 v[140:143], v140 offset:3072
	ds_read_b128 v[144:147], v166
	ds_read_b128 v[148:151], v166 offset:1024
	ds_read_b128 v[152:155], v166 offset:2048
	ds_read_b128 v[166:169], v166 offset:3072
	v_lshl_add_u64 v[174:175], s[28:29], 0, v[162:163]
	s_add_i32 m0, s38, 0xc000
	ds_read_b128 v[170:173], v197
	ds_read_b128 v[186:189], v197 offset:1024
	ds_read_b128 v[190:193], v197 offset:2048
	ds_read_b128 v[198:201], v197 offset:3072
	ds_read_b128 v[202:205], v197 offset:4096
	ds_read_b128 v[206:209], v197 offset:5120
	ds_read_b128 v[210:213], v197 offset:6144
	ds_read_b128 v[214:217], v197 offset:7168
	global_load_lds_dwordx4 v[174:175], off
	v_lshl_add_u64 v[174:175], s[28:29], 0, v[164:165]
	s_add_i32 m0, s38, 0xe000
	s_nop 0
	global_load_lds_dwordx4 v[174:175], off
	s_waitcnt vmcnt(8)
	s_waitcnt lgkmcnt(0)
	s_barrier
	s_waitcnt lgkmcnt(0)
	v_mfma_f32_16x16x32_bf16 v[120:123], v[128:131], v[170:173], 0
	v_mfma_f32_16x16x32_bf16 v[124:127], v[136:139], v[170:173], 0
	v_lshl_add_u64 v[174:175], s[4:5], 0, v[176:177]
	v_mfma_f32_16x16x32_bf16 v[108:111], v[128:131], v[190:193], 0
	v_lshl_add_u64 v[222:223], s[4:5], 0, v[156:157]
	v_mfma_f32_16x16x32_bf16 v[104:107], v[136:139], v[190:193], 0
	s_add_u32 s4, s4, s6
	v_mfma_f32_16x16x32_bf16 v[92:95], v[128:131], v[202:205], 0
	s_addc_u32 s5, s5, s7
	v_mfma_f32_16x16x32_bf16 v[88:91], v[136:139], v[202:205], 0
	v_lshl_add_u64 v[224:225], s[4:5], 0, v[176:177]
	v_mfma_f32_16x16x32_bf16 v[76:79], v[128:131], v[210:213], 0
	v_lshl_add_u64 v[226:227], s[4:5], 0, v[156:157]
	v_mfma_f32_16x16x32_bf16 v[72:75], v[136:139], v[210:213], 0
	v_lshl_add_u64 v[228:229], s[30:31], 0, v[160:161]
	v_mfma_f32_16x16x32_bf16 v[120:123], v[132:135], v[186:189], v[120:123]
	v_lshl_add_u64 v[230:231], s[30:31], 0, v[158:159]
	v_mfma_f32_16x16x32_bf16 v[124:127], v[140:143], v[186:189], v[124:127]
	v_mfma_f32_16x16x32_bf16 v[108:111], v[132:135], v[198:201], v[108:111]
	v_mfma_f32_16x16x32_bf16 v[104:107], v[140:143], v[198:201], v[104:107]
	v_mfma_f32_16x16x32_bf16 v[92:95], v[132:135], v[206:209], v[92:95]
	v_mfma_f32_16x16x32_bf16 v[88:91], v[140:143], v[206:209], v[88:91]
	v_mfma_f32_16x16x32_bf16 v[76:79], v[132:135], v[214:217], v[76:79]
	v_mfma_f32_16x16x32_bf16 v[72:75], v[140:143], v[214:217], v[72:75]
	v_mfma_f32_16x16x32_bf16 v[116:119], v[144:147], v[170:173], 0
	v_mfma_f32_16x16x32_bf16 v[112:115], v[152:155], v[170:173], 0
	v_mfma_f32_16x16x32_bf16 v[100:103], v[144:147], v[190:193], 0
	v_mfma_f32_16x16x32_bf16 v[96:99], v[152:155], v[190:193], 0
	v_mfma_f32_16x16x32_bf16 v[84:87], v[144:147], v[202:205], 0
	v_mfma_f32_16x16x32_bf16 v[80:83], v[152:155], v[202:205], 0
	v_mfma_f32_16x16x32_bf16 v[68:71], v[144:147], v[210:213], 0
	v_mfma_f32_16x16x32_bf16 v[64:67], v[152:155], v[210:213], 0
	v_mfma_f32_16x16x32_bf16 v[116:119], v[148:151], v[186:189], v[116:119]
	v_mfma_f32_16x16x32_bf16 v[112:115], v[166:169], v[186:189], v[112:115]
	v_mfma_f32_16x16x32_bf16 v[100:103], v[148:151], v[198:201], v[100:103]
	v_mfma_f32_16x16x32_bf16 v[96:99], v[166:169], v[198:201], v[96:99]
	v_mfma_f32_16x16x32_bf16 v[84:87], v[148:151], v[206:209], v[84:87]
	v_mfma_f32_16x16x32_bf16 v[80:83], v[166:169], v[206:209], v[80:83]
	v_mfma_f32_16x16x32_bf16 v[68:71], v[148:151], v[214:217], v[68:71]
	v_mfma_f32_16x16x32_bf16 v[64:67], v[166:169], v[214:217], v[64:67]
	s_barrier
	s_add_i32 s45, s45, s37
	s_mov_b32 m0, s45
	ds_read_b128 v[170:173], v197 offset:16384
	ds_read_b128 v[186:189], v197 offset:17408
	ds_read_b128 v[190:193], v197 offset:18432
	ds_read_b128 v[198:201], v197 offset:19456
	ds_read_b128 v[202:205], v197 offset:20480
	ds_read_b128 v[206:209], v197 offset:21504
	ds_read_b128 v[210:213], v197 offset:22528
	ds_read_b128 v[214:217], v197 offset:23552
	global_load_lds_dwordx4 v[174:175], off
	s_add_i32 m0, s45, 0x2000
	s_add_i32 s45, s54, s37
	global_load_lds_dwordx4 v[222:223], off
	s_mov_b32 m0, s45
	s_nop 0
	global_load_lds_dwordx4 v[224:225], off
	s_add_i32 m0, s45, 0x2000
	s_nop 0
	global_load_lds_dwordx4 v[226:227], off
	s_mov_b32 m0, s38
	s_nop 0
	global_load_lds_dwordx4 v[228:229], off
	s_mov_b32 m0, s39
	s_nop 0
	global_load_lds_dwordx4 v[230:231], off
	s_waitcnt vmcnt(8)
	s_waitcnt lgkmcnt(0)
	s_barrier
	s_waitcnt lgkmcnt(0)
	v_mfma_f32_16x16x32_bf16 v[60:63], v[128:131], v[170:173], 0
	v_mfma_f32_16x16x32_bf16 v[56:59], v[136:139], v[170:173], 0
	v_mfma_f32_16x16x32_bf16 v[44:47], v[128:131], v[190:193], 0
	v_mfma_f32_16x16x32_bf16 v[40:43], v[136:139], v[190:193], 0
	v_mfma_f32_16x16x32_bf16 v[28:31], v[128:131], v[202:205], 0
	v_mfma_f32_16x16x32_bf16 v[24:27], v[136:139], v[202:205], 0
	v_mfma_f32_16x16x32_bf16 v[12:15], v[128:131], v[210:213], 0
	v_mfma_f32_16x16x32_bf16 v[8:11], v[136:139], v[210:213], 0
	v_mfma_f32_16x16x32_bf16 v[60:63], v[132:135], v[186:189], v[60:63]
	v_mfma_f32_16x16x32_bf16 v[56:59], v[140:143], v[186:189], v[56:59]
	v_mfma_f32_16x16x32_bf16 v[44:47], v[132:135], v[198:201], v[44:47]
	v_mfma_f32_16x16x32_bf16 v[40:43], v[140:143], v[198:201], v[40:43]
	v_mfma_f32_16x16x32_bf16 v[28:31], v[132:135], v[206:209], v[28:31]
	v_mfma_f32_16x16x32_bf16 v[24:27], v[140:143], v[206:209], v[24:27]
	v_mfma_f32_16x16x32_bf16 v[12:15], v[132:135], v[214:217], v[12:15]
	v_mfma_f32_16x16x32_bf16 v[8:11], v[140:143], v[214:217], v[8:11]
	v_mfma_f32_16x16x32_bf16 v[52:55], v[144:147], v[170:173], 0
	v_mfma_f32_16x16x32_bf16 v[48:51], v[152:155], v[170:173], 0
	v_mfma_f32_16x16x32_bf16 v[36:39], v[144:147], v[190:193], 0
	v_mfma_f32_16x16x32_bf16 v[32:35], v[152:155], v[190:193], 0
	v_mfma_f32_16x16x32_bf16 v[20:23], v[144:147], v[202:205], 0
	v_mfma_f32_16x16x32_bf16 v[16:19], v[152:155], v[202:205], 0
	v_mfma_f32_16x16x32_bf16 v[4:7], v[144:147], v[210:213], 0
	v_mfma_f32_16x16x32_bf16 v[0:3], v[152:155], v[210:213], 0
	v_mfma_f32_16x16x32_bf16 v[52:55], v[148:151], v[186:189], v[52:55]
	v_mfma_f32_16x16x32_bf16 v[48:51], v[166:169], v[186:189], v[48:51]
	v_mfma_f32_16x16x32_bf16 v[36:39], v[148:151], v[198:201], v[36:39]
	v_mfma_f32_16x16x32_bf16 v[32:35], v[166:169], v[198:201], v[32:35]
	v_mfma_f32_16x16x32_bf16 v[20:23], v[148:151], v[206:209], v[20:23]
	v_mfma_f32_16x16x32_bf16 v[16:19], v[166:169], v[206:209], v[16:19]
	v_mfma_f32_16x16x32_bf16 v[4:7], v[148:151], v[214:217], v[4:7]
	v_mfma_f32_16x16x32_bf16 v[0:3], v[166:169], v[214:217], v[0:3]
	s_barrier
	s_add_i32 s45, 0, 0x18000
	s_add_i32 s54, 0, 0x1c000
	v_add_u32_e32 v140, s45, v195
	v_add_u32_e32 v166, s54, v195
	ds_read_b128 v[128:131], v140
	ds_read_b128 v[132:135], v140 offset:1024
	ds_read_b128 v[136:139], v140 offset:2048
	ds_read_b128 v[140:143], v140 offset:3072
	ds_read_b128 v[144:147], v166
	ds_read_b128 v[148:151], v166 offset:1024
	ds_read_b128 v[152:155], v166 offset:2048
	ds_read_b128 v[166:169], v166 offset:3072
	s_add_u32 s4, s30, s6
	s_addc_u32 s5, s31, s7
	s_mov_b32 m0, s48
	v_lshl_add_u64 v[232:233], s[4:5], 0, v[160:161]
	ds_read_b128 v[170:173], v197 offset:32768
	ds_read_b128 v[186:189], v197 offset:33792
	ds_read_b128 v[190:193], v197 offset:34816
	ds_read_b128 v[198:201], v197 offset:35840
	ds_read_b128 v[202:205], v197 offset:36864
	ds_read_b128 v[206:209], v197 offset:37888
	ds_read_b128 v[210:213], v197 offset:38912
	ds_read_b128 v[214:217], v197 offset:39936
	global_load_lds_dwordx4 v[232:233], off
	v_lshl_add_u64 v[232:233], s[4:5], 0, v[158:159]
	s_mov_b32 m0, s49
	s_nop 0
	global_load_lds_dwordx4 v[232:233], off
	s_waitcnt vmcnt(8)
	s_waitcnt lgkmcnt(0)
	s_barrier
	s_waitcnt lgkmcnt(0)
	v_mfma_f32_16x16x32_bf16 v[120:123], v[128:131], v[170:173], v[120:123]
	v_mfma_f32_16x16x32_bf16 v[124:127], v[136:139], v[170:173], v[124:127]
	v_lshl_add_u64 v[174:175], v[174:175], 0, s[14:15]
	v_mfma_f32_16x16x32_bf16 v[108:111], v[128:131], v[190:193], v[108:111]
	v_lshl_add_u64 v[222:223], v[222:223], 0, s[14:15]
	v_mfma_f32_16x16x32_bf16 v[104:107], v[136:139], v[190:193], v[104:107]
	v_lshl_add_u64 v[224:225], v[224:225], 0, s[14:15]
	v_mfma_f32_16x16x32_bf16 v[92:95], v[128:131], v[202:205], v[92:95]
	v_lshl_add_u64 v[226:227], v[226:227], 0, s[14:15]
	v_mfma_f32_16x16x32_bf16 v[88:91], v[136:139], v[202:205], v[88:91]
	v_lshl_add_u64 v[228:229], v[228:229], 0, s[14:15]
	v_mfma_f32_16x16x32_bf16 v[76:79], v[128:131], v[210:213], v[76:79]
	v_lshl_add_u64 v[230:231], v[230:231], 0, s[14:15]
	v_mfma_f32_16x16x32_bf16 v[72:75], v[136:139], v[210:213], v[72:75]
	v_mfma_f32_16x16x32_bf16 v[120:123], v[132:135], v[186:189], v[120:123]
	v_mfma_f32_16x16x32_bf16 v[124:127], v[140:143], v[186:189], v[124:127]
	v_mfma_f32_16x16x32_bf16 v[108:111], v[132:135], v[198:201], v[108:111]
	v_mfma_f32_16x16x32_bf16 v[104:107], v[140:143], v[198:201], v[104:107]
	v_mfma_f32_16x16x32_bf16 v[92:95], v[132:135], v[206:209], v[92:95]
	v_mfma_f32_16x16x32_bf16 v[88:91], v[140:143], v[206:209], v[88:91]
	v_mfma_f32_16x16x32_bf16 v[76:79], v[132:135], v[214:217], v[76:79]
	v_mfma_f32_16x16x32_bf16 v[72:75], v[140:143], v[214:217], v[72:75]
	v_mfma_f32_16x16x32_bf16 v[116:119], v[144:147], v[170:173], v[116:119]
	v_mfma_f32_16x16x32_bf16 v[112:115], v[152:155], v[170:173], v[112:115]
	v_mfma_f32_16x16x32_bf16 v[100:103], v[144:147], v[190:193], v[100:103]
	v_mfma_f32_16x16x32_bf16 v[96:99], v[152:155], v[190:193], v[96:99]
	v_mfma_f32_16x16x32_bf16 v[84:87], v[144:147], v[202:205], v[84:87]
	v_mfma_f32_16x16x32_bf16 v[80:83], v[152:155], v[202:205], v[80:83]
	v_mfma_f32_16x16x32_bf16 v[68:71], v[144:147], v[210:213], v[68:71]
	v_mfma_f32_16x16x32_bf16 v[64:67], v[152:155], v[210:213], v[64:67]
	v_mfma_f32_16x16x32_bf16 v[116:119], v[148:151], v[186:189], v[116:119]
	v_mfma_f32_16x16x32_bf16 v[112:115], v[166:169], v[186:189], v[112:115]
	v_mfma_f32_16x16x32_bf16 v[100:103], v[148:151], v[198:201], v[100:103]
	v_mfma_f32_16x16x32_bf16 v[96:99], v[166:169], v[198:201], v[96:99]
	v_mfma_f32_16x16x32_bf16 v[84:87], v[148:151], v[206:209], v[84:87]
	v_mfma_f32_16x16x32_bf16 v[80:83], v[166:169], v[206:209], v[80:83]
	v_mfma_f32_16x16x32_bf16 v[68:71], v[148:151], v[214:217], v[68:71]
	v_mfma_f32_16x16x32_bf16 v[64:67], v[166:169], v[214:217], v[64:67]
	s_barrier
	s_add_i32 s4, s45, s37
	s_mov_b32 m0, s4
	ds_read_b128 v[170:173], v197 offset:49152
	ds_read_b128 v[186:189], v197 offset:50176
	ds_read_b128 v[190:193], v197 offset:51200
	ds_read_b128 v[198:201], v197 offset:52224
	ds_read_b128 v[202:205], v197 offset:53248
	ds_read_b128 v[206:209], v197 offset:54272
	ds_read_b128 v[210:213], v197 offset:55296
	ds_read_b128 v[214:217], v197 offset:56320
	global_load_lds_dwordx4 v[174:175], off
	s_add_i32 m0, s4, 0x2000
	s_add_i32 s4, s54, s37
	global_load_lds_dwordx4 v[222:223], off
	s_mov_b32 m0, s4
	s_nop 0
	global_load_lds_dwordx4 v[224:225], off
	s_add_i32 m0, s4, 0x2000
	s_nop 0
	global_load_lds_dwordx4 v[226:227], off
	s_mov_b32 m0, s59
	s_nop 0
	global_load_lds_dwordx4 v[228:229], off
	s_mov_b32 m0, s60
	s_nop 0
	global_load_lds_dwordx4 v[230:231], off
	s_waitcnt vmcnt(8)
	s_waitcnt lgkmcnt(0)
	s_barrier
	s_waitcnt lgkmcnt(0)
	v_mfma_f32_16x16x32_bf16 v[60:63], v[128:131], v[170:173], v[60:63]
	s_add_u32 s28, s28, 0x100
	v_mfma_f32_16x16x32_bf16 v[56:59], v[136:139], v[170:173], v[56:59]
	s_addc_u32 s29, s29, 0
	v_mfma_f32_16x16x32_bf16 v[44:47], v[128:131], v[190:193], v[44:47]
	s_add_u32 s10, s10, 0x100
	v_mfma_f32_16x16x32_bf16 v[40:43], v[136:139], v[190:193], v[40:43]
	s_addc_u32 s11, s11, 0
	v_mfma_f32_16x16x32_bf16 v[28:31], v[128:131], v[202:205], v[28:31]
	s_mov_b32 s30, s44
	v_mfma_f32_16x16x32_bf16 v[24:27], v[136:139], v[202:205], v[24:27]
	s_cmp_ge_i32 s44, s58
	v_mfma_f32_16x16x32_bf16 v[12:15], v[128:131], v[210:213], v[12:15]
	s_cselect_b32 s99, 1, 0
	v_mfma_f32_16x16x32_bf16 v[8:11], v[136:139], v[210:213], v[8:11]
	s_add_i32 s44, s30, 2
	v_mfma_f32_16x16x32_bf16 v[60:63], v[132:135], v[186:189], v[60:63]
	s_add_u32 s4, s28, 0x80
	v_mfma_f32_16x16x32_bf16 v[56:59], v[140:143], v[186:189], v[56:59]
	s_addc_u32 s5, s29, 0
	v_mfma_f32_16x16x32_bf16 v[44:47], v[132:135], v[198:201], v[44:47]
	s_add_i32 s45, 0, 0x10000
	v_mfma_f32_16x16x32_bf16 v[40:43], v[140:143], v[198:201], v[40:43]
	s_cmp_eq_u32 s61, s30
	v_mfma_f32_16x16x32_bf16 v[28:31], v[132:135], v[206:209], v[28:31]
	s_cselect_b32 s31, s25, s5
	v_mfma_f32_16x16x32_bf16 v[24:27], v[140:143], v[206:209], v[24:27]
	s_cselect_b32 s30, s24, s4
	v_mfma_f32_16x16x32_bf16 v[12:15], v[132:135], v[214:217], v[12:15]
	s_cselect_b32 s5, s27, s11
	v_mfma_f32_16x16x32_bf16 v[8:11], v[140:143], v[214:217], v[8:11]
	s_cselect_b32 s4, s26, s10
	v_mfma_f32_16x16x32_bf16 v[52:55], v[144:147], v[170:173], v[52:55]
	s_add_i32 s54, 0, 0x14000
	v_mfma_f32_16x16x32_bf16 v[48:51], v[152:155], v[170:173], v[48:51]
	v_mfma_f32_16x16x32_bf16 v[36:39], v[144:147], v[190:193], v[36:39]
	v_mfma_f32_16x16x32_bf16 v[32:35], v[152:155], v[190:193], v[32:35]
	v_mfma_f32_16x16x32_bf16 v[20:23], v[144:147], v[202:205], v[20:23]
	v_mfma_f32_16x16x32_bf16 v[16:19], v[152:155], v[202:205], v[16:19]
	v_mfma_f32_16x16x32_bf16 v[4:7], v[144:147], v[210:213], v[4:7]
	v_mfma_f32_16x16x32_bf16 v[0:3], v[152:155], v[210:213], v[0:3]
	v_mfma_f32_16x16x32_bf16 v[52:55], v[148:151], v[186:189], v[52:55]
	v_mfma_f32_16x16x32_bf16 v[48:51], v[166:169], v[186:189], v[48:51]
	v_mfma_f32_16x16x32_bf16 v[36:39], v[148:151], v[198:201], v[36:39]
	v_mfma_f32_16x16x32_bf16 v[32:35], v[166:169], v[198:201], v[32:35]
	v_mfma_f32_16x16x32_bf16 v[20:23], v[148:151], v[206:209], v[20:23]
	v_mfma_f32_16x16x32_bf16 v[16:19], v[166:169], v[206:209], v[16:19]
	v_mfma_f32_16x16x32_bf16 v[4:7], v[148:151], v[214:217], v[4:7]
	v_mfma_f32_16x16x32_bf16 v[0:3], v[166:169], v[214:217], v[0:3]
	s_barrier
	s_cmp_lg_u32 s99, 0
	s_cbranch_scc1 .Lpeelx_8
.LBB0_475:
	v_add_u32_e32 v140, s45, v195
	v_add_u32_e32 v166, s54, v195
	ds_read_b128 v[128:131], v140
	ds_read_b128 v[132:135], v140 offset:1024
	ds_read_b128 v[136:139], v140 offset:2048
	ds_read_b128 v[140:143], v140 offset:3072
	ds_read_b128 v[144:147], v166
	ds_read_b128 v[148:151], v166 offset:1024
	ds_read_b128 v[152:155], v166 offset:2048
	ds_read_b128 v[166:169], v166 offset:3072
	v_lshl_add_u64 v[174:175], s[28:29], 0, v[162:163]
	s_add_i32 m0, s38, 0xc000
	ds_read_b128 v[170:173], v197
	ds_read_b128 v[186:189], v197 offset:1024
	ds_read_b128 v[190:193], v197 offset:2048
	ds_read_b128 v[198:201], v197 offset:3072
	ds_read_b128 v[202:205], v197 offset:4096
	ds_read_b128 v[206:209], v197 offset:5120
	ds_read_b128 v[210:213], v197 offset:6144
	ds_read_b128 v[214:217], v197 offset:7168
	global_load_lds_dwordx4 v[174:175], off
	v_lshl_add_u64 v[174:175], s[28:29], 0, v[164:165]
	s_add_i32 m0, s38, 0xe000
	s_nop 0
	global_load_lds_dwordx4 v[174:175], off
	s_waitcnt vmcnt(8)
	s_waitcnt lgkmcnt(0)
	s_barrier
	s_waitcnt lgkmcnt(0)
	v_mfma_f32_16x16x32_bf16 v[120:123], v[128:131], v[170:173], v[120:123]
	v_mfma_f32_16x16x32_bf16 v[124:127], v[136:139], v[170:173], v[124:127]
	v_lshl_add_u64 v[174:175], s[4:5], 0, v[176:177]
	v_mfma_f32_16x16x32_bf16 v[108:111], v[128:131], v[190:193], v[108:111]
	v_lshl_add_u64 v[222:223], s[4:5], 0, v[156:157]
	v_mfma_f32_16x16x32_bf16 v[104:107], v[136:139], v[190:193], v[104:107]
	s_add_u32 s4, s4, s6
	v_mfma_f32_16x16x32_bf16 v[92:95], v[128:131], v[202:205], v[92:95]
	s_addc_u32 s5, s5, s7
	v_mfma_f32_16x16x32_bf16 v[88:91], v[136:139], v[202:205], v[88:91]
	v_lshl_add_u64 v[224:225], s[4:5], 0, v[176:177]
	v_mfma_f32_16x16x32_bf16 v[76:79], v[128:131], v[210:213], v[76:79]
	v_lshl_add_u64 v[226:227], s[4:5], 0, v[156:157]
	v_mfma_f32_16x16x32_bf16 v[72:75], v[136:139], v[210:213], v[72:75]
	v_lshl_add_u64 v[228:229], s[30:31], 0, v[160:161]
	v_mfma_f32_16x16x32_bf16 v[120:123], v[132:135], v[186:189], v[120:123]
	v_lshl_add_u64 v[230:231], s[30:31], 0, v[158:159]
	v_mfma_f32_16x16x32_bf16 v[124:127], v[140:143], v[186:189], v[124:127]
	v_mfma_f32_16x16x32_bf16 v[108:111], v[132:135], v[198:201], v[108:111]
	v_mfma_f32_16x16x32_bf16 v[104:107], v[140:143], v[198:201], v[104:107]
	v_mfma_f32_16x16x32_bf16 v[92:95], v[132:135], v[206:209], v[92:95]
	v_mfma_f32_16x16x32_bf16 v[88:91], v[140:143], v[206:209], v[88:91]
	v_mfma_f32_16x16x32_bf16 v[76:79], v[132:135], v[214:217], v[76:79]
	v_mfma_f32_16x16x32_bf16 v[72:75], v[140:143], v[214:217], v[72:75]
	v_mfma_f32_16x16x32_bf16 v[116:119], v[144:147], v[170:173], v[116:119]
	v_mfma_f32_16x16x32_bf16 v[112:115], v[152:155], v[170:173], v[112:115]
	v_mfma_f32_16x16x32_bf16 v[100:103], v[144:147], v[190:193], v[100:103]
	v_mfma_f32_16x16x32_bf16 v[96:99], v[152:155], v[190:193], v[96:99]
	v_mfma_f32_16x16x32_bf16 v[84:87], v[144:147], v[202:205], v[84:87]
	v_mfma_f32_16x16x32_bf16 v[80:83], v[152:155], v[202:205], v[80:83]
	v_mfma_f32_16x16x32_bf16 v[68:71], v[144:147], v[210:213], v[68:71]
	v_mfma_f32_16x16x32_bf16 v[64:67], v[152:155], v[210:213], v[64:67]
	v_mfma_f32_16x16x32_bf16 v[116:119], v[148:151], v[186:189], v[116:119]
	v_mfma_f32_16x16x32_bf16 v[112:115], v[166:169], v[186:189], v[112:115]
	v_mfma_f32_16x16x32_bf16 v[100:103], v[148:151], v[198:201], v[100:103]
	v_mfma_f32_16x16x32_bf16 v[96:99], v[166:169], v[198:201], v[96:99]
	v_mfma_f32_16x16x32_bf16 v[84:87], v[148:151], v[206:209], v[84:87]
	v_mfma_f32_16x16x32_bf16 v[80:83], v[166:169], v[206:209], v[80:83]
	v_mfma_f32_16x16x32_bf16 v[68:71], v[148:151], v[214:217], v[68:71]
	v_mfma_f32_16x16x32_bf16 v[64:67], v[166:169], v[214:217], v[64:67]
	s_barrier
	s_add_i32 s45, s45, s37
	s_mov_b32 m0, s45
	ds_read_b128 v[170:173], v197 offset:16384
	ds_read_b128 v[186:189], v197 offset:17408
	ds_read_b128 v[190:193], v197 offset:18432
	ds_read_b128 v[198:201], v197 offset:19456
	ds_read_b128 v[202:205], v197 offset:20480
	ds_read_b128 v[206:209], v197 offset:21504
	ds_read_b128 v[210:213], v197 offset:22528
	ds_read_b128 v[214:217], v197 offset:23552
	global_load_lds_dwordx4 v[174:175], off
	s_add_i32 m0, s45, 0x2000
	s_add_i32 s45, s54, s37
	global_load_lds_dwordx4 v[222:223], off
	s_mov_b32 m0, s45
	s_nop 0
	global_load_lds_dwordx4 v[224:225], off
	s_add_i32 m0, s45, 0x2000
	s_nop 0
	global_load_lds_dwordx4 v[226:227], off
	s_mov_b32 m0, s38
	s_nop 0
	global_load_lds_dwordx4 v[228:229], off
	s_mov_b32 m0, s39
	s_nop 0
	global_load_lds_dwordx4 v[230:231], off
	s_waitcnt vmcnt(8)
	s_waitcnt lgkmcnt(0)
	s_barrier
	s_waitcnt lgkmcnt(0)
	v_mfma_f32_16x16x32_bf16 v[60:63], v[128:131], v[170:173], v[60:63]
	v_mfma_f32_16x16x32_bf16 v[56:59], v[136:139], v[170:173], v[56:59]
	v_mfma_f32_16x16x32_bf16 v[44:47], v[128:131], v[190:193], v[44:47]
	v_mfma_f32_16x16x32_bf16 v[40:43], v[136:139], v[190:193], v[40:43]
	v_mfma_f32_16x16x32_bf16 v[28:31], v[128:131], v[202:205], v[28:31]
	v_mfma_f32_16x16x32_bf16 v[24:27], v[136:139], v[202:205], v[24:27]
	v_mfma_f32_16x16x32_bf16 v[12:15], v[128:131], v[210:213], v[12:15]
	v_mfma_f32_16x16x32_bf16 v[8:11], v[136:139], v[210:213], v[8:11]
	v_mfma_f32_16x16x32_bf16 v[60:63], v[132:135], v[186:189], v[60:63]
	v_mfma_f32_16x16x32_bf16 v[56:59], v[140:143], v[186:189], v[56:59]
	v_mfma_f32_16x16x32_bf16 v[44:47], v[132:135], v[198:201], v[44:47]
	v_mfma_f32_16x16x32_bf16 v[40:43], v[140:143], v[198:201], v[40:43]
	v_mfma_f32_16x16x32_bf16 v[28:31], v[132:135], v[206:209], v[28:31]
	v_mfma_f32_16x16x32_bf16 v[24:27], v[140:143], v[206:209], v[24:27]
	v_mfma_f32_16x16x32_bf16 v[12:15], v[132:135], v[214:217], v[12:15]
	v_mfma_f32_16x16x32_bf16 v[8:11], v[140:143], v[214:217], v[8:11]
	v_mfma_f32_16x16x32_bf16 v[52:55], v[144:147], v[170:173], v[52:55]
	v_mfma_f32_16x16x32_bf16 v[48:51], v[152:155], v[170:173], v[48:51]
	v_mfma_f32_16x16x32_bf16 v[36:39], v[144:147], v[190:193], v[36:39]
	v_mfma_f32_16x16x32_bf16 v[32:35], v[152:155], v[190:193], v[32:35]
	v_mfma_f32_16x16x32_bf16 v[20:23], v[144:147], v[202:205], v[20:23]
	v_mfma_f32_16x16x32_bf16 v[16:19], v[152:155], v[202:205], v[16:19]
	v_mfma_f32_16x16x32_bf16 v[4:7], v[144:147], v[210:213], v[4:7]
	v_mfma_f32_16x16x32_bf16 v[0:3], v[152:155], v[210:213], v[0:3]
	v_mfma_f32_16x16x32_bf16 v[52:55], v[148:151], v[186:189], v[52:55]
	v_mfma_f32_16x16x32_bf16 v[48:51], v[166:169], v[186:189], v[48:51]
	v_mfma_f32_16x16x32_bf16 v[36:39], v[148:151], v[198:201], v[36:39]
	v_mfma_f32_16x16x32_bf16 v[32:35], v[166:169], v[198:201], v[32:35]
	v_mfma_f32_16x16x32_bf16 v[20:23], v[148:151], v[206:209], v[20:23]
	v_mfma_f32_16x16x32_bf16 v[16:19], v[166:169], v[206:209], v[16:19]
	v_mfma_f32_16x16x32_bf16 v[4:7], v[148:151], v[214:217], v[4:7]
	v_mfma_f32_16x16x32_bf16 v[0:3], v[166:169], v[214:217], v[0:3]
	s_barrier
	s_add_i32 s45, 0, 0x18000
	s_add_i32 s54, 0, 0x1c000
	v_add_u32_e32 v140, s45, v195
	v_add_u32_e32 v166, s54, v195
	ds_read_b128 v[128:131], v140
	ds_read_b128 v[132:135], v140 offset:1024
	ds_read_b128 v[136:139], v140 offset:2048
	ds_read_b128 v[140:143], v140 offset:3072
	ds_read_b128 v[144:147], v166
	ds_read_b128 v[148:151], v166 offset:1024
	ds_read_b128 v[152:155], v166 offset:2048
	ds_read_b128 v[166:169], v166 offset:3072
	s_add_u32 s4, s30, s6
	s_addc_u32 s5, s31, s7
	s_mov_b32 m0, s48
	v_lshl_add_u64 v[232:233], s[4:5], 0, v[160:161]
	ds_read_b128 v[170:173], v197 offset:32768
	ds_read_b128 v[186:189], v197 offset:33792
	ds_read_b128 v[190:193], v197 offset:34816
	ds_read_b128 v[198:201], v197 offset:35840
	ds_read_b128 v[202:205], v197 offset:36864
	ds_read_b128 v[206:209], v197 offset:37888
	ds_read_b128 v[210:213], v197 offset:38912
	ds_read_b128 v[214:217], v197 offset:39936
	global_load_lds_dwordx4 v[232:233], off
	v_lshl_add_u64 v[232:233], s[4:5], 0, v[158:159]
	s_mov_b32 m0, s49
	s_nop 0
	global_load_lds_dwordx4 v[232:233], off
	s_waitcnt vmcnt(8)
	s_waitcnt lgkmcnt(0)
	s_barrier
	s_waitcnt lgkmcnt(0)
	v_mfma_f32_16x16x32_bf16 v[120:123], v[128:131], v[170:173], v[120:123]
	v_mfma_f32_16x16x32_bf16 v[124:127], v[136:139], v[170:173], v[124:127]
	v_lshl_add_u64 v[174:175], v[174:175], 0, s[14:15]
	v_mfma_f32_16x16x32_bf16 v[108:111], v[128:131], v[190:193], v[108:111]
	v_lshl_add_u64 v[222:223], v[222:223], 0, s[14:15]
	v_mfma_f32_16x16x32_bf16 v[104:107], v[136:139], v[190:193], v[104:107]
	v_lshl_add_u64 v[224:225], v[224:225], 0, s[14:15]
	v_mfma_f32_16x16x32_bf16 v[92:95], v[128:131], v[202:205], v[92:95]
	v_lshl_add_u64 v[226:227], v[226:227], 0, s[14:15]
	v_mfma_f32_16x16x32_bf16 v[88:91], v[136:139], v[202:205], v[88:91]
	v_lshl_add_u64 v[228:229], v[228:229], 0, s[14:15]
	v_mfma_f32_16x16x32_bf16 v[76:79], v[128:131], v[210:213], v[76:79]
	v_lshl_add_u64 v[230:231], v[230:231], 0, s[14:15]
	v_mfma_f32_16x16x32_bf16 v[72:75], v[136:139], v[210:213], v[72:75]
	v_mfma_f32_16x16x32_bf16 v[120:123], v[132:135], v[186:189], v[120:123]
	v_mfma_f32_16x16x32_bf16 v[124:127], v[140:143], v[186:189], v[124:127]
	v_mfma_f32_16x16x32_bf16 v[108:111], v[132:135], v[198:201], v[108:111]
	v_mfma_f32_16x16x32_bf16 v[104:107], v[140:143], v[198:201], v[104:107]
	v_mfma_f32_16x16x32_bf16 v[92:95], v[132:135], v[206:209], v[92:95]
	v_mfma_f32_16x16x32_bf16 v[88:91], v[140:143], v[206:209], v[88:91]
	v_mfma_f32_16x16x32_bf16 v[76:79], v[132:135], v[214:217], v[76:79]
	v_mfma_f32_16x16x32_bf16 v[72:75], v[140:143], v[214:217], v[72:75]
	v_mfma_f32_16x16x32_bf16 v[116:119], v[144:147], v[170:173], v[116:119]
	v_mfma_f32_16x16x32_bf16 v[112:115], v[152:155], v[170:173], v[112:115]
	v_mfma_f32_16x16x32_bf16 v[100:103], v[144:147], v[190:193], v[100:103]
	v_mfma_f32_16x16x32_bf16 v[96:99], v[152:155], v[190:193], v[96:99]
	v_mfma_f32_16x16x32_bf16 v[84:87], v[144:147], v[202:205], v[84:87]
	v_mfma_f32_16x16x32_bf16 v[80:83], v[152:155], v[202:205], v[80:83]
	v_mfma_f32_16x16x32_bf16 v[68:71], v[144:147], v[210:213], v[68:71]
	v_mfma_f32_16x16x32_bf16 v[64:67], v[152:155], v[210:213], v[64:67]
	v_mfma_f32_16x16x32_bf16 v[116:119], v[148:151], v[186:189], v[116:119]
	v_mfma_f32_16x16x32_bf16 v[112:115], v[166:169], v[186:189], v[112:115]
	v_mfma_f32_16x16x32_bf16 v[100:103], v[148:151], v[198:201], v[100:103]
	v_mfma_f32_16x16x32_bf16 v[96:99], v[166:169], v[198:201], v[96:99]
	v_mfma_f32_16x16x32_bf16 v[84:87], v[148:151], v[206:209], v[84:87]
	v_mfma_f32_16x16x32_bf16 v[80:83], v[166:169], v[206:209], v[80:83]
	v_mfma_f32_16x16x32_bf16 v[68:71], v[148:151], v[214:217], v[68:71]
	v_mfma_f32_16x16x32_bf16 v[64:67], v[166:169], v[214:217], v[64:67]
	s_barrier
	s_add_i32 s4, s45, s37
	s_mov_b32 m0, s4
	ds_read_b128 v[170:173], v197 offset:49152
	ds_read_b128 v[186:189], v197 offset:50176
	ds_read_b128 v[190:193], v197 offset:51200
	ds_read_b128 v[198:201], v197 offset:52224
	ds_read_b128 v[202:205], v197 offset:53248
	ds_read_b128 v[206:209], v197 offset:54272
	ds_read_b128 v[210:213], v197 offset:55296
	ds_read_b128 v[214:217], v197 offset:56320
	global_load_lds_dwordx4 v[174:175], off
	s_add_i32 m0, s4, 0x2000
	s_add_i32 s4, s54, s37
	global_load_lds_dwordx4 v[222:223], off
	s_mov_b32 m0, s4
	s_nop 0
	global_load_lds_dwordx4 v[224:225], off
	s_add_i32 m0, s4, 0x2000
	s_nop 0
	global_load_lds_dwordx4 v[226:227], off
	s_mov_b32 m0, s59
	s_nop 0
	global_load_lds_dwordx4 v[228:229], off
	s_mov_b32 m0, s60
	s_nop 0
	global_load_lds_dwordx4 v[230:231], off
	s_waitcnt vmcnt(8)
	s_waitcnt lgkmcnt(0)
	s_barrier
	s_waitcnt lgkmcnt(0)
	v_mfma_f32_16x16x32_bf16 v[60:63], v[128:131], v[170:173], v[60:63]
	s_add_u32 s28, s28, 0x100
	v_mfma_f32_16x16x32_bf16 v[56:59], v[136:139], v[170:173], v[56:59]
	s_addc_u32 s29, s29, 0
	v_mfma_f32_16x16x32_bf16 v[44:47], v[128:131], v[190:193], v[44:47]
	s_add_u32 s10, s10, 0x100
	v_mfma_f32_16x16x32_bf16 v[40:43], v[136:139], v[190:193], v[40:43]
	s_addc_u32 s11, s11, 0
	v_mfma_f32_16x16x32_bf16 v[28:31], v[128:131], v[202:205], v[28:31]
	s_mov_b32 s30, s44
	v_mfma_f32_16x16x32_bf16 v[24:27], v[136:139], v[202:205], v[24:27]
	s_cmp_ge_i32 s44, s58
	v_mfma_f32_16x16x32_bf16 v[12:15], v[128:131], v[210:213], v[12:15]
	s_cselect_b32 s99, 1, 0
	v_mfma_f32_16x16x32_bf16 v[8:11], v[136:139], v[210:213], v[8:11]
	s_add_i32 s44, s30, 2
	v_mfma_f32_16x16x32_bf16 v[60:63], v[132:135], v[186:189], v[60:63]
	s_add_u32 s4, s28, 0x80
	v_mfma_f32_16x16x32_bf16 v[56:59], v[140:143], v[186:189], v[56:59]
	s_addc_u32 s5, s29, 0
	v_mfma_f32_16x16x32_bf16 v[44:47], v[132:135], v[198:201], v[44:47]
	s_add_i32 s45, 0, 0x10000
	v_mfma_f32_16x16x32_bf16 v[40:43], v[140:143], v[198:201], v[40:43]
	s_cmp_eq_u32 s61, s30
	v_mfma_f32_16x16x32_bf16 v[28:31], v[132:135], v[206:209], v[28:31]
	s_cselect_b32 s31, s25, s5
	v_mfma_f32_16x16x32_bf16 v[24:27], v[140:143], v[206:209], v[24:27]
	s_cselect_b32 s30, s24, s4
	v_mfma_f32_16x16x32_bf16 v[12:15], v[132:135], v[214:217], v[12:15]
	s_cselect_b32 s5, s27, s11
	v_mfma_f32_16x16x32_bf16 v[8:11], v[140:143], v[214:217], v[8:11]
	s_cselect_b32 s4, s26, s10
	v_mfma_f32_16x16x32_bf16 v[52:55], v[144:147], v[170:173], v[52:55]
	s_add_i32 s54, 0, 0x14000
	v_mfma_f32_16x16x32_bf16 v[48:51], v[152:155], v[170:173], v[48:51]
	v_mfma_f32_16x16x32_bf16 v[36:39], v[144:147], v[190:193], v[36:39]
	v_mfma_f32_16x16x32_bf16 v[32:35], v[152:155], v[190:193], v[32:35]
	v_mfma_f32_16x16x32_bf16 v[20:23], v[144:147], v[202:205], v[20:23]
	v_mfma_f32_16x16x32_bf16 v[16:19], v[152:155], v[202:205], v[16:19]
	v_mfma_f32_16x16x32_bf16 v[4:7], v[144:147], v[210:213], v[4:7]
	v_mfma_f32_16x16x32_bf16 v[0:3], v[152:155], v[210:213], v[0:3]
	v_mfma_f32_16x16x32_bf16 v[52:55], v[148:151], v[186:189], v[52:55]
	v_mfma_f32_16x16x32_bf16 v[48:51], v[166:169], v[186:189], v[48:51]
	v_mfma_f32_16x16x32_bf16 v[36:39], v[148:151], v[198:201], v[36:39]
	v_mfma_f32_16x16x32_bf16 v[32:35], v[166:169], v[198:201], v[32:35]
	v_mfma_f32_16x16x32_bf16 v[20:23], v[148:151], v[206:209], v[20:23]
	v_mfma_f32_16x16x32_bf16 v[16:19], v[166:169], v[206:209], v[16:19]
	v_mfma_f32_16x16x32_bf16 v[4:7], v[148:151], v[214:217], v[4:7]
	v_mfma_f32_16x16x32_bf16 v[0:3], v[166:169], v[214:217], v[0:3]
	s_barrier
	s_cmp_lg_u32 s99, 0
	s_cbranch_scc0 .LBB0_475

.Llbb_5:
	s_add_i32 s44, s16, 2
	s_add_u32 s45, s0, 0x80
	s_addc_u32 s17, s1, 0
	s_add_i32 s64, 0, 0x10000
	s_cmp_eq_u32 s63, s16
	s_cselect_b32 s17, s57, s17
	s_cselect_b32 s16, s56, s45
	v_add_u32_e32 v152, s64, v153
	s_cselect_b32 s47, s9, s39
	s_cselect_b32 s46, s8, s38
	s_add_i32 s45, 0, 0x14000
	ds_read_b128 v[128:131], v152
	ds_read_b128 v[158:161], v152 offset:1024
	ds_read_b128 v[162:165], v152 offset:2048
	ds_read_b128 v[166:169], v152 offset:3072
	v_add_u32_e32 v152, s45, v153
	ds_read_b128 v[170:173], v152
	ds_read_b128 v[174:177], v152 offset:1024
	ds_read_b128 v[194:197], v152 offset:2048
	ds_read_b128 v[206:209], v152 offset:3072
	v_lshl_add_u64 v[178:179], s[0:1], 0, v[148:149]
	s_add_i32 m0, s52, 0xc000
	ds_read_b128 v[210:213], v157
	ds_read_b128 v[214:217], v157 offset:1024
	ds_read_b128 v[220:223], v157 offset:2048
	ds_read_b128 v[224:227], v157 offset:3072
	ds_read_b128 v[228:231], v157 offset:4096
	ds_read_b128 v[232:235], v157 offset:5120
	ds_read_b128 v[236:239], v157 offset:6144
	ds_read_b128 v[240:243], v157 offset:7168
	global_load_lds_dwordx4 v[178:179], off
	v_lshl_add_u64 v[178:179], s[0:1], 0, v[150:151]
	s_add_i32 m0, s52, 0xe000
	s_nop 0
	global_load_lds_dwordx4 v[178:179], off
	s_waitcnt vmcnt(8)
	s_waitcnt lgkmcnt(0)
	s_barrier
	s_waitcnt lgkmcnt(0)
	v_mfma_f32_16x16x32_bf16 v[124:127], v[128:131], v[210:213], 0
	v_mfma_f32_16x16x32_bf16 v[120:123], v[162:165], v[210:213], 0
	v_lshl_add_u64 v[178:179], s[46:47], 0, v[134:135]
	v_mfma_f32_16x16x32_bf16 v[108:111], v[128:131], v[220:223], 0
	v_lshl_add_u64 v[198:199], s[46:47], 0, v[138:139]
	v_mfma_f32_16x16x32_bf16 v[104:107], v[162:165], v[220:223], 0
	s_add_u32 s46, s46, s24
	v_mfma_f32_16x16x32_bf16 v[92:95], v[128:131], v[228:231], 0
	s_addc_u32 s47, s47, s25
	v_mfma_f32_16x16x32_bf16 v[88:91], v[162:165], v[228:231], 0
	v_lshl_add_u64 v[244:245], s[46:47], 0, v[134:135]
	v_mfma_f32_16x16x32_bf16 v[76:79], v[128:131], v[236:239], 0
	v_lshl_add_u64 v[246:247], s[46:47], 0, v[138:139]
	v_mfma_f32_16x16x32_bf16 v[72:75], v[162:165], v[236:239], 0
	v_lshl_add_u64 v[248:249], s[16:17], 0, v[132:133]
	v_mfma_f32_16x16x32_bf16 v[124:127], v[158:161], v[214:217], v[124:127]
	v_lshl_add_u64 v[250:251], s[16:17], 0, v[136:137]
	v_mfma_f32_16x16x32_bf16 v[120:123], v[166:169], v[214:217], v[120:123]
	v_mfma_f32_16x16x32_bf16 v[108:111], v[158:161], v[224:227], v[108:111]
	v_mfma_f32_16x16x32_bf16 v[104:107], v[166:169], v[224:227], v[104:107]
	v_mfma_f32_16x16x32_bf16 v[92:95], v[158:161], v[232:235], v[92:95]
	v_mfma_f32_16x16x32_bf16 v[88:91], v[166:169], v[232:235], v[88:91]
	v_mfma_f32_16x16x32_bf16 v[76:79], v[158:161], v[240:243], v[76:79]
	v_mfma_f32_16x16x32_bf16 v[72:75], v[166:169], v[240:243], v[72:75]
	v_mfma_f32_16x16x32_bf16 v[116:119], v[170:173], v[210:213], 0
	v_mfma_f32_16x16x32_bf16 v[112:115], v[194:197], v[210:213], 0
	v_mfma_f32_16x16x32_bf16 v[100:103], v[170:173], v[220:223], 0
	v_mfma_f32_16x16x32_bf16 v[96:99], v[194:197], v[220:223], 0
	v_mfma_f32_16x16x32_bf16 v[84:87], v[170:173], v[228:231], 0
	v_mfma_f32_16x16x32_bf16 v[80:83], v[194:197], v[228:231], 0
	v_mfma_f32_16x16x32_bf16 v[68:71], v[170:173], v[236:239], 0
	v_mfma_f32_16x16x32_bf16 v[64:67], v[194:197], v[236:239], 0
	v_mfma_f32_16x16x32_bf16 v[116:119], v[174:177], v[214:217], v[116:119]
	v_mfma_f32_16x16x32_bf16 v[112:115], v[206:209], v[214:217], v[112:115]
	v_mfma_f32_16x16x32_bf16 v[100:103], v[174:177], v[224:227], v[100:103]
	v_mfma_f32_16x16x32_bf16 v[96:99], v[206:209], v[224:227], v[96:99]
	v_mfma_f32_16x16x32_bf16 v[84:87], v[174:177], v[232:235], v[84:87]
	v_mfma_f32_16x16x32_bf16 v[80:83], v[206:209], v[232:235], v[80:83]
	v_mfma_f32_16x16x32_bf16 v[68:71], v[174:177], v[240:243], v[68:71]
	v_mfma_f32_16x16x32_bf16 v[64:67], v[206:209], v[240:243], v[64:67]
	s_barrier
	s_add_i32 s64, s64, s4
	s_mov_b32 m0, s64
	ds_read_b128 v[210:213], v157 offset:16384
	ds_read_b128 v[214:217], v157 offset:17408
	ds_read_b128 v[220:223], v157 offset:18432
	ds_read_b128 v[224:227], v157 offset:19456
	ds_read_b128 v[228:231], v157 offset:20480
	ds_read_b128 v[232:235], v157 offset:21504
	ds_read_b128 v[236:239], v157 offset:22528
	ds_read_b128 v[240:243], v157 offset:23552
	global_load_lds_dwordx4 v[178:179], off
	s_add_i32 m0, s64, 0x2000
	s_add_i32 s45, s45, s4
	global_load_lds_dwordx4 v[198:199], off
	s_mov_b32 m0, s45
	s_nop 0
	global_load_lds_dwordx4 v[244:245], off
	s_add_i32 m0, s45, 0x2000
	s_nop 0
	global_load_lds_dwordx4 v[246:247], off
	s_mov_b32 m0, s52
	s_nop 0
	global_load_lds_dwordx4 v[248:249], off
	s_mov_b32 m0, s18
	s_nop 0
	global_load_lds_dwordx4 v[250:251], off
	s_waitcnt vmcnt(8)
	s_waitcnt lgkmcnt(0)
	s_barrier
	s_waitcnt lgkmcnt(0)
	v_mfma_f32_16x16x32_bf16 v[60:63], v[128:131], v[210:213], 0
	v_mfma_f32_16x16x32_bf16 v[56:59], v[162:165], v[210:213], 0
	v_mfma_f32_16x16x32_bf16 v[44:47], v[128:131], v[220:223], 0
	v_mfma_f32_16x16x32_bf16 v[40:43], v[162:165], v[220:223], 0
	v_mfma_f32_16x16x32_bf16 v[28:31], v[128:131], v[228:231], 0
	v_mfma_f32_16x16x32_bf16 v[24:27], v[162:165], v[228:231], 0
	v_mfma_f32_16x16x32_bf16 v[12:15], v[128:131], v[236:239], 0
	v_mfma_f32_16x16x32_bf16 v[8:11], v[162:165], v[236:239], 0
	v_mfma_f32_16x16x32_bf16 v[60:63], v[158:161], v[214:217], v[60:63]
	v_mfma_f32_16x16x32_bf16 v[56:59], v[166:169], v[214:217], v[56:59]
	v_mfma_f32_16x16x32_bf16 v[44:47], v[158:161], v[224:227], v[44:47]
	v_mfma_f32_16x16x32_bf16 v[40:43], v[166:169], v[224:227], v[40:43]
	v_mfma_f32_16x16x32_bf16 v[28:31], v[158:161], v[232:235], v[28:31]
	v_mfma_f32_16x16x32_bf16 v[24:27], v[166:169], v[232:235], v[24:27]
	v_mfma_f32_16x16x32_bf16 v[12:15], v[158:161], v[240:243], v[12:15]
	v_mfma_f32_16x16x32_bf16 v[8:11], v[166:169], v[240:243], v[8:11]
	v_mfma_f32_16x16x32_bf16 v[52:55], v[170:173], v[210:213], 0
	v_mfma_f32_16x16x32_bf16 v[48:51], v[194:197], v[210:213], 0
	v_mfma_f32_16x16x32_bf16 v[36:39], v[170:173], v[220:223], 0
	v_mfma_f32_16x16x32_bf16 v[32:35], v[194:197], v[220:223], 0
	v_mfma_f32_16x16x32_bf16 v[20:23], v[170:173], v[228:231], 0
	v_mfma_f32_16x16x32_bf16 v[16:19], v[194:197], v[228:231], 0
	v_mfma_f32_16x16x32_bf16 v[4:7], v[170:173], v[236:239], 0
	v_mfma_f32_16x16x32_bf16 v[0:3], v[194:197], v[236:239], 0
	v_mfma_f32_16x16x32_bf16 v[52:55], v[174:177], v[214:217], v[52:55]
	v_mfma_f32_16x16x32_bf16 v[48:51], v[206:209], v[214:217], v[48:51]
	v_mfma_f32_16x16x32_bf16 v[36:39], v[174:177], v[224:227], v[36:39]
	v_mfma_f32_16x16x32_bf16 v[32:35], v[206:209], v[224:227], v[32:35]
	v_mfma_f32_16x16x32_bf16 v[20:23], v[174:177], v[232:235], v[20:23]
	v_mfma_f32_16x16x32_bf16 v[16:19], v[206:209], v[232:235], v[16:19]
	v_mfma_f32_16x16x32_bf16 v[4:7], v[174:177], v[240:243], v[4:7]
	v_mfma_f32_16x16x32_bf16 v[0:3], v[206:209], v[240:243], v[0:3]
	s_barrier
	s_add_i32 s45, 0, 0x18000
	v_add_u32_e32 v152, s45, v153
	s_add_i32 s46, 0, 0x1c000
	ds_read_b128 v[128:131], v152
	ds_read_b128 v[158:161], v152 offset:1024
	ds_read_b128 v[162:165], v152 offset:2048
	ds_read_b128 v[166:169], v152 offset:3072
	v_add_u32_e32 v152, s46, v153
	ds_read_b128 v[170:173], v152
	ds_read_b128 v[174:177], v152 offset:1024
	ds_read_b128 v[194:197], v152 offset:2048
	ds_read_b128 v[206:209], v152 offset:3072
	s_add_u32 s16, s16, s24
	s_addc_u32 s17, s17, s25
	s_mov_b32 m0, s19
	v_lshl_add_u64 v[202:203], s[16:17], 0, v[132:133]
	ds_read_b128 v[210:213], v157 offset:32768
	ds_read_b128 v[214:217], v157 offset:33792
	ds_read_b128 v[220:223], v157 offset:34816
	ds_read_b128 v[224:227], v157 offset:35840
	ds_read_b128 v[228:231], v157 offset:36864
	ds_read_b128 v[232:235], v157 offset:37888
	ds_read_b128 v[236:239], v157 offset:38912
	ds_read_b128 v[240:243], v157 offset:39936
	global_load_lds_dwordx4 v[202:203], off
	v_lshl_add_u64 v[202:203], s[16:17], 0, v[136:137]
	s_mov_b32 m0, s33
	s_nop 0
	global_load_lds_dwordx4 v[202:203], off
	s_waitcnt vmcnt(8)
	s_waitcnt lgkmcnt(0)
	s_barrier
	s_waitcnt lgkmcnt(0)
	v_mfma_f32_16x16x32_bf16 v[124:127], v[128:131], v[210:213], v[124:127]
	v_mfma_f32_16x16x32_bf16 v[120:123], v[162:165], v[210:213], v[120:123]
	v_lshl_add_u64 v[178:179], v[178:179], 0, s[12:13]
	v_mfma_f32_16x16x32_bf16 v[108:111], v[128:131], v[220:223], v[108:111]
	v_lshl_add_u64 v[198:199], v[198:199], 0, s[12:13]
	v_mfma_f32_16x16x32_bf16 v[104:107], v[162:165], v[220:223], v[104:107]
	v_lshl_add_u64 v[244:245], v[244:245], 0, s[12:13]
	v_mfma_f32_16x16x32_bf16 v[92:95], v[128:131], v[228:231], v[92:95]
	v_lshl_add_u64 v[246:247], v[246:247], 0, s[12:13]
	v_mfma_f32_16x16x32_bf16 v[88:91], v[162:165], v[228:231], v[88:91]
	v_lshl_add_u64 v[248:249], v[248:249], 0, s[12:13]
	v_mfma_f32_16x16x32_bf16 v[76:79], v[128:131], v[236:239], v[76:79]
	v_lshl_add_u64 v[250:251], v[250:251], 0, s[12:13]
	v_mfma_f32_16x16x32_bf16 v[72:75], v[162:165], v[236:239], v[72:75]
	v_mfma_f32_16x16x32_bf16 v[124:127], v[158:161], v[214:217], v[124:127]
	v_mfma_f32_16x16x32_bf16 v[120:123], v[166:169], v[214:217], v[120:123]
	v_mfma_f32_16x16x32_bf16 v[108:111], v[158:161], v[224:227], v[108:111]
	v_mfma_f32_16x16x32_bf16 v[104:107], v[166:169], v[224:227], v[104:107]
	v_mfma_f32_16x16x32_bf16 v[92:95], v[158:161], v[232:235], v[92:95]
	v_mfma_f32_16x16x32_bf16 v[88:91], v[166:169], v[232:235], v[88:91]
	v_mfma_f32_16x16x32_bf16 v[76:79], v[158:161], v[240:243], v[76:79]
	v_mfma_f32_16x16x32_bf16 v[72:75], v[166:169], v[240:243], v[72:75]
	v_mfma_f32_16x16x32_bf16 v[116:119], v[170:173], v[210:213], v[116:119]
	v_mfma_f32_16x16x32_bf16 v[112:115], v[194:197], v[210:213], v[112:115]
	v_mfma_f32_16x16x32_bf16 v[100:103], v[170:173], v[220:223], v[100:103]
	v_mfma_f32_16x16x32_bf16 v[96:99], v[194:197], v[220:223], v[96:99]
	v_mfma_f32_16x16x32_bf16 v[84:87], v[170:173], v[228:231], v[84:87]
	v_mfma_f32_16x16x32_bf16 v[80:83], v[194:197], v[228:231], v[80:83]
	v_mfma_f32_16x16x32_bf16 v[68:71], v[170:173], v[236:239], v[68:71]
	v_mfma_f32_16x16x32_bf16 v[64:67], v[194:197], v[236:239], v[64:67]
	v_mfma_f32_16x16x32_bf16 v[116:119], v[174:177], v[214:217], v[116:119]
	v_mfma_f32_16x16x32_bf16 v[112:115], v[206:209], v[214:217], v[112:115]
	v_mfma_f32_16x16x32_bf16 v[100:103], v[174:177], v[224:227], v[100:103]
	v_mfma_f32_16x16x32_bf16 v[96:99], v[206:209], v[224:227], v[96:99]
	v_mfma_f32_16x16x32_bf16 v[84:87], v[174:177], v[232:235], v[84:87]
	v_mfma_f32_16x16x32_bf16 v[80:83], v[206:209], v[232:235], v[80:83]
	v_mfma_f32_16x16x32_bf16 v[68:71], v[174:177], v[240:243], v[68:71]
	v_mfma_f32_16x16x32_bf16 v[64:67], v[206:209], v[240:243], v[64:67]
	s_barrier
	s_add_i32 s16, s45, s4
	s_mov_b32 m0, s16
	ds_read_b128 v[210:213], v157 offset:49152
	ds_read_b128 v[214:217], v157 offset:50176
	ds_read_b128 v[220:223], v157 offset:51200
	ds_read_b128 v[224:227], v157 offset:52224
	ds_read_b128 v[228:231], v157 offset:53248
	ds_read_b128 v[232:235], v157 offset:54272
	ds_read_b128 v[236:239], v157 offset:55296
	ds_read_b128 v[240:243], v157 offset:56320
	global_load_lds_dwordx4 v[178:179], off
	s_add_i32 m0, s16, 0x2000
	s_add_i32 s16, s46, s4
	global_load_lds_dwordx4 v[198:199], off
	s_mov_b32 m0, s16
	s_nop 0
	global_load_lds_dwordx4 v[244:245], off
	s_add_i32 m0, s16, 0x2000
	s_nop 0
	global_load_lds_dwordx4 v[246:247], off
	s_mov_b32 m0, s59
	s_nop 0
	global_load_lds_dwordx4 v[248:249], off
	s_mov_b32 m0, s60
	s_nop 0
	global_load_lds_dwordx4 v[250:251], off
	s_waitcnt vmcnt(8)
	s_waitcnt lgkmcnt(0)
	s_barrier
	s_waitcnt lgkmcnt(0)
	v_mfma_f32_16x16x32_bf16 v[60:63], v[128:131], v[210:213], v[60:63]
	s_add_u32 s0, s0, 0x100
	v_mfma_f32_16x16x32_bf16 v[56:59], v[162:165], v[210:213], v[56:59]
	s_addc_u32 s1, s1, 0
	v_mfma_f32_16x16x32_bf16 v[44:47], v[128:131], v[220:223], v[44:47]
	s_add_u32 s38, s38, 0x100
	v_mfma_f32_16x16x32_bf16 v[40:43], v[162:165], v[220:223], v[40:43]
	s_addc_u32 s39, s39, 0
	v_mfma_f32_16x16x32_bf16 v[28:31], v[128:131], v[228:231], v[28:31]
	s_mov_b32 s16, s44
	v_mfma_f32_16x16x32_bf16 v[24:27], v[162:165], v[228:231], v[24:27]
	s_cmp_ge_i32 s44, s68
	v_mfma_f32_16x16x32_bf16 v[12:15], v[128:131], v[236:239], v[12:15]
	s_cselect_b32 s99, 1, 0
	v_mfma_f32_16x16x32_bf16 v[8:11], v[162:165], v[236:239], v[8:11]
	s_add_i32 s44, s16, 2
	v_mfma_f32_16x16x32_bf16 v[60:63], v[158:161], v[214:217], v[60:63]
	s_add_u32 s45, s0, 0x80
	v_mfma_f32_16x16x32_bf16 v[56:59], v[166:169], v[214:217], v[56:59]
	s_addc_u32 s17, s1, 0
	v_mfma_f32_16x16x32_bf16 v[44:47], v[158:161], v[224:227], v[44:47]
	s_add_i32 s64, 0, 0x10000
	v_mfma_f32_16x16x32_bf16 v[40:43], v[166:169], v[224:227], v[40:43]
	s_cmp_eq_u32 s63, s16
	v_mfma_f32_16x16x32_bf16 v[28:31], v[158:161], v[232:235], v[28:31]
	s_cselect_b32 s17, s57, s17
	v_mfma_f32_16x16x32_bf16 v[24:27], v[166:169], v[232:235], v[24:27]
	s_cselect_b32 s16, s56, s45
	v_mfma_f32_16x16x32_bf16 v[12:15], v[158:161], v[240:243], v[12:15]
	s_cselect_b32 s47, s9, s39
	v_mfma_f32_16x16x32_bf16 v[8:11], v[166:169], v[240:243], v[8:11]
	s_cselect_b32 s46, s8, s38
	v_mfma_f32_16x16x32_bf16 v[52:55], v[170:173], v[210:213], v[52:55]
	s_add_i32 s45, 0, 0x14000
	v_mfma_f32_16x16x32_bf16 v[48:51], v[194:197], v[210:213], v[48:51]
	v_mfma_f32_16x16x32_bf16 v[36:39], v[170:173], v[220:223], v[36:39]
	v_mfma_f32_16x16x32_bf16 v[32:35], v[194:197], v[220:223], v[32:35]
	v_mfma_f32_16x16x32_bf16 v[20:23], v[170:173], v[228:231], v[20:23]
	v_mfma_f32_16x16x32_bf16 v[16:19], v[194:197], v[228:231], v[16:19]
	v_mfma_f32_16x16x32_bf16 v[4:7], v[170:173], v[236:239], v[4:7]
	v_mfma_f32_16x16x32_bf16 v[0:3], v[194:197], v[236:239], v[0:3]
	v_mfma_f32_16x16x32_bf16 v[52:55], v[174:177], v[214:217], v[52:55]
	v_mfma_f32_16x16x32_bf16 v[48:51], v[206:209], v[214:217], v[48:51]
	v_mfma_f32_16x16x32_bf16 v[36:39], v[174:177], v[224:227], v[36:39]
	v_mfma_f32_16x16x32_bf16 v[32:35], v[206:209], v[224:227], v[32:35]
	v_mfma_f32_16x16x32_bf16 v[20:23], v[174:177], v[232:235], v[20:23]
	v_mfma_f32_16x16x32_bf16 v[16:19], v[206:209], v[232:235], v[16:19]
	v_mfma_f32_16x16x32_bf16 v[4:7], v[174:177], v[240:243], v[4:7]
	v_mfma_f32_16x16x32_bf16 v[0:3], v[206:209], v[240:243], v[0:3]
	s_barrier
	s_cmp_lg_u32 s99, 0
	s_cbranch_scc1 .Lpeelx_9
.LBB0_576:
	v_add_u32_e32 v152, s64, v153
	ds_read_b128 v[128:131], v152
	ds_read_b128 v[158:161], v152 offset:1024
	ds_read_b128 v[162:165], v152 offset:2048
	ds_read_b128 v[166:169], v152 offset:3072
	v_add_u32_e32 v152, s45, v153
	ds_read_b128 v[170:173], v152
	ds_read_b128 v[174:177], v152 offset:1024
	ds_read_b128 v[194:197], v152 offset:2048
	ds_read_b128 v[206:209], v152 offset:3072
	v_lshl_add_u64 v[178:179], s[0:1], 0, v[148:149]
	s_add_i32 m0, s52, 0xc000
	ds_read_b128 v[210:213], v157
	ds_read_b128 v[214:217], v157 offset:1024
	ds_read_b128 v[220:223], v157 offset:2048
	ds_read_b128 v[224:227], v157 offset:3072
	ds_read_b128 v[228:231], v157 offset:4096
	ds_read_b128 v[232:235], v157 offset:5120
	ds_read_b128 v[236:239], v157 offset:6144
	ds_read_b128 v[240:243], v157 offset:7168
	global_load_lds_dwordx4 v[178:179], off
	v_lshl_add_u64 v[178:179], s[0:1], 0, v[150:151]
	s_add_i32 m0, s52, 0xe000
	s_nop 0
	global_load_lds_dwordx4 v[178:179], off
	s_waitcnt vmcnt(8)
	s_waitcnt lgkmcnt(0)
	s_barrier
	s_waitcnt lgkmcnt(0)
	v_mfma_f32_16x16x32_bf16 v[124:127], v[128:131], v[210:213], v[124:127]
	v_mfma_f32_16x16x32_bf16 v[120:123], v[162:165], v[210:213], v[120:123]
	v_lshl_add_u64 v[178:179], s[46:47], 0, v[134:135]
	v_mfma_f32_16x16x32_bf16 v[108:111], v[128:131], v[220:223], v[108:111]
	v_lshl_add_u64 v[198:199], s[46:47], 0, v[138:139]
	v_mfma_f32_16x16x32_bf16 v[104:107], v[162:165], v[220:223], v[104:107]
	s_add_u32 s46, s46, s24
	v_mfma_f32_16x16x32_bf16 v[92:95], v[128:131], v[228:231], v[92:95]
	s_addc_u32 s47, s47, s25
	v_mfma_f32_16x16x32_bf16 v[88:91], v[162:165], v[228:231], v[88:91]
	v_lshl_add_u64 v[244:245], s[46:47], 0, v[134:135]
	v_mfma_f32_16x16x32_bf16 v[76:79], v[128:131], v[236:239], v[76:79]
	v_lshl_add_u64 v[246:247], s[46:47], 0, v[138:139]
	v_mfma_f32_16x16x32_bf16 v[72:75], v[162:165], v[236:239], v[72:75]
	v_lshl_add_u64 v[248:249], s[16:17], 0, v[132:133]
	v_mfma_f32_16x16x32_bf16 v[124:127], v[158:161], v[214:217], v[124:127]
	v_lshl_add_u64 v[250:251], s[16:17], 0, v[136:137]
	v_mfma_f32_16x16x32_bf16 v[120:123], v[166:169], v[214:217], v[120:123]
	v_mfma_f32_16x16x32_bf16 v[108:111], v[158:161], v[224:227], v[108:111]
	v_mfma_f32_16x16x32_bf16 v[104:107], v[166:169], v[224:227], v[104:107]
	v_mfma_f32_16x16x32_bf16 v[92:95], v[158:161], v[232:235], v[92:95]
	v_mfma_f32_16x16x32_bf16 v[88:91], v[166:169], v[232:235], v[88:91]
	v_mfma_f32_16x16x32_bf16 v[76:79], v[158:161], v[240:243], v[76:79]
	v_mfma_f32_16x16x32_bf16 v[72:75], v[166:169], v[240:243], v[72:75]
	v_mfma_f32_16x16x32_bf16 v[116:119], v[170:173], v[210:213], v[116:119]
	v_mfma_f32_16x16x32_bf16 v[112:115], v[194:197], v[210:213], v[112:115]
	v_mfma_f32_16x16x32_bf16 v[100:103], v[170:173], v[220:223], v[100:103]
	v_mfma_f32_16x16x32_bf16 v[96:99], v[194:197], v[220:223], v[96:99]
	v_mfma_f32_16x16x32_bf16 v[84:87], v[170:173], v[228:231], v[84:87]
	v_mfma_f32_16x16x32_bf16 v[80:83], v[194:197], v[228:231], v[80:83]
	v_mfma_f32_16x16x32_bf16 v[68:71], v[170:173], v[236:239], v[68:71]
	v_mfma_f32_16x16x32_bf16 v[64:67], v[194:197], v[236:239], v[64:67]
	v_mfma_f32_16x16x32_bf16 v[116:119], v[174:177], v[214:217], v[116:119]
	v_mfma_f32_16x16x32_bf16 v[112:115], v[206:209], v[214:217], v[112:115]
	v_mfma_f32_16x16x32_bf16 v[100:103], v[174:177], v[224:227], v[100:103]
	v_mfma_f32_16x16x32_bf16 v[96:99], v[206:209], v[224:227], v[96:99]
	v_mfma_f32_16x16x32_bf16 v[84:87], v[174:177], v[232:235], v[84:87]
	v_mfma_f32_16x16x32_bf16 v[80:83], v[206:209], v[232:235], v[80:83]
	v_mfma_f32_16x16x32_bf16 v[68:71], v[174:177], v[240:243], v[68:71]
	v_mfma_f32_16x16x32_bf16 v[64:67], v[206:209], v[240:243], v[64:67]
	s_barrier
	s_add_i32 s64, s64, s4
	s_mov_b32 m0, s64
	ds_read_b128 v[210:213], v157 offset:16384
	ds_read_b128 v[214:217], v157 offset:17408
	ds_read_b128 v[220:223], v157 offset:18432
	ds_read_b128 v[224:227], v157 offset:19456
	ds_read_b128 v[228:231], v157 offset:20480
	ds_read_b128 v[232:235], v157 offset:21504
	ds_read_b128 v[236:239], v157 offset:22528
	ds_read_b128 v[240:243], v157 offset:23552
	global_load_lds_dwordx4 v[178:179], off
	s_add_i32 m0, s64, 0x2000
	s_add_i32 s45, s45, s4
	global_load_lds_dwordx4 v[198:199], off
	s_mov_b32 m0, s45
	s_nop 0
	global_load_lds_dwordx4 v[244:245], off
	s_add_i32 m0, s45, 0x2000
	s_nop 0
	global_load_lds_dwordx4 v[246:247], off
	s_mov_b32 m0, s52
	s_nop 0
	global_load_lds_dwordx4 v[248:249], off
	s_mov_b32 m0, s18
	s_nop 0
	global_load_lds_dwordx4 v[250:251], off
	s_waitcnt vmcnt(8)
	s_waitcnt lgkmcnt(0)
	s_barrier
	s_waitcnt lgkmcnt(0)
	v_mfma_f32_16x16x32_bf16 v[60:63], v[128:131], v[210:213], v[60:63]
	v_mfma_f32_16x16x32_bf16 v[56:59], v[162:165], v[210:213], v[56:59]
	v_mfma_f32_16x16x32_bf16 v[44:47], v[128:131], v[220:223], v[44:47]
	v_mfma_f32_16x16x32_bf16 v[40:43], v[162:165], v[220:223], v[40:43]
	v_mfma_f32_16x16x32_bf16 v[28:31], v[128:131], v[228:231], v[28:31]
	v_mfma_f32_16x16x32_bf16 v[24:27], v[162:165], v[228:231], v[24:27]
	v_mfma_f32_16x16x32_bf16 v[12:15], v[128:131], v[236:239], v[12:15]
	v_mfma_f32_16x16x32_bf16 v[8:11], v[162:165], v[236:239], v[8:11]
	v_mfma_f32_16x16x32_bf16 v[60:63], v[158:161], v[214:217], v[60:63]
	v_mfma_f32_16x16x32_bf16 v[56:59], v[166:169], v[214:217], v[56:59]
	v_mfma_f32_16x16x32_bf16 v[44:47], v[158:161], v[224:227], v[44:47]
	v_mfma_f32_16x16x32_bf16 v[40:43], v[166:169], v[224:227], v[40:43]
	v_mfma_f32_16x16x32_bf16 v[28:31], v[158:161], v[232:235], v[28:31]
	v_mfma_f32_16x16x32_bf16 v[24:27], v[166:169], v[232:235], v[24:27]
	v_mfma_f32_16x16x32_bf16 v[12:15], v[158:161], v[240:243], v[12:15]
	v_mfma_f32_16x16x32_bf16 v[8:11], v[166:169], v[240:243], v[8:11]
	v_mfma_f32_16x16x32_bf16 v[52:55], v[170:173], v[210:213], v[52:55]
	v_mfma_f32_16x16x32_bf16 v[48:51], v[194:197], v[210:213], v[48:51]
	v_mfma_f32_16x16x32_bf16 v[36:39], v[170:173], v[220:223], v[36:39]
	v_mfma_f32_16x16x32_bf16 v[32:35], v[194:197], v[220:223], v[32:35]
	v_mfma_f32_16x16x32_bf16 v[20:23], v[170:173], v[228:231], v[20:23]
	v_mfma_f32_16x16x32_bf16 v[16:19], v[194:197], v[228:231], v[16:19]
	v_mfma_f32_16x16x32_bf16 v[4:7], v[170:173], v[236:239], v[4:7]
	v_mfma_f32_16x16x32_bf16 v[0:3], v[194:197], v[236:239], v[0:3]
	v_mfma_f32_16x16x32_bf16 v[52:55], v[174:177], v[214:217], v[52:55]
	v_mfma_f32_16x16x32_bf16 v[48:51], v[206:209], v[214:217], v[48:51]
	v_mfma_f32_16x16x32_bf16 v[36:39], v[174:177], v[224:227], v[36:39]
	v_mfma_f32_16x16x32_bf16 v[32:35], v[206:209], v[224:227], v[32:35]
	v_mfma_f32_16x16x32_bf16 v[20:23], v[174:177], v[232:235], v[20:23]
	v_mfma_f32_16x16x32_bf16 v[16:19], v[206:209], v[232:235], v[16:19]
	v_mfma_f32_16x16x32_bf16 v[4:7], v[174:177], v[240:243], v[4:7]
	v_mfma_f32_16x16x32_bf16 v[0:3], v[206:209], v[240:243], v[0:3]
	s_barrier
	s_add_i32 s45, 0, 0x18000
	v_add_u32_e32 v152, s45, v153
	s_add_i32 s46, 0, 0x1c000
	ds_read_b128 v[128:131], v152
	ds_read_b128 v[158:161], v152 offset:1024
	ds_read_b128 v[162:165], v152 offset:2048
	ds_read_b128 v[166:169], v152 offset:3072
	v_add_u32_e32 v152, s46, v153
	ds_read_b128 v[170:173], v152
	ds_read_b128 v[174:177], v152 offset:1024
	ds_read_b128 v[194:197], v152 offset:2048
	ds_read_b128 v[206:209], v152 offset:3072
	s_add_u32 s16, s16, s24
	s_addc_u32 s17, s17, s25
	s_mov_b32 m0, s19
	v_lshl_add_u64 v[202:203], s[16:17], 0, v[132:133]
	ds_read_b128 v[210:213], v157 offset:32768
	ds_read_b128 v[214:217], v157 offset:33792
	ds_read_b128 v[220:223], v157 offset:34816
	ds_read_b128 v[224:227], v157 offset:35840
	ds_read_b128 v[228:231], v157 offset:36864
	ds_read_b128 v[232:235], v157 offset:37888
	ds_read_b128 v[236:239], v157 offset:38912
	ds_read_b128 v[240:243], v157 offset:39936
	global_load_lds_dwordx4 v[202:203], off
	v_lshl_add_u64 v[202:203], s[16:17], 0, v[136:137]
	s_mov_b32 m0, s33
	s_nop 0
	global_load_lds_dwordx4 v[202:203], off
	s_waitcnt vmcnt(8)
	s_waitcnt lgkmcnt(0)
	s_barrier
	s_waitcnt lgkmcnt(0)
	v_mfma_f32_16x16x32_bf16 v[124:127], v[128:131], v[210:213], v[124:127]
	v_mfma_f32_16x16x32_bf16 v[120:123], v[162:165], v[210:213], v[120:123]
	v_lshl_add_u64 v[178:179], v[178:179], 0, s[12:13]
	v_mfma_f32_16x16x32_bf16 v[108:111], v[128:131], v[220:223], v[108:111]
	v_lshl_add_u64 v[198:199], v[198:199], 0, s[12:13]
	v_mfma_f32_16x16x32_bf16 v[104:107], v[162:165], v[220:223], v[104:107]
	v_lshl_add_u64 v[244:245], v[244:245], 0, s[12:13]
	v_mfma_f32_16x16x32_bf16 v[92:95], v[128:131], v[228:231], v[92:95]
	v_lshl_add_u64 v[246:247], v[246:247], 0, s[12:13]
	v_mfma_f32_16x16x32_bf16 v[88:91], v[162:165], v[228:231], v[88:91]
	v_lshl_add_u64 v[248:249], v[248:249], 0, s[12:13]
	v_mfma_f32_16x16x32_bf16 v[76:79], v[128:131], v[236:239], v[76:79]
	v_lshl_add_u64 v[250:251], v[250:251], 0, s[12:13]
	v_mfma_f32_16x16x32_bf16 v[72:75], v[162:165], v[236:239], v[72:75]
	v_mfma_f32_16x16x32_bf16 v[124:127], v[158:161], v[214:217], v[124:127]
	v_mfma_f32_16x16x32_bf16 v[120:123], v[166:169], v[214:217], v[120:123]
	v_mfma_f32_16x16x32_bf16 v[108:111], v[158:161], v[224:227], v[108:111]
	v_mfma_f32_16x16x32_bf16 v[104:107], v[166:169], v[224:227], v[104:107]
	v_mfma_f32_16x16x32_bf16 v[92:95], v[158:161], v[232:235], v[92:95]
	v_mfma_f32_16x16x32_bf16 v[88:91], v[166:169], v[232:235], v[88:91]
	v_mfma_f32_16x16x32_bf16 v[76:79], v[158:161], v[240:243], v[76:79]
	v_mfma_f32_16x16x32_bf16 v[72:75], v[166:169], v[240:243], v[72:75]
	v_mfma_f32_16x16x32_bf16 v[116:119], v[170:173], v[210:213], v[116:119]
	v_mfma_f32_16x16x32_bf16 v[112:115], v[194:197], v[210:213], v[112:115]
	v_mfma_f32_16x16x32_bf16 v[100:103], v[170:173], v[220:223], v[100:103]
	v_mfma_f32_16x16x32_bf16 v[96:99], v[194:197], v[220:223], v[96:99]
	v_mfma_f32_16x16x32_bf16 v[84:87], v[170:173], v[228:231], v[84:87]
	v_mfma_f32_16x16x32_bf16 v[80:83], v[194:197], v[228:231], v[80:83]
	v_mfma_f32_16x16x32_bf16 v[68:71], v[170:173], v[236:239], v[68:71]
	v_mfma_f32_16x16x32_bf16 v[64:67], v[194:197], v[236:239], v[64:67]
	v_mfma_f32_16x16x32_bf16 v[116:119], v[174:177], v[214:217], v[116:119]
	v_mfma_f32_16x16x32_bf16 v[112:115], v[206:209], v[214:217], v[112:115]
	v_mfma_f32_16x16x32_bf16 v[100:103], v[174:177], v[224:227], v[100:103]
	v_mfma_f32_16x16x32_bf16 v[96:99], v[206:209], v[224:227], v[96:99]
	v_mfma_f32_16x16x32_bf16 v[84:87], v[174:177], v[232:235], v[84:87]
	v_mfma_f32_16x16x32_bf16 v[80:83], v[206:209], v[232:235], v[80:83]
	v_mfma_f32_16x16x32_bf16 v[68:71], v[174:177], v[240:243], v[68:71]
	v_mfma_f32_16x16x32_bf16 v[64:67], v[206:209], v[240:243], v[64:67]
	s_barrier
	s_add_i32 s16, s45, s4
	s_mov_b32 m0, s16
	ds_read_b128 v[210:213], v157 offset:49152
	ds_read_b128 v[214:217], v157 offset:50176
	ds_read_b128 v[220:223], v157 offset:51200
	ds_read_b128 v[224:227], v157 offset:52224
	ds_read_b128 v[228:231], v157 offset:53248
	ds_read_b128 v[232:235], v157 offset:54272
	ds_read_b128 v[236:239], v157 offset:55296
	ds_read_b128 v[240:243], v157 offset:56320
	global_load_lds_dwordx4 v[178:179], off
	s_add_i32 m0, s16, 0x2000
	s_add_i32 s16, s46, s4
	global_load_lds_dwordx4 v[198:199], off
	s_mov_b32 m0, s16
	s_nop 0
	global_load_lds_dwordx4 v[244:245], off
	s_add_i32 m0, s16, 0x2000
	s_nop 0
	global_load_lds_dwordx4 v[246:247], off
	s_mov_b32 m0, s59
	s_nop 0
	global_load_lds_dwordx4 v[248:249], off
	s_mov_b32 m0, s60
	s_nop 0
	global_load_lds_dwordx4 v[250:251], off
	s_waitcnt vmcnt(8)
	s_waitcnt lgkmcnt(0)
	s_barrier
	s_waitcnt lgkmcnt(0)
	v_mfma_f32_16x16x32_bf16 v[60:63], v[128:131], v[210:213], v[60:63]
	s_add_u32 s0, s0, 0x100
	v_mfma_f32_16x16x32_bf16 v[56:59], v[162:165], v[210:213], v[56:59]
	s_addc_u32 s1, s1, 0
	v_mfma_f32_16x16x32_bf16 v[44:47], v[128:131], v[220:223], v[44:47]
	s_add_u32 s38, s38, 0x100
	v_mfma_f32_16x16x32_bf16 v[40:43], v[162:165], v[220:223], v[40:43]
	s_addc_u32 s39, s39, 0
	v_mfma_f32_16x16x32_bf16 v[28:31], v[128:131], v[228:231], v[28:31]
	s_mov_b32 s16, s44
	v_mfma_f32_16x16x32_bf16 v[24:27], v[162:165], v[228:231], v[24:27]
	s_cmp_ge_i32 s44, s68
	v_mfma_f32_16x16x32_bf16 v[12:15], v[128:131], v[236:239], v[12:15]
	s_cselect_b32 s99, 1, 0
	v_mfma_f32_16x16x32_bf16 v[8:11], v[162:165], v[236:239], v[8:11]
	s_add_i32 s44, s16, 2
	v_mfma_f32_16x16x32_bf16 v[60:63], v[158:161], v[214:217], v[60:63]
	s_add_u32 s45, s0, 0x80
	v_mfma_f32_16x16x32_bf16 v[56:59], v[166:169], v[214:217], v[56:59]
	s_addc_u32 s17, s1, 0
	v_mfma_f32_16x16x32_bf16 v[44:47], v[158:161], v[224:227], v[44:47]
	s_add_i32 s64, 0, 0x10000
	v_mfma_f32_16x16x32_bf16 v[40:43], v[166:169], v[224:227], v[40:43]
	s_cmp_eq_u32 s63, s16
	v_mfma_f32_16x16x32_bf16 v[28:31], v[158:161], v[232:235], v[28:31]
	s_cselect_b32 s17, s57, s17
	v_mfma_f32_16x16x32_bf16 v[24:27], v[166:169], v[232:235], v[24:27]
	s_cselect_b32 s16, s56, s45
	v_mfma_f32_16x16x32_bf16 v[12:15], v[158:161], v[240:243], v[12:15]
	s_cselect_b32 s47, s9, s39
	v_mfma_f32_16x16x32_bf16 v[8:11], v[166:169], v[240:243], v[8:11]
	s_cselect_b32 s46, s8, s38
	v_mfma_f32_16x16x32_bf16 v[52:55], v[170:173], v[210:213], v[52:55]
	s_add_i32 s45, 0, 0x14000
	v_mfma_f32_16x16x32_bf16 v[48:51], v[194:197], v[210:213], v[48:51]
	v_mfma_f32_16x16x32_bf16 v[36:39], v[170:173], v[220:223], v[36:39]
	v_mfma_f32_16x16x32_bf16 v[32:35], v[194:197], v[220:223], v[32:35]
	v_mfma_f32_16x16x32_bf16 v[20:23], v[170:173], v[228:231], v[20:23]
	v_mfma_f32_16x16x32_bf16 v[16:19], v[194:197], v[228:231], v[16:19]
	v_mfma_f32_16x16x32_bf16 v[4:7], v[170:173], v[236:239], v[4:7]
	v_mfma_f32_16x16x32_bf16 v[0:3], v[194:197], v[236:239], v[0:3]
	v_mfma_f32_16x16x32_bf16 v[52:55], v[174:177], v[214:217], v[52:55]
	v_mfma_f32_16x16x32_bf16 v[48:51], v[206:209], v[214:217], v[48:51]
	v_mfma_f32_16x16x32_bf16 v[36:39], v[174:177], v[224:227], v[36:39]
	v_mfma_f32_16x16x32_bf16 v[32:35], v[206:209], v[224:227], v[32:35]
	v_mfma_f32_16x16x32_bf16 v[20:23], v[174:177], v[232:235], v[20:23]
	v_mfma_f32_16x16x32_bf16 v[16:19], v[206:209], v[232:235], v[16:19]
	v_mfma_f32_16x16x32_bf16 v[4:7], v[174:177], v[240:243], v[4:7]
	v_mfma_f32_16x16x32_bf16 v[0:3], v[206:209], v[240:243], v[0:3]
	s_barrier
	s_cmp_lg_u32 s99, 0
	s_cbranch_scc0 .LBB0_576

.Llbb_6:
	s_add_i32 s30, s16, 2
	s_add_u32 s31, s28, 0x80
	s_addc_u32 s17, s29, 0
	s_add_i32 s59, 0, 0x10000
	s_cmp_eq_u32 s48, s16
	s_cselect_b32 s17, s25, s17
	s_cselect_b32 s16, s24, s31
	v_add_u32_e32 v140, s59, v143
	s_cselect_b32 s43, s27, s11
	s_cselect_b32 s42, s26, s10
	s_add_i32 s31, 0, 0x14000
	ds_read_b128 v[146:149], v140
	ds_read_b128 v[150:153], v140 offset:1024
	ds_read_b128 v[154:157], v140 offset:2048
	ds_read_b128 v[158:161], v140 offset:3072
	v_add_u32_e32 v140, s31, v143
	ds_read_b128 v[162:165], v140
	ds_read_b128 v[166:169], v140 offset:1024
	ds_read_b128 v[170:173], v140 offset:2048
	ds_read_b128 v[174:177], v140 offset:3072
	v_lshl_add_u64 v[178:179], s[28:29], 0, v[136:137]
	s_add_i32 m0, s37, 0xc000
	ds_read_b128 v[194:197], v145
	ds_read_b128 v[206:209], v145 offset:1024
	ds_read_b128 v[210:213], v145 offset:2048
	ds_read_b128 v[214:217], v145 offset:3072
	ds_read_b128 v[220:223], v145 offset:4096
	ds_read_b128 v[224:227], v145 offset:5120
	ds_read_b128 v[228:231], v145 offset:6144
	ds_read_b128 v[232:235], v145 offset:7168
	global_load_lds_dwordx4 v[178:179], off
	v_lshl_add_u64 v[178:179], s[28:29], 0, v[138:139]
	s_add_i32 m0, s37, 0xe000
	s_nop 0
	global_load_lds_dwordx4 v[178:179], off
	s_waitcnt vmcnt(8)
	s_waitcnt lgkmcnt(0)
	s_barrier
	s_waitcnt lgkmcnt(0)
	v_mfma_f32_16x16x32_bf16 v[124:127], v[146:149], v[194:197], 0
	v_mfma_f32_16x16x32_bf16 v[120:123], v[154:157], v[194:197], 0
	v_lshl_add_u64 v[178:179], s[42:43], 0, v[132:133]
	v_mfma_f32_16x16x32_bf16 v[108:111], v[146:149], v[210:213], 0
	v_lshl_add_u64 v[198:199], s[42:43], 0, v[128:129]
	v_mfma_f32_16x16x32_bf16 v[104:107], v[154:157], v[210:213], 0
	s_add_u32 s42, s42, s0
	v_mfma_f32_16x16x32_bf16 v[92:95], v[146:149], v[220:223], 0
	s_addc_u32 s43, s43, s1
	v_mfma_f32_16x16x32_bf16 v[88:91], v[154:157], v[220:223], 0
	v_lshl_add_u64 v[202:203], s[42:43], 0, v[132:133]
	v_mfma_f32_16x16x32_bf16 v[76:79], v[146:149], v[228:231], 0
	v_lshl_add_u64 v[236:237], s[42:43], 0, v[128:129]
	v_mfma_f32_16x16x32_bf16 v[72:75], v[154:157], v[228:231], 0
	v_lshl_add_u64 v[238:239], s[16:17], 0, v[134:135]
	v_mfma_f32_16x16x32_bf16 v[124:127], v[150:153], v[206:209], v[124:127]
	v_lshl_add_u64 v[240:241], s[16:17], 0, v[130:131]
	v_mfma_f32_16x16x32_bf16 v[120:123], v[158:161], v[206:209], v[120:123]
	v_mfma_f32_16x16x32_bf16 v[108:111], v[150:153], v[214:217], v[108:111]
	v_mfma_f32_16x16x32_bf16 v[104:107], v[158:161], v[214:217], v[104:107]
	v_mfma_f32_16x16x32_bf16 v[92:95], v[150:153], v[224:227], v[92:95]
	v_mfma_f32_16x16x32_bf16 v[88:91], v[158:161], v[224:227], v[88:91]
	v_mfma_f32_16x16x32_bf16 v[76:79], v[150:153], v[232:235], v[76:79]
	v_mfma_f32_16x16x32_bf16 v[72:75], v[158:161], v[232:235], v[72:75]
	v_mfma_f32_16x16x32_bf16 v[116:119], v[162:165], v[194:197], 0
	v_mfma_f32_16x16x32_bf16 v[112:115], v[170:173], v[194:197], 0
	v_mfma_f32_16x16x32_bf16 v[100:103], v[162:165], v[210:213], 0
	v_mfma_f32_16x16x32_bf16 v[96:99], v[170:173], v[210:213], 0
	v_mfma_f32_16x16x32_bf16 v[84:87], v[162:165], v[220:223], 0
	v_mfma_f32_16x16x32_bf16 v[80:83], v[170:173], v[220:223], 0
	v_mfma_f32_16x16x32_bf16 v[68:71], v[162:165], v[228:231], 0
	v_mfma_f32_16x16x32_bf16 v[64:67], v[170:173], v[228:231], 0
	v_mfma_f32_16x16x32_bf16 v[116:119], v[166:169], v[206:209], v[116:119]
	v_mfma_f32_16x16x32_bf16 v[112:115], v[174:177], v[206:209], v[112:115]
	v_mfma_f32_16x16x32_bf16 v[100:103], v[166:169], v[214:217], v[100:103]
	v_mfma_f32_16x16x32_bf16 v[96:99], v[174:177], v[214:217], v[96:99]
	v_mfma_f32_16x16x32_bf16 v[84:87], v[166:169], v[224:227], v[84:87]
	v_mfma_f32_16x16x32_bf16 v[80:83], v[174:177], v[224:227], v[80:83]
	v_mfma_f32_16x16x32_bf16 v[68:71], v[166:169], v[232:235], v[68:71]
	v_mfma_f32_16x16x32_bf16 v[64:67], v[174:177], v[232:235], v[64:67]
	s_barrier
	s_add_i32 s59, s59, s36
	s_mov_b32 m0, s59
	ds_read_b128 v[194:197], v145 offset:16384
	ds_read_b128 v[206:209], v145 offset:17408
	ds_read_b128 v[210:213], v145 offset:18432
	ds_read_b128 v[214:217], v145 offset:19456
	ds_read_b128 v[220:223], v145 offset:20480
	ds_read_b128 v[224:227], v145 offset:21504
	ds_read_b128 v[228:231], v145 offset:22528
	ds_read_b128 v[232:235], v145 offset:23552
	global_load_lds_dwordx4 v[178:179], off
	s_add_i32 m0, s59, 0x2000
	s_add_i32 s31, s31, s36
	global_load_lds_dwordx4 v[198:199], off
	s_mov_b32 m0, s31
	s_nop 0
	global_load_lds_dwordx4 v[202:203], off
	s_add_i32 m0, s31, 0x2000
	s_nop 0
	global_load_lds_dwordx4 v[236:237], off
	s_mov_b32 m0, s37
	s_nop 0
	global_load_lds_dwordx4 v[238:239], off
	s_mov_b32 m0, s38
	s_nop 0
	global_load_lds_dwordx4 v[240:241], off
	s_waitcnt vmcnt(8)
	s_waitcnt lgkmcnt(0)
	s_barrier
	s_waitcnt lgkmcnt(0)
	v_mfma_f32_16x16x32_bf16 v[60:63], v[146:149], v[194:197], 0
	v_mfma_f32_16x16x32_bf16 v[56:59], v[154:157], v[194:197], 0
	v_mfma_f32_16x16x32_bf16 v[44:47], v[146:149], v[210:213], 0
	v_mfma_f32_16x16x32_bf16 v[40:43], v[154:157], v[210:213], 0
	v_mfma_f32_16x16x32_bf16 v[28:31], v[146:149], v[220:223], 0
	v_mfma_f32_16x16x32_bf16 v[24:27], v[154:157], v[220:223], 0
	v_mfma_f32_16x16x32_bf16 v[12:15], v[146:149], v[228:231], 0
	v_mfma_f32_16x16x32_bf16 v[8:11], v[154:157], v[228:231], 0
	v_mfma_f32_16x16x32_bf16 v[60:63], v[150:153], v[206:209], v[60:63]
	v_mfma_f32_16x16x32_bf16 v[56:59], v[158:161], v[206:209], v[56:59]
	v_mfma_f32_16x16x32_bf16 v[44:47], v[150:153], v[214:217], v[44:47]
	v_mfma_f32_16x16x32_bf16 v[40:43], v[158:161], v[214:217], v[40:43]
	v_mfma_f32_16x16x32_bf16 v[28:31], v[150:153], v[224:227], v[28:31]
	v_mfma_f32_16x16x32_bf16 v[24:27], v[158:161], v[224:227], v[24:27]
	v_mfma_f32_16x16x32_bf16 v[12:15], v[150:153], v[232:235], v[12:15]
	v_mfma_f32_16x16x32_bf16 v[8:11], v[158:161], v[232:235], v[8:11]
	v_mfma_f32_16x16x32_bf16 v[52:55], v[162:165], v[194:197], 0
	v_mfma_f32_16x16x32_bf16 v[48:51], v[170:173], v[194:197], 0
	v_mfma_f32_16x16x32_bf16 v[36:39], v[162:165], v[210:213], 0
	v_mfma_f32_16x16x32_bf16 v[32:35], v[170:173], v[210:213], 0
	v_mfma_f32_16x16x32_bf16 v[20:23], v[162:165], v[220:223], 0
	v_mfma_f32_16x16x32_bf16 v[16:19], v[170:173], v[220:223], 0
	v_mfma_f32_16x16x32_bf16 v[4:7], v[162:165], v[228:231], 0
	v_mfma_f32_16x16x32_bf16 v[0:3], v[170:173], v[228:231], 0
	v_mfma_f32_16x16x32_bf16 v[52:55], v[166:169], v[206:209], v[52:55]
	v_mfma_f32_16x16x32_bf16 v[48:51], v[174:177], v[206:209], v[48:51]
	v_mfma_f32_16x16x32_bf16 v[36:39], v[166:169], v[214:217], v[36:39]
	v_mfma_f32_16x16x32_bf16 v[32:35], v[174:177], v[214:217], v[32:35]
	v_mfma_f32_16x16x32_bf16 v[20:23], v[166:169], v[224:227], v[20:23]
	v_mfma_f32_16x16x32_bf16 v[16:19], v[174:177], v[224:227], v[16:19]
	v_mfma_f32_16x16x32_bf16 v[4:7], v[166:169], v[232:235], v[4:7]
	v_mfma_f32_16x16x32_bf16 v[0:3], v[174:177], v[232:235], v[0:3]
	s_barrier
	s_add_i32 s31, 0, 0x18000
	v_add_u32_e32 v140, s31, v143
	s_add_i32 s42, 0, 0x1c000
	ds_read_b128 v[146:149], v140
	ds_read_b128 v[150:153], v140 offset:1024
	ds_read_b128 v[154:157], v140 offset:2048
	ds_read_b128 v[158:161], v140 offset:3072
	v_add_u32_e32 v140, s42, v143
	ds_read_b128 v[162:165], v140
	ds_read_b128 v[166:169], v140 offset:1024
	ds_read_b128 v[170:173], v140 offset:2048
	ds_read_b128 v[174:177], v140 offset:3072
	s_add_u32 s16, s16, s0
	s_addc_u32 s17, s17, s1
	s_mov_b32 m0, s39
	v_lshl_add_u64 v[242:243], s[16:17], 0, v[134:135]
	ds_read_b128 v[194:197], v145 offset:32768
	ds_read_b128 v[206:209], v145 offset:33792
	ds_read_b128 v[210:213], v145 offset:34816
	ds_read_b128 v[214:217], v145 offset:35840
	ds_read_b128 v[220:223], v145 offset:36864
	ds_read_b128 v[224:227], v145 offset:37888
	ds_read_b128 v[228:231], v145 offset:38912
	ds_read_b128 v[232:235], v145 offset:39936
	global_load_lds_dwordx4 v[242:243], off
	v_lshl_add_u64 v[242:243], s[16:17], 0, v[130:131]
	s_mov_b32 m0, s44
	s_nop 0
	global_load_lds_dwordx4 v[242:243], off
	s_waitcnt vmcnt(8)
	s_waitcnt lgkmcnt(0)
	s_barrier
	s_waitcnt lgkmcnt(0)
	v_mfma_f32_16x16x32_bf16 v[124:127], v[146:149], v[194:197], v[124:127]
	v_mfma_f32_16x16x32_bf16 v[120:123], v[154:157], v[194:197], v[120:123]
	v_lshl_add_u64 v[178:179], v[178:179], 0, s[12:13]
	v_mfma_f32_16x16x32_bf16 v[108:111], v[146:149], v[210:213], v[108:111]
	v_lshl_add_u64 v[198:199], v[198:199], 0, s[12:13]
	v_mfma_f32_16x16x32_bf16 v[104:107], v[154:157], v[210:213], v[104:107]
	v_lshl_add_u64 v[202:203], v[202:203], 0, s[12:13]
	v_mfma_f32_16x16x32_bf16 v[92:95], v[146:149], v[220:223], v[92:95]
	v_lshl_add_u64 v[236:237], v[236:237], 0, s[12:13]
	v_mfma_f32_16x16x32_bf16 v[88:91], v[154:157], v[220:223], v[88:91]
	v_lshl_add_u64 v[238:239], v[238:239], 0, s[12:13]
	v_mfma_f32_16x16x32_bf16 v[76:79], v[146:149], v[228:231], v[76:79]
	v_lshl_add_u64 v[240:241], v[240:241], 0, s[12:13]
	v_mfma_f32_16x16x32_bf16 v[72:75], v[154:157], v[228:231], v[72:75]
	v_mfma_f32_16x16x32_bf16 v[124:127], v[150:153], v[206:209], v[124:127]
	v_mfma_f32_16x16x32_bf16 v[120:123], v[158:161], v[206:209], v[120:123]
	v_mfma_f32_16x16x32_bf16 v[108:111], v[150:153], v[214:217], v[108:111]
	v_mfma_f32_16x16x32_bf16 v[104:107], v[158:161], v[214:217], v[104:107]
	v_mfma_f32_16x16x32_bf16 v[92:95], v[150:153], v[224:227], v[92:95]
	v_mfma_f32_16x16x32_bf16 v[88:91], v[158:161], v[224:227], v[88:91]
	v_mfma_f32_16x16x32_bf16 v[76:79], v[150:153], v[232:235], v[76:79]
	v_mfma_f32_16x16x32_bf16 v[72:75], v[158:161], v[232:235], v[72:75]
	v_mfma_f32_16x16x32_bf16 v[116:119], v[162:165], v[194:197], v[116:119]
	v_mfma_f32_16x16x32_bf16 v[112:115], v[170:173], v[194:197], v[112:115]
	v_mfma_f32_16x16x32_bf16 v[100:103], v[162:165], v[210:213], v[100:103]
	v_mfma_f32_16x16x32_bf16 v[96:99], v[170:173], v[210:213], v[96:99]
	v_mfma_f32_16x16x32_bf16 v[84:87], v[162:165], v[220:223], v[84:87]
	v_mfma_f32_16x16x32_bf16 v[80:83], v[170:173], v[220:223], v[80:83]
	v_mfma_f32_16x16x32_bf16 v[68:71], v[162:165], v[228:231], v[68:71]
	v_mfma_f32_16x16x32_bf16 v[64:67], v[170:173], v[228:231], v[64:67]
	v_mfma_f32_16x16x32_bf16 v[116:119], v[166:169], v[206:209], v[116:119]
	v_mfma_f32_16x16x32_bf16 v[112:115], v[174:177], v[206:209], v[112:115]
	v_mfma_f32_16x16x32_bf16 v[100:103], v[166:169], v[214:217], v[100:103]
	v_mfma_f32_16x16x32_bf16 v[96:99], v[174:177], v[214:217], v[96:99]
	v_mfma_f32_16x16x32_bf16 v[84:87], v[166:169], v[224:227], v[84:87]
	v_mfma_f32_16x16x32_bf16 v[80:83], v[174:177], v[224:227], v[80:83]
	v_mfma_f32_16x16x32_bf16 v[68:71], v[166:169], v[232:235], v[68:71]
	v_mfma_f32_16x16x32_bf16 v[64:67], v[174:177], v[232:235], v[64:67]
	s_barrier
	s_add_i32 s16, s31, s36
	s_mov_b32 m0, s16
	ds_read_b128 v[194:197], v145 offset:49152
	ds_read_b128 v[206:209], v145 offset:50176
	ds_read_b128 v[210:213], v145 offset:51200
	ds_read_b128 v[214:217], v145 offset:52224
	ds_read_b128 v[220:223], v145 offset:53248
	ds_read_b128 v[224:227], v145 offset:54272
	ds_read_b128 v[228:231], v145 offset:55296
	ds_read_b128 v[232:235], v145 offset:56320
	global_load_lds_dwordx4 v[178:179], off
	s_add_i32 m0, s16, 0x2000
	s_add_i32 s16, s42, s36
	global_load_lds_dwordx4 v[198:199], off
	s_mov_b32 m0, s16
	s_nop 0
	global_load_lds_dwordx4 v[202:203], off
	s_add_i32 m0, s16, 0x2000
	s_nop 0
	global_load_lds_dwordx4 v[236:237], off
	s_mov_b32 m0, s45
	s_nop 0
	global_load_lds_dwordx4 v[238:239], off
	s_mov_b32 m0, s46
	s_nop 0
	global_load_lds_dwordx4 v[240:241], off
	s_waitcnt vmcnt(8)
	s_waitcnt lgkmcnt(0)
	s_barrier
	s_waitcnt lgkmcnt(0)
	v_mfma_f32_16x16x32_bf16 v[60:63], v[146:149], v[194:197], v[60:63]
	s_add_u32 s28, s28, 0x100
	v_mfma_f32_16x16x32_bf16 v[56:59], v[154:157], v[194:197], v[56:59]
	s_addc_u32 s29, s29, 0
	v_mfma_f32_16x16x32_bf16 v[44:47], v[146:149], v[210:213], v[44:47]
	s_add_u32 s10, s10, 0x100
	v_mfma_f32_16x16x32_bf16 v[40:43], v[154:157], v[210:213], v[40:43]
	s_addc_u32 s11, s11, 0
	v_mfma_f32_16x16x32_bf16 v[28:31], v[146:149], v[220:223], v[28:31]
	s_mov_b32 s16, s30
	v_mfma_f32_16x16x32_bf16 v[24:27], v[154:157], v[220:223], v[24:27]
	s_cmp_ge_i32 s30, s47
	v_mfma_f32_16x16x32_bf16 v[12:15], v[146:149], v[228:231], v[12:15]
	s_cselect_b32 s99, 1, 0
	v_mfma_f32_16x16x32_bf16 v[8:11], v[154:157], v[228:231], v[8:11]
	s_add_i32 s30, s16, 2
	v_mfma_f32_16x16x32_bf16 v[60:63], v[150:153], v[206:209], v[60:63]
	s_add_u32 s31, s28, 0x80
	v_mfma_f32_16x16x32_bf16 v[56:59], v[158:161], v[206:209], v[56:59]
	s_addc_u32 s17, s29, 0
	v_mfma_f32_16x16x32_bf16 v[44:47], v[150:153], v[214:217], v[44:47]
	s_add_i32 s59, 0, 0x10000
	v_mfma_f32_16x16x32_bf16 v[40:43], v[158:161], v[214:217], v[40:43]
	s_cmp_eq_u32 s48, s16
	v_mfma_f32_16x16x32_bf16 v[28:31], v[150:153], v[224:227], v[28:31]
	s_cselect_b32 s17, s25, s17
	v_mfma_f32_16x16x32_bf16 v[24:27], v[158:161], v[224:227], v[24:27]
	s_cselect_b32 s16, s24, s31
	v_mfma_f32_16x16x32_bf16 v[12:15], v[150:153], v[232:235], v[12:15]
	s_cselect_b32 s43, s27, s11
	v_mfma_f32_16x16x32_bf16 v[8:11], v[158:161], v[232:235], v[8:11]
	s_cselect_b32 s42, s26, s10
	v_mfma_f32_16x16x32_bf16 v[52:55], v[162:165], v[194:197], v[52:55]
	s_add_i32 s31, 0, 0x14000
	v_mfma_f32_16x16x32_bf16 v[48:51], v[170:173], v[194:197], v[48:51]
	v_mfma_f32_16x16x32_bf16 v[36:39], v[162:165], v[210:213], v[36:39]
	v_mfma_f32_16x16x32_bf16 v[32:35], v[170:173], v[210:213], v[32:35]
	v_mfma_f32_16x16x32_bf16 v[20:23], v[162:165], v[220:223], v[20:23]
	v_mfma_f32_16x16x32_bf16 v[16:19], v[170:173], v[220:223], v[16:19]
	v_mfma_f32_16x16x32_bf16 v[4:7], v[162:165], v[228:231], v[4:7]
	v_mfma_f32_16x16x32_bf16 v[0:3], v[170:173], v[228:231], v[0:3]
	v_mfma_f32_16x16x32_bf16 v[52:55], v[166:169], v[206:209], v[52:55]
	v_mfma_f32_16x16x32_bf16 v[48:51], v[174:177], v[206:209], v[48:51]
	v_mfma_f32_16x16x32_bf16 v[36:39], v[166:169], v[214:217], v[36:39]
	v_mfma_f32_16x16x32_bf16 v[32:35], v[174:177], v[214:217], v[32:35]
	v_mfma_f32_16x16x32_bf16 v[20:23], v[166:169], v[224:227], v[20:23]
	v_mfma_f32_16x16x32_bf16 v[16:19], v[174:177], v[224:227], v[16:19]
	v_mfma_f32_16x16x32_bf16 v[4:7], v[166:169], v[232:235], v[4:7]
	v_mfma_f32_16x16x32_bf16 v[0:3], v[174:177], v[232:235], v[0:3]
	s_barrier
	s_cmp_lg_u32 s99, 0
	s_cbranch_scc1 .Lpeelx_10
.LBB0_798:
	v_add_u32_e32 v140, s59, v143
	ds_read_b128 v[146:149], v140
	ds_read_b128 v[150:153], v140 offset:1024
	ds_read_b128 v[154:157], v140 offset:2048
	ds_read_b128 v[158:161], v140 offset:3072
	v_add_u32_e32 v140, s31, v143
	ds_read_b128 v[162:165], v140
	ds_read_b128 v[166:169], v140 offset:1024
	ds_read_b128 v[170:173], v140 offset:2048
	ds_read_b128 v[174:177], v140 offset:3072
	v_lshl_add_u64 v[178:179], s[28:29], 0, v[136:137]
	s_add_i32 m0, s37, 0xc000
	ds_read_b128 v[194:197], v145
	ds_read_b128 v[206:209], v145 offset:1024
	ds_read_b128 v[210:213], v145 offset:2048
	ds_read_b128 v[214:217], v145 offset:3072
	ds_read_b128 v[220:223], v145 offset:4096
	ds_read_b128 v[224:227], v145 offset:5120
	ds_read_b128 v[228:231], v145 offset:6144
	ds_read_b128 v[232:235], v145 offset:7168
	global_load_lds_dwordx4 v[178:179], off
	v_lshl_add_u64 v[178:179], s[28:29], 0, v[138:139]
	s_add_i32 m0, s37, 0xe000
	s_nop 0
	global_load_lds_dwordx4 v[178:179], off
	s_waitcnt vmcnt(8)
	s_waitcnt lgkmcnt(0)
	s_barrier
	s_waitcnt lgkmcnt(0)
	v_mfma_f32_16x16x32_bf16 v[124:127], v[146:149], v[194:197], v[124:127]
	v_mfma_f32_16x16x32_bf16 v[120:123], v[154:157], v[194:197], v[120:123]
	v_lshl_add_u64 v[178:179], s[42:43], 0, v[132:133]
	v_mfma_f32_16x16x32_bf16 v[108:111], v[146:149], v[210:213], v[108:111]
	v_lshl_add_u64 v[198:199], s[42:43], 0, v[128:129]
	v_mfma_f32_16x16x32_bf16 v[104:107], v[154:157], v[210:213], v[104:107]
	s_add_u32 s42, s42, s0
	v_mfma_f32_16x16x32_bf16 v[92:95], v[146:149], v[220:223], v[92:95]
	s_addc_u32 s43, s43, s1
	v_mfma_f32_16x16x32_bf16 v[88:91], v[154:157], v[220:223], v[88:91]
	v_lshl_add_u64 v[202:203], s[42:43], 0, v[132:133]
	v_mfma_f32_16x16x32_bf16 v[76:79], v[146:149], v[228:231], v[76:79]
	v_lshl_add_u64 v[236:237], s[42:43], 0, v[128:129]
	v_mfma_f32_16x16x32_bf16 v[72:75], v[154:157], v[228:231], v[72:75]
	v_lshl_add_u64 v[238:239], s[16:17], 0, v[134:135]
	v_mfma_f32_16x16x32_bf16 v[124:127], v[150:153], v[206:209], v[124:127]
	v_lshl_add_u64 v[240:241], s[16:17], 0, v[130:131]
	v_mfma_f32_16x16x32_bf16 v[120:123], v[158:161], v[206:209], v[120:123]
	v_mfma_f32_16x16x32_bf16 v[108:111], v[150:153], v[214:217], v[108:111]
	v_mfma_f32_16x16x32_bf16 v[104:107], v[158:161], v[214:217], v[104:107]
	v_mfma_f32_16x16x32_bf16 v[92:95], v[150:153], v[224:227], v[92:95]
	v_mfma_f32_16x16x32_bf16 v[88:91], v[158:161], v[224:227], v[88:91]
	v_mfma_f32_16x16x32_bf16 v[76:79], v[150:153], v[232:235], v[76:79]
	v_mfma_f32_16x16x32_bf16 v[72:75], v[158:161], v[232:235], v[72:75]
	v_mfma_f32_16x16x32_bf16 v[116:119], v[162:165], v[194:197], v[116:119]
	v_mfma_f32_16x16x32_bf16 v[112:115], v[170:173], v[194:197], v[112:115]
	v_mfma_f32_16x16x32_bf16 v[100:103], v[162:165], v[210:213], v[100:103]
	v_mfma_f32_16x16x32_bf16 v[96:99], v[170:173], v[210:213], v[96:99]
	v_mfma_f32_16x16x32_bf16 v[84:87], v[162:165], v[220:223], v[84:87]
	v_mfma_f32_16x16x32_bf16 v[80:83], v[170:173], v[220:223], v[80:83]
	v_mfma_f32_16x16x32_bf16 v[68:71], v[162:165], v[228:231], v[68:71]
	v_mfma_f32_16x16x32_bf16 v[64:67], v[170:173], v[228:231], v[64:67]
	v_mfma_f32_16x16x32_bf16 v[116:119], v[166:169], v[206:209], v[116:119]
	v_mfma_f32_16x16x32_bf16 v[112:115], v[174:177], v[206:209], v[112:115]
	v_mfma_f32_16x16x32_bf16 v[100:103], v[166:169], v[214:217], v[100:103]
	v_mfma_f32_16x16x32_bf16 v[96:99], v[174:177], v[214:217], v[96:99]
	v_mfma_f32_16x16x32_bf16 v[84:87], v[166:169], v[224:227], v[84:87]
	v_mfma_f32_16x16x32_bf16 v[80:83], v[174:177], v[224:227], v[80:83]
	v_mfma_f32_16x16x32_bf16 v[68:71], v[166:169], v[232:235], v[68:71]
	v_mfma_f32_16x16x32_bf16 v[64:67], v[174:177], v[232:235], v[64:67]
	s_barrier
	s_add_i32 s59, s59, s36
	s_mov_b32 m0, s59
	ds_read_b128 v[194:197], v145 offset:16384
	ds_read_b128 v[206:209], v145 offset:17408
	ds_read_b128 v[210:213], v145 offset:18432
	ds_read_b128 v[214:217], v145 offset:19456
	ds_read_b128 v[220:223], v145 offset:20480
	ds_read_b128 v[224:227], v145 offset:21504
	ds_read_b128 v[228:231], v145 offset:22528
	ds_read_b128 v[232:235], v145 offset:23552
	global_load_lds_dwordx4 v[178:179], off
	s_add_i32 m0, s59, 0x2000
	s_add_i32 s31, s31, s36
	global_load_lds_dwordx4 v[198:199], off
	s_mov_b32 m0, s31
	s_nop 0
	global_load_lds_dwordx4 v[202:203], off
	s_add_i32 m0, s31, 0x2000
	s_nop 0
	global_load_lds_dwordx4 v[236:237], off
	s_mov_b32 m0, s37
	s_nop 0
	global_load_lds_dwordx4 v[238:239], off
	s_mov_b32 m0, s38
	s_nop 0
	global_load_lds_dwordx4 v[240:241], off
	s_waitcnt vmcnt(8)
	s_waitcnt lgkmcnt(0)
	s_barrier
	s_waitcnt lgkmcnt(0)
	v_mfma_f32_16x16x32_bf16 v[60:63], v[146:149], v[194:197], v[60:63]
	v_mfma_f32_16x16x32_bf16 v[56:59], v[154:157], v[194:197], v[56:59]
	v_mfma_f32_16x16x32_bf16 v[44:47], v[146:149], v[210:213], v[44:47]
	v_mfma_f32_16x16x32_bf16 v[40:43], v[154:157], v[210:213], v[40:43]
	v_mfma_f32_16x16x32_bf16 v[28:31], v[146:149], v[220:223], v[28:31]
	v_mfma_f32_16x16x32_bf16 v[24:27], v[154:157], v[220:223], v[24:27]
	v_mfma_f32_16x16x32_bf16 v[12:15], v[146:149], v[228:231], v[12:15]
	v_mfma_f32_16x16x32_bf16 v[8:11], v[154:157], v[228:231], v[8:11]
	v_mfma_f32_16x16x32_bf16 v[60:63], v[150:153], v[206:209], v[60:63]
	v_mfma_f32_16x16x32_bf16 v[56:59], v[158:161], v[206:209], v[56:59]
	v_mfma_f32_16x16x32_bf16 v[44:47], v[150:153], v[214:217], v[44:47]
	v_mfma_f32_16x16x32_bf16 v[40:43], v[158:161], v[214:217], v[40:43]
	v_mfma_f32_16x16x32_bf16 v[28:31], v[150:153], v[224:227], v[28:31]
	v_mfma_f32_16x16x32_bf16 v[24:27], v[158:161], v[224:227], v[24:27]
	v_mfma_f32_16x16x32_bf16 v[12:15], v[150:153], v[232:235], v[12:15]
	v_mfma_f32_16x16x32_bf16 v[8:11], v[158:161], v[232:235], v[8:11]
	v_mfma_f32_16x16x32_bf16 v[52:55], v[162:165], v[194:197], v[52:55]
	v_mfma_f32_16x16x32_bf16 v[48:51], v[170:173], v[194:197], v[48:51]
	v_mfma_f32_16x16x32_bf16 v[36:39], v[162:165], v[210:213], v[36:39]
	v_mfma_f32_16x16x32_bf16 v[32:35], v[170:173], v[210:213], v[32:35]
	v_mfma_f32_16x16x32_bf16 v[20:23], v[162:165], v[220:223], v[20:23]
	v_mfma_f32_16x16x32_bf16 v[16:19], v[170:173], v[220:223], v[16:19]
	v_mfma_f32_16x16x32_bf16 v[4:7], v[162:165], v[228:231], v[4:7]
	v_mfma_f32_16x16x32_bf16 v[0:3], v[170:173], v[228:231], v[0:3]
	v_mfma_f32_16x16x32_bf16 v[52:55], v[166:169], v[206:209], v[52:55]
	v_mfma_f32_16x16x32_bf16 v[48:51], v[174:177], v[206:209], v[48:51]
	v_mfma_f32_16x16x32_bf16 v[36:39], v[166:169], v[214:217], v[36:39]
	v_mfma_f32_16x16x32_bf16 v[32:35], v[174:177], v[214:217], v[32:35]
	v_mfma_f32_16x16x32_bf16 v[20:23], v[166:169], v[224:227], v[20:23]
	v_mfma_f32_16x16x32_bf16 v[16:19], v[174:177], v[224:227], v[16:19]
	v_mfma_f32_16x16x32_bf16 v[4:7], v[166:169], v[232:235], v[4:7]
	v_mfma_f32_16x16x32_bf16 v[0:3], v[174:177], v[232:235], v[0:3]
	s_barrier
	s_add_i32 s31, 0, 0x18000
	v_add_u32_e32 v140, s31, v143
	s_add_i32 s42, 0, 0x1c000
	ds_read_b128 v[146:149], v140
	ds_read_b128 v[150:153], v140 offset:1024
	ds_read_b128 v[154:157], v140 offset:2048
	ds_read_b128 v[158:161], v140 offset:3072
	v_add_u32_e32 v140, s42, v143
	ds_read_b128 v[162:165], v140
	ds_read_b128 v[166:169], v140 offset:1024
	ds_read_b128 v[170:173], v140 offset:2048
	ds_read_b128 v[174:177], v140 offset:3072
	s_add_u32 s16, s16, s0
	s_addc_u32 s17, s17, s1
	s_mov_b32 m0, s39
	v_lshl_add_u64 v[242:243], s[16:17], 0, v[134:135]
	ds_read_b128 v[194:197], v145 offset:32768
	ds_read_b128 v[206:209], v145 offset:33792
	ds_read_b128 v[210:213], v145 offset:34816
	ds_read_b128 v[214:217], v145 offset:35840
	ds_read_b128 v[220:223], v145 offset:36864
	ds_read_b128 v[224:227], v145 offset:37888
	ds_read_b128 v[228:231], v145 offset:38912
	ds_read_b128 v[232:235], v145 offset:39936
	global_load_lds_dwordx4 v[242:243], off
	v_lshl_add_u64 v[242:243], s[16:17], 0, v[130:131]
	s_mov_b32 m0, s44
	s_nop 0
	global_load_lds_dwordx4 v[242:243], off
	s_waitcnt vmcnt(8)
	s_waitcnt lgkmcnt(0)
	s_barrier
	s_waitcnt lgkmcnt(0)
	v_mfma_f32_16x16x32_bf16 v[124:127], v[146:149], v[194:197], v[124:127]
	v_mfma_f32_16x16x32_bf16 v[120:123], v[154:157], v[194:197], v[120:123]
	v_lshl_add_u64 v[178:179], v[178:179], 0, s[12:13]
	v_mfma_f32_16x16x32_bf16 v[108:111], v[146:149], v[210:213], v[108:111]
	v_lshl_add_u64 v[198:199], v[198:199], 0, s[12:13]
	v_mfma_f32_16x16x32_bf16 v[104:107], v[154:157], v[210:213], v[104:107]
	v_lshl_add_u64 v[202:203], v[202:203], 0, s[12:13]
	v_mfma_f32_16x16x32_bf16 v[92:95], v[146:149], v[220:223], v[92:95]
	v_lshl_add_u64 v[236:237], v[236:237], 0, s[12:13]
	v_mfma_f32_16x16x32_bf16 v[88:91], v[154:157], v[220:223], v[88:91]
	v_lshl_add_u64 v[238:239], v[238:239], 0, s[12:13]
	v_mfma_f32_16x16x32_bf16 v[76:79], v[146:149], v[228:231], v[76:79]
	v_lshl_add_u64 v[240:241], v[240:241], 0, s[12:13]
	v_mfma_f32_16x16x32_bf16 v[72:75], v[154:157], v[228:231], v[72:75]
	v_mfma_f32_16x16x32_bf16 v[124:127], v[150:153], v[206:209], v[124:127]
	v_mfma_f32_16x16x32_bf16 v[120:123], v[158:161], v[206:209], v[120:123]
	v_mfma_f32_16x16x32_bf16 v[108:111], v[150:153], v[214:217], v[108:111]
	v_mfma_f32_16x16x32_bf16 v[104:107], v[158:161], v[214:217], v[104:107]
	v_mfma_f32_16x16x32_bf16 v[92:95], v[150:153], v[224:227], v[92:95]
	v_mfma_f32_16x16x32_bf16 v[88:91], v[158:161], v[224:227], v[88:91]
	v_mfma_f32_16x16x32_bf16 v[76:79], v[150:153], v[232:235], v[76:79]
	v_mfma_f32_16x16x32_bf16 v[72:75], v[158:161], v[232:235], v[72:75]
	v_mfma_f32_16x16x32_bf16 v[116:119], v[162:165], v[194:197], v[116:119]
	v_mfma_f32_16x16x32_bf16 v[112:115], v[170:173], v[194:197], v[112:115]
	v_mfma_f32_16x16x32_bf16 v[100:103], v[162:165], v[210:213], v[100:103]
	v_mfma_f32_16x16x32_bf16 v[96:99], v[170:173], v[210:213], v[96:99]
	v_mfma_f32_16x16x32_bf16 v[84:87], v[162:165], v[220:223], v[84:87]
	v_mfma_f32_16x16x32_bf16 v[80:83], v[170:173], v[220:223], v[80:83]
	v_mfma_f32_16x16x32_bf16 v[68:71], v[162:165], v[228:231], v[68:71]
	v_mfma_f32_16x16x32_bf16 v[64:67], v[170:173], v[228:231], v[64:67]
	v_mfma_f32_16x16x32_bf16 v[116:119], v[166:169], v[206:209], v[116:119]
	v_mfma_f32_16x16x32_bf16 v[112:115], v[174:177], v[206:209], v[112:115]
	v_mfma_f32_16x16x32_bf16 v[100:103], v[166:169], v[214:217], v[100:103]
	v_mfma_f32_16x16x32_bf16 v[96:99], v[174:177], v[214:217], v[96:99]
	v_mfma_f32_16x16x32_bf16 v[84:87], v[166:169], v[224:227], v[84:87]
	v_mfma_f32_16x16x32_bf16 v[80:83], v[174:177], v[224:227], v[80:83]
	v_mfma_f32_16x16x32_bf16 v[68:71], v[166:169], v[232:235], v[68:71]
	v_mfma_f32_16x16x32_bf16 v[64:67], v[174:177], v[232:235], v[64:67]
	s_barrier
	s_add_i32 s16, s31, s36
	s_mov_b32 m0, s16
	ds_read_b128 v[194:197], v145 offset:49152
	ds_read_b128 v[206:209], v145 offset:50176
	ds_read_b128 v[210:213], v145 offset:51200
	ds_read_b128 v[214:217], v145 offset:52224
	ds_read_b128 v[220:223], v145 offset:53248
	ds_read_b128 v[224:227], v145 offset:54272
	ds_read_b128 v[228:231], v145 offset:55296
	ds_read_b128 v[232:235], v145 offset:56320
	global_load_lds_dwordx4 v[178:179], off
	s_add_i32 m0, s16, 0x2000
	s_add_i32 s16, s42, s36
	global_load_lds_dwordx4 v[198:199], off
	s_mov_b32 m0, s16
	s_nop 0
	global_load_lds_dwordx4 v[202:203], off
	s_add_i32 m0, s16, 0x2000
	s_nop 0
	global_load_lds_dwordx4 v[236:237], off
	s_mov_b32 m0, s45
	s_nop 0
	global_load_lds_dwordx4 v[238:239], off
	s_mov_b32 m0, s46
	s_nop 0
	global_load_lds_dwordx4 v[240:241], off
	s_waitcnt vmcnt(8)
	s_waitcnt lgkmcnt(0)
	s_barrier
	s_waitcnt lgkmcnt(0)
	v_mfma_f32_16x16x32_bf16 v[60:63], v[146:149], v[194:197], v[60:63]
	s_add_u32 s28, s28, 0x100
	v_mfma_f32_16x16x32_bf16 v[56:59], v[154:157], v[194:197], v[56:59]
	s_addc_u32 s29, s29, 0
	v_mfma_f32_16x16x32_bf16 v[44:47], v[146:149], v[210:213], v[44:47]
	s_add_u32 s10, s10, 0x100
	v_mfma_f32_16x16x32_bf16 v[40:43], v[154:157], v[210:213], v[40:43]
	s_addc_u32 s11, s11, 0
	v_mfma_f32_16x16x32_bf16 v[28:31], v[146:149], v[220:223], v[28:31]
	s_mov_b32 s16, s30
	v_mfma_f32_16x16x32_bf16 v[24:27], v[154:157], v[220:223], v[24:27]
	s_cmp_ge_i32 s30, s47
	v_mfma_f32_16x16x32_bf16 v[12:15], v[146:149], v[228:231], v[12:15]
	s_cselect_b32 s99, 1, 0
	v_mfma_f32_16x16x32_bf16 v[8:11], v[154:157], v[228:231], v[8:11]
	s_add_i32 s30, s16, 2
	v_mfma_f32_16x16x32_bf16 v[60:63], v[150:153], v[206:209], v[60:63]
	s_add_u32 s31, s28, 0x80
	v_mfma_f32_16x16x32_bf16 v[56:59], v[158:161], v[206:209], v[56:59]
	s_addc_u32 s17, s29, 0
	v_mfma_f32_16x16x32_bf16 v[44:47], v[150:153], v[214:217], v[44:47]
	s_add_i32 s59, 0, 0x10000
	v_mfma_f32_16x16x32_bf16 v[40:43], v[158:161], v[214:217], v[40:43]
	s_cmp_eq_u32 s48, s16
	v_mfma_f32_16x16x32_bf16 v[28:31], v[150:153], v[224:227], v[28:31]
	s_cselect_b32 s17, s25, s17
	v_mfma_f32_16x16x32_bf16 v[24:27], v[158:161], v[224:227], v[24:27]
	s_cselect_b32 s16, s24, s31
	v_mfma_f32_16x16x32_bf16 v[12:15], v[150:153], v[232:235], v[12:15]
	s_cselect_b32 s43, s27, s11
	v_mfma_f32_16x16x32_bf16 v[8:11], v[158:161], v[232:235], v[8:11]
	s_cselect_b32 s42, s26, s10
	v_mfma_f32_16x16x32_bf16 v[52:55], v[162:165], v[194:197], v[52:55]
	s_add_i32 s31, 0, 0x14000
	v_mfma_f32_16x16x32_bf16 v[48:51], v[170:173], v[194:197], v[48:51]
	v_mfma_f32_16x16x32_bf16 v[36:39], v[162:165], v[210:213], v[36:39]
	v_mfma_f32_16x16x32_bf16 v[32:35], v[170:173], v[210:213], v[32:35]
	v_mfma_f32_16x16x32_bf16 v[20:23], v[162:165], v[220:223], v[20:23]
	v_mfma_f32_16x16x32_bf16 v[16:19], v[170:173], v[220:223], v[16:19]
	v_mfma_f32_16x16x32_bf16 v[4:7], v[162:165], v[228:231], v[4:7]
	v_mfma_f32_16x16x32_bf16 v[0:3], v[170:173], v[228:231], v[0:3]
	v_mfma_f32_16x16x32_bf16 v[52:55], v[166:169], v[206:209], v[52:55]
	v_mfma_f32_16x16x32_bf16 v[48:51], v[174:177], v[206:209], v[48:51]
	v_mfma_f32_16x16x32_bf16 v[36:39], v[166:169], v[214:217], v[36:39]
	v_mfma_f32_16x16x32_bf16 v[32:35], v[174:177], v[214:217], v[32:35]
	v_mfma_f32_16x16x32_bf16 v[20:23], v[166:169], v[224:227], v[20:23]
	v_mfma_f32_16x16x32_bf16 v[16:19], v[174:177], v[224:227], v[16:19]
	v_mfma_f32_16x16x32_bf16 v[4:7], v[166:169], v[232:235], v[4:7]
	v_mfma_f32_16x16x32_bf16 v[0:3], v[174:177], v[232:235], v[0:3]
	s_barrier
	s_cmp_lg_u32 s99, 0
	s_cbranch_scc0 .LBB0_798

.Llbb_7:
	s_add_i32 s28, s16, 2
	s_add_u32 s29, s26, 0x80
	s_addc_u32 s17, s27, 0
	s_add_i32 s59, 0, 0x10000
	s_cmp_eq_u32 s48, s16
	s_cselect_b32 s17, s23, s17
	s_cselect_b32 s16, s22, s29
	v_add_u32_e32 v140, s59, v143
	s_cselect_b32 s43, s25, s11
	s_cselect_b32 s42, s24, s10
	s_add_i32 s29, 0, 0x14000
	ds_read_b128 v[146:149], v140
	ds_read_b128 v[150:153], v140 offset:1024
	ds_read_b128 v[154:157], v140 offset:2048
	ds_read_b128 v[158:161], v140 offset:3072
	v_add_u32_e32 v140, s29, v143
	ds_read_b128 v[162:165], v140
	ds_read_b128 v[166:169], v140 offset:1024
	ds_read_b128 v[170:173], v140 offset:2048
	ds_read_b128 v[174:177], v140 offset:3072
	v_lshl_add_u64 v[140:141], s[26:27], 0, v[136:137]
	s_add_i32 m0, s35, 0xc000
	ds_read_b128 v[194:197], v145
	ds_read_b128 v[206:209], v145 offset:1024
	ds_read_b128 v[210:213], v145 offset:2048
	ds_read_b128 v[214:217], v145 offset:3072
	ds_read_b128 v[220:223], v145 offset:4096
	ds_read_b128 v[224:227], v145 offset:5120
	ds_read_b128 v[228:231], v145 offset:6144
	ds_read_b128 v[232:235], v145 offset:7168
	global_load_lds_dwordx4 v[140:141], off
	v_lshl_add_u64 v[140:141], s[26:27], 0, v[138:139]
	s_add_i32 m0, s35, 0xe000
	s_nop 0
	global_load_lds_dwordx4 v[140:141], off
	s_waitcnt vmcnt(8)
	s_waitcnt lgkmcnt(0)
	s_barrier
	s_waitcnt lgkmcnt(0)
	v_mfma_f32_16x16x32_bf16 v[120:123], v[146:149], v[194:197], 0
	v_mfma_f32_16x16x32_bf16 v[124:127], v[154:157], v[194:197], 0
	v_lshl_add_u64 v[140:141], s[42:43], 0, v[132:133]
	v_mfma_f32_16x16x32_bf16 v[116:119], v[146:149], v[210:213], 0
	v_lshl_add_u64 v[178:179], s[42:43], 0, v[128:129]
	v_mfma_f32_16x16x32_bf16 v[112:115], v[154:157], v[210:213], 0
	s_add_u32 s42, s42, s0
	v_mfma_f32_16x16x32_bf16 v[108:111], v[146:149], v[220:223], 0
	s_addc_u32 s43, s43, s1
	v_mfma_f32_16x16x32_bf16 v[104:107], v[154:157], v[220:223], 0
	v_lshl_add_u64 v[198:199], s[42:43], 0, v[132:133]
	v_mfma_f32_16x16x32_bf16 v[100:103], v[146:149], v[228:231], 0
	v_lshl_add_u64 v[202:203], s[42:43], 0, v[128:129]
	v_mfma_f32_16x16x32_bf16 v[96:99], v[154:157], v[228:231], 0
	v_lshl_add_u64 v[236:237], s[16:17], 0, v[134:135]
	v_mfma_f32_16x16x32_bf16 v[120:123], v[150:153], v[206:209], v[120:123]
	v_lshl_add_u64 v[238:239], s[16:17], 0, v[130:131]
	v_mfma_f32_16x16x32_bf16 v[124:127], v[158:161], v[206:209], v[124:127]
	v_mfma_f32_16x16x32_bf16 v[116:119], v[150:153], v[214:217], v[116:119]
	v_mfma_f32_16x16x32_bf16 v[112:115], v[158:161], v[214:217], v[112:115]
	v_mfma_f32_16x16x32_bf16 v[108:111], v[150:153], v[224:227], v[108:111]
	v_mfma_f32_16x16x32_bf16 v[104:107], v[158:161], v[224:227], v[104:107]
	v_mfma_f32_16x16x32_bf16 v[100:103], v[150:153], v[232:235], v[100:103]
	v_mfma_f32_16x16x32_bf16 v[96:99], v[158:161], v[232:235], v[96:99]
	v_mfma_f32_16x16x32_bf16 v[60:63], v[162:165], v[194:197], 0
	v_mfma_f32_16x16x32_bf16 v[56:59], v[170:173], v[194:197], 0
	v_mfma_f32_16x16x32_bf16 v[52:55], v[162:165], v[210:213], 0
	v_mfma_f32_16x16x32_bf16 v[48:51], v[170:173], v[210:213], 0
	v_mfma_f32_16x16x32_bf16 v[44:47], v[162:165], v[220:223], 0
	v_mfma_f32_16x16x32_bf16 v[40:43], v[170:173], v[220:223], 0
	v_mfma_f32_16x16x32_bf16 v[36:39], v[162:165], v[228:231], 0
	v_mfma_f32_16x16x32_bf16 v[32:35], v[170:173], v[228:231], 0
	v_mfma_f32_16x16x32_bf16 v[60:63], v[166:169], v[206:209], v[60:63]
	v_mfma_f32_16x16x32_bf16 v[56:59], v[174:177], v[206:209], v[56:59]
	v_mfma_f32_16x16x32_bf16 v[52:55], v[166:169], v[214:217], v[52:55]
	v_mfma_f32_16x16x32_bf16 v[48:51], v[174:177], v[214:217], v[48:51]
	v_mfma_f32_16x16x32_bf16 v[44:47], v[166:169], v[224:227], v[44:47]
	v_mfma_f32_16x16x32_bf16 v[40:43], v[174:177], v[224:227], v[40:43]
	v_mfma_f32_16x16x32_bf16 v[36:39], v[166:169], v[232:235], v[36:39]
	v_mfma_f32_16x16x32_bf16 v[32:35], v[174:177], v[232:235], v[32:35]
	s_barrier
	s_add_i32 s59, s59, s34
	s_mov_b32 m0, s59
	ds_read_b128 v[194:197], v145 offset:16384
	ds_read_b128 v[206:209], v145 offset:17408
	ds_read_b128 v[210:213], v145 offset:18432
	ds_read_b128 v[214:217], v145 offset:19456
	ds_read_b128 v[220:223], v145 offset:20480
	ds_read_b128 v[224:227], v145 offset:21504
	ds_read_b128 v[228:231], v145 offset:22528
	ds_read_b128 v[232:235], v145 offset:23552
	global_load_lds_dwordx4 v[140:141], off
	s_add_i32 m0, s59, 0x2000
	s_add_i32 s29, s29, s34
	global_load_lds_dwordx4 v[178:179], off
	s_mov_b32 m0, s29
	s_nop 0
	global_load_lds_dwordx4 v[198:199], off
	s_add_i32 m0, s29, 0x2000
	s_nop 0
	global_load_lds_dwordx4 v[202:203], off
	s_mov_b32 m0, s35
	s_nop 0
	global_load_lds_dwordx4 v[236:237], off
	s_mov_b32 m0, s36
	s_nop 0
	global_load_lds_dwordx4 v[238:239], off
	s_waitcnt vmcnt(8)
	s_waitcnt lgkmcnt(0)
	s_barrier
	s_waitcnt lgkmcnt(0)
	v_mfma_f32_16x16x32_bf16 v[92:95], v[146:149], v[194:197], 0
	v_mfma_f32_16x16x32_bf16 v[88:91], v[154:157], v[194:197], 0
	v_mfma_f32_16x16x32_bf16 v[84:87], v[146:149], v[210:213], 0
	v_mfma_f32_16x16x32_bf16 v[80:83], v[154:157], v[210:213], 0
	v_mfma_f32_16x16x32_bf16 v[76:79], v[146:149], v[220:223], 0
	v_mfma_f32_16x16x32_bf16 v[72:75], v[154:157], v[220:223], 0
	v_mfma_f32_16x16x32_bf16 v[68:71], v[146:149], v[228:231], 0
	v_mfma_f32_16x16x32_bf16 v[64:67], v[154:157], v[228:231], 0
	v_mfma_f32_16x16x32_bf16 v[92:95], v[150:153], v[206:209], v[92:95]
	v_mfma_f32_16x16x32_bf16 v[88:91], v[158:161], v[206:209], v[88:91]
	v_mfma_f32_16x16x32_bf16 v[84:87], v[150:153], v[214:217], v[84:87]
	v_mfma_f32_16x16x32_bf16 v[80:83], v[158:161], v[214:217], v[80:83]
	v_mfma_f32_16x16x32_bf16 v[76:79], v[150:153], v[224:227], v[76:79]
	v_mfma_f32_16x16x32_bf16 v[72:75], v[158:161], v[224:227], v[72:75]
	v_mfma_f32_16x16x32_bf16 v[68:71], v[150:153], v[232:235], v[68:71]
	v_mfma_f32_16x16x32_bf16 v[64:67], v[158:161], v[232:235], v[64:67]
	v_mfma_f32_16x16x32_bf16 v[28:31], v[162:165], v[194:197], 0
	v_mfma_f32_16x16x32_bf16 v[24:27], v[170:173], v[194:197], 0
	v_mfma_f32_16x16x32_bf16 v[20:23], v[162:165], v[210:213], 0
	v_mfma_f32_16x16x32_bf16 v[16:19], v[170:173], v[210:213], 0
	v_mfma_f32_16x16x32_bf16 v[12:15], v[162:165], v[220:223], 0
	v_mfma_f32_16x16x32_bf16 v[8:11], v[170:173], v[220:223], 0
	v_mfma_f32_16x16x32_bf16 v[4:7], v[162:165], v[228:231], 0
	v_mfma_f32_16x16x32_bf16 v[0:3], v[170:173], v[228:231], 0
	v_mfma_f32_16x16x32_bf16 v[28:31], v[166:169], v[206:209], v[28:31]
	v_mfma_f32_16x16x32_bf16 v[24:27], v[174:177], v[206:209], v[24:27]
	v_mfma_f32_16x16x32_bf16 v[20:23], v[166:169], v[214:217], v[20:23]
	v_mfma_f32_16x16x32_bf16 v[16:19], v[174:177], v[214:217], v[16:19]
	v_mfma_f32_16x16x32_bf16 v[12:15], v[166:169], v[224:227], v[12:15]
	v_mfma_f32_16x16x32_bf16 v[8:11], v[174:177], v[224:227], v[8:11]
	v_mfma_f32_16x16x32_bf16 v[4:7], v[166:169], v[232:235], v[4:7]
	v_mfma_f32_16x16x32_bf16 v[0:3], v[174:177], v[232:235], v[0:3]
	s_barrier
	s_add_i32 s29, 0, 0x18000
	s_add_i32 s42, 0, 0x1c000
	v_add_u32_e32 v158, s29, v143
	v_add_u32_e32 v174, s42, v143
	ds_read_b128 v[146:149], v158
	ds_read_b128 v[150:153], v158 offset:1024
	ds_read_b128 v[154:157], v158 offset:2048
	ds_read_b128 v[158:161], v158 offset:3072
	ds_read_b128 v[162:165], v174
	ds_read_b128 v[166:169], v174 offset:1024
	ds_read_b128 v[170:173], v174 offset:2048
	ds_read_b128 v[174:177], v174 offset:3072
	s_add_u32 s16, s16, s0
	s_addc_u32 s17, s17, s1
	s_mov_b32 m0, s37
	v_lshl_add_u64 v[240:241], s[16:17], 0, v[134:135]
	ds_read_b128 v[194:197], v145 offset:32768
	ds_read_b128 v[206:209], v145 offset:33792
	ds_read_b128 v[210:213], v145 offset:34816
	ds_read_b128 v[214:217], v145 offset:35840
	ds_read_b128 v[220:223], v145 offset:36864
	ds_read_b128 v[224:227], v145 offset:37888
	ds_read_b128 v[228:231], v145 offset:38912
	ds_read_b128 v[232:235], v145 offset:39936
	global_load_lds_dwordx4 v[240:241], off
	v_lshl_add_u64 v[240:241], s[16:17], 0, v[130:131]
	s_mov_b32 m0, s38
	s_nop 0
	global_load_lds_dwordx4 v[240:241], off
	s_waitcnt vmcnt(8)
	s_waitcnt lgkmcnt(0)
	s_barrier
	s_waitcnt lgkmcnt(0)
	v_mfma_f32_16x16x32_bf16 v[120:123], v[146:149], v[194:197], v[120:123]
	v_mfma_f32_16x16x32_bf16 v[124:127], v[154:157], v[194:197], v[124:127]
	v_lshl_add_u64 v[140:141], v[140:141], 0, s[12:13]
	v_mfma_f32_16x16x32_bf16 v[116:119], v[146:149], v[210:213], v[116:119]
	v_lshl_add_u64 v[178:179], v[178:179], 0, s[12:13]
	v_mfma_f32_16x16x32_bf16 v[112:115], v[154:157], v[210:213], v[112:115]
	v_lshl_add_u64 v[198:199], v[198:199], 0, s[12:13]
	v_mfma_f32_16x16x32_bf16 v[108:111], v[146:149], v[220:223], v[108:111]
	v_lshl_add_u64 v[202:203], v[202:203], 0, s[12:13]
	v_mfma_f32_16x16x32_bf16 v[104:107], v[154:157], v[220:223], v[104:107]
	v_lshl_add_u64 v[236:237], v[236:237], 0, s[12:13]
	v_mfma_f32_16x16x32_bf16 v[100:103], v[146:149], v[228:231], v[100:103]
	v_lshl_add_u64 v[238:239], v[238:239], 0, s[12:13]
	v_mfma_f32_16x16x32_bf16 v[96:99], v[154:157], v[228:231], v[96:99]
	v_mfma_f32_16x16x32_bf16 v[120:123], v[150:153], v[206:209], v[120:123]
	v_mfma_f32_16x16x32_bf16 v[124:127], v[158:161], v[206:209], v[124:127]
	v_mfma_f32_16x16x32_bf16 v[116:119], v[150:153], v[214:217], v[116:119]
	v_mfma_f32_16x16x32_bf16 v[112:115], v[158:161], v[214:217], v[112:115]
	v_mfma_f32_16x16x32_bf16 v[108:111], v[150:153], v[224:227], v[108:111]
	v_mfma_f32_16x16x32_bf16 v[104:107], v[158:161], v[224:227], v[104:107]
	v_mfma_f32_16x16x32_bf16 v[100:103], v[150:153], v[232:235], v[100:103]
	v_mfma_f32_16x16x32_bf16 v[96:99], v[158:161], v[232:235], v[96:99]
	v_mfma_f32_16x16x32_bf16 v[60:63], v[162:165], v[194:197], v[60:63]
	v_mfma_f32_16x16x32_bf16 v[56:59], v[170:173], v[194:197], v[56:59]
	v_mfma_f32_16x16x32_bf16 v[52:55], v[162:165], v[210:213], v[52:55]
	v_mfma_f32_16x16x32_bf16 v[48:51], v[170:173], v[210:213], v[48:51]
	v_mfma_f32_16x16x32_bf16 v[44:47], v[162:165], v[220:223], v[44:47]
	v_mfma_f32_16x16x32_bf16 v[40:43], v[170:173], v[220:223], v[40:43]
	v_mfma_f32_16x16x32_bf16 v[36:39], v[162:165], v[228:231], v[36:39]
	v_mfma_f32_16x16x32_bf16 v[32:35], v[170:173], v[228:231], v[32:35]
	v_mfma_f32_16x16x32_bf16 v[60:63], v[166:169], v[206:209], v[60:63]
	v_mfma_f32_16x16x32_bf16 v[56:59], v[174:177], v[206:209], v[56:59]
	v_mfma_f32_16x16x32_bf16 v[52:55], v[166:169], v[214:217], v[52:55]
	v_mfma_f32_16x16x32_bf16 v[48:51], v[174:177], v[214:217], v[48:51]
	v_mfma_f32_16x16x32_bf16 v[44:47], v[166:169], v[224:227], v[44:47]
	v_mfma_f32_16x16x32_bf16 v[40:43], v[174:177], v[224:227], v[40:43]
	v_mfma_f32_16x16x32_bf16 v[36:39], v[166:169], v[232:235], v[36:39]
	v_mfma_f32_16x16x32_bf16 v[32:35], v[174:177], v[232:235], v[32:35]
	s_barrier
	s_add_i32 s16, s29, s34
	s_mov_b32 m0, s16
	ds_read_b128 v[194:197], v145 offset:49152
	ds_read_b128 v[206:209], v145 offset:50176
	ds_read_b128 v[210:213], v145 offset:51200
	ds_read_b128 v[214:217], v145 offset:52224
	ds_read_b128 v[220:223], v145 offset:53248
	ds_read_b128 v[224:227], v145 offset:54272
	ds_read_b128 v[228:231], v145 offset:55296
	ds_read_b128 v[232:235], v145 offset:56320
	global_load_lds_dwordx4 v[140:141], off
	s_add_i32 m0, s16, 0x2000
	s_add_i32 s16, s42, s34
	global_load_lds_dwordx4 v[178:179], off
	s_mov_b32 m0, s16
	s_nop 0
	global_load_lds_dwordx4 v[198:199], off
	s_add_i32 m0, s16, 0x2000
	s_nop 0
	global_load_lds_dwordx4 v[202:203], off
	s_mov_b32 m0, s46
	s_nop 0
	global_load_lds_dwordx4 v[236:237], off
	s_mov_b32 m0, s47
	s_nop 0
	global_load_lds_dwordx4 v[238:239], off
	s_waitcnt vmcnt(8)
	s_waitcnt lgkmcnt(0)
	s_barrier
	s_waitcnt lgkmcnt(0)
	v_mfma_f32_16x16x32_bf16 v[92:95], v[146:149], v[194:197], v[92:95]
	s_add_u32 s26, s26, 0x100
	v_mfma_f32_16x16x32_bf16 v[88:91], v[154:157], v[194:197], v[88:91]
	s_addc_u32 s27, s27, 0
	v_mfma_f32_16x16x32_bf16 v[84:87], v[146:149], v[210:213], v[84:87]
	s_add_u32 s10, s10, 0x100
	v_mfma_f32_16x16x32_bf16 v[80:83], v[154:157], v[210:213], v[80:83]
	s_addc_u32 s11, s11, 0
	v_mfma_f32_16x16x32_bf16 v[76:79], v[146:149], v[220:223], v[76:79]
	s_mov_b32 s16, s28
	v_mfma_f32_16x16x32_bf16 v[72:75], v[154:157], v[220:223], v[72:75]
	s_cmp_ge_i32 s28, s45
	v_mfma_f32_16x16x32_bf16 v[68:71], v[146:149], v[228:231], v[68:71]
	s_cselect_b32 s99, 1, 0
	v_mfma_f32_16x16x32_bf16 v[64:67], v[154:157], v[228:231], v[64:67]
	s_add_i32 s28, s16, 2
	v_mfma_f32_16x16x32_bf16 v[92:95], v[150:153], v[206:209], v[92:95]
	s_add_u32 s29, s26, 0x80
	v_mfma_f32_16x16x32_bf16 v[88:91], v[158:161], v[206:209], v[88:91]
	s_addc_u32 s17, s27, 0
	v_mfma_f32_16x16x32_bf16 v[84:87], v[150:153], v[214:217], v[84:87]
	s_add_i32 s59, 0, 0x10000
	v_mfma_f32_16x16x32_bf16 v[80:83], v[158:161], v[214:217], v[80:83]
	s_cmp_eq_u32 s48, s16
	v_mfma_f32_16x16x32_bf16 v[76:79], v[150:153], v[224:227], v[76:79]
	s_cselect_b32 s17, s23, s17
	v_mfma_f32_16x16x32_bf16 v[72:75], v[158:161], v[224:227], v[72:75]
	s_cselect_b32 s16, s22, s29
	v_mfma_f32_16x16x32_bf16 v[68:71], v[150:153], v[232:235], v[68:71]
	s_cselect_b32 s43, s25, s11
	v_mfma_f32_16x16x32_bf16 v[64:67], v[158:161], v[232:235], v[64:67]
	s_cselect_b32 s42, s24, s10
	v_mfma_f32_16x16x32_bf16 v[28:31], v[162:165], v[194:197], v[28:31]
	s_add_i32 s29, 0, 0x14000
	v_mfma_f32_16x16x32_bf16 v[24:27], v[170:173], v[194:197], v[24:27]
	v_mfma_f32_16x16x32_bf16 v[20:23], v[162:165], v[210:213], v[20:23]
	v_mfma_f32_16x16x32_bf16 v[16:19], v[170:173], v[210:213], v[16:19]
	v_mfma_f32_16x16x32_bf16 v[12:15], v[162:165], v[220:223], v[12:15]
	v_mfma_f32_16x16x32_bf16 v[8:11], v[170:173], v[220:223], v[8:11]
	v_mfma_f32_16x16x32_bf16 v[4:7], v[162:165], v[228:231], v[4:7]
	v_mfma_f32_16x16x32_bf16 v[0:3], v[170:173], v[228:231], v[0:3]
	v_mfma_f32_16x16x32_bf16 v[28:31], v[166:169], v[206:209], v[28:31]
	v_mfma_f32_16x16x32_bf16 v[24:27], v[174:177], v[206:209], v[24:27]
	v_mfma_f32_16x16x32_bf16 v[20:23], v[166:169], v[214:217], v[20:23]
	v_mfma_f32_16x16x32_bf16 v[16:19], v[174:177], v[214:217], v[16:19]
	v_mfma_f32_16x16x32_bf16 v[12:15], v[166:169], v[224:227], v[12:15]
	v_mfma_f32_16x16x32_bf16 v[8:11], v[174:177], v[224:227], v[8:11]
	v_mfma_f32_16x16x32_bf16 v[4:7], v[166:169], v[232:235], v[4:7]
	v_mfma_f32_16x16x32_bf16 v[0:3], v[174:177], v[232:235], v[0:3]
	s_barrier
	s_cmp_lg_u32 s99, 0
	s_cbranch_scc1 .Lpeelx_11
.LBB0_823:
	v_add_u32_e32 v140, s59, v143
	ds_read_b128 v[146:149], v140
	ds_read_b128 v[150:153], v140 offset:1024
	ds_read_b128 v[154:157], v140 offset:2048
	ds_read_b128 v[158:161], v140 offset:3072
	v_add_u32_e32 v140, s29, v143
	ds_read_b128 v[162:165], v140
	ds_read_b128 v[166:169], v140 offset:1024
	ds_read_b128 v[170:173], v140 offset:2048
	ds_read_b128 v[174:177], v140 offset:3072
	v_lshl_add_u64 v[140:141], s[26:27], 0, v[136:137]
	s_add_i32 m0, s35, 0xc000
	ds_read_b128 v[194:197], v145
	ds_read_b128 v[206:209], v145 offset:1024
	ds_read_b128 v[210:213], v145 offset:2048
	ds_read_b128 v[214:217], v145 offset:3072
	ds_read_b128 v[220:223], v145 offset:4096
	ds_read_b128 v[224:227], v145 offset:5120
	ds_read_b128 v[228:231], v145 offset:6144
	ds_read_b128 v[232:235], v145 offset:7168
	global_load_lds_dwordx4 v[140:141], off
	v_lshl_add_u64 v[140:141], s[26:27], 0, v[138:139]
	s_add_i32 m0, s35, 0xe000
	s_nop 0
	global_load_lds_dwordx4 v[140:141], off
	s_waitcnt vmcnt(8)
	s_waitcnt lgkmcnt(0)
	s_barrier
	s_waitcnt lgkmcnt(0)
	v_mfma_f32_16x16x32_bf16 v[120:123], v[146:149], v[194:197], v[120:123]
	v_mfma_f32_16x16x32_bf16 v[124:127], v[154:157], v[194:197], v[124:127]
	v_lshl_add_u64 v[140:141], s[42:43], 0, v[132:133]
	v_mfma_f32_16x16x32_bf16 v[116:119], v[146:149], v[210:213], v[116:119]
	v_lshl_add_u64 v[178:179], s[42:43], 0, v[128:129]
	v_mfma_f32_16x16x32_bf16 v[112:115], v[154:157], v[210:213], v[112:115]
	s_add_u32 s42, s42, s0
	v_mfma_f32_16x16x32_bf16 v[108:111], v[146:149], v[220:223], v[108:111]
	s_addc_u32 s43, s43, s1
	v_mfma_f32_16x16x32_bf16 v[104:107], v[154:157], v[220:223], v[104:107]
	v_lshl_add_u64 v[198:199], s[42:43], 0, v[132:133]
	v_mfma_f32_16x16x32_bf16 v[100:103], v[146:149], v[228:231], v[100:103]
	v_lshl_add_u64 v[202:203], s[42:43], 0, v[128:129]
	v_mfma_f32_16x16x32_bf16 v[96:99], v[154:157], v[228:231], v[96:99]
	v_lshl_add_u64 v[236:237], s[16:17], 0, v[134:135]
	v_mfma_f32_16x16x32_bf16 v[120:123], v[150:153], v[206:209], v[120:123]
	v_lshl_add_u64 v[238:239], s[16:17], 0, v[130:131]
	v_mfma_f32_16x16x32_bf16 v[124:127], v[158:161], v[206:209], v[124:127]
	v_mfma_f32_16x16x32_bf16 v[116:119], v[150:153], v[214:217], v[116:119]
	v_mfma_f32_16x16x32_bf16 v[112:115], v[158:161], v[214:217], v[112:115]
	v_mfma_f32_16x16x32_bf16 v[108:111], v[150:153], v[224:227], v[108:111]
	v_mfma_f32_16x16x32_bf16 v[104:107], v[158:161], v[224:227], v[104:107]
	v_mfma_f32_16x16x32_bf16 v[100:103], v[150:153], v[232:235], v[100:103]
	v_mfma_f32_16x16x32_bf16 v[96:99], v[158:161], v[232:235], v[96:99]
	v_mfma_f32_16x16x32_bf16 v[60:63], v[162:165], v[194:197], v[60:63]
	v_mfma_f32_16x16x32_bf16 v[56:59], v[170:173], v[194:197], v[56:59]
	v_mfma_f32_16x16x32_bf16 v[52:55], v[162:165], v[210:213], v[52:55]
	v_mfma_f32_16x16x32_bf16 v[48:51], v[170:173], v[210:213], v[48:51]
	v_mfma_f32_16x16x32_bf16 v[44:47], v[162:165], v[220:223], v[44:47]
	v_mfma_f32_16x16x32_bf16 v[40:43], v[170:173], v[220:223], v[40:43]
	v_mfma_f32_16x16x32_bf16 v[36:39], v[162:165], v[228:231], v[36:39]
	v_mfma_f32_16x16x32_bf16 v[32:35], v[170:173], v[228:231], v[32:35]
	v_mfma_f32_16x16x32_bf16 v[60:63], v[166:169], v[206:209], v[60:63]
	v_mfma_f32_16x16x32_bf16 v[56:59], v[174:177], v[206:209], v[56:59]
	v_mfma_f32_16x16x32_bf16 v[52:55], v[166:169], v[214:217], v[52:55]
	v_mfma_f32_16x16x32_bf16 v[48:51], v[174:177], v[214:217], v[48:51]
	v_mfma_f32_16x16x32_bf16 v[44:47], v[166:169], v[224:227], v[44:47]
	v_mfma_f32_16x16x32_bf16 v[40:43], v[174:177], v[224:227], v[40:43]
	v_mfma_f32_16x16x32_bf16 v[36:39], v[166:169], v[232:235], v[36:39]
	v_mfma_f32_16x16x32_bf16 v[32:35], v[174:177], v[232:235], v[32:35]
	s_barrier
	s_add_i32 s59, s59, s34
	s_mov_b32 m0, s59
	ds_read_b128 v[194:197], v145 offset:16384
	ds_read_b128 v[206:209], v145 offset:17408
	ds_read_b128 v[210:213], v145 offset:18432
	ds_read_b128 v[214:217], v145 offset:19456
	ds_read_b128 v[220:223], v145 offset:20480
	ds_read_b128 v[224:227], v145 offset:21504
	ds_read_b128 v[228:231], v145 offset:22528
	ds_read_b128 v[232:235], v145 offset:23552
	global_load_lds_dwordx4 v[140:141], off
	s_add_i32 m0, s59, 0x2000
	s_add_i32 s29, s29, s34
	global_load_lds_dwordx4 v[178:179], off
	s_mov_b32 m0, s29
	s_nop 0
	global_load_lds_dwordx4 v[198:199], off
	s_add_i32 m0, s29, 0x2000
	s_nop 0
	global_load_lds_dwordx4 v[202:203], off
	s_mov_b32 m0, s35
	s_nop 0
	global_load_lds_dwordx4 v[236:237], off
	s_mov_b32 m0, s36
	s_nop 0
	global_load_lds_dwordx4 v[238:239], off
	s_waitcnt vmcnt(8)
	s_waitcnt lgkmcnt(0)
	s_barrier
	s_waitcnt lgkmcnt(0)
	v_mfma_f32_16x16x32_bf16 v[92:95], v[146:149], v[194:197], v[92:95]
	v_mfma_f32_16x16x32_bf16 v[88:91], v[154:157], v[194:197], v[88:91]
	v_mfma_f32_16x16x32_bf16 v[84:87], v[146:149], v[210:213], v[84:87]
	v_mfma_f32_16x16x32_bf16 v[80:83], v[154:157], v[210:213], v[80:83]
	v_mfma_f32_16x16x32_bf16 v[76:79], v[146:149], v[220:223], v[76:79]
	v_mfma_f32_16x16x32_bf16 v[72:75], v[154:157], v[220:223], v[72:75]
	v_mfma_f32_16x16x32_bf16 v[68:71], v[146:149], v[228:231], v[68:71]
	v_mfma_f32_16x16x32_bf16 v[64:67], v[154:157], v[228:231], v[64:67]
	v_mfma_f32_16x16x32_bf16 v[92:95], v[150:153], v[206:209], v[92:95]
	v_mfma_f32_16x16x32_bf16 v[88:91], v[158:161], v[206:209], v[88:91]
	v_mfma_f32_16x16x32_bf16 v[84:87], v[150:153], v[214:217], v[84:87]
	v_mfma_f32_16x16x32_bf16 v[80:83], v[158:161], v[214:217], v[80:83]
	v_mfma_f32_16x16x32_bf16 v[76:79], v[150:153], v[224:227], v[76:79]
	v_mfma_f32_16x16x32_bf16 v[72:75], v[158:161], v[224:227], v[72:75]
	v_mfma_f32_16x16x32_bf16 v[68:71], v[150:153], v[232:235], v[68:71]
	v_mfma_f32_16x16x32_bf16 v[64:67], v[158:161], v[232:235], v[64:67]
	v_mfma_f32_16x16x32_bf16 v[28:31], v[162:165], v[194:197], v[28:31]
	v_mfma_f32_16x16x32_bf16 v[24:27], v[170:173], v[194:197], v[24:27]
	v_mfma_f32_16x16x32_bf16 v[20:23], v[162:165], v[210:213], v[20:23]
	v_mfma_f32_16x16x32_bf16 v[16:19], v[170:173], v[210:213], v[16:19]
	v_mfma_f32_16x16x32_bf16 v[12:15], v[162:165], v[220:223], v[12:15]
	v_mfma_f32_16x16x32_bf16 v[8:11], v[170:173], v[220:223], v[8:11]
	v_mfma_f32_16x16x32_bf16 v[4:7], v[162:165], v[228:231], v[4:7]
	v_mfma_f32_16x16x32_bf16 v[0:3], v[170:173], v[228:231], v[0:3]
	v_mfma_f32_16x16x32_bf16 v[28:31], v[166:169], v[206:209], v[28:31]
	v_mfma_f32_16x16x32_bf16 v[24:27], v[174:177], v[206:209], v[24:27]
	v_mfma_f32_16x16x32_bf16 v[20:23], v[166:169], v[214:217], v[20:23]
	v_mfma_f32_16x16x32_bf16 v[16:19], v[174:177], v[214:217], v[16:19]
	v_mfma_f32_16x16x32_bf16 v[12:15], v[166:169], v[224:227], v[12:15]
	v_mfma_f32_16x16x32_bf16 v[8:11], v[174:177], v[224:227], v[8:11]
	v_mfma_f32_16x16x32_bf16 v[4:7], v[166:169], v[232:235], v[4:7]
	v_mfma_f32_16x16x32_bf16 v[0:3], v[174:177], v[232:235], v[0:3]
	s_barrier
	s_add_i32 s29, 0, 0x18000
	s_add_i32 s42, 0, 0x1c000
	v_add_u32_e32 v158, s29, v143
	v_add_u32_e32 v174, s42, v143
	ds_read_b128 v[146:149], v158
	ds_read_b128 v[150:153], v158 offset:1024
	ds_read_b128 v[154:157], v158 offset:2048
	ds_read_b128 v[158:161], v158 offset:3072
	ds_read_b128 v[162:165], v174
	ds_read_b128 v[166:169], v174 offset:1024
	ds_read_b128 v[170:173], v174 offset:2048
	ds_read_b128 v[174:177], v174 offset:3072
	s_add_u32 s16, s16, s0
	s_addc_u32 s17, s17, s1
	s_mov_b32 m0, s37
	v_lshl_add_u64 v[240:241], s[16:17], 0, v[134:135]
	ds_read_b128 v[194:197], v145 offset:32768
	ds_read_b128 v[206:209], v145 offset:33792
	ds_read_b128 v[210:213], v145 offset:34816
	ds_read_b128 v[214:217], v145 offset:35840
	ds_read_b128 v[220:223], v145 offset:36864
	ds_read_b128 v[224:227], v145 offset:37888
	ds_read_b128 v[228:231], v145 offset:38912
	ds_read_b128 v[232:235], v145 offset:39936
	global_load_lds_dwordx4 v[240:241], off
	v_lshl_add_u64 v[240:241], s[16:17], 0, v[130:131]
	s_mov_b32 m0, s38
	s_nop 0
	global_load_lds_dwordx4 v[240:241], off
	s_waitcnt vmcnt(8)
	s_waitcnt lgkmcnt(0)
	s_barrier
	s_waitcnt lgkmcnt(0)
	v_mfma_f32_16x16x32_bf16 v[120:123], v[146:149], v[194:197], v[120:123]
	v_mfma_f32_16x16x32_bf16 v[124:127], v[154:157], v[194:197], v[124:127]
	v_lshl_add_u64 v[140:141], v[140:141], 0, s[12:13]
	v_mfma_f32_16x16x32_bf16 v[116:119], v[146:149], v[210:213], v[116:119]
	v_lshl_add_u64 v[178:179], v[178:179], 0, s[12:13]
	v_mfma_f32_16x16x32_bf16 v[112:115], v[154:157], v[210:213], v[112:115]
	v_lshl_add_u64 v[198:199], v[198:199], 0, s[12:13]
	v_mfma_f32_16x16x32_bf16 v[108:111], v[146:149], v[220:223], v[108:111]
	v_lshl_add_u64 v[202:203], v[202:203], 0, s[12:13]
	v_mfma_f32_16x16x32_bf16 v[104:107], v[154:157], v[220:223], v[104:107]
	v_lshl_add_u64 v[236:237], v[236:237], 0, s[12:13]
	v_mfma_f32_16x16x32_bf16 v[100:103], v[146:149], v[228:231], v[100:103]
	v_lshl_add_u64 v[238:239], v[238:239], 0, s[12:13]
	v_mfma_f32_16x16x32_bf16 v[96:99], v[154:157], v[228:231], v[96:99]
	v_mfma_f32_16x16x32_bf16 v[120:123], v[150:153], v[206:209], v[120:123]
	v_mfma_f32_16x16x32_bf16 v[124:127], v[158:161], v[206:209], v[124:127]
	v_mfma_f32_16x16x32_bf16 v[116:119], v[150:153], v[214:217], v[116:119]
	v_mfma_f32_16x16x32_bf16 v[112:115], v[158:161], v[214:217], v[112:115]
	v_mfma_f32_16x16x32_bf16 v[108:111], v[150:153], v[224:227], v[108:111]
	v_mfma_f32_16x16x32_bf16 v[104:107], v[158:161], v[224:227], v[104:107]
	v_mfma_f32_16x16x32_bf16 v[100:103], v[150:153], v[232:235], v[100:103]
	v_mfma_f32_16x16x32_bf16 v[96:99], v[158:161], v[232:235], v[96:99]
	v_mfma_f32_16x16x32_bf16 v[60:63], v[162:165], v[194:197], v[60:63]
	v_mfma_f32_16x16x32_bf16 v[56:59], v[170:173], v[194:197], v[56:59]
	v_mfma_f32_16x16x32_bf16 v[52:55], v[162:165], v[210:213], v[52:55]
	v_mfma_f32_16x16x32_bf16 v[48:51], v[170:173], v[210:213], v[48:51]
	v_mfma_f32_16x16x32_bf16 v[44:47], v[162:165], v[220:223], v[44:47]
	v_mfma_f32_16x16x32_bf16 v[40:43], v[170:173], v[220:223], v[40:43]
	v_mfma_f32_16x16x32_bf16 v[36:39], v[162:165], v[228:231], v[36:39]
	v_mfma_f32_16x16x32_bf16 v[32:35], v[170:173], v[228:231], v[32:35]
	v_mfma_f32_16x16x32_bf16 v[60:63], v[166:169], v[206:209], v[60:63]
	v_mfma_f32_16x16x32_bf16 v[56:59], v[174:177], v[206:209], v[56:59]
	v_mfma_f32_16x16x32_bf16 v[52:55], v[166:169], v[214:217], v[52:55]
	v_mfma_f32_16x16x32_bf16 v[48:51], v[174:177], v[214:217], v[48:51]
	v_mfma_f32_16x16x32_bf16 v[44:47], v[166:169], v[224:227], v[44:47]
	v_mfma_f32_16x16x32_bf16 v[40:43], v[174:177], v[224:227], v[40:43]
	v_mfma_f32_16x16x32_bf16 v[36:39], v[166:169], v[232:235], v[36:39]
	v_mfma_f32_16x16x32_bf16 v[32:35], v[174:177], v[232:235], v[32:35]
	s_barrier
	s_add_i32 s16, s29, s34
	s_mov_b32 m0, s16
	ds_read_b128 v[194:197], v145 offset:49152
	ds_read_b128 v[206:209], v145 offset:50176
	ds_read_b128 v[210:213], v145 offset:51200
	ds_read_b128 v[214:217], v145 offset:52224
	ds_read_b128 v[220:223], v145 offset:53248
	ds_read_b128 v[224:227], v145 offset:54272
	ds_read_b128 v[228:231], v145 offset:55296
	ds_read_b128 v[232:235], v145 offset:56320
	global_load_lds_dwordx4 v[140:141], off
	s_add_i32 m0, s16, 0x2000
	s_add_i32 s16, s42, s34
	global_load_lds_dwordx4 v[178:179], off
	s_mov_b32 m0, s16
	s_nop 0
	global_load_lds_dwordx4 v[198:199], off
	s_add_i32 m0, s16, 0x2000
	s_nop 0
	global_load_lds_dwordx4 v[202:203], off
	s_mov_b32 m0, s46
	s_nop 0
	global_load_lds_dwordx4 v[236:237], off
	s_mov_b32 m0, s47
	s_nop 0
	global_load_lds_dwordx4 v[238:239], off
	s_waitcnt vmcnt(8)
	s_waitcnt lgkmcnt(0)
	s_barrier
	s_waitcnt lgkmcnt(0)
	v_mfma_f32_16x16x32_bf16 v[92:95], v[146:149], v[194:197], v[92:95]
	s_add_u32 s26, s26, 0x100
	v_mfma_f32_16x16x32_bf16 v[88:91], v[154:157], v[194:197], v[88:91]
	s_addc_u32 s27, s27, 0
	v_mfma_f32_16x16x32_bf16 v[84:87], v[146:149], v[210:213], v[84:87]
	s_add_u32 s10, s10, 0x100
	v_mfma_f32_16x16x32_bf16 v[80:83], v[154:157], v[210:213], v[80:83]
	s_addc_u32 s11, s11, 0
	v_mfma_f32_16x16x32_bf16 v[76:79], v[146:149], v[220:223], v[76:79]
	s_mov_b32 s16, s28
	v_mfma_f32_16x16x32_bf16 v[72:75], v[154:157], v[220:223], v[72:75]
	s_cmp_ge_i32 s28, s45
	v_mfma_f32_16x16x32_bf16 v[68:71], v[146:149], v[228:231], v[68:71]
	s_cselect_b32 s99, 1, 0
	v_mfma_f32_16x16x32_bf16 v[64:67], v[154:157], v[228:231], v[64:67]
	s_add_i32 s28, s16, 2
	v_mfma_f32_16x16x32_bf16 v[92:95], v[150:153], v[206:209], v[92:95]
	s_add_u32 s29, s26, 0x80
	v_mfma_f32_16x16x32_bf16 v[88:91], v[158:161], v[206:209], v[88:91]
	s_addc_u32 s17, s27, 0
	v_mfma_f32_16x16x32_bf16 v[84:87], v[150:153], v[214:217], v[84:87]
	s_add_i32 s59, 0, 0x10000
	v_mfma_f32_16x16x32_bf16 v[80:83], v[158:161], v[214:217], v[80:83]
	s_cmp_eq_u32 s48, s16
	v_mfma_f32_16x16x32_bf16 v[76:79], v[150:153], v[224:227], v[76:79]
	s_cselect_b32 s17, s23, s17
	v_mfma_f32_16x16x32_bf16 v[72:75], v[158:161], v[224:227], v[72:75]
	s_cselect_b32 s16, s22, s29
	v_mfma_f32_16x16x32_bf16 v[68:71], v[150:153], v[232:235], v[68:71]
	s_cselect_b32 s43, s25, s11
	v_mfma_f32_16x16x32_bf16 v[64:67], v[158:161], v[232:235], v[64:67]
	s_cselect_b32 s42, s24, s10
	v_mfma_f32_16x16x32_bf16 v[28:31], v[162:165], v[194:197], v[28:31]
	s_add_i32 s29, 0, 0x14000
	v_mfma_f32_16x16x32_bf16 v[24:27], v[170:173], v[194:197], v[24:27]
	v_mfma_f32_16x16x32_bf16 v[20:23], v[162:165], v[210:213], v[20:23]
	v_mfma_f32_16x16x32_bf16 v[16:19], v[170:173], v[210:213], v[16:19]
	v_mfma_f32_16x16x32_bf16 v[12:15], v[162:165], v[220:223], v[12:15]
	v_mfma_f32_16x16x32_bf16 v[8:11], v[170:173], v[220:223], v[8:11]
	v_mfma_f32_16x16x32_bf16 v[4:7], v[162:165], v[228:231], v[4:7]
	v_mfma_f32_16x16x32_bf16 v[0:3], v[170:173], v[228:231], v[0:3]
	v_mfma_f32_16x16x32_bf16 v[28:31], v[166:169], v[206:209], v[28:31]
	v_mfma_f32_16x16x32_bf16 v[24:27], v[174:177], v[206:209], v[24:27]
	v_mfma_f32_16x16x32_bf16 v[20:23], v[166:169], v[214:217], v[20:23]
	v_mfma_f32_16x16x32_bf16 v[16:19], v[174:177], v[214:217], v[16:19]
	v_mfma_f32_16x16x32_bf16 v[12:15], v[166:169], v[224:227], v[12:15]
	v_mfma_f32_16x16x32_bf16 v[8:11], v[174:177], v[224:227], v[8:11]
	v_mfma_f32_16x16x32_bf16 v[4:7], v[166:169], v[232:235], v[4:7]
	v_mfma_f32_16x16x32_bf16 v[0:3], v[174:177], v[232:235], v[0:3]
	s_barrier
	s_cmp_lg_u32 s99, 0
	s_cbranch_scc0 .LBB0_823

.Llbb_8:
	s_add_i32 s30, s16, 2
	s_add_u32 s31, s0, 0x80
	s_addc_u32 s17, s1, 0
	s_add_i32 s35, 0, 0x10000
	s_cmp_eq_u32 s57, s16
	s_cselect_b32 s17, s27, s17
	s_cselect_b32 s16, s26, s31
	s_cselect_b32 s43, s29, s11
	s_cselect_b32 s42, s28, s10
	s_add_i32 s31, 0, 0x14000
	v_add_u32_e32 v156, s35, v164
	v_add_u32_e32 v167, s31, v164
	ds_read_b128 v[144:147], v156
	ds_read_b128 v[148:151], v156 offset:1024
	ds_read_b128 v[152:155], v156 offset:2048
	ds_read_b128 v[156:159], v156 offset:3072
	ds_read_b128 v[160:163], v167
	ds_read_b128 v[168:171], v167 offset:1024
	ds_read_b128 v[172:175], v167 offset:2048
	ds_read_b128 v[176:179], v167 offset:3072
	v_lshl_add_u64 v[198:199], s[0:1], 0, v[140:141]
	s_add_i32 m0, s39, 0xc000
	ds_read_b128 v[194:197], v166
	ds_read_b128 v[206:209], v166 offset:1024
	ds_read_b128 v[210:213], v166 offset:2048
	ds_read_b128 v[214:217], v166 offset:3072
	ds_read_b128 v[220:223], v166 offset:4096
	ds_read_b128 v[224:227], v166 offset:5120
	ds_read_b128 v[228:231], v166 offset:6144
	ds_read_b128 v[232:235], v166 offset:7168
	global_load_lds_dwordx4 v[198:199], off
	v_lshl_add_u64 v[198:199], s[0:1], 0, v[142:143]
	s_add_i32 m0, s39, 0xe000
	s_nop 0
	global_load_lds_dwordx4 v[198:199], off
	s_waitcnt vmcnt(8)
	s_waitcnt lgkmcnt(0)
	s_barrier
	s_waitcnt lgkmcnt(0)
	v_mfma_f32_16x16x32_bf16 v[124:127], v[144:147], v[194:197], 0
	v_mfma_f32_16x16x32_bf16 v[120:123], v[152:155], v[194:197], 0
	v_lshl_add_u64 v[198:199], s[42:43], 0, v[132:133]
	v_mfma_f32_16x16x32_bf16 v[108:111], v[144:147], v[210:213], 0
	v_lshl_add_u64 v[202:203], s[42:43], 0, v[128:129]
	v_mfma_f32_16x16x32_bf16 v[104:107], v[152:155], v[210:213], 0
	s_add_u32 s42, s42, s6
	v_mfma_f32_16x16x32_bf16 v[92:95], v[144:147], v[220:223], 0
	s_addc_u32 s43, s43, s7
	v_mfma_f32_16x16x32_bf16 v[88:91], v[152:155], v[220:223], 0
	v_lshl_add_u64 v[236:237], s[42:43], 0, v[132:133]
	v_mfma_f32_16x16x32_bf16 v[76:79], v[144:147], v[228:231], 0
	v_lshl_add_u64 v[238:239], s[42:43], 0, v[128:129]
	v_mfma_f32_16x16x32_bf16 v[72:75], v[152:155], v[228:231], 0
	v_lshl_add_u64 v[240:241], s[16:17], 0, v[134:135]
	v_mfma_f32_16x16x32_bf16 v[124:127], v[148:151], v[206:209], v[124:127]
	v_lshl_add_u64 v[242:243], s[16:17], 0, v[130:131]
	v_mfma_f32_16x16x32_bf16 v[120:123], v[156:159], v[206:209], v[120:123]
	v_mfma_f32_16x16x32_bf16 v[108:111], v[148:151], v[214:217], v[108:111]
	v_mfma_f32_16x16x32_bf16 v[104:107], v[156:159], v[214:217], v[104:107]
	v_mfma_f32_16x16x32_bf16 v[92:95], v[148:151], v[224:227], v[92:95]
	v_mfma_f32_16x16x32_bf16 v[88:91], v[156:159], v[224:227], v[88:91]
	v_mfma_f32_16x16x32_bf16 v[76:79], v[148:151], v[232:235], v[76:79]
	v_mfma_f32_16x16x32_bf16 v[72:75], v[156:159], v[232:235], v[72:75]
	v_mfma_f32_16x16x32_bf16 v[116:119], v[160:163], v[194:197], 0
	v_mfma_f32_16x16x32_bf16 v[112:115], v[172:175], v[194:197], 0
	v_mfma_f32_16x16x32_bf16 v[100:103], v[160:163], v[210:213], 0
	v_mfma_f32_16x16x32_bf16 v[96:99], v[172:175], v[210:213], 0
	v_mfma_f32_16x16x32_bf16 v[84:87], v[160:163], v[220:223], 0
	v_mfma_f32_16x16x32_bf16 v[80:83], v[172:175], v[220:223], 0
	v_mfma_f32_16x16x32_bf16 v[68:71], v[160:163], v[228:231], 0
	v_mfma_f32_16x16x32_bf16 v[64:67], v[172:175], v[228:231], 0
	v_mfma_f32_16x16x32_bf16 v[116:119], v[168:171], v[206:209], v[116:119]
	v_mfma_f32_16x16x32_bf16 v[112:115], v[176:179], v[206:209], v[112:115]
	v_mfma_f32_16x16x32_bf16 v[100:103], v[168:171], v[214:217], v[100:103]
	v_mfma_f32_16x16x32_bf16 v[96:99], v[176:179], v[214:217], v[96:99]
	v_mfma_f32_16x16x32_bf16 v[84:87], v[168:171], v[224:227], v[84:87]
	v_mfma_f32_16x16x32_bf16 v[80:83], v[176:179], v[224:227], v[80:83]
	v_mfma_f32_16x16x32_bf16 v[68:71], v[168:171], v[232:235], v[68:71]
	v_mfma_f32_16x16x32_bf16 v[64:67], v[176:179], v[232:235], v[64:67]
	s_barrier
	s_add_i32 s35, s35, s38
	s_mov_b32 m0, s35
	ds_read_b128 v[194:197], v166 offset:16384
	ds_read_b128 v[206:209], v166 offset:17408
	ds_read_b128 v[210:213], v166 offset:18432
	ds_read_b128 v[214:217], v166 offset:19456
	ds_read_b128 v[220:223], v166 offset:20480
	ds_read_b128 v[224:227], v166 offset:21504
	ds_read_b128 v[228:231], v166 offset:22528
	ds_read_b128 v[232:235], v166 offset:23552
	global_load_lds_dwordx4 v[198:199], off
	s_add_i32 m0, s35, 0x2000
	s_add_i32 s31, s31, s38
	global_load_lds_dwordx4 v[202:203], off
	s_mov_b32 m0, s31
	s_nop 0
	global_load_lds_dwordx4 v[236:237], off
	s_add_i32 m0, s31, 0x2000
	s_nop 0
	global_load_lds_dwordx4 v[238:239], off
	s_mov_b32 m0, s39
	s_nop 0
	global_load_lds_dwordx4 v[240:241], off
	s_mov_b32 m0, s44
	s_nop 0
	global_load_lds_dwordx4 v[242:243], off
	s_waitcnt vmcnt(8)
	s_waitcnt lgkmcnt(0)
	s_barrier
	s_waitcnt lgkmcnt(0)
	v_mfma_f32_16x16x32_bf16 v[60:63], v[144:147], v[194:197], 0
	v_mfma_f32_16x16x32_bf16 v[56:59], v[152:155], v[194:197], 0
	v_mfma_f32_16x16x32_bf16 v[44:47], v[144:147], v[210:213], 0
	v_mfma_f32_16x16x32_bf16 v[40:43], v[152:155], v[210:213], 0
	v_mfma_f32_16x16x32_bf16 v[28:31], v[144:147], v[220:223], 0
	v_mfma_f32_16x16x32_bf16 v[24:27], v[152:155], v[220:223], 0
	v_mfma_f32_16x16x32_bf16 v[12:15], v[144:147], v[228:231], 0
	v_mfma_f32_16x16x32_bf16 v[8:11], v[152:155], v[228:231], 0
	v_mfma_f32_16x16x32_bf16 v[60:63], v[148:151], v[206:209], v[60:63]
	v_mfma_f32_16x16x32_bf16 v[56:59], v[156:159], v[206:209], v[56:59]
	v_mfma_f32_16x16x32_bf16 v[44:47], v[148:151], v[214:217], v[44:47]
	v_mfma_f32_16x16x32_bf16 v[40:43], v[156:159], v[214:217], v[40:43]
	v_mfma_f32_16x16x32_bf16 v[28:31], v[148:151], v[224:227], v[28:31]
	v_mfma_f32_16x16x32_bf16 v[24:27], v[156:159], v[224:227], v[24:27]
	v_mfma_f32_16x16x32_bf16 v[12:15], v[148:151], v[232:235], v[12:15]
	v_mfma_f32_16x16x32_bf16 v[8:11], v[156:159], v[232:235], v[8:11]
	v_mfma_f32_16x16x32_bf16 v[52:55], v[160:163], v[194:197], 0
	v_mfma_f32_16x16x32_bf16 v[48:51], v[172:175], v[194:197], 0
	v_mfma_f32_16x16x32_bf16 v[36:39], v[160:163], v[210:213], 0
	v_mfma_f32_16x16x32_bf16 v[32:35], v[172:175], v[210:213], 0
	v_mfma_f32_16x16x32_bf16 v[20:23], v[160:163], v[220:223], 0
	v_mfma_f32_16x16x32_bf16 v[16:19], v[172:175], v[220:223], 0
	v_mfma_f32_16x16x32_bf16 v[4:7], v[160:163], v[228:231], 0
	v_mfma_f32_16x16x32_bf16 v[0:3], v[172:175], v[228:231], 0
	v_mfma_f32_16x16x32_bf16 v[52:55], v[168:171], v[206:209], v[52:55]
	v_mfma_f32_16x16x32_bf16 v[48:51], v[176:179], v[206:209], v[48:51]
	v_mfma_f32_16x16x32_bf16 v[36:39], v[168:171], v[214:217], v[36:39]
	v_mfma_f32_16x16x32_bf16 v[32:35], v[176:179], v[214:217], v[32:35]
	v_mfma_f32_16x16x32_bf16 v[20:23], v[168:171], v[224:227], v[20:23]
	v_mfma_f32_16x16x32_bf16 v[16:19], v[176:179], v[224:227], v[16:19]
	v_mfma_f32_16x16x32_bf16 v[4:7], v[168:171], v[232:235], v[4:7]
	v_mfma_f32_16x16x32_bf16 v[0:3], v[176:179], v[232:235], v[0:3]
	s_barrier
	s_add_i32 s31, 0, 0x18000
	s_add_i32 s35, 0, 0x1c000
	v_add_u32_e32 v156, s31, v164
	v_add_u32_e32 v167, s35, v164
	ds_read_b128 v[144:147], v156
	ds_read_b128 v[148:151], v156 offset:1024
	ds_read_b128 v[152:155], v156 offset:2048
	ds_read_b128 v[156:159], v156 offset:3072
	ds_read_b128 v[160:163], v167
	ds_read_b128 v[168:171], v167 offset:1024
	ds_read_b128 v[172:175], v167 offset:2048
	ds_read_b128 v[176:179], v167 offset:3072
	s_add_u32 s16, s16, s6
	s_addc_u32 s17, s17, s7
	s_mov_b32 m0, s45
	v_lshl_add_u64 v[244:245], s[16:17], 0, v[134:135]
	ds_read_b128 v[194:197], v166 offset:32768
	ds_read_b128 v[206:209], v166 offset:33792
	ds_read_b128 v[210:213], v166 offset:34816
	ds_read_b128 v[214:217], v166 offset:35840
	ds_read_b128 v[220:223], v166 offset:36864
	ds_read_b128 v[224:227], v166 offset:37888
	ds_read_b128 v[228:231], v166 offset:38912
	ds_read_b128 v[232:235], v166 offset:39936
	global_load_lds_dwordx4 v[244:245], off
	v_lshl_add_u64 v[244:245], s[16:17], 0, v[130:131]
	s_mov_b32 m0, s46
	s_nop 0
	global_load_lds_dwordx4 v[244:245], off
	s_waitcnt vmcnt(8)
	s_waitcnt lgkmcnt(0)
	s_barrier
	s_waitcnt lgkmcnt(0)
	v_mfma_f32_16x16x32_bf16 v[124:127], v[144:147], v[194:197], v[124:127]
	v_mfma_f32_16x16x32_bf16 v[120:123], v[152:155], v[194:197], v[120:123]
	v_lshl_add_u64 v[198:199], v[198:199], 0, s[12:13]
	v_mfma_f32_16x16x32_bf16 v[108:111], v[144:147], v[210:213], v[108:111]
	v_lshl_add_u64 v[202:203], v[202:203], 0, s[12:13]
	v_mfma_f32_16x16x32_bf16 v[104:107], v[152:155], v[210:213], v[104:107]
	v_lshl_add_u64 v[236:237], v[236:237], 0, s[12:13]
	v_mfma_f32_16x16x32_bf16 v[92:95], v[144:147], v[220:223], v[92:95]
	v_lshl_add_u64 v[238:239], v[238:239], 0, s[12:13]
	v_mfma_f32_16x16x32_bf16 v[88:91], v[152:155], v[220:223], v[88:91]
	v_lshl_add_u64 v[240:241], v[240:241], 0, s[12:13]
	v_mfma_f32_16x16x32_bf16 v[76:79], v[144:147], v[228:231], v[76:79]
	v_lshl_add_u64 v[242:243], v[242:243], 0, s[12:13]
	v_mfma_f32_16x16x32_bf16 v[72:75], v[152:155], v[228:231], v[72:75]
	v_mfma_f32_16x16x32_bf16 v[124:127], v[148:151], v[206:209], v[124:127]
	v_mfma_f32_16x16x32_bf16 v[120:123], v[156:159], v[206:209], v[120:123]
	v_mfma_f32_16x16x32_bf16 v[108:111], v[148:151], v[214:217], v[108:111]
	v_mfma_f32_16x16x32_bf16 v[104:107], v[156:159], v[214:217], v[104:107]
	v_mfma_f32_16x16x32_bf16 v[92:95], v[148:151], v[224:227], v[92:95]
	v_mfma_f32_16x16x32_bf16 v[88:91], v[156:159], v[224:227], v[88:91]
	v_mfma_f32_16x16x32_bf16 v[76:79], v[148:151], v[232:235], v[76:79]
	v_mfma_f32_16x16x32_bf16 v[72:75], v[156:159], v[232:235], v[72:75]
	v_mfma_f32_16x16x32_bf16 v[116:119], v[160:163], v[194:197], v[116:119]
	v_mfma_f32_16x16x32_bf16 v[112:115], v[172:175], v[194:197], v[112:115]
	v_mfma_f32_16x16x32_bf16 v[100:103], v[160:163], v[210:213], v[100:103]
	v_mfma_f32_16x16x32_bf16 v[96:99], v[172:175], v[210:213], v[96:99]
	v_mfma_f32_16x16x32_bf16 v[84:87], v[160:163], v[220:223], v[84:87]
	v_mfma_f32_16x16x32_bf16 v[80:83], v[172:175], v[220:223], v[80:83]
	v_mfma_f32_16x16x32_bf16 v[68:71], v[160:163], v[228:231], v[68:71]
	v_mfma_f32_16x16x32_bf16 v[64:67], v[172:175], v[228:231], v[64:67]
	v_mfma_f32_16x16x32_bf16 v[116:119], v[168:171], v[206:209], v[116:119]
	v_mfma_f32_16x16x32_bf16 v[112:115], v[176:179], v[206:209], v[112:115]
	v_mfma_f32_16x16x32_bf16 v[100:103], v[168:171], v[214:217], v[100:103]
	v_mfma_f32_16x16x32_bf16 v[96:99], v[176:179], v[214:217], v[96:99]
	v_mfma_f32_16x16x32_bf16 v[84:87], v[168:171], v[224:227], v[84:87]
	v_mfma_f32_16x16x32_bf16 v[80:83], v[176:179], v[224:227], v[80:83]
	v_mfma_f32_16x16x32_bf16 v[68:71], v[168:171], v[232:235], v[68:71]
	v_mfma_f32_16x16x32_bf16 v[64:67], v[176:179], v[232:235], v[64:67]
	s_barrier
	s_add_i32 s16, s31, s38
	s_mov_b32 m0, s16
	ds_read_b128 v[194:197], v166 offset:49152
	ds_read_b128 v[206:209], v166 offset:50176
	ds_read_b128 v[210:213], v166 offset:51200
	ds_read_b128 v[214:217], v166 offset:52224
	ds_read_b128 v[220:223], v166 offset:53248
	ds_read_b128 v[224:227], v166 offset:54272
	ds_read_b128 v[228:231], v166 offset:55296
	ds_read_b128 v[232:235], v166 offset:56320
	global_load_lds_dwordx4 v[198:199], off
	s_add_i32 m0, s16, 0x2000
	s_add_i32 s16, s35, s38
	global_load_lds_dwordx4 v[202:203], off
	s_mov_b32 m0, s16
	s_nop 0
	global_load_lds_dwordx4 v[236:237], off
	s_add_i32 m0, s16, 0x2000
	s_nop 0
	global_load_lds_dwordx4 v[238:239], off
	s_mov_b32 m0, s47
	s_nop 0
	global_load_lds_dwordx4 v[240:241], off
	s_mov_b32 m0, s48
	s_nop 0
	global_load_lds_dwordx4 v[242:243], off
	s_waitcnt vmcnt(8)
	s_waitcnt lgkmcnt(0)
	s_barrier
	s_waitcnt lgkmcnt(0)
	v_mfma_f32_16x16x32_bf16 v[60:63], v[144:147], v[194:197], v[60:63]
	s_add_u32 s0, s0, 0x100
	v_mfma_f32_16x16x32_bf16 v[56:59], v[152:155], v[194:197], v[56:59]
	s_addc_u32 s1, s1, 0
	v_mfma_f32_16x16x32_bf16 v[44:47], v[144:147], v[210:213], v[44:47]
	s_add_u32 s10, s10, 0x100
	v_mfma_f32_16x16x32_bf16 v[40:43], v[152:155], v[210:213], v[40:43]
	s_addc_u32 s11, s11, 0
	v_mfma_f32_16x16x32_bf16 v[28:31], v[144:147], v[220:223], v[28:31]
	s_mov_b32 s16, s30
	v_mfma_f32_16x16x32_bf16 v[24:27], v[152:155], v[220:223], v[24:27]
	s_cmp_ge_i32 s30, s49
	v_mfma_f32_16x16x32_bf16 v[12:15], v[144:147], v[228:231], v[12:15]
	s_cselect_b32 s99, 1, 0
	v_mfma_f32_16x16x32_bf16 v[8:11], v[152:155], v[228:231], v[8:11]
	s_add_i32 s30, s16, 2
	v_mfma_f32_16x16x32_bf16 v[60:63], v[148:151], v[206:209], v[60:63]
	s_add_u32 s31, s0, 0x80
	v_mfma_f32_16x16x32_bf16 v[56:59], v[156:159], v[206:209], v[56:59]
	s_addc_u32 s17, s1, 0
	v_mfma_f32_16x16x32_bf16 v[44:47], v[148:151], v[214:217], v[44:47]
	s_add_i32 s35, 0, 0x10000
	v_mfma_f32_16x16x32_bf16 v[40:43], v[156:159], v[214:217], v[40:43]
	s_cmp_eq_u32 s57, s16
	v_mfma_f32_16x16x32_bf16 v[28:31], v[148:151], v[224:227], v[28:31]
	s_cselect_b32 s17, s27, s17
	v_mfma_f32_16x16x32_bf16 v[24:27], v[156:159], v[224:227], v[24:27]
	s_cselect_b32 s16, s26, s31
	v_mfma_f32_16x16x32_bf16 v[12:15], v[148:151], v[232:235], v[12:15]
	s_cselect_b32 s43, s29, s11
	v_mfma_f32_16x16x32_bf16 v[8:11], v[156:159], v[232:235], v[8:11]
	s_cselect_b32 s42, s28, s10
	v_mfma_f32_16x16x32_bf16 v[52:55], v[160:163], v[194:197], v[52:55]
	s_add_i32 s31, 0, 0x14000
	v_mfma_f32_16x16x32_bf16 v[48:51], v[172:175], v[194:197], v[48:51]
	v_mfma_f32_16x16x32_bf16 v[36:39], v[160:163], v[210:213], v[36:39]
	v_mfma_f32_16x16x32_bf16 v[32:35], v[172:175], v[210:213], v[32:35]
	v_mfma_f32_16x16x32_bf16 v[20:23], v[160:163], v[220:223], v[20:23]
	v_mfma_f32_16x16x32_bf16 v[16:19], v[172:175], v[220:223], v[16:19]
	v_mfma_f32_16x16x32_bf16 v[4:7], v[160:163], v[228:231], v[4:7]
	v_mfma_f32_16x16x32_bf16 v[0:3], v[172:175], v[228:231], v[0:3]
	v_mfma_f32_16x16x32_bf16 v[52:55], v[168:171], v[206:209], v[52:55]
	v_mfma_f32_16x16x32_bf16 v[48:51], v[176:179], v[206:209], v[48:51]
	v_mfma_f32_16x16x32_bf16 v[36:39], v[168:171], v[214:217], v[36:39]
	v_mfma_f32_16x16x32_bf16 v[32:35], v[176:179], v[214:217], v[32:35]
	v_mfma_f32_16x16x32_bf16 v[20:23], v[168:171], v[224:227], v[20:23]
	v_mfma_f32_16x16x32_bf16 v[16:19], v[176:179], v[224:227], v[16:19]
	v_mfma_f32_16x16x32_bf16 v[4:7], v[168:171], v[232:235], v[4:7]
	v_mfma_f32_16x16x32_bf16 v[0:3], v[176:179], v[232:235], v[0:3]
	s_barrier
	s_cmp_lg_u32 s99, 0
	s_cbranch_scc1 .Lpeelx_12
.LBB0_844:
	v_add_u32_e32 v156, s35, v164
	v_add_u32_e32 v167, s31, v164
	ds_read_b128 v[144:147], v156
	ds_read_b128 v[148:151], v156 offset:1024
	ds_read_b128 v[152:155], v156 offset:2048
	ds_read_b128 v[156:159], v156 offset:3072
	ds_read_b128 v[160:163], v167
	ds_read_b128 v[168:171], v167 offset:1024
	ds_read_b128 v[172:175], v167 offset:2048
	ds_read_b128 v[176:179], v167 offset:3072
	v_lshl_add_u64 v[198:199], s[0:1], 0, v[140:141]
	s_add_i32 m0, s39, 0xc000
	ds_read_b128 v[194:197], v166
	ds_read_b128 v[206:209], v166 offset:1024
	ds_read_b128 v[210:213], v166 offset:2048
	ds_read_b128 v[214:217], v166 offset:3072
	ds_read_b128 v[220:223], v166 offset:4096
	ds_read_b128 v[224:227], v166 offset:5120
	ds_read_b128 v[228:231], v166 offset:6144
	ds_read_b128 v[232:235], v166 offset:7168
	global_load_lds_dwordx4 v[198:199], off
	v_lshl_add_u64 v[198:199], s[0:1], 0, v[142:143]
	s_add_i32 m0, s39, 0xe000
	s_nop 0
	global_load_lds_dwordx4 v[198:199], off
	s_waitcnt vmcnt(8)
	s_waitcnt lgkmcnt(0)
	s_barrier
	s_waitcnt lgkmcnt(0)
	v_mfma_f32_16x16x32_bf16 v[124:127], v[144:147], v[194:197], v[124:127]
	v_mfma_f32_16x16x32_bf16 v[120:123], v[152:155], v[194:197], v[120:123]
	v_lshl_add_u64 v[198:199], s[42:43], 0, v[132:133]
	v_mfma_f32_16x16x32_bf16 v[108:111], v[144:147], v[210:213], v[108:111]
	v_lshl_add_u64 v[202:203], s[42:43], 0, v[128:129]
	v_mfma_f32_16x16x32_bf16 v[104:107], v[152:155], v[210:213], v[104:107]
	s_add_u32 s42, s42, s6
	v_mfma_f32_16x16x32_bf16 v[92:95], v[144:147], v[220:223], v[92:95]
	s_addc_u32 s43, s43, s7
	v_mfma_f32_16x16x32_bf16 v[88:91], v[152:155], v[220:223], v[88:91]
	v_lshl_add_u64 v[236:237], s[42:43], 0, v[132:133]
	v_mfma_f32_16x16x32_bf16 v[76:79], v[144:147], v[228:231], v[76:79]
	v_lshl_add_u64 v[238:239], s[42:43], 0, v[128:129]
	v_mfma_f32_16x16x32_bf16 v[72:75], v[152:155], v[228:231], v[72:75]
	v_lshl_add_u64 v[240:241], s[16:17], 0, v[134:135]
	v_mfma_f32_16x16x32_bf16 v[124:127], v[148:151], v[206:209], v[124:127]
	v_lshl_add_u64 v[242:243], s[16:17], 0, v[130:131]
	v_mfma_f32_16x16x32_bf16 v[120:123], v[156:159], v[206:209], v[120:123]
	v_mfma_f32_16x16x32_bf16 v[108:111], v[148:151], v[214:217], v[108:111]
	v_mfma_f32_16x16x32_bf16 v[104:107], v[156:159], v[214:217], v[104:107]
	v_mfma_f32_16x16x32_bf16 v[92:95], v[148:151], v[224:227], v[92:95]
	v_mfma_f32_16x16x32_bf16 v[88:91], v[156:159], v[224:227], v[88:91]
	v_mfma_f32_16x16x32_bf16 v[76:79], v[148:151], v[232:235], v[76:79]
	v_mfma_f32_16x16x32_bf16 v[72:75], v[156:159], v[232:235], v[72:75]
	v_mfma_f32_16x16x32_bf16 v[116:119], v[160:163], v[194:197], v[116:119]
	v_mfma_f32_16x16x32_bf16 v[112:115], v[172:175], v[194:197], v[112:115]
	v_mfma_f32_16x16x32_bf16 v[100:103], v[160:163], v[210:213], v[100:103]
	v_mfma_f32_16x16x32_bf16 v[96:99], v[172:175], v[210:213], v[96:99]
	v_mfma_f32_16x16x32_bf16 v[84:87], v[160:163], v[220:223], v[84:87]
	v_mfma_f32_16x16x32_bf16 v[80:83], v[172:175], v[220:223], v[80:83]
	v_mfma_f32_16x16x32_bf16 v[68:71], v[160:163], v[228:231], v[68:71]
	v_mfma_f32_16x16x32_bf16 v[64:67], v[172:175], v[228:231], v[64:67]
	v_mfma_f32_16x16x32_bf16 v[116:119], v[168:171], v[206:209], v[116:119]
	v_mfma_f32_16x16x32_bf16 v[112:115], v[176:179], v[206:209], v[112:115]
	v_mfma_f32_16x16x32_bf16 v[100:103], v[168:171], v[214:217], v[100:103]
	v_mfma_f32_16x16x32_bf16 v[96:99], v[176:179], v[214:217], v[96:99]
	v_mfma_f32_16x16x32_bf16 v[84:87], v[168:171], v[224:227], v[84:87]
	v_mfma_f32_16x16x32_bf16 v[80:83], v[176:179], v[224:227], v[80:83]
	v_mfma_f32_16x16x32_bf16 v[68:71], v[168:171], v[232:235], v[68:71]
	v_mfma_f32_16x16x32_bf16 v[64:67], v[176:179], v[232:235], v[64:67]
	s_barrier
	s_add_i32 s35, s35, s38
	s_mov_b32 m0, s35
	ds_read_b128 v[194:197], v166 offset:16384
	ds_read_b128 v[206:209], v166 offset:17408
	ds_read_b128 v[210:213], v166 offset:18432
	ds_read_b128 v[214:217], v166 offset:19456
	ds_read_b128 v[220:223], v166 offset:20480
	ds_read_b128 v[224:227], v166 offset:21504
	ds_read_b128 v[228:231], v166 offset:22528
	ds_read_b128 v[232:235], v166 offset:23552
	global_load_lds_dwordx4 v[198:199], off
	s_add_i32 m0, s35, 0x2000
	s_add_i32 s31, s31, s38
	global_load_lds_dwordx4 v[202:203], off
	s_mov_b32 m0, s31
	s_nop 0
	global_load_lds_dwordx4 v[236:237], off
	s_add_i32 m0, s31, 0x2000
	s_nop 0
	global_load_lds_dwordx4 v[238:239], off
	s_mov_b32 m0, s39
	s_nop 0
	global_load_lds_dwordx4 v[240:241], off
	s_mov_b32 m0, s44
	s_nop 0
	global_load_lds_dwordx4 v[242:243], off
	s_waitcnt vmcnt(8)
	s_waitcnt lgkmcnt(0)
	s_barrier
	s_waitcnt lgkmcnt(0)
	v_mfma_f32_16x16x32_bf16 v[60:63], v[144:147], v[194:197], v[60:63]
	v_mfma_f32_16x16x32_bf16 v[56:59], v[152:155], v[194:197], v[56:59]
	v_mfma_f32_16x16x32_bf16 v[44:47], v[144:147], v[210:213], v[44:47]
	v_mfma_f32_16x16x32_bf16 v[40:43], v[152:155], v[210:213], v[40:43]
	v_mfma_f32_16x16x32_bf16 v[28:31], v[144:147], v[220:223], v[28:31]
	v_mfma_f32_16x16x32_bf16 v[24:27], v[152:155], v[220:223], v[24:27]
	v_mfma_f32_16x16x32_bf16 v[12:15], v[144:147], v[228:231], v[12:15]
	v_mfma_f32_16x16x32_bf16 v[8:11], v[152:155], v[228:231], v[8:11]
	v_mfma_f32_16x16x32_bf16 v[60:63], v[148:151], v[206:209], v[60:63]
	v_mfma_f32_16x16x32_bf16 v[56:59], v[156:159], v[206:209], v[56:59]
	v_mfma_f32_16x16x32_bf16 v[44:47], v[148:151], v[214:217], v[44:47]
	v_mfma_f32_16x16x32_bf16 v[40:43], v[156:159], v[214:217], v[40:43]
	v_mfma_f32_16x16x32_bf16 v[28:31], v[148:151], v[224:227], v[28:31]
	v_mfma_f32_16x16x32_bf16 v[24:27], v[156:159], v[224:227], v[24:27]
	v_mfma_f32_16x16x32_bf16 v[12:15], v[148:151], v[232:235], v[12:15]
	v_mfma_f32_16x16x32_bf16 v[8:11], v[156:159], v[232:235], v[8:11]
	v_mfma_f32_16x16x32_bf16 v[52:55], v[160:163], v[194:197], v[52:55]
	v_mfma_f32_16x16x32_bf16 v[48:51], v[172:175], v[194:197], v[48:51]
	v_mfma_f32_16x16x32_bf16 v[36:39], v[160:163], v[210:213], v[36:39]
	v_mfma_f32_16x16x32_bf16 v[32:35], v[172:175], v[210:213], v[32:35]
	v_mfma_f32_16x16x32_bf16 v[20:23], v[160:163], v[220:223], v[20:23]
	v_mfma_f32_16x16x32_bf16 v[16:19], v[172:175], v[220:223], v[16:19]
	v_mfma_f32_16x16x32_bf16 v[4:7], v[160:163], v[228:231], v[4:7]
	v_mfma_f32_16x16x32_bf16 v[0:3], v[172:175], v[228:231], v[0:3]
	v_mfma_f32_16x16x32_bf16 v[52:55], v[168:171], v[206:209], v[52:55]
	v_mfma_f32_16x16x32_bf16 v[48:51], v[176:179], v[206:209], v[48:51]
	v_mfma_f32_16x16x32_bf16 v[36:39], v[168:171], v[214:217], v[36:39]
	v_mfma_f32_16x16x32_bf16 v[32:35], v[176:179], v[214:217], v[32:35]
	v_mfma_f32_16x16x32_bf16 v[20:23], v[168:171], v[224:227], v[20:23]
	v_mfma_f32_16x16x32_bf16 v[16:19], v[176:179], v[224:227], v[16:19]
	v_mfma_f32_16x16x32_bf16 v[4:7], v[168:171], v[232:235], v[4:7]
	v_mfma_f32_16x16x32_bf16 v[0:3], v[176:179], v[232:235], v[0:3]
	s_barrier
	s_add_i32 s31, 0, 0x18000
	s_add_i32 s35, 0, 0x1c000
	v_add_u32_e32 v156, s31, v164
	v_add_u32_e32 v167, s35, v164
	ds_read_b128 v[144:147], v156
	ds_read_b128 v[148:151], v156 offset:1024
	ds_read_b128 v[152:155], v156 offset:2048
	ds_read_b128 v[156:159], v156 offset:3072
	ds_read_b128 v[160:163], v167
	ds_read_b128 v[168:171], v167 offset:1024
	ds_read_b128 v[172:175], v167 offset:2048
	ds_read_b128 v[176:179], v167 offset:3072
	s_add_u32 s16, s16, s6
	s_addc_u32 s17, s17, s7
	s_mov_b32 m0, s45
	v_lshl_add_u64 v[244:245], s[16:17], 0, v[134:135]
	ds_read_b128 v[194:197], v166 offset:32768
	ds_read_b128 v[206:209], v166 offset:33792
	ds_read_b128 v[210:213], v166 offset:34816
	ds_read_b128 v[214:217], v166 offset:35840
	ds_read_b128 v[220:223], v166 offset:36864
	ds_read_b128 v[224:227], v166 offset:37888
	ds_read_b128 v[228:231], v166 offset:38912
	ds_read_b128 v[232:235], v166 offset:39936
	global_load_lds_dwordx4 v[244:245], off
	v_lshl_add_u64 v[244:245], s[16:17], 0, v[130:131]
	s_mov_b32 m0, s46
	s_nop 0
	global_load_lds_dwordx4 v[244:245], off
	s_waitcnt vmcnt(8)
	s_waitcnt lgkmcnt(0)
	s_barrier
	s_waitcnt lgkmcnt(0)
	v_mfma_f32_16x16x32_bf16 v[124:127], v[144:147], v[194:197], v[124:127]
	v_mfma_f32_16x16x32_bf16 v[120:123], v[152:155], v[194:197], v[120:123]
	v_lshl_add_u64 v[198:199], v[198:199], 0, s[12:13]
	v_mfma_f32_16x16x32_bf16 v[108:111], v[144:147], v[210:213], v[108:111]
	v_lshl_add_u64 v[202:203], v[202:203], 0, s[12:13]
	v_mfma_f32_16x16x32_bf16 v[104:107], v[152:155], v[210:213], v[104:107]
	v_lshl_add_u64 v[236:237], v[236:237], 0, s[12:13]
	v_mfma_f32_16x16x32_bf16 v[92:95], v[144:147], v[220:223], v[92:95]
	v_lshl_add_u64 v[238:239], v[238:239], 0, s[12:13]
	v_mfma_f32_16x16x32_bf16 v[88:91], v[152:155], v[220:223], v[88:91]
	v_lshl_add_u64 v[240:241], v[240:241], 0, s[12:13]
	v_mfma_f32_16x16x32_bf16 v[76:79], v[144:147], v[228:231], v[76:79]
	v_lshl_add_u64 v[242:243], v[242:243], 0, s[12:13]
	v_mfma_f32_16x16x32_bf16 v[72:75], v[152:155], v[228:231], v[72:75]
	v_mfma_f32_16x16x32_bf16 v[124:127], v[148:151], v[206:209], v[124:127]
	v_mfma_f32_16x16x32_bf16 v[120:123], v[156:159], v[206:209], v[120:123]
	v_mfma_f32_16x16x32_bf16 v[108:111], v[148:151], v[214:217], v[108:111]
	v_mfma_f32_16x16x32_bf16 v[104:107], v[156:159], v[214:217], v[104:107]
	v_mfma_f32_16x16x32_bf16 v[92:95], v[148:151], v[224:227], v[92:95]
	v_mfma_f32_16x16x32_bf16 v[88:91], v[156:159], v[224:227], v[88:91]
	v_mfma_f32_16x16x32_bf16 v[76:79], v[148:151], v[232:235], v[76:79]
	v_mfma_f32_16x16x32_bf16 v[72:75], v[156:159], v[232:235], v[72:75]
	v_mfma_f32_16x16x32_bf16 v[116:119], v[160:163], v[194:197], v[116:119]
	v_mfma_f32_16x16x32_bf16 v[112:115], v[172:175], v[194:197], v[112:115]
	v_mfma_f32_16x16x32_bf16 v[100:103], v[160:163], v[210:213], v[100:103]
	v_mfma_f32_16x16x32_bf16 v[96:99], v[172:175], v[210:213], v[96:99]
	v_mfma_f32_16x16x32_bf16 v[84:87], v[160:163], v[220:223], v[84:87]
	v_mfma_f32_16x16x32_bf16 v[80:83], v[172:175], v[220:223], v[80:83]
	v_mfma_f32_16x16x32_bf16 v[68:71], v[160:163], v[228:231], v[68:71]
	v_mfma_f32_16x16x32_bf16 v[64:67], v[172:175], v[228:231], v[64:67]
	v_mfma_f32_16x16x32_bf16 v[116:119], v[168:171], v[206:209], v[116:119]
	v_mfma_f32_16x16x32_bf16 v[112:115], v[176:179], v[206:209], v[112:115]
	v_mfma_f32_16x16x32_bf16 v[100:103], v[168:171], v[214:217], v[100:103]
	v_mfma_f32_16x16x32_bf16 v[96:99], v[176:179], v[214:217], v[96:99]
	v_mfma_f32_16x16x32_bf16 v[84:87], v[168:171], v[224:227], v[84:87]
	v_mfma_f32_16x16x32_bf16 v[80:83], v[176:179], v[224:227], v[80:83]
	v_mfma_f32_16x16x32_bf16 v[68:71], v[168:171], v[232:235], v[68:71]
	v_mfma_f32_16x16x32_bf16 v[64:67], v[176:179], v[232:235], v[64:67]
	s_barrier
	s_add_i32 s16, s31, s38
	s_mov_b32 m0, s16
	ds_read_b128 v[194:197], v166 offset:49152
	ds_read_b128 v[206:209], v166 offset:50176
	ds_read_b128 v[210:213], v166 offset:51200
	ds_read_b128 v[214:217], v166 offset:52224
	ds_read_b128 v[220:223], v166 offset:53248
	ds_read_b128 v[224:227], v166 offset:54272
	ds_read_b128 v[228:231], v166 offset:55296
	ds_read_b128 v[232:235], v166 offset:56320
	global_load_lds_dwordx4 v[198:199], off
	s_add_i32 m0, s16, 0x2000
	s_add_i32 s16, s35, s38
	global_load_lds_dwordx4 v[202:203], off
	s_mov_b32 m0, s16
	s_nop 0
	global_load_lds_dwordx4 v[236:237], off
	s_add_i32 m0, s16, 0x2000
	s_nop 0
	global_load_lds_dwordx4 v[238:239], off
	s_mov_b32 m0, s47
	s_nop 0
	global_load_lds_dwordx4 v[240:241], off
	s_mov_b32 m0, s48
	s_nop 0
	global_load_lds_dwordx4 v[242:243], off
	s_waitcnt vmcnt(8)
	s_waitcnt lgkmcnt(0)
	s_barrier
	s_waitcnt lgkmcnt(0)
	v_mfma_f32_16x16x32_bf16 v[60:63], v[144:147], v[194:197], v[60:63]
	s_add_u32 s0, s0, 0x100
	v_mfma_f32_16x16x32_bf16 v[56:59], v[152:155], v[194:197], v[56:59]
	s_addc_u32 s1, s1, 0
	v_mfma_f32_16x16x32_bf16 v[44:47], v[144:147], v[210:213], v[44:47]
	s_add_u32 s10, s10, 0x100
	v_mfma_f32_16x16x32_bf16 v[40:43], v[152:155], v[210:213], v[40:43]
	s_addc_u32 s11, s11, 0
	v_mfma_f32_16x16x32_bf16 v[28:31], v[144:147], v[220:223], v[28:31]
	s_mov_b32 s16, s30
	v_mfma_f32_16x16x32_bf16 v[24:27], v[152:155], v[220:223], v[24:27]
	s_cmp_ge_i32 s30, s49
	v_mfma_f32_16x16x32_bf16 v[12:15], v[144:147], v[228:231], v[12:15]
	s_cselect_b32 s99, 1, 0
	v_mfma_f32_16x16x32_bf16 v[8:11], v[152:155], v[228:231], v[8:11]
	s_add_i32 s30, s16, 2
	v_mfma_f32_16x16x32_bf16 v[60:63], v[148:151], v[206:209], v[60:63]
	s_add_u32 s31, s0, 0x80
	v_mfma_f32_16x16x32_bf16 v[56:59], v[156:159], v[206:209], v[56:59]
	s_addc_u32 s17, s1, 0
	v_mfma_f32_16x16x32_bf16 v[44:47], v[148:151], v[214:217], v[44:47]
	s_add_i32 s35, 0, 0x10000
	v_mfma_f32_16x16x32_bf16 v[40:43], v[156:159], v[214:217], v[40:43]
	s_cmp_eq_u32 s57, s16
	v_mfma_f32_16x16x32_bf16 v[28:31], v[148:151], v[224:227], v[28:31]
	s_cselect_b32 s17, s27, s17
	v_mfma_f32_16x16x32_bf16 v[24:27], v[156:159], v[224:227], v[24:27]
	s_cselect_b32 s16, s26, s31
	v_mfma_f32_16x16x32_bf16 v[12:15], v[148:151], v[232:235], v[12:15]
	s_cselect_b32 s43, s29, s11
	v_mfma_f32_16x16x32_bf16 v[8:11], v[156:159], v[232:235], v[8:11]
	s_cselect_b32 s42, s28, s10
	v_mfma_f32_16x16x32_bf16 v[52:55], v[160:163], v[194:197], v[52:55]
	s_add_i32 s31, 0, 0x14000
	v_mfma_f32_16x16x32_bf16 v[48:51], v[172:175], v[194:197], v[48:51]
	v_mfma_f32_16x16x32_bf16 v[36:39], v[160:163], v[210:213], v[36:39]
	v_mfma_f32_16x16x32_bf16 v[32:35], v[172:175], v[210:213], v[32:35]
	v_mfma_f32_16x16x32_bf16 v[20:23], v[160:163], v[220:223], v[20:23]
	v_mfma_f32_16x16x32_bf16 v[16:19], v[172:175], v[220:223], v[16:19]
	v_mfma_f32_16x16x32_bf16 v[4:7], v[160:163], v[228:231], v[4:7]
	v_mfma_f32_16x16x32_bf16 v[0:3], v[172:175], v[228:231], v[0:3]
	v_mfma_f32_16x16x32_bf16 v[52:55], v[168:171], v[206:209], v[52:55]
	v_mfma_f32_16x16x32_bf16 v[48:51], v[176:179], v[206:209], v[48:51]
	v_mfma_f32_16x16x32_bf16 v[36:39], v[168:171], v[214:217], v[36:39]
	v_mfma_f32_16x16x32_bf16 v[32:35], v[176:179], v[214:217], v[32:35]
	v_mfma_f32_16x16x32_bf16 v[20:23], v[168:171], v[224:227], v[20:23]
	v_mfma_f32_16x16x32_bf16 v[16:19], v[176:179], v[224:227], v[16:19]
	v_mfma_f32_16x16x32_bf16 v[4:7], v[168:171], v[232:235], v[4:7]
	v_mfma_f32_16x16x32_bf16 v[0:3], v[176:179], v[232:235], v[0:3]
	s_barrier
	s_cmp_lg_u32 s99, 0
	s_cbranch_scc0 .LBB0_844

.Llbb_9:
	s_add_i32 s30, s16, 2
	s_add_u32 s31, s28, 0x80
	s_addc_u32 s17, s29, 0
	s_add_i32 s62, 0, 0x10000
	s_cmp_eq_u32 s56, s16
	s_cselect_b32 s17, s25, s17
	s_cselect_b32 s16, s24, s31
	s_cselect_b32 s45, s27, s11
	s_cselect_b32 s44, s26, s10
	s_add_i32 s31, 0, 0x14000
	v_add_u32_e32 v140, s62, v199
	v_add_u32_e32 v166, s31, v199
	ds_read_b128 v[128:131], v140
	ds_read_b128 v[132:135], v140 offset:1024
	ds_read_b128 v[136:139], v140 offset:2048
	ds_read_b128 v[140:143], v140 offset:3072
	ds_read_b128 v[144:147], v166
	ds_read_b128 v[148:151], v166 offset:1024
	ds_read_b128 v[152:155], v166 offset:2048
	ds_read_b128 v[166:169], v166 offset:3072
	v_lshl_add_u64 v[178:179], s[28:29], 0, v[162:163]
	s_add_i32 m0, s37, 0xc000
	ds_read_b128 v[170:173], v206
	ds_read_b128 v[174:177], v206 offset:1024
	ds_read_b128 v[194:197], v206 offset:2048
	ds_read_b128 v[208:211], v206 offset:3072
	ds_read_b128 v[212:215], v206 offset:4096
	ds_read_b128 v[220:223], v206 offset:5120
	ds_read_b128 v[224:227], v206 offset:6144
	ds_read_b128 v[228:231], v206 offset:7168
	global_load_lds_dwordx4 v[178:179], off
	v_lshl_add_u64 v[178:179], s[28:29], 0, v[164:165]
	s_add_i32 m0, s37, 0xe000
	s_nop 0
	global_load_lds_dwordx4 v[178:179], off
	s_waitcnt vmcnt(8)
	s_waitcnt lgkmcnt(0)
	s_barrier
	s_waitcnt lgkmcnt(0)
	v_mfma_f32_16x16x32_bf16 v[120:123], v[128:131], v[170:173], 0
	v_mfma_f32_16x16x32_bf16 v[124:127], v[136:139], v[170:173], 0
	v_lshl_add_u64 v[178:179], s[44:45], 0, v[180:181]
	v_mfma_f32_16x16x32_bf16 v[108:111], v[128:131], v[194:197], 0
	v_lshl_add_u64 v[202:203], s[44:45], 0, v[156:157]
	v_mfma_f32_16x16x32_bf16 v[104:107], v[136:139], v[194:197], 0
	s_add_u32 s44, s44, s6
	v_mfma_f32_16x16x32_bf16 v[92:95], v[128:131], v[212:215], 0
	s_addc_u32 s45, s45, s7
	v_mfma_f32_16x16x32_bf16 v[88:91], v[136:139], v[212:215], 0
	v_lshl_add_u64 v[216:217], s[44:45], 0, v[180:181]
	v_mfma_f32_16x16x32_bf16 v[76:79], v[128:131], v[224:227], 0
	v_lshl_add_u64 v[232:233], s[44:45], 0, v[156:157]
	v_mfma_f32_16x16x32_bf16 v[72:75], v[136:139], v[224:227], 0
	v_lshl_add_u64 v[234:235], s[16:17], 0, v[160:161]
	v_mfma_f32_16x16x32_bf16 v[120:123], v[132:135], v[174:177], v[120:123]
	v_lshl_add_u64 v[236:237], s[16:17], 0, v[158:159]
	v_mfma_f32_16x16x32_bf16 v[124:127], v[140:143], v[174:177], v[124:127]
	v_mfma_f32_16x16x32_bf16 v[108:111], v[132:135], v[208:211], v[108:111]
	v_mfma_f32_16x16x32_bf16 v[104:107], v[140:143], v[208:211], v[104:107]
	v_mfma_f32_16x16x32_bf16 v[92:95], v[132:135], v[220:223], v[92:95]
	v_mfma_f32_16x16x32_bf16 v[88:91], v[140:143], v[220:223], v[88:91]
	v_mfma_f32_16x16x32_bf16 v[76:79], v[132:135], v[228:231], v[76:79]
	v_mfma_f32_16x16x32_bf16 v[72:75], v[140:143], v[228:231], v[72:75]
	v_mfma_f32_16x16x32_bf16 v[116:119], v[144:147], v[170:173], 0
	v_mfma_f32_16x16x32_bf16 v[112:115], v[152:155], v[170:173], 0
	v_mfma_f32_16x16x32_bf16 v[100:103], v[144:147], v[194:197], 0
	v_mfma_f32_16x16x32_bf16 v[96:99], v[152:155], v[194:197], 0
	v_mfma_f32_16x16x32_bf16 v[84:87], v[144:147], v[212:215], 0
	v_mfma_f32_16x16x32_bf16 v[80:83], v[152:155], v[212:215], 0
	v_mfma_f32_16x16x32_bf16 v[68:71], v[144:147], v[224:227], 0
	v_mfma_f32_16x16x32_bf16 v[64:67], v[152:155], v[224:227], 0
	v_mfma_f32_16x16x32_bf16 v[116:119], v[148:151], v[174:177], v[116:119]
	v_mfma_f32_16x16x32_bf16 v[112:115], v[166:169], v[174:177], v[112:115]
	v_mfma_f32_16x16x32_bf16 v[100:103], v[148:151], v[208:211], v[100:103]
	v_mfma_f32_16x16x32_bf16 v[96:99], v[166:169], v[208:211], v[96:99]
	v_mfma_f32_16x16x32_bf16 v[84:87], v[148:151], v[220:223], v[84:87]
	v_mfma_f32_16x16x32_bf16 v[80:83], v[166:169], v[220:223], v[80:83]
	v_mfma_f32_16x16x32_bf16 v[68:71], v[148:151], v[228:231], v[68:71]
	v_mfma_f32_16x16x32_bf16 v[64:67], v[166:169], v[228:231], v[64:67]
	s_barrier
	s_add_i32 s62, s62, s36
	s_mov_b32 m0, s62
	ds_read_b128 v[170:173], v206 offset:16384
	ds_read_b128 v[174:177], v206 offset:17408
	ds_read_b128 v[194:197], v206 offset:18432
	ds_read_b128 v[208:211], v206 offset:19456
	ds_read_b128 v[212:215], v206 offset:20480
	ds_read_b128 v[220:223], v206 offset:21504
	ds_read_b128 v[224:227], v206 offset:22528
	ds_read_b128 v[228:231], v206 offset:23552
	global_load_lds_dwordx4 v[178:179], off
	s_add_i32 m0, s62, 0x2000
	s_add_i32 s31, s31, s36
	global_load_lds_dwordx4 v[202:203], off
	s_mov_b32 m0, s31
	s_nop 0
	global_load_lds_dwordx4 v[216:217], off
	s_add_i32 m0, s31, 0x2000
	s_nop 0
	global_load_lds_dwordx4 v[232:233], off
	s_mov_b32 m0, s37
	s_nop 0
	global_load_lds_dwordx4 v[234:235], off
	s_mov_b32 m0, s38
	s_nop 0
	global_load_lds_dwordx4 v[236:237], off
	s_waitcnt vmcnt(8)
	s_waitcnt lgkmcnt(0)
	s_barrier
	s_waitcnt lgkmcnt(0)
	v_mfma_f32_16x16x32_bf16 v[60:63], v[128:131], v[170:173], 0
	v_mfma_f32_16x16x32_bf16 v[56:59], v[136:139], v[170:173], 0
	v_mfma_f32_16x16x32_bf16 v[44:47], v[128:131], v[194:197], 0
	v_mfma_f32_16x16x32_bf16 v[40:43], v[136:139], v[194:197], 0
	v_mfma_f32_16x16x32_bf16 v[28:31], v[128:131], v[212:215], 0
	v_mfma_f32_16x16x32_bf16 v[24:27], v[136:139], v[212:215], 0
	v_mfma_f32_16x16x32_bf16 v[12:15], v[128:131], v[224:227], 0
	v_mfma_f32_16x16x32_bf16 v[8:11], v[136:139], v[224:227], 0
	v_mfma_f32_16x16x32_bf16 v[60:63], v[132:135], v[174:177], v[60:63]
	v_mfma_f32_16x16x32_bf16 v[56:59], v[140:143], v[174:177], v[56:59]
	v_mfma_f32_16x16x32_bf16 v[44:47], v[132:135], v[208:211], v[44:47]
	v_mfma_f32_16x16x32_bf16 v[40:43], v[140:143], v[208:211], v[40:43]
	v_mfma_f32_16x16x32_bf16 v[28:31], v[132:135], v[220:223], v[28:31]
	v_mfma_f32_16x16x32_bf16 v[24:27], v[140:143], v[220:223], v[24:27]
	v_mfma_f32_16x16x32_bf16 v[12:15], v[132:135], v[228:231], v[12:15]
	v_mfma_f32_16x16x32_bf16 v[8:11], v[140:143], v[228:231], v[8:11]
	v_mfma_f32_16x16x32_bf16 v[52:55], v[144:147], v[170:173], 0
	v_mfma_f32_16x16x32_bf16 v[48:51], v[152:155], v[170:173], 0
	v_mfma_f32_16x16x32_bf16 v[36:39], v[144:147], v[194:197], 0
	v_mfma_f32_16x16x32_bf16 v[32:35], v[152:155], v[194:197], 0
	v_mfma_f32_16x16x32_bf16 v[20:23], v[144:147], v[212:215], 0
	v_mfma_f32_16x16x32_bf16 v[16:19], v[152:155], v[212:215], 0
	v_mfma_f32_16x16x32_bf16 v[4:7], v[144:147], v[224:227], 0
	v_mfma_f32_16x16x32_bf16 v[0:3], v[152:155], v[224:227], 0
	v_mfma_f32_16x16x32_bf16 v[52:55], v[148:151], v[174:177], v[52:55]
	v_mfma_f32_16x16x32_bf16 v[48:51], v[166:169], v[174:177], v[48:51]
	v_mfma_f32_16x16x32_bf16 v[36:39], v[148:151], v[208:211], v[36:39]
	v_mfma_f32_16x16x32_bf16 v[32:35], v[166:169], v[208:211], v[32:35]
	v_mfma_f32_16x16x32_bf16 v[20:23], v[148:151], v[220:223], v[20:23]
	v_mfma_f32_16x16x32_bf16 v[16:19], v[166:169], v[220:223], v[16:19]
	v_mfma_f32_16x16x32_bf16 v[4:7], v[148:151], v[228:231], v[4:7]
	v_mfma_f32_16x16x32_bf16 v[0:3], v[166:169], v[228:231], v[0:3]
	s_barrier
	s_add_i32 s31, 0, 0x18000
	s_add_i32 s44, 0, 0x1c000
	v_add_u32_e32 v140, s31, v199
	v_add_u32_e32 v166, s44, v199
	ds_read_b128 v[128:131], v140
	ds_read_b128 v[132:135], v140 offset:1024
	ds_read_b128 v[136:139], v140 offset:2048
	ds_read_b128 v[140:143], v140 offset:3072
	ds_read_b128 v[144:147], v166
	ds_read_b128 v[148:151], v166 offset:1024
	ds_read_b128 v[152:155], v166 offset:2048
	ds_read_b128 v[166:169], v166 offset:3072
	s_add_u32 s16, s16, s6
	s_addc_u32 s17, s17, s7
	s_mov_b32 m0, s39
	v_lshl_add_u64 v[238:239], s[16:17], 0, v[160:161]
	ds_read_b128 v[170:173], v206 offset:32768
	ds_read_b128 v[174:177], v206 offset:33792
	ds_read_b128 v[194:197], v206 offset:34816
	ds_read_b128 v[208:211], v206 offset:35840
	ds_read_b128 v[212:215], v206 offset:36864
	ds_read_b128 v[220:223], v206 offset:37888
	ds_read_b128 v[224:227], v206 offset:38912
	ds_read_b128 v[228:231], v206 offset:39936
	global_load_lds_dwordx4 v[238:239], off
	v_lshl_add_u64 v[238:239], s[16:17], 0, v[158:159]
	s_mov_b32 m0, s46
	s_nop 0
	global_load_lds_dwordx4 v[238:239], off
	s_waitcnt vmcnt(8)
	s_waitcnt lgkmcnt(0)
	s_barrier
	s_waitcnt lgkmcnt(0)
	v_mfma_f32_16x16x32_bf16 v[120:123], v[128:131], v[170:173], v[120:123]
	v_mfma_f32_16x16x32_bf16 v[124:127], v[136:139], v[170:173], v[124:127]
	v_lshl_add_u64 v[178:179], v[178:179], 0, s[12:13]
	v_mfma_f32_16x16x32_bf16 v[108:111], v[128:131], v[194:197], v[108:111]
	v_lshl_add_u64 v[202:203], v[202:203], 0, s[12:13]
	v_mfma_f32_16x16x32_bf16 v[104:107], v[136:139], v[194:197], v[104:107]
	v_lshl_add_u64 v[216:217], v[216:217], 0, s[12:13]
	v_mfma_f32_16x16x32_bf16 v[92:95], v[128:131], v[212:215], v[92:95]
	v_lshl_add_u64 v[232:233], v[232:233], 0, s[12:13]
	v_mfma_f32_16x16x32_bf16 v[88:91], v[136:139], v[212:215], v[88:91]
	v_lshl_add_u64 v[234:235], v[234:235], 0, s[12:13]
	v_mfma_f32_16x16x32_bf16 v[76:79], v[128:131], v[224:227], v[76:79]
	v_lshl_add_u64 v[236:237], v[236:237], 0, s[12:13]
	v_mfma_f32_16x16x32_bf16 v[72:75], v[136:139], v[224:227], v[72:75]
	v_mfma_f32_16x16x32_bf16 v[120:123], v[132:135], v[174:177], v[120:123]
	v_mfma_f32_16x16x32_bf16 v[124:127], v[140:143], v[174:177], v[124:127]
	v_mfma_f32_16x16x32_bf16 v[108:111], v[132:135], v[208:211], v[108:111]
	v_mfma_f32_16x16x32_bf16 v[104:107], v[140:143], v[208:211], v[104:107]
	v_mfma_f32_16x16x32_bf16 v[92:95], v[132:135], v[220:223], v[92:95]
	v_mfma_f32_16x16x32_bf16 v[88:91], v[140:143], v[220:223], v[88:91]
	v_mfma_f32_16x16x32_bf16 v[76:79], v[132:135], v[228:231], v[76:79]
	v_mfma_f32_16x16x32_bf16 v[72:75], v[140:143], v[228:231], v[72:75]
	v_mfma_f32_16x16x32_bf16 v[116:119], v[144:147], v[170:173], v[116:119]
	v_mfma_f32_16x16x32_bf16 v[112:115], v[152:155], v[170:173], v[112:115]
	v_mfma_f32_16x16x32_bf16 v[100:103], v[144:147], v[194:197], v[100:103]
	v_mfma_f32_16x16x32_bf16 v[96:99], v[152:155], v[194:197], v[96:99]
	v_mfma_f32_16x16x32_bf16 v[84:87], v[144:147], v[212:215], v[84:87]
	v_mfma_f32_16x16x32_bf16 v[80:83], v[152:155], v[212:215], v[80:83]
	v_mfma_f32_16x16x32_bf16 v[68:71], v[144:147], v[224:227], v[68:71]
	v_mfma_f32_16x16x32_bf16 v[64:67], v[152:155], v[224:227], v[64:67]
	v_mfma_f32_16x16x32_bf16 v[116:119], v[148:151], v[174:177], v[116:119]
	v_mfma_f32_16x16x32_bf16 v[112:115], v[166:169], v[174:177], v[112:115]
	v_mfma_f32_16x16x32_bf16 v[100:103], v[148:151], v[208:211], v[100:103]
	v_mfma_f32_16x16x32_bf16 v[96:99], v[166:169], v[208:211], v[96:99]
	v_mfma_f32_16x16x32_bf16 v[84:87], v[148:151], v[220:223], v[84:87]
	v_mfma_f32_16x16x32_bf16 v[80:83], v[166:169], v[220:223], v[80:83]
	v_mfma_f32_16x16x32_bf16 v[68:71], v[148:151], v[228:231], v[68:71]
	v_mfma_f32_16x16x32_bf16 v[64:67], v[166:169], v[228:231], v[64:67]
	s_barrier
	s_add_i32 s16, s31, s36
	s_mov_b32 m0, s16
	ds_read_b128 v[170:173], v206 offset:49152
	ds_read_b128 v[174:177], v206 offset:50176
	ds_read_b128 v[194:197], v206 offset:51200
	ds_read_b128 v[208:211], v206 offset:52224
	ds_read_b128 v[212:215], v206 offset:53248
	ds_read_b128 v[220:223], v206 offset:54272
	ds_read_b128 v[224:227], v206 offset:55296
	ds_read_b128 v[228:231], v206 offset:56320
	global_load_lds_dwordx4 v[178:179], off
	s_add_i32 m0, s16, 0x2000
	s_add_i32 s16, s44, s36
	global_load_lds_dwordx4 v[202:203], off
	s_mov_b32 m0, s16
	s_nop 0
	global_load_lds_dwordx4 v[216:217], off
	s_add_i32 m0, s16, 0x2000
	s_nop 0
	global_load_lds_dwordx4 v[232:233], off
	s_mov_b32 m0, s49
	s_nop 0
	global_load_lds_dwordx4 v[234:235], off
	s_mov_b32 m0, s52
	s_nop 0
	global_load_lds_dwordx4 v[236:237], off
	s_waitcnt vmcnt(8)
	s_waitcnt lgkmcnt(0)
	s_barrier
	s_waitcnt lgkmcnt(0)
	v_mfma_f32_16x16x32_bf16 v[60:63], v[128:131], v[170:173], v[60:63]
	s_add_u32 s28, s28, 0x100
	v_mfma_f32_16x16x32_bf16 v[56:59], v[136:139], v[170:173], v[56:59]
	s_addc_u32 s29, s29, 0
	v_mfma_f32_16x16x32_bf16 v[44:47], v[128:131], v[194:197], v[44:47]
	s_add_u32 s10, s10, 0x100
	v_mfma_f32_16x16x32_bf16 v[40:43], v[136:139], v[194:197], v[40:43]
	s_addc_u32 s11, s11, 0
	v_mfma_f32_16x16x32_bf16 v[28:31], v[128:131], v[212:215], v[28:31]
	s_mov_b32 s16, s30
	v_mfma_f32_16x16x32_bf16 v[24:27], v[136:139], v[212:215], v[24:27]
	s_cmp_ge_i32 s30, s48
	v_mfma_f32_16x16x32_bf16 v[12:15], v[128:131], v[224:227], v[12:15]
	s_cselect_b32 s99, 1, 0
	v_mfma_f32_16x16x32_bf16 v[8:11], v[136:139], v[224:227], v[8:11]
	s_add_i32 s30, s16, 2
	v_mfma_f32_16x16x32_bf16 v[60:63], v[132:135], v[174:177], v[60:63]
	s_add_u32 s31, s28, 0x80
	v_mfma_f32_16x16x32_bf16 v[56:59], v[140:143], v[174:177], v[56:59]
	s_addc_u32 s17, s29, 0
	v_mfma_f32_16x16x32_bf16 v[44:47], v[132:135], v[208:211], v[44:47]
	s_add_i32 s62, 0, 0x10000
	v_mfma_f32_16x16x32_bf16 v[40:43], v[140:143], v[208:211], v[40:43]
	s_cmp_eq_u32 s56, s16
	v_mfma_f32_16x16x32_bf16 v[28:31], v[132:135], v[220:223], v[28:31]
	s_cselect_b32 s17, s25, s17
	v_mfma_f32_16x16x32_bf16 v[24:27], v[140:143], v[220:223], v[24:27]
	s_cselect_b32 s16, s24, s31
	v_mfma_f32_16x16x32_bf16 v[12:15], v[132:135], v[228:231], v[12:15]
	s_cselect_b32 s45, s27, s11
	v_mfma_f32_16x16x32_bf16 v[8:11], v[140:143], v[228:231], v[8:11]
	s_cselect_b32 s44, s26, s10
	v_mfma_f32_16x16x32_bf16 v[52:55], v[144:147], v[170:173], v[52:55]
	s_add_i32 s31, 0, 0x14000
	v_mfma_f32_16x16x32_bf16 v[48:51], v[152:155], v[170:173], v[48:51]
	v_mfma_f32_16x16x32_bf16 v[36:39], v[144:147], v[194:197], v[36:39]
	v_mfma_f32_16x16x32_bf16 v[32:35], v[152:155], v[194:197], v[32:35]
	v_mfma_f32_16x16x32_bf16 v[20:23], v[144:147], v[212:215], v[20:23]
	v_mfma_f32_16x16x32_bf16 v[16:19], v[152:155], v[212:215], v[16:19]
	v_mfma_f32_16x16x32_bf16 v[4:7], v[144:147], v[224:227], v[4:7]
	v_mfma_f32_16x16x32_bf16 v[0:3], v[152:155], v[224:227], v[0:3]
	v_mfma_f32_16x16x32_bf16 v[52:55], v[148:151], v[174:177], v[52:55]
	v_mfma_f32_16x16x32_bf16 v[48:51], v[166:169], v[174:177], v[48:51]
	v_mfma_f32_16x16x32_bf16 v[36:39], v[148:151], v[208:211], v[36:39]
	v_mfma_f32_16x16x32_bf16 v[32:35], v[166:169], v[208:211], v[32:35]
	v_mfma_f32_16x16x32_bf16 v[20:23], v[148:151], v[220:223], v[20:23]
	v_mfma_f32_16x16x32_bf16 v[16:19], v[166:169], v[220:223], v[16:19]
	v_mfma_f32_16x16x32_bf16 v[4:7], v[148:151], v[228:231], v[4:7]
	v_mfma_f32_16x16x32_bf16 v[0:3], v[166:169], v[228:231], v[0:3]
	s_barrier
	s_cmp_lg_u32 s99, 0
	s_cbranch_scc1 .Lpeelx_13
.LBB0_1053:
	v_add_u32_e32 v140, s62, v199
	v_add_u32_e32 v166, s31, v199
	ds_read_b128 v[128:131], v140
	ds_read_b128 v[132:135], v140 offset:1024
	ds_read_b128 v[136:139], v140 offset:2048
	ds_read_b128 v[140:143], v140 offset:3072
	ds_read_b128 v[144:147], v166
	ds_read_b128 v[148:151], v166 offset:1024
	ds_read_b128 v[152:155], v166 offset:2048
	ds_read_b128 v[166:169], v166 offset:3072
	v_lshl_add_u64 v[178:179], s[28:29], 0, v[162:163]
	s_add_i32 m0, s37, 0xc000
	ds_read_b128 v[170:173], v206
	ds_read_b128 v[174:177], v206 offset:1024
	ds_read_b128 v[194:197], v206 offset:2048
	ds_read_b128 v[208:211], v206 offset:3072
	ds_read_b128 v[212:215], v206 offset:4096
	ds_read_b128 v[220:223], v206 offset:5120
	ds_read_b128 v[224:227], v206 offset:6144
	ds_read_b128 v[228:231], v206 offset:7168
	global_load_lds_dwordx4 v[178:179], off
	v_lshl_add_u64 v[178:179], s[28:29], 0, v[164:165]
	s_add_i32 m0, s37, 0xe000
	s_nop 0
	global_load_lds_dwordx4 v[178:179], off
	s_waitcnt vmcnt(8)
	s_waitcnt lgkmcnt(0)
	s_barrier
	s_waitcnt lgkmcnt(0)
	v_mfma_f32_16x16x32_bf16 v[120:123], v[128:131], v[170:173], v[120:123]
	v_mfma_f32_16x16x32_bf16 v[124:127], v[136:139], v[170:173], v[124:127]
	v_lshl_add_u64 v[178:179], s[44:45], 0, v[180:181]
	v_mfma_f32_16x16x32_bf16 v[108:111], v[128:131], v[194:197], v[108:111]
	v_lshl_add_u64 v[202:203], s[44:45], 0, v[156:157]
	v_mfma_f32_16x16x32_bf16 v[104:107], v[136:139], v[194:197], v[104:107]
	s_add_u32 s44, s44, s6
	v_mfma_f32_16x16x32_bf16 v[92:95], v[128:131], v[212:215], v[92:95]
	s_addc_u32 s45, s45, s7
	v_mfma_f32_16x16x32_bf16 v[88:91], v[136:139], v[212:215], v[88:91]
	v_lshl_add_u64 v[216:217], s[44:45], 0, v[180:181]
	v_mfma_f32_16x16x32_bf16 v[76:79], v[128:131], v[224:227], v[76:79]
	v_lshl_add_u64 v[232:233], s[44:45], 0, v[156:157]
	v_mfma_f32_16x16x32_bf16 v[72:75], v[136:139], v[224:227], v[72:75]
	v_lshl_add_u64 v[234:235], s[16:17], 0, v[160:161]
	v_mfma_f32_16x16x32_bf16 v[120:123], v[132:135], v[174:177], v[120:123]
	v_lshl_add_u64 v[236:237], s[16:17], 0, v[158:159]
	v_mfma_f32_16x16x32_bf16 v[124:127], v[140:143], v[174:177], v[124:127]
	v_mfma_f32_16x16x32_bf16 v[108:111], v[132:135], v[208:211], v[108:111]
	v_mfma_f32_16x16x32_bf16 v[104:107], v[140:143], v[208:211], v[104:107]
	v_mfma_f32_16x16x32_bf16 v[92:95], v[132:135], v[220:223], v[92:95]
	v_mfma_f32_16x16x32_bf16 v[88:91], v[140:143], v[220:223], v[88:91]
	v_mfma_f32_16x16x32_bf16 v[76:79], v[132:135], v[228:231], v[76:79]
	v_mfma_f32_16x16x32_bf16 v[72:75], v[140:143], v[228:231], v[72:75]
	v_mfma_f32_16x16x32_bf16 v[116:119], v[144:147], v[170:173], v[116:119]
	v_mfma_f32_16x16x32_bf16 v[112:115], v[152:155], v[170:173], v[112:115]
	v_mfma_f32_16x16x32_bf16 v[100:103], v[144:147], v[194:197], v[100:103]
	v_mfma_f32_16x16x32_bf16 v[96:99], v[152:155], v[194:197], v[96:99]
	v_mfma_f32_16x16x32_bf16 v[84:87], v[144:147], v[212:215], v[84:87]
	v_mfma_f32_16x16x32_bf16 v[80:83], v[152:155], v[212:215], v[80:83]
	v_mfma_f32_16x16x32_bf16 v[68:71], v[144:147], v[224:227], v[68:71]
	v_mfma_f32_16x16x32_bf16 v[64:67], v[152:155], v[224:227], v[64:67]
	v_mfma_f32_16x16x32_bf16 v[116:119], v[148:151], v[174:177], v[116:119]
	v_mfma_f32_16x16x32_bf16 v[112:115], v[166:169], v[174:177], v[112:115]
	v_mfma_f32_16x16x32_bf16 v[100:103], v[148:151], v[208:211], v[100:103]
	v_mfma_f32_16x16x32_bf16 v[96:99], v[166:169], v[208:211], v[96:99]
	v_mfma_f32_16x16x32_bf16 v[84:87], v[148:151], v[220:223], v[84:87]
	v_mfma_f32_16x16x32_bf16 v[80:83], v[166:169], v[220:223], v[80:83]
	v_mfma_f32_16x16x32_bf16 v[68:71], v[148:151], v[228:231], v[68:71]
	v_mfma_f32_16x16x32_bf16 v[64:67], v[166:169], v[228:231], v[64:67]
	s_barrier
	s_add_i32 s62, s62, s36
	s_mov_b32 m0, s62
	ds_read_b128 v[170:173], v206 offset:16384
	ds_read_b128 v[174:177], v206 offset:17408
	ds_read_b128 v[194:197], v206 offset:18432
	ds_read_b128 v[208:211], v206 offset:19456
	ds_read_b128 v[212:215], v206 offset:20480
	ds_read_b128 v[220:223], v206 offset:21504
	ds_read_b128 v[224:227], v206 offset:22528
	ds_read_b128 v[228:231], v206 offset:23552
	global_load_lds_dwordx4 v[178:179], off
	s_add_i32 m0, s62, 0x2000
	s_add_i32 s31, s31, s36
	global_load_lds_dwordx4 v[202:203], off
	s_mov_b32 m0, s31
	s_nop 0
	global_load_lds_dwordx4 v[216:217], off
	s_add_i32 m0, s31, 0x2000
	s_nop 0
	global_load_lds_dwordx4 v[232:233], off
	s_mov_b32 m0, s37
	s_nop 0
	global_load_lds_dwordx4 v[234:235], off
	s_mov_b32 m0, s38
	s_nop 0
	global_load_lds_dwordx4 v[236:237], off
	s_waitcnt vmcnt(8)
	s_waitcnt lgkmcnt(0)
	s_barrier
	s_waitcnt lgkmcnt(0)
	v_mfma_f32_16x16x32_bf16 v[60:63], v[128:131], v[170:173], v[60:63]
	v_mfma_f32_16x16x32_bf16 v[56:59], v[136:139], v[170:173], v[56:59]
	v_mfma_f32_16x16x32_bf16 v[44:47], v[128:131], v[194:197], v[44:47]
	v_mfma_f32_16x16x32_bf16 v[40:43], v[136:139], v[194:197], v[40:43]
	v_mfma_f32_16x16x32_bf16 v[28:31], v[128:131], v[212:215], v[28:31]
	v_mfma_f32_16x16x32_bf16 v[24:27], v[136:139], v[212:215], v[24:27]
	v_mfma_f32_16x16x32_bf16 v[12:15], v[128:131], v[224:227], v[12:15]
	v_mfma_f32_16x16x32_bf16 v[8:11], v[136:139], v[224:227], v[8:11]
	v_mfma_f32_16x16x32_bf16 v[60:63], v[132:135], v[174:177], v[60:63]
	v_mfma_f32_16x16x32_bf16 v[56:59], v[140:143], v[174:177], v[56:59]
	v_mfma_f32_16x16x32_bf16 v[44:47], v[132:135], v[208:211], v[44:47]
	v_mfma_f32_16x16x32_bf16 v[40:43], v[140:143], v[208:211], v[40:43]
	v_mfma_f32_16x16x32_bf16 v[28:31], v[132:135], v[220:223], v[28:31]
	v_mfma_f32_16x16x32_bf16 v[24:27], v[140:143], v[220:223], v[24:27]
	v_mfma_f32_16x16x32_bf16 v[12:15], v[132:135], v[228:231], v[12:15]
	v_mfma_f32_16x16x32_bf16 v[8:11], v[140:143], v[228:231], v[8:11]
	v_mfma_f32_16x16x32_bf16 v[52:55], v[144:147], v[170:173], v[52:55]
	v_mfma_f32_16x16x32_bf16 v[48:51], v[152:155], v[170:173], v[48:51]
	v_mfma_f32_16x16x32_bf16 v[36:39], v[144:147], v[194:197], v[36:39]
	v_mfma_f32_16x16x32_bf16 v[32:35], v[152:155], v[194:197], v[32:35]
	v_mfma_f32_16x16x32_bf16 v[20:23], v[144:147], v[212:215], v[20:23]
	v_mfma_f32_16x16x32_bf16 v[16:19], v[152:155], v[212:215], v[16:19]
	v_mfma_f32_16x16x32_bf16 v[4:7], v[144:147], v[224:227], v[4:7]
	v_mfma_f32_16x16x32_bf16 v[0:3], v[152:155], v[224:227], v[0:3]
	v_mfma_f32_16x16x32_bf16 v[52:55], v[148:151], v[174:177], v[52:55]
	v_mfma_f32_16x16x32_bf16 v[48:51], v[166:169], v[174:177], v[48:51]
	v_mfma_f32_16x16x32_bf16 v[36:39], v[148:151], v[208:211], v[36:39]
	v_mfma_f32_16x16x32_bf16 v[32:35], v[166:169], v[208:211], v[32:35]
	v_mfma_f32_16x16x32_bf16 v[20:23], v[148:151], v[220:223], v[20:23]
	v_mfma_f32_16x16x32_bf16 v[16:19], v[166:169], v[220:223], v[16:19]
	v_mfma_f32_16x16x32_bf16 v[4:7], v[148:151], v[228:231], v[4:7]
	v_mfma_f32_16x16x32_bf16 v[0:3], v[166:169], v[228:231], v[0:3]
	s_barrier
	s_add_i32 s31, 0, 0x18000
	s_add_i32 s44, 0, 0x1c000
	v_add_u32_e32 v140, s31, v199
	v_add_u32_e32 v166, s44, v199
	ds_read_b128 v[128:131], v140
	ds_read_b128 v[132:135], v140 offset:1024
	ds_read_b128 v[136:139], v140 offset:2048
	ds_read_b128 v[140:143], v140 offset:3072
	ds_read_b128 v[144:147], v166
	ds_read_b128 v[148:151], v166 offset:1024
	ds_read_b128 v[152:155], v166 offset:2048
	ds_read_b128 v[166:169], v166 offset:3072
	s_add_u32 s16, s16, s6
	s_addc_u32 s17, s17, s7
	s_mov_b32 m0, s39
	v_lshl_add_u64 v[238:239], s[16:17], 0, v[160:161]
	ds_read_b128 v[170:173], v206 offset:32768
	ds_read_b128 v[174:177], v206 offset:33792
	ds_read_b128 v[194:197], v206 offset:34816
	ds_read_b128 v[208:211], v206 offset:35840
	ds_read_b128 v[212:215], v206 offset:36864
	ds_read_b128 v[220:223], v206 offset:37888
	ds_read_b128 v[224:227], v206 offset:38912
	ds_read_b128 v[228:231], v206 offset:39936
	global_load_lds_dwordx4 v[238:239], off
	v_lshl_add_u64 v[238:239], s[16:17], 0, v[158:159]
	s_mov_b32 m0, s46
	s_nop 0
	global_load_lds_dwordx4 v[238:239], off
	s_waitcnt vmcnt(8)
	s_waitcnt lgkmcnt(0)
	s_barrier
	s_waitcnt lgkmcnt(0)
	v_mfma_f32_16x16x32_bf16 v[120:123], v[128:131], v[170:173], v[120:123]
	v_mfma_f32_16x16x32_bf16 v[124:127], v[136:139], v[170:173], v[124:127]
	v_lshl_add_u64 v[178:179], v[178:179], 0, s[12:13]
	v_mfma_f32_16x16x32_bf16 v[108:111], v[128:131], v[194:197], v[108:111]
	v_lshl_add_u64 v[202:203], v[202:203], 0, s[12:13]
	v_mfma_f32_16x16x32_bf16 v[104:107], v[136:139], v[194:197], v[104:107]
	v_lshl_add_u64 v[216:217], v[216:217], 0, s[12:13]
	v_mfma_f32_16x16x32_bf16 v[92:95], v[128:131], v[212:215], v[92:95]
	v_lshl_add_u64 v[232:233], v[232:233], 0, s[12:13]
	v_mfma_f32_16x16x32_bf16 v[88:91], v[136:139], v[212:215], v[88:91]
	v_lshl_add_u64 v[234:235], v[234:235], 0, s[12:13]
	v_mfma_f32_16x16x32_bf16 v[76:79], v[128:131], v[224:227], v[76:79]
	v_lshl_add_u64 v[236:237], v[236:237], 0, s[12:13]
	v_mfma_f32_16x16x32_bf16 v[72:75], v[136:139], v[224:227], v[72:75]
	v_mfma_f32_16x16x32_bf16 v[120:123], v[132:135], v[174:177], v[120:123]
	v_mfma_f32_16x16x32_bf16 v[124:127], v[140:143], v[174:177], v[124:127]
	v_mfma_f32_16x16x32_bf16 v[108:111], v[132:135], v[208:211], v[108:111]
	v_mfma_f32_16x16x32_bf16 v[104:107], v[140:143], v[208:211], v[104:107]
	v_mfma_f32_16x16x32_bf16 v[92:95], v[132:135], v[220:223], v[92:95]
	v_mfma_f32_16x16x32_bf16 v[88:91], v[140:143], v[220:223], v[88:91]
	v_mfma_f32_16x16x32_bf16 v[76:79], v[132:135], v[228:231], v[76:79]
	v_mfma_f32_16x16x32_bf16 v[72:75], v[140:143], v[228:231], v[72:75]
	v_mfma_f32_16x16x32_bf16 v[116:119], v[144:147], v[170:173], v[116:119]
	v_mfma_f32_16x16x32_bf16 v[112:115], v[152:155], v[170:173], v[112:115]
	v_mfma_f32_16x16x32_bf16 v[100:103], v[144:147], v[194:197], v[100:103]
	v_mfma_f32_16x16x32_bf16 v[96:99], v[152:155], v[194:197], v[96:99]
	v_mfma_f32_16x16x32_bf16 v[84:87], v[144:147], v[212:215], v[84:87]
	v_mfma_f32_16x16x32_bf16 v[80:83], v[152:155], v[212:215], v[80:83]
	v_mfma_f32_16x16x32_bf16 v[68:71], v[144:147], v[224:227], v[68:71]
	v_mfma_f32_16x16x32_bf16 v[64:67], v[152:155], v[224:227], v[64:67]
	v_mfma_f32_16x16x32_bf16 v[116:119], v[148:151], v[174:177], v[116:119]
	v_mfma_f32_16x16x32_bf16 v[112:115], v[166:169], v[174:177], v[112:115]
	v_mfma_f32_16x16x32_bf16 v[100:103], v[148:151], v[208:211], v[100:103]
	v_mfma_f32_16x16x32_bf16 v[96:99], v[166:169], v[208:211], v[96:99]
	v_mfma_f32_16x16x32_bf16 v[84:87], v[148:151], v[220:223], v[84:87]
	v_mfma_f32_16x16x32_bf16 v[80:83], v[166:169], v[220:223], v[80:83]
	v_mfma_f32_16x16x32_bf16 v[68:71], v[148:151], v[228:231], v[68:71]
	v_mfma_f32_16x16x32_bf16 v[64:67], v[166:169], v[228:231], v[64:67]
	s_barrier
	s_add_i32 s16, s31, s36
	s_mov_b32 m0, s16
	ds_read_b128 v[170:173], v206 offset:49152
	ds_read_b128 v[174:177], v206 offset:50176
	ds_read_b128 v[194:197], v206 offset:51200
	ds_read_b128 v[208:211], v206 offset:52224
	ds_read_b128 v[212:215], v206 offset:53248
	ds_read_b128 v[220:223], v206 offset:54272
	ds_read_b128 v[224:227], v206 offset:55296
	ds_read_b128 v[228:231], v206 offset:56320
	global_load_lds_dwordx4 v[178:179], off
	s_add_i32 m0, s16, 0x2000
	s_add_i32 s16, s44, s36
	global_load_lds_dwordx4 v[202:203], off
	s_mov_b32 m0, s16
	s_nop 0
	global_load_lds_dwordx4 v[216:217], off
	s_add_i32 m0, s16, 0x2000
	s_nop 0
	global_load_lds_dwordx4 v[232:233], off
	s_mov_b32 m0, s49
	s_nop 0
	global_load_lds_dwordx4 v[234:235], off
	s_mov_b32 m0, s52
	s_nop 0
	global_load_lds_dwordx4 v[236:237], off
	s_waitcnt vmcnt(8)
	s_waitcnt lgkmcnt(0)
	s_barrier
	s_waitcnt lgkmcnt(0)
	v_mfma_f32_16x16x32_bf16 v[60:63], v[128:131], v[170:173], v[60:63]
	s_add_u32 s28, s28, 0x100
	v_mfma_f32_16x16x32_bf16 v[56:59], v[136:139], v[170:173], v[56:59]
	s_addc_u32 s29, s29, 0
	v_mfma_f32_16x16x32_bf16 v[44:47], v[128:131], v[194:197], v[44:47]
	s_add_u32 s10, s10, 0x100
	v_mfma_f32_16x16x32_bf16 v[40:43], v[136:139], v[194:197], v[40:43]
	s_addc_u32 s11, s11, 0
	v_mfma_f32_16x16x32_bf16 v[28:31], v[128:131], v[212:215], v[28:31]
	s_mov_b32 s16, s30
	v_mfma_f32_16x16x32_bf16 v[24:27], v[136:139], v[212:215], v[24:27]
	s_cmp_ge_i32 s30, s48
	v_mfma_f32_16x16x32_bf16 v[12:15], v[128:131], v[224:227], v[12:15]
	s_cselect_b32 s99, 1, 0
	v_mfma_f32_16x16x32_bf16 v[8:11], v[136:139], v[224:227], v[8:11]
	s_add_i32 s30, s16, 2
	v_mfma_f32_16x16x32_bf16 v[60:63], v[132:135], v[174:177], v[60:63]
	s_add_u32 s31, s28, 0x80
	v_mfma_f32_16x16x32_bf16 v[56:59], v[140:143], v[174:177], v[56:59]
	s_addc_u32 s17, s29, 0
	v_mfma_f32_16x16x32_bf16 v[44:47], v[132:135], v[208:211], v[44:47]
	s_add_i32 s62, 0, 0x10000
	v_mfma_f32_16x16x32_bf16 v[40:43], v[140:143], v[208:211], v[40:43]
	s_cmp_eq_u32 s56, s16
	v_mfma_f32_16x16x32_bf16 v[28:31], v[132:135], v[220:223], v[28:31]
	s_cselect_b32 s17, s25, s17
	v_mfma_f32_16x16x32_bf16 v[24:27], v[140:143], v[220:223], v[24:27]
	s_cselect_b32 s16, s24, s31
	v_mfma_f32_16x16x32_bf16 v[12:15], v[132:135], v[228:231], v[12:15]
	s_cselect_b32 s45, s27, s11
	v_mfma_f32_16x16x32_bf16 v[8:11], v[140:143], v[228:231], v[8:11]
	s_cselect_b32 s44, s26, s10
	v_mfma_f32_16x16x32_bf16 v[52:55], v[144:147], v[170:173], v[52:55]
	s_add_i32 s31, 0, 0x14000
	v_mfma_f32_16x16x32_bf16 v[48:51], v[152:155], v[170:173], v[48:51]
	v_mfma_f32_16x16x32_bf16 v[36:39], v[144:147], v[194:197], v[36:39]
	v_mfma_f32_16x16x32_bf16 v[32:35], v[152:155], v[194:197], v[32:35]
	v_mfma_f32_16x16x32_bf16 v[20:23], v[144:147], v[212:215], v[20:23]
	v_mfma_f32_16x16x32_bf16 v[16:19], v[152:155], v[212:215], v[16:19]
	v_mfma_f32_16x16x32_bf16 v[4:7], v[144:147], v[224:227], v[4:7]
	v_mfma_f32_16x16x32_bf16 v[0:3], v[152:155], v[224:227], v[0:3]
	v_mfma_f32_16x16x32_bf16 v[52:55], v[148:151], v[174:177], v[52:55]
	v_mfma_f32_16x16x32_bf16 v[48:51], v[166:169], v[174:177], v[48:51]
	v_mfma_f32_16x16x32_bf16 v[36:39], v[148:151], v[208:211], v[36:39]
	v_mfma_f32_16x16x32_bf16 v[32:35], v[166:169], v[208:211], v[32:35]
	v_mfma_f32_16x16x32_bf16 v[20:23], v[148:151], v[220:223], v[20:23]
	v_mfma_f32_16x16x32_bf16 v[16:19], v[166:169], v[220:223], v[16:19]
	v_mfma_f32_16x16x32_bf16 v[4:7], v[148:151], v[228:231], v[4:7]
	v_mfma_f32_16x16x32_bf16 v[0:3], v[166:169], v[228:231], v[0:3]
	s_barrier
	s_cmp_lg_u32 s99, 0
	s_cbranch_scc0 .LBB0_1053

.Llbb_10:
	s_add_i32 s30, s16, 2
	s_add_u32 s31, s28, 0x80
	s_addc_u32 s17, s29, 0
	s_add_i32 s63, 0, 0x10000
	s_cmp_eq_u32 s56, s16
	s_cselect_b32 s17, s25, s17
	s_cselect_b32 s16, s24, s31
	s_cselect_b32 s45, s27, s11
	s_cselect_b32 s44, s26, s10
	s_add_i32 s31, 0, 0x14000
	v_add_u32_e32 v156, s63, v151
	v_add_u32_e32 v172, s31, v151
	ds_read_b128 v[128:131], v156
	ds_read_b128 v[142:145], v156 offset:1024
	ds_read_b128 v[146:149], v156 offset:2048
	ds_read_b128 v[156:159], v156 offset:3072
	ds_read_b128 v[160:163], v172
	ds_read_b128 v[164:167], v172 offset:1024
	ds_read_b128 v[168:171], v172 offset:2048
	ds_read_b128 v[172:175], v172 offset:3072
	v_lshl_add_u64 v[198:199], s[28:29], 0, v[138:139]
	s_add_i32 m0, s37, 0xc000
	ds_read_b128 v[176:179], v155
	ds_read_b128 v[194:197], v155 offset:1024
	ds_read_b128 v[206:209], v155 offset:2048
	ds_read_b128 v[210:213], v155 offset:3072
	ds_read_b128 v[214:217], v155 offset:4096
	ds_read_b128 v[220:223], v155 offset:5120
	ds_read_b128 v[224:227], v155 offset:6144
	ds_read_b128 v[228:231], v155 offset:7168
	global_load_lds_dwordx4 v[198:199], off
	v_lshl_add_u64 v[198:199], s[28:29], 0, v[140:141]
	s_add_i32 m0, s37, 0xe000
	s_nop 0
	global_load_lds_dwordx4 v[198:199], off
	s_waitcnt vmcnt(8)
	s_waitcnt lgkmcnt(0)
	s_barrier
	s_waitcnt lgkmcnt(0)
	v_mfma_f32_16x16x32_bf16 v[120:123], v[128:131], v[176:179], 0
	v_mfma_f32_16x16x32_bf16 v[116:119], v[146:149], v[176:179], 0
	v_lshl_add_u64 v[198:199], s[44:45], 0, v[180:181]
	v_mfma_f32_16x16x32_bf16 v[108:111], v[128:131], v[206:209], 0
	v_lshl_add_u64 v[202:203], s[44:45], 0, v[132:133]
	v_mfma_f32_16x16x32_bf16 v[100:103], v[146:149], v[206:209], 0
	s_add_u32 s44, s44, s6
	v_mfma_f32_16x16x32_bf16 v[92:95], v[128:131], v[214:217], 0
	s_addc_u32 s45, s45, s7
	v_mfma_f32_16x16x32_bf16 v[84:87], v[146:149], v[214:217], 0
	v_lshl_add_u64 v[232:233], s[44:45], 0, v[180:181]
	v_mfma_f32_16x16x32_bf16 v[76:79], v[128:131], v[224:227], 0
	v_lshl_add_u64 v[234:235], s[44:45], 0, v[132:133]
	v_mfma_f32_16x16x32_bf16 v[68:71], v[146:149], v[224:227], 0
	v_lshl_add_u64 v[236:237], s[16:17], 0, v[136:137]
	v_mfma_f32_16x16x32_bf16 v[120:123], v[142:145], v[194:197], v[120:123]
	v_lshl_add_u64 v[238:239], s[16:17], 0, v[134:135]
	v_mfma_f32_16x16x32_bf16 v[116:119], v[156:159], v[194:197], v[116:119]
	v_mfma_f32_16x16x32_bf16 v[108:111], v[142:145], v[210:213], v[108:111]
	v_mfma_f32_16x16x32_bf16 v[100:103], v[156:159], v[210:213], v[100:103]
	v_mfma_f32_16x16x32_bf16 v[92:95], v[142:145], v[220:223], v[92:95]
	v_mfma_f32_16x16x32_bf16 v[84:87], v[156:159], v[220:223], v[84:87]
	v_mfma_f32_16x16x32_bf16 v[76:79], v[142:145], v[228:231], v[76:79]
	v_mfma_f32_16x16x32_bf16 v[68:71], v[156:159], v[228:231], v[68:71]
	v_mfma_f32_16x16x32_bf16 v[124:127], v[160:163], v[176:179], 0
	v_mfma_f32_16x16x32_bf16 v[112:115], v[168:171], v[176:179], 0
	v_mfma_f32_16x16x32_bf16 v[104:107], v[160:163], v[206:209], 0
	v_mfma_f32_16x16x32_bf16 v[96:99], v[168:171], v[206:209], 0
	v_mfma_f32_16x16x32_bf16 v[88:91], v[160:163], v[214:217], 0
	v_mfma_f32_16x16x32_bf16 v[80:83], v[168:171], v[214:217], 0
	v_mfma_f32_16x16x32_bf16 v[72:75], v[160:163], v[224:227], 0
	v_mfma_f32_16x16x32_bf16 v[64:67], v[168:171], v[224:227], 0
	v_mfma_f32_16x16x32_bf16 v[124:127], v[164:167], v[194:197], v[124:127]
	v_mfma_f32_16x16x32_bf16 v[112:115], v[172:175], v[194:197], v[112:115]
	v_mfma_f32_16x16x32_bf16 v[104:107], v[164:167], v[210:213], v[104:107]
	v_mfma_f32_16x16x32_bf16 v[96:99], v[172:175], v[210:213], v[96:99]
	v_mfma_f32_16x16x32_bf16 v[88:91], v[164:167], v[220:223], v[88:91]
	v_mfma_f32_16x16x32_bf16 v[80:83], v[172:175], v[220:223], v[80:83]
	v_mfma_f32_16x16x32_bf16 v[72:75], v[164:167], v[228:231], v[72:75]
	v_mfma_f32_16x16x32_bf16 v[64:67], v[172:175], v[228:231], v[64:67]
	s_barrier
	s_add_i32 s63, s63, s36
	s_mov_b32 m0, s63
	ds_read_b128 v[176:179], v155 offset:16384
	ds_read_b128 v[194:197], v155 offset:17408
	ds_read_b128 v[206:209], v155 offset:18432
	ds_read_b128 v[210:213], v155 offset:19456
	ds_read_b128 v[214:217], v155 offset:20480
	ds_read_b128 v[220:223], v155 offset:21504
	ds_read_b128 v[224:227], v155 offset:22528
	ds_read_b128 v[228:231], v155 offset:23552
	global_load_lds_dwordx4 v[198:199], off
	s_add_i32 m0, s63, 0x2000
	s_add_i32 s31, s31, s36
	global_load_lds_dwordx4 v[202:203], off
	s_mov_b32 m0, s31
	s_nop 0
	global_load_lds_dwordx4 v[232:233], off
	s_add_i32 m0, s31, 0x2000
	s_nop 0
	global_load_lds_dwordx4 v[234:235], off
	s_mov_b32 m0, s37
	s_nop 0
	global_load_lds_dwordx4 v[236:237], off
	s_mov_b32 m0, s38
	s_nop 0
	global_load_lds_dwordx4 v[238:239], off
	s_waitcnt vmcnt(8)
	s_waitcnt lgkmcnt(0)
	s_barrier
	s_waitcnt lgkmcnt(0)
	v_mfma_f32_16x16x32_bf16 v[60:63], v[128:131], v[176:179], 0
	v_mfma_f32_16x16x32_bf16 v[52:55], v[146:149], v[176:179], 0
	v_mfma_f32_16x16x32_bf16 v[44:47], v[128:131], v[206:209], 0
	v_mfma_f32_16x16x32_bf16 v[36:39], v[146:149], v[206:209], 0
	v_mfma_f32_16x16x32_bf16 v[28:31], v[128:131], v[214:217], 0
	v_mfma_f32_16x16x32_bf16 v[20:23], v[146:149], v[214:217], 0
	v_mfma_f32_16x16x32_bf16 v[12:15], v[128:131], v[224:227], 0
	v_mfma_f32_16x16x32_bf16 v[4:7], v[146:149], v[224:227], 0
	v_mfma_f32_16x16x32_bf16 v[60:63], v[142:145], v[194:197], v[60:63]
	v_mfma_f32_16x16x32_bf16 v[52:55], v[156:159], v[194:197], v[52:55]
	v_mfma_f32_16x16x32_bf16 v[44:47], v[142:145], v[210:213], v[44:47]
	v_mfma_f32_16x16x32_bf16 v[36:39], v[156:159], v[210:213], v[36:39]
	v_mfma_f32_16x16x32_bf16 v[28:31], v[142:145], v[220:223], v[28:31]
	v_mfma_f32_16x16x32_bf16 v[20:23], v[156:159], v[220:223], v[20:23]
	v_mfma_f32_16x16x32_bf16 v[12:15], v[142:145], v[228:231], v[12:15]
	v_mfma_f32_16x16x32_bf16 v[4:7], v[156:159], v[228:231], v[4:7]
	v_mfma_f32_16x16x32_bf16 v[56:59], v[160:163], v[176:179], 0
	v_mfma_f32_16x16x32_bf16 v[48:51], v[168:171], v[176:179], 0
	v_mfma_f32_16x16x32_bf16 v[40:43], v[160:163], v[206:209], 0
	v_mfma_f32_16x16x32_bf16 v[32:35], v[168:171], v[206:209], 0
	v_mfma_f32_16x16x32_bf16 v[24:27], v[160:163], v[214:217], 0
	v_mfma_f32_16x16x32_bf16 v[16:19], v[168:171], v[214:217], 0
	v_mfma_f32_16x16x32_bf16 v[8:11], v[160:163], v[224:227], 0
	v_mfma_f32_16x16x32_bf16 v[0:3], v[168:171], v[224:227], 0
	v_mfma_f32_16x16x32_bf16 v[56:59], v[164:167], v[194:197], v[56:59]
	v_mfma_f32_16x16x32_bf16 v[48:51], v[172:175], v[194:197], v[48:51]
	v_mfma_f32_16x16x32_bf16 v[40:43], v[164:167], v[210:213], v[40:43]
	v_mfma_f32_16x16x32_bf16 v[32:35], v[172:175], v[210:213], v[32:35]
	v_mfma_f32_16x16x32_bf16 v[24:27], v[164:167], v[220:223], v[24:27]
	v_mfma_f32_16x16x32_bf16 v[16:19], v[172:175], v[220:223], v[16:19]
	v_mfma_f32_16x16x32_bf16 v[8:11], v[164:167], v[228:231], v[8:11]
	v_mfma_f32_16x16x32_bf16 v[0:3], v[172:175], v[228:231], v[0:3]
	s_barrier
	s_add_i32 s31, 0, 0x18000
	s_add_i32 s44, 0, 0x1c000
	v_add_u32_e32 v156, s31, v151
	v_add_u32_e32 v172, s44, v151
	ds_read_b128 v[128:131], v156
	ds_read_b128 v[142:145], v156 offset:1024
	ds_read_b128 v[146:149], v156 offset:2048
	ds_read_b128 v[156:159], v156 offset:3072
	ds_read_b128 v[160:163], v172
	ds_read_b128 v[164:167], v172 offset:1024
	ds_read_b128 v[168:171], v172 offset:2048
	ds_read_b128 v[172:175], v172 offset:3072
	s_add_u32 s16, s16, s6
	s_addc_u32 s17, s17, s7
	s_mov_b32 m0, s39
	v_lshl_add_u64 v[240:241], s[16:17], 0, v[136:137]
	ds_read_b128 v[176:179], v155 offset:32768
	ds_read_b128 v[194:197], v155 offset:33792
	ds_read_b128 v[206:209], v155 offset:34816
	ds_read_b128 v[210:213], v155 offset:35840
	ds_read_b128 v[214:217], v155 offset:36864
	ds_read_b128 v[220:223], v155 offset:37888
	ds_read_b128 v[224:227], v155 offset:38912
	ds_read_b128 v[228:231], v155 offset:39936
	global_load_lds_dwordx4 v[240:241], off
	v_lshl_add_u64 v[240:241], s[16:17], 0, v[134:135]
	s_mov_b32 m0, s46
	s_nop 0
	global_load_lds_dwordx4 v[240:241], off
	s_waitcnt vmcnt(8)
	s_waitcnt lgkmcnt(0)
	s_barrier
	s_waitcnt lgkmcnt(0)
	v_mfma_f32_16x16x32_bf16 v[120:123], v[128:131], v[176:179], v[120:123]
	v_mfma_f32_16x16x32_bf16 v[116:119], v[146:149], v[176:179], v[116:119]
	v_lshl_add_u64 v[198:199], v[198:199], 0, s[12:13]
	v_mfma_f32_16x16x32_bf16 v[108:111], v[128:131], v[206:209], v[108:111]
	v_lshl_add_u64 v[202:203], v[202:203], 0, s[12:13]
	v_mfma_f32_16x16x32_bf16 v[100:103], v[146:149], v[206:209], v[100:103]
	v_lshl_add_u64 v[232:233], v[232:233], 0, s[12:13]
	v_mfma_f32_16x16x32_bf16 v[92:95], v[128:131], v[214:217], v[92:95]
	v_lshl_add_u64 v[234:235], v[234:235], 0, s[12:13]
	v_mfma_f32_16x16x32_bf16 v[84:87], v[146:149], v[214:217], v[84:87]
	v_lshl_add_u64 v[236:237], v[236:237], 0, s[12:13]
	v_mfma_f32_16x16x32_bf16 v[76:79], v[128:131], v[224:227], v[76:79]
	v_lshl_add_u64 v[238:239], v[238:239], 0, s[12:13]
	v_mfma_f32_16x16x32_bf16 v[68:71], v[146:149], v[224:227], v[68:71]
	v_mfma_f32_16x16x32_bf16 v[120:123], v[142:145], v[194:197], v[120:123]
	v_mfma_f32_16x16x32_bf16 v[116:119], v[156:159], v[194:197], v[116:119]
	v_mfma_f32_16x16x32_bf16 v[108:111], v[142:145], v[210:213], v[108:111]
	v_mfma_f32_16x16x32_bf16 v[100:103], v[156:159], v[210:213], v[100:103]
	v_mfma_f32_16x16x32_bf16 v[92:95], v[142:145], v[220:223], v[92:95]
	v_mfma_f32_16x16x32_bf16 v[84:87], v[156:159], v[220:223], v[84:87]
	v_mfma_f32_16x16x32_bf16 v[76:79], v[142:145], v[228:231], v[76:79]
	v_mfma_f32_16x16x32_bf16 v[68:71], v[156:159], v[228:231], v[68:71]
	v_mfma_f32_16x16x32_bf16 v[124:127], v[160:163], v[176:179], v[124:127]
	v_mfma_f32_16x16x32_bf16 v[112:115], v[168:171], v[176:179], v[112:115]
	v_mfma_f32_16x16x32_bf16 v[104:107], v[160:163], v[206:209], v[104:107]
	v_mfma_f32_16x16x32_bf16 v[96:99], v[168:171], v[206:209], v[96:99]
	v_mfma_f32_16x16x32_bf16 v[88:91], v[160:163], v[214:217], v[88:91]
	v_mfma_f32_16x16x32_bf16 v[80:83], v[168:171], v[214:217], v[80:83]
	v_mfma_f32_16x16x32_bf16 v[72:75], v[160:163], v[224:227], v[72:75]
	v_mfma_f32_16x16x32_bf16 v[64:67], v[168:171], v[224:227], v[64:67]
	v_mfma_f32_16x16x32_bf16 v[124:127], v[164:167], v[194:197], v[124:127]
	v_mfma_f32_16x16x32_bf16 v[112:115], v[172:175], v[194:197], v[112:115]
	v_mfma_f32_16x16x32_bf16 v[104:107], v[164:167], v[210:213], v[104:107]
	v_mfma_f32_16x16x32_bf16 v[96:99], v[172:175], v[210:213], v[96:99]
	v_mfma_f32_16x16x32_bf16 v[88:91], v[164:167], v[220:223], v[88:91]
	v_mfma_f32_16x16x32_bf16 v[80:83], v[172:175], v[220:223], v[80:83]
	v_mfma_f32_16x16x32_bf16 v[72:75], v[164:167], v[228:231], v[72:75]
	v_mfma_f32_16x16x32_bf16 v[64:67], v[172:175], v[228:231], v[64:67]
	s_barrier
	s_add_i32 s16, s31, s36
	s_mov_b32 m0, s16
	ds_read_b128 v[176:179], v155 offset:49152
	ds_read_b128 v[194:197], v155 offset:50176
	ds_read_b128 v[206:209], v155 offset:51200
	ds_read_b128 v[210:213], v155 offset:52224
	ds_read_b128 v[214:217], v155 offset:53248
	ds_read_b128 v[220:223], v155 offset:54272
	ds_read_b128 v[224:227], v155 offset:55296
	ds_read_b128 v[228:231], v155 offset:56320
	global_load_lds_dwordx4 v[198:199], off
	s_add_i32 m0, s16, 0x2000
	s_add_i32 s16, s44, s36
	global_load_lds_dwordx4 v[202:203], off
	s_mov_b32 m0, s16
	s_nop 0
	global_load_lds_dwordx4 v[232:233], off
	s_add_i32 m0, s16, 0x2000
	s_nop 0
	global_load_lds_dwordx4 v[234:235], off
	s_mov_b32 m0, s49
	s_nop 0
	global_load_lds_dwordx4 v[236:237], off
	s_mov_b32 m0, s52
	s_nop 0
	global_load_lds_dwordx4 v[238:239], off
	s_waitcnt vmcnt(8)
	s_waitcnt lgkmcnt(0)
	s_barrier
	s_waitcnt lgkmcnt(0)
	v_mfma_f32_16x16x32_bf16 v[60:63], v[128:131], v[176:179], v[60:63]
	s_add_u32 s28, s28, 0x100
	v_mfma_f32_16x16x32_bf16 v[52:55], v[146:149], v[176:179], v[52:55]
	s_addc_u32 s29, s29, 0
	v_mfma_f32_16x16x32_bf16 v[44:47], v[128:131], v[206:209], v[44:47]
	s_add_u32 s10, s10, 0x100
	v_mfma_f32_16x16x32_bf16 v[36:39], v[146:149], v[206:209], v[36:39]
	s_addc_u32 s11, s11, 0
	v_mfma_f32_16x16x32_bf16 v[28:31], v[128:131], v[214:217], v[28:31]
	s_mov_b32 s16, s30
	v_mfma_f32_16x16x32_bf16 v[20:23], v[146:149], v[214:217], v[20:23]
	s_cmp_ge_i32 s30, s47
	v_mfma_f32_16x16x32_bf16 v[12:15], v[128:131], v[224:227], v[12:15]
	s_cselect_b32 s99, 1, 0
	v_mfma_f32_16x16x32_bf16 v[4:7], v[146:149], v[224:227], v[4:7]
	s_add_i32 s30, s16, 2
	v_mfma_f32_16x16x32_bf16 v[60:63], v[142:145], v[194:197], v[60:63]
	s_add_u32 s31, s28, 0x80
	v_mfma_f32_16x16x32_bf16 v[52:55], v[156:159], v[194:197], v[52:55]
	s_addc_u32 s17, s29, 0
	v_mfma_f32_16x16x32_bf16 v[44:47], v[142:145], v[210:213], v[44:47]
	s_add_i32 s63, 0, 0x10000
	v_mfma_f32_16x16x32_bf16 v[36:39], v[156:159], v[210:213], v[36:39]
	s_cmp_eq_u32 s56, s16
	v_mfma_f32_16x16x32_bf16 v[28:31], v[142:145], v[220:223], v[28:31]
	s_cselect_b32 s17, s25, s17
	v_mfma_f32_16x16x32_bf16 v[20:23], v[156:159], v[220:223], v[20:23]
	s_cselect_b32 s16, s24, s31
	v_mfma_f32_16x16x32_bf16 v[12:15], v[142:145], v[228:231], v[12:15]
	s_cselect_b32 s45, s27, s11
	v_mfma_f32_16x16x32_bf16 v[4:7], v[156:159], v[228:231], v[4:7]
	s_cselect_b32 s44, s26, s10
	v_mfma_f32_16x16x32_bf16 v[56:59], v[160:163], v[176:179], v[56:59]
	s_add_i32 s31, 0, 0x14000
	v_mfma_f32_16x16x32_bf16 v[48:51], v[168:171], v[176:179], v[48:51]
	v_mfma_f32_16x16x32_bf16 v[40:43], v[160:163], v[206:209], v[40:43]
	v_mfma_f32_16x16x32_bf16 v[32:35], v[168:171], v[206:209], v[32:35]
	v_mfma_f32_16x16x32_bf16 v[24:27], v[160:163], v[214:217], v[24:27]
	v_mfma_f32_16x16x32_bf16 v[16:19], v[168:171], v[214:217], v[16:19]
	v_mfma_f32_16x16x32_bf16 v[8:11], v[160:163], v[224:227], v[8:11]
	v_mfma_f32_16x16x32_bf16 v[0:3], v[168:171], v[224:227], v[0:3]
	v_mfma_f32_16x16x32_bf16 v[56:59], v[164:167], v[194:197], v[56:59]
	v_mfma_f32_16x16x32_bf16 v[48:51], v[172:175], v[194:197], v[48:51]
	v_mfma_f32_16x16x32_bf16 v[40:43], v[164:167], v[210:213], v[40:43]
	v_mfma_f32_16x16x32_bf16 v[32:35], v[172:175], v[210:213], v[32:35]
	v_mfma_f32_16x16x32_bf16 v[24:27], v[164:167], v[220:223], v[24:27]
	v_mfma_f32_16x16x32_bf16 v[16:19], v[172:175], v[220:223], v[16:19]
	v_mfma_f32_16x16x32_bf16 v[8:11], v[164:167], v[228:231], v[8:11]
	v_mfma_f32_16x16x32_bf16 v[0:3], v[172:175], v[228:231], v[0:3]
	s_barrier
	s_cmp_lg_u32 s99, 0
	s_cbranch_scc1 .Lpeelx_14
.LBB0_1144:
	v_add_u32_e32 v156, s63, v151
	v_add_u32_e32 v172, s31, v151
	ds_read_b128 v[128:131], v156
	ds_read_b128 v[142:145], v156 offset:1024
	ds_read_b128 v[146:149], v156 offset:2048
	ds_read_b128 v[156:159], v156 offset:3072
	ds_read_b128 v[160:163], v172
	ds_read_b128 v[164:167], v172 offset:1024
	ds_read_b128 v[168:171], v172 offset:2048
	ds_read_b128 v[172:175], v172 offset:3072
	v_lshl_add_u64 v[198:199], s[28:29], 0, v[138:139]
	s_add_i32 m0, s37, 0xc000
	ds_read_b128 v[176:179], v155
	ds_read_b128 v[194:197], v155 offset:1024
	ds_read_b128 v[206:209], v155 offset:2048
	ds_read_b128 v[210:213], v155 offset:3072
	ds_read_b128 v[214:217], v155 offset:4096
	ds_read_b128 v[220:223], v155 offset:5120
	ds_read_b128 v[224:227], v155 offset:6144
	ds_read_b128 v[228:231], v155 offset:7168
	global_load_lds_dwordx4 v[198:199], off
	v_lshl_add_u64 v[198:199], s[28:29], 0, v[140:141]
	s_add_i32 m0, s37, 0xe000
	s_nop 0
	global_load_lds_dwordx4 v[198:199], off
	s_waitcnt vmcnt(8)
	s_waitcnt lgkmcnt(0)
	s_barrier
	s_waitcnt lgkmcnt(0)
	v_mfma_f32_16x16x32_bf16 v[120:123], v[128:131], v[176:179], v[120:123]
	v_mfma_f32_16x16x32_bf16 v[116:119], v[146:149], v[176:179], v[116:119]
	v_lshl_add_u64 v[198:199], s[44:45], 0, v[180:181]
	v_mfma_f32_16x16x32_bf16 v[108:111], v[128:131], v[206:209], v[108:111]
	v_lshl_add_u64 v[202:203], s[44:45], 0, v[132:133]
	v_mfma_f32_16x16x32_bf16 v[100:103], v[146:149], v[206:209], v[100:103]
	s_add_u32 s44, s44, s6
	v_mfma_f32_16x16x32_bf16 v[92:95], v[128:131], v[214:217], v[92:95]
	s_addc_u32 s45, s45, s7
	v_mfma_f32_16x16x32_bf16 v[84:87], v[146:149], v[214:217], v[84:87]
	v_lshl_add_u64 v[232:233], s[44:45], 0, v[180:181]
	v_mfma_f32_16x16x32_bf16 v[76:79], v[128:131], v[224:227], v[76:79]
	v_lshl_add_u64 v[234:235], s[44:45], 0, v[132:133]
	v_mfma_f32_16x16x32_bf16 v[68:71], v[146:149], v[224:227], v[68:71]
	v_lshl_add_u64 v[236:237], s[16:17], 0, v[136:137]
	v_mfma_f32_16x16x32_bf16 v[120:123], v[142:145], v[194:197], v[120:123]
	v_lshl_add_u64 v[238:239], s[16:17], 0, v[134:135]
	v_mfma_f32_16x16x32_bf16 v[116:119], v[156:159], v[194:197], v[116:119]
	v_mfma_f32_16x16x32_bf16 v[108:111], v[142:145], v[210:213], v[108:111]
	v_mfma_f32_16x16x32_bf16 v[100:103], v[156:159], v[210:213], v[100:103]
	v_mfma_f32_16x16x32_bf16 v[92:95], v[142:145], v[220:223], v[92:95]
	v_mfma_f32_16x16x32_bf16 v[84:87], v[156:159], v[220:223], v[84:87]
	v_mfma_f32_16x16x32_bf16 v[76:79], v[142:145], v[228:231], v[76:79]
	v_mfma_f32_16x16x32_bf16 v[68:71], v[156:159], v[228:231], v[68:71]
	v_mfma_f32_16x16x32_bf16 v[124:127], v[160:163], v[176:179], v[124:127]
	v_mfma_f32_16x16x32_bf16 v[112:115], v[168:171], v[176:179], v[112:115]
	v_mfma_f32_16x16x32_bf16 v[104:107], v[160:163], v[206:209], v[104:107]
	v_mfma_f32_16x16x32_bf16 v[96:99], v[168:171], v[206:209], v[96:99]
	v_mfma_f32_16x16x32_bf16 v[88:91], v[160:163], v[214:217], v[88:91]
	v_mfma_f32_16x16x32_bf16 v[80:83], v[168:171], v[214:217], v[80:83]
	v_mfma_f32_16x16x32_bf16 v[72:75], v[160:163], v[224:227], v[72:75]
	v_mfma_f32_16x16x32_bf16 v[64:67], v[168:171], v[224:227], v[64:67]
	v_mfma_f32_16x16x32_bf16 v[124:127], v[164:167], v[194:197], v[124:127]
	v_mfma_f32_16x16x32_bf16 v[112:115], v[172:175], v[194:197], v[112:115]
	v_mfma_f32_16x16x32_bf16 v[104:107], v[164:167], v[210:213], v[104:107]
	v_mfma_f32_16x16x32_bf16 v[96:99], v[172:175], v[210:213], v[96:99]
	v_mfma_f32_16x16x32_bf16 v[88:91], v[164:167], v[220:223], v[88:91]
	v_mfma_f32_16x16x32_bf16 v[80:83], v[172:175], v[220:223], v[80:83]
	v_mfma_f32_16x16x32_bf16 v[72:75], v[164:167], v[228:231], v[72:75]
	v_mfma_f32_16x16x32_bf16 v[64:67], v[172:175], v[228:231], v[64:67]
	s_barrier
	s_add_i32 s63, s63, s36
	s_mov_b32 m0, s63
	ds_read_b128 v[176:179], v155 offset:16384
	ds_read_b128 v[194:197], v155 offset:17408
	ds_read_b128 v[206:209], v155 offset:18432
	ds_read_b128 v[210:213], v155 offset:19456
	ds_read_b128 v[214:217], v155 offset:20480
	ds_read_b128 v[220:223], v155 offset:21504
	ds_read_b128 v[224:227], v155 offset:22528
	ds_read_b128 v[228:231], v155 offset:23552
	global_load_lds_dwordx4 v[198:199], off
	s_add_i32 m0, s63, 0x2000
	s_add_i32 s31, s31, s36
	global_load_lds_dwordx4 v[202:203], off
	s_mov_b32 m0, s31
	s_nop 0
	global_load_lds_dwordx4 v[232:233], off
	s_add_i32 m0, s31, 0x2000
	s_nop 0
	global_load_lds_dwordx4 v[234:235], off
	s_mov_b32 m0, s37
	s_nop 0
	global_load_lds_dwordx4 v[236:237], off
	s_mov_b32 m0, s38
	s_nop 0
	global_load_lds_dwordx4 v[238:239], off
	s_waitcnt vmcnt(8)
	s_waitcnt lgkmcnt(0)
	s_barrier
	s_waitcnt lgkmcnt(0)
	v_mfma_f32_16x16x32_bf16 v[60:63], v[128:131], v[176:179], v[60:63]
	v_mfma_f32_16x16x32_bf16 v[52:55], v[146:149], v[176:179], v[52:55]
	v_mfma_f32_16x16x32_bf16 v[44:47], v[128:131], v[206:209], v[44:47]
	v_mfma_f32_16x16x32_bf16 v[36:39], v[146:149], v[206:209], v[36:39]
	v_mfma_f32_16x16x32_bf16 v[28:31], v[128:131], v[214:217], v[28:31]
	v_mfma_f32_16x16x32_bf16 v[20:23], v[146:149], v[214:217], v[20:23]
	v_mfma_f32_16x16x32_bf16 v[12:15], v[128:131], v[224:227], v[12:15]
	v_mfma_f32_16x16x32_bf16 v[4:7], v[146:149], v[224:227], v[4:7]
	v_mfma_f32_16x16x32_bf16 v[60:63], v[142:145], v[194:197], v[60:63]
	v_mfma_f32_16x16x32_bf16 v[52:55], v[156:159], v[194:197], v[52:55]
	v_mfma_f32_16x16x32_bf16 v[44:47], v[142:145], v[210:213], v[44:47]
	v_mfma_f32_16x16x32_bf16 v[36:39], v[156:159], v[210:213], v[36:39]
	v_mfma_f32_16x16x32_bf16 v[28:31], v[142:145], v[220:223], v[28:31]
	v_mfma_f32_16x16x32_bf16 v[20:23], v[156:159], v[220:223], v[20:23]
	v_mfma_f32_16x16x32_bf16 v[12:15], v[142:145], v[228:231], v[12:15]
	v_mfma_f32_16x16x32_bf16 v[4:7], v[156:159], v[228:231], v[4:7]
	v_mfma_f32_16x16x32_bf16 v[56:59], v[160:163], v[176:179], v[56:59]
	v_mfma_f32_16x16x32_bf16 v[48:51], v[168:171], v[176:179], v[48:51]
	v_mfma_f32_16x16x32_bf16 v[40:43], v[160:163], v[206:209], v[40:43]
	v_mfma_f32_16x16x32_bf16 v[32:35], v[168:171], v[206:209], v[32:35]
	v_mfma_f32_16x16x32_bf16 v[24:27], v[160:163], v[214:217], v[24:27]
	v_mfma_f32_16x16x32_bf16 v[16:19], v[168:171], v[214:217], v[16:19]
	v_mfma_f32_16x16x32_bf16 v[8:11], v[160:163], v[224:227], v[8:11]
	v_mfma_f32_16x16x32_bf16 v[0:3], v[168:171], v[224:227], v[0:3]
	v_mfma_f32_16x16x32_bf16 v[56:59], v[164:167], v[194:197], v[56:59]
	v_mfma_f32_16x16x32_bf16 v[48:51], v[172:175], v[194:197], v[48:51]
	v_mfma_f32_16x16x32_bf16 v[40:43], v[164:167], v[210:213], v[40:43]
	v_mfma_f32_16x16x32_bf16 v[32:35], v[172:175], v[210:213], v[32:35]
	v_mfma_f32_16x16x32_bf16 v[24:27], v[164:167], v[220:223], v[24:27]
	v_mfma_f32_16x16x32_bf16 v[16:19], v[172:175], v[220:223], v[16:19]
	v_mfma_f32_16x16x32_bf16 v[8:11], v[164:167], v[228:231], v[8:11]
	v_mfma_f32_16x16x32_bf16 v[0:3], v[172:175], v[228:231], v[0:3]
	s_barrier
	s_add_i32 s31, 0, 0x18000
	s_add_i32 s44, 0, 0x1c000
	v_add_u32_e32 v156, s31, v151
	v_add_u32_e32 v172, s44, v151
	ds_read_b128 v[128:131], v156
	ds_read_b128 v[142:145], v156 offset:1024
	ds_read_b128 v[146:149], v156 offset:2048
	ds_read_b128 v[156:159], v156 offset:3072
	ds_read_b128 v[160:163], v172
	ds_read_b128 v[164:167], v172 offset:1024
	ds_read_b128 v[168:171], v172 offset:2048
	ds_read_b128 v[172:175], v172 offset:3072
	s_add_u32 s16, s16, s6
	s_addc_u32 s17, s17, s7
	s_mov_b32 m0, s39
	v_lshl_add_u64 v[240:241], s[16:17], 0, v[136:137]
	ds_read_b128 v[176:179], v155 offset:32768
	ds_read_b128 v[194:197], v155 offset:33792
	ds_read_b128 v[206:209], v155 offset:34816
	ds_read_b128 v[210:213], v155 offset:35840
	ds_read_b128 v[214:217], v155 offset:36864
	ds_read_b128 v[220:223], v155 offset:37888
	ds_read_b128 v[224:227], v155 offset:38912
	ds_read_b128 v[228:231], v155 offset:39936
	global_load_lds_dwordx4 v[240:241], off
	v_lshl_add_u64 v[240:241], s[16:17], 0, v[134:135]
	s_mov_b32 m0, s46
	s_nop 0
	global_load_lds_dwordx4 v[240:241], off
	s_waitcnt vmcnt(8)
	s_waitcnt lgkmcnt(0)
	s_barrier
	s_waitcnt lgkmcnt(0)
	v_mfma_f32_16x16x32_bf16 v[120:123], v[128:131], v[176:179], v[120:123]
	v_mfma_f32_16x16x32_bf16 v[116:119], v[146:149], v[176:179], v[116:119]
	v_lshl_add_u64 v[198:199], v[198:199], 0, s[12:13]
	v_mfma_f32_16x16x32_bf16 v[108:111], v[128:131], v[206:209], v[108:111]
	v_lshl_add_u64 v[202:203], v[202:203], 0, s[12:13]
	v_mfma_f32_16x16x32_bf16 v[100:103], v[146:149], v[206:209], v[100:103]
	v_lshl_add_u64 v[232:233], v[232:233], 0, s[12:13]
	v_mfma_f32_16x16x32_bf16 v[92:95], v[128:131], v[214:217], v[92:95]
	v_lshl_add_u64 v[234:235], v[234:235], 0, s[12:13]
	v_mfma_f32_16x16x32_bf16 v[84:87], v[146:149], v[214:217], v[84:87]
	v_lshl_add_u64 v[236:237], v[236:237], 0, s[12:13]
	v_mfma_f32_16x16x32_bf16 v[76:79], v[128:131], v[224:227], v[76:79]
	v_lshl_add_u64 v[238:239], v[238:239], 0, s[12:13]
	v_mfma_f32_16x16x32_bf16 v[68:71], v[146:149], v[224:227], v[68:71]
	v_mfma_f32_16x16x32_bf16 v[120:123], v[142:145], v[194:197], v[120:123]
	v_mfma_f32_16x16x32_bf16 v[116:119], v[156:159], v[194:197], v[116:119]
	v_mfma_f32_16x16x32_bf16 v[108:111], v[142:145], v[210:213], v[108:111]
	v_mfma_f32_16x16x32_bf16 v[100:103], v[156:159], v[210:213], v[100:103]
	v_mfma_f32_16x16x32_bf16 v[92:95], v[142:145], v[220:223], v[92:95]
	v_mfma_f32_16x16x32_bf16 v[84:87], v[156:159], v[220:223], v[84:87]
	v_mfma_f32_16x16x32_bf16 v[76:79], v[142:145], v[228:231], v[76:79]
	v_mfma_f32_16x16x32_bf16 v[68:71], v[156:159], v[228:231], v[68:71]
	v_mfma_f32_16x16x32_bf16 v[124:127], v[160:163], v[176:179], v[124:127]
	v_mfma_f32_16x16x32_bf16 v[112:115], v[168:171], v[176:179], v[112:115]
	v_mfma_f32_16x16x32_bf16 v[104:107], v[160:163], v[206:209], v[104:107]
	v_mfma_f32_16x16x32_bf16 v[96:99], v[168:171], v[206:209], v[96:99]
	v_mfma_f32_16x16x32_bf16 v[88:91], v[160:163], v[214:217], v[88:91]
	v_mfma_f32_16x16x32_bf16 v[80:83], v[168:171], v[214:217], v[80:83]
	v_mfma_f32_16x16x32_bf16 v[72:75], v[160:163], v[224:227], v[72:75]
	v_mfma_f32_16x16x32_bf16 v[64:67], v[168:171], v[224:227], v[64:67]
	v_mfma_f32_16x16x32_bf16 v[124:127], v[164:167], v[194:197], v[124:127]
	v_mfma_f32_16x16x32_bf16 v[112:115], v[172:175], v[194:197], v[112:115]
	v_mfma_f32_16x16x32_bf16 v[104:107], v[164:167], v[210:213], v[104:107]
	v_mfma_f32_16x16x32_bf16 v[96:99], v[172:175], v[210:213], v[96:99]
	v_mfma_f32_16x16x32_bf16 v[88:91], v[164:167], v[220:223], v[88:91]
	v_mfma_f32_16x16x32_bf16 v[80:83], v[172:175], v[220:223], v[80:83]
	v_mfma_f32_16x16x32_bf16 v[72:75], v[164:167], v[228:231], v[72:75]
	v_mfma_f32_16x16x32_bf16 v[64:67], v[172:175], v[228:231], v[64:67]
	s_barrier
	s_add_i32 s16, s31, s36
	s_mov_b32 m0, s16
	ds_read_b128 v[176:179], v155 offset:49152
	ds_read_b128 v[194:197], v155 offset:50176
	ds_read_b128 v[206:209], v155 offset:51200
	ds_read_b128 v[210:213], v155 offset:52224
	ds_read_b128 v[214:217], v155 offset:53248
	ds_read_b128 v[220:223], v155 offset:54272
	ds_read_b128 v[224:227], v155 offset:55296
	ds_read_b128 v[228:231], v155 offset:56320
	global_load_lds_dwordx4 v[198:199], off
	s_add_i32 m0, s16, 0x2000
	s_add_i32 s16, s44, s36
	global_load_lds_dwordx4 v[202:203], off
	s_mov_b32 m0, s16
	s_nop 0
	global_load_lds_dwordx4 v[232:233], off
	s_add_i32 m0, s16, 0x2000
	s_nop 0
	global_load_lds_dwordx4 v[234:235], off
	s_mov_b32 m0, s49
	s_nop 0
	global_load_lds_dwordx4 v[236:237], off
	s_mov_b32 m0, s52
	s_nop 0
	global_load_lds_dwordx4 v[238:239], off
	s_waitcnt vmcnt(8)
	s_waitcnt lgkmcnt(0)
	s_barrier
	s_waitcnt lgkmcnt(0)
	v_mfma_f32_16x16x32_bf16 v[60:63], v[128:131], v[176:179], v[60:63]
	s_add_u32 s28, s28, 0x100
	v_mfma_f32_16x16x32_bf16 v[52:55], v[146:149], v[176:179], v[52:55]
	s_addc_u32 s29, s29, 0
	v_mfma_f32_16x16x32_bf16 v[44:47], v[128:131], v[206:209], v[44:47]
	s_add_u32 s10, s10, 0x100
	v_mfma_f32_16x16x32_bf16 v[36:39], v[146:149], v[206:209], v[36:39]
	s_addc_u32 s11, s11, 0
	v_mfma_f32_16x16x32_bf16 v[28:31], v[128:131], v[214:217], v[28:31]
	s_mov_b32 s16, s30
	v_mfma_f32_16x16x32_bf16 v[20:23], v[146:149], v[214:217], v[20:23]
	s_cmp_ge_i32 s30, s47
	v_mfma_f32_16x16x32_bf16 v[12:15], v[128:131], v[224:227], v[12:15]
	s_cselect_b32 s99, 1, 0
	v_mfma_f32_16x16x32_bf16 v[4:7], v[146:149], v[224:227], v[4:7]
	s_add_i32 s30, s16, 2
	v_mfma_f32_16x16x32_bf16 v[60:63], v[142:145], v[194:197], v[60:63]
	s_add_u32 s31, s28, 0x80
	v_mfma_f32_16x16x32_bf16 v[52:55], v[156:159], v[194:197], v[52:55]
	s_addc_u32 s17, s29, 0
	v_mfma_f32_16x16x32_bf16 v[44:47], v[142:145], v[210:213], v[44:47]
	s_add_i32 s63, 0, 0x10000
	v_mfma_f32_16x16x32_bf16 v[36:39], v[156:159], v[210:213], v[36:39]
	s_cmp_eq_u32 s56, s16
	v_mfma_f32_16x16x32_bf16 v[28:31], v[142:145], v[220:223], v[28:31]
	s_cselect_b32 s17, s25, s17
	v_mfma_f32_16x16x32_bf16 v[20:23], v[156:159], v[220:223], v[20:23]
	s_cselect_b32 s16, s24, s31
	v_mfma_f32_16x16x32_bf16 v[12:15], v[142:145], v[228:231], v[12:15]
	s_cselect_b32 s45, s27, s11
	v_mfma_f32_16x16x32_bf16 v[4:7], v[156:159], v[228:231], v[4:7]
	s_cselect_b32 s44, s26, s10
	v_mfma_f32_16x16x32_bf16 v[56:59], v[160:163], v[176:179], v[56:59]
	s_add_i32 s31, 0, 0x14000
	v_mfma_f32_16x16x32_bf16 v[48:51], v[168:171], v[176:179], v[48:51]
	v_mfma_f32_16x16x32_bf16 v[40:43], v[160:163], v[206:209], v[40:43]
	v_mfma_f32_16x16x32_bf16 v[32:35], v[168:171], v[206:209], v[32:35]
	v_mfma_f32_16x16x32_bf16 v[24:27], v[160:163], v[214:217], v[24:27]
	v_mfma_f32_16x16x32_bf16 v[16:19], v[168:171], v[214:217], v[16:19]
	v_mfma_f32_16x16x32_bf16 v[8:11], v[160:163], v[224:227], v[8:11]
	v_mfma_f32_16x16x32_bf16 v[0:3], v[168:171], v[224:227], v[0:3]
	v_mfma_f32_16x16x32_bf16 v[56:59], v[164:167], v[194:197], v[56:59]
	v_mfma_f32_16x16x32_bf16 v[48:51], v[172:175], v[194:197], v[48:51]
	v_mfma_f32_16x16x32_bf16 v[40:43], v[164:167], v[210:213], v[40:43]
	v_mfma_f32_16x16x32_bf16 v[32:35], v[172:175], v[210:213], v[32:35]
	v_mfma_f32_16x16x32_bf16 v[24:27], v[164:167], v[220:223], v[24:27]
	v_mfma_f32_16x16x32_bf16 v[16:19], v[172:175], v[220:223], v[16:19]
	v_mfma_f32_16x16x32_bf16 v[8:11], v[164:167], v[228:231], v[8:11]
	v_mfma_f32_16x16x32_bf16 v[0:3], v[172:175], v[228:231], v[0:3]
	s_barrier
	s_cmp_lg_u32 s99, 0
	s_cbranch_scc0 .LBB0_1144

.Llbb_11:
	s_add_i32 s44, s28, 2
	s_add_u32 s45, s26, 0x80
	s_addc_u32 s29, s27, 0
	s_add_i32 s62, 0, 0x10000
	s_cmp_eq_u32 s49, s28
	s_cselect_b32 s29, s23, s29
	s_cselect_b32 s28, s22, s45
	s_cselect_b32 s61, s25, s11
	s_cselect_b32 s60, s24, s10
	s_add_i32 s45, 0, 0x14000
	v_add_u32_e32 v140, s62, v199
	v_add_u32_e32 v166, s45, v199
	ds_read_b128 v[128:131], v140
	ds_read_b128 v[132:135], v140 offset:1024
	ds_read_b128 v[136:139], v140 offset:2048
	ds_read_b128 v[140:143], v140 offset:3072
	ds_read_b128 v[144:147], v166
	ds_read_b128 v[148:151], v166 offset:1024
	ds_read_b128 v[152:155], v166 offset:2048
	ds_read_b128 v[166:169], v166 offset:3072
	v_lshl_add_u64 v[178:179], s[26:27], 0, v[162:163]
	s_add_i32 m0, s35, 0xc000
	ds_read_b128 v[170:173], v206
	ds_read_b128 v[174:177], v206 offset:1024
	ds_read_b128 v[194:197], v206 offset:2048
	ds_read_b128 v[208:211], v206 offset:3072
	ds_read_b128 v[212:215], v206 offset:4096
	ds_read_b128 v[220:223], v206 offset:5120
	ds_read_b128 v[224:227], v206 offset:6144
	ds_read_b128 v[228:231], v206 offset:7168
	global_load_lds_dwordx4 v[178:179], off
	v_lshl_add_u64 v[178:179], s[26:27], 0, v[164:165]
	s_add_i32 m0, s35, 0xe000
	s_nop 0
	global_load_lds_dwordx4 v[178:179], off
	s_waitcnt vmcnt(8)
	s_waitcnt lgkmcnt(0)
	s_barrier
	s_waitcnt lgkmcnt(0)
	v_mfma_f32_16x16x32_bf16 v[120:123], v[128:131], v[170:173], 0
	v_mfma_f32_16x16x32_bf16 v[124:127], v[136:139], v[170:173], 0
	v_lshl_add_u64 v[178:179], s[60:61], 0, v[180:181]
	v_mfma_f32_16x16x32_bf16 v[108:111], v[128:131], v[194:197], 0
	v_lshl_add_u64 v[202:203], s[60:61], 0, v[156:157]
	v_mfma_f32_16x16x32_bf16 v[104:107], v[136:139], v[194:197], 0
	s_add_u32 s60, s60, s6
	v_mfma_f32_16x16x32_bf16 v[92:95], v[128:131], v[212:215], 0
	s_addc_u32 s61, s61, s7
	v_mfma_f32_16x16x32_bf16 v[88:91], v[136:139], v[212:215], 0
	v_lshl_add_u64 v[216:217], s[60:61], 0, v[180:181]
	v_mfma_f32_16x16x32_bf16 v[76:79], v[128:131], v[224:227], 0
	v_lshl_add_u64 v[232:233], s[60:61], 0, v[156:157]
	v_mfma_f32_16x16x32_bf16 v[72:75], v[136:139], v[224:227], 0
	v_lshl_add_u64 v[234:235], s[28:29], 0, v[160:161]
	v_mfma_f32_16x16x32_bf16 v[120:123], v[132:135], v[174:177], v[120:123]
	v_lshl_add_u64 v[236:237], s[28:29], 0, v[158:159]
	v_mfma_f32_16x16x32_bf16 v[124:127], v[140:143], v[174:177], v[124:127]
	v_mfma_f32_16x16x32_bf16 v[108:111], v[132:135], v[208:211], v[108:111]
	v_mfma_f32_16x16x32_bf16 v[104:107], v[140:143], v[208:211], v[104:107]
	v_mfma_f32_16x16x32_bf16 v[92:95], v[132:135], v[220:223], v[92:95]
	v_mfma_f32_16x16x32_bf16 v[88:91], v[140:143], v[220:223], v[88:91]
	v_mfma_f32_16x16x32_bf16 v[76:79], v[132:135], v[228:231], v[76:79]
	v_mfma_f32_16x16x32_bf16 v[72:75], v[140:143], v[228:231], v[72:75]
	v_mfma_f32_16x16x32_bf16 v[116:119], v[144:147], v[170:173], 0
	v_mfma_f32_16x16x32_bf16 v[112:115], v[152:155], v[170:173], 0
	v_mfma_f32_16x16x32_bf16 v[100:103], v[144:147], v[194:197], 0
	v_mfma_f32_16x16x32_bf16 v[96:99], v[152:155], v[194:197], 0
	v_mfma_f32_16x16x32_bf16 v[84:87], v[144:147], v[212:215], 0
	v_mfma_f32_16x16x32_bf16 v[80:83], v[152:155], v[212:215], 0
	v_mfma_f32_16x16x32_bf16 v[68:71], v[144:147], v[224:227], 0
	v_mfma_f32_16x16x32_bf16 v[64:67], v[152:155], v[224:227], 0
	v_mfma_f32_16x16x32_bf16 v[116:119], v[148:151], v[174:177], v[116:119]
	v_mfma_f32_16x16x32_bf16 v[112:115], v[166:169], v[174:177], v[112:115]
	v_mfma_f32_16x16x32_bf16 v[100:103], v[148:151], v[208:211], v[100:103]
	v_mfma_f32_16x16x32_bf16 v[96:99], v[166:169], v[208:211], v[96:99]
	v_mfma_f32_16x16x32_bf16 v[84:87], v[148:151], v[220:223], v[84:87]
	v_mfma_f32_16x16x32_bf16 v[80:83], v[166:169], v[220:223], v[80:83]
	v_mfma_f32_16x16x32_bf16 v[68:71], v[148:151], v[228:231], v[68:71]
	v_mfma_f32_16x16x32_bf16 v[64:67], v[166:169], v[228:231], v[64:67]
	s_barrier
	s_add_i32 s62, s62, s34
	s_mov_b32 m0, s62
	ds_read_b128 v[170:173], v206 offset:16384
	ds_read_b128 v[174:177], v206 offset:17408
	ds_read_b128 v[194:197], v206 offset:18432
	ds_read_b128 v[208:211], v206 offset:19456
	ds_read_b128 v[212:215], v206 offset:20480
	ds_read_b128 v[220:223], v206 offset:21504
	ds_read_b128 v[224:227], v206 offset:22528
	ds_read_b128 v[228:231], v206 offset:23552
	global_load_lds_dwordx4 v[178:179], off
	s_add_i32 m0, s62, 0x2000
	s_add_i32 s45, s45, s34
	global_load_lds_dwordx4 v[202:203], off
	s_mov_b32 m0, s45
	s_nop 0
	global_load_lds_dwordx4 v[216:217], off
	s_add_i32 m0, s45, 0x2000
	s_nop 0
	global_load_lds_dwordx4 v[232:233], off
	s_mov_b32 m0, s35
	s_nop 0
	global_load_lds_dwordx4 v[234:235], off
	s_mov_b32 m0, s36
	s_nop 0
	global_load_lds_dwordx4 v[236:237], off
	s_waitcnt vmcnt(8)
	s_waitcnt lgkmcnt(0)
	s_barrier
	s_waitcnt lgkmcnt(0)
	v_mfma_f32_16x16x32_bf16 v[60:63], v[128:131], v[170:173], 0
	v_mfma_f32_16x16x32_bf16 v[56:59], v[136:139], v[170:173], 0
	v_mfma_f32_16x16x32_bf16 v[44:47], v[128:131], v[194:197], 0
	v_mfma_f32_16x16x32_bf16 v[40:43], v[136:139], v[194:197], 0
	v_mfma_f32_16x16x32_bf16 v[28:31], v[128:131], v[212:215], 0
	v_mfma_f32_16x16x32_bf16 v[24:27], v[136:139], v[212:215], 0
	v_mfma_f32_16x16x32_bf16 v[12:15], v[128:131], v[224:227], 0
	v_mfma_f32_16x16x32_bf16 v[8:11], v[136:139], v[224:227], 0
	v_mfma_f32_16x16x32_bf16 v[60:63], v[132:135], v[174:177], v[60:63]
	v_mfma_f32_16x16x32_bf16 v[56:59], v[140:143], v[174:177], v[56:59]
	v_mfma_f32_16x16x32_bf16 v[44:47], v[132:135], v[208:211], v[44:47]
	v_mfma_f32_16x16x32_bf16 v[40:43], v[140:143], v[208:211], v[40:43]
	v_mfma_f32_16x16x32_bf16 v[28:31], v[132:135], v[220:223], v[28:31]
	v_mfma_f32_16x16x32_bf16 v[24:27], v[140:143], v[220:223], v[24:27]
	v_mfma_f32_16x16x32_bf16 v[12:15], v[132:135], v[228:231], v[12:15]
	v_mfma_f32_16x16x32_bf16 v[8:11], v[140:143], v[228:231], v[8:11]
	v_mfma_f32_16x16x32_bf16 v[52:55], v[144:147], v[170:173], 0
	v_mfma_f32_16x16x32_bf16 v[48:51], v[152:155], v[170:173], 0
	v_mfma_f32_16x16x32_bf16 v[36:39], v[144:147], v[194:197], 0
	v_mfma_f32_16x16x32_bf16 v[32:35], v[152:155], v[194:197], 0
	v_mfma_f32_16x16x32_bf16 v[20:23], v[144:147], v[212:215], 0
	v_mfma_f32_16x16x32_bf16 v[16:19], v[152:155], v[212:215], 0
	v_mfma_f32_16x16x32_bf16 v[4:7], v[144:147], v[224:227], 0
	v_mfma_f32_16x16x32_bf16 v[0:3], v[152:155], v[224:227], 0
	v_mfma_f32_16x16x32_bf16 v[52:55], v[148:151], v[174:177], v[52:55]
	v_mfma_f32_16x16x32_bf16 v[48:51], v[166:169], v[174:177], v[48:51]
	v_mfma_f32_16x16x32_bf16 v[36:39], v[148:151], v[208:211], v[36:39]
	v_mfma_f32_16x16x32_bf16 v[32:35], v[166:169], v[208:211], v[32:35]
	v_mfma_f32_16x16x32_bf16 v[20:23], v[148:151], v[220:223], v[20:23]
	v_mfma_f32_16x16x32_bf16 v[16:19], v[166:169], v[220:223], v[16:19]
	v_mfma_f32_16x16x32_bf16 v[4:7], v[148:151], v[228:231], v[4:7]
	v_mfma_f32_16x16x32_bf16 v[0:3], v[166:169], v[228:231], v[0:3]
	s_barrier
	s_add_i32 s45, 0, 0x18000
	s_add_i32 s60, 0, 0x1c000
	v_add_u32_e32 v140, s45, v199
	v_add_u32_e32 v166, s60, v199
	ds_read_b128 v[128:131], v140
	ds_read_b128 v[132:135], v140 offset:1024
	ds_read_b128 v[136:139], v140 offset:2048
	ds_read_b128 v[140:143], v140 offset:3072
	ds_read_b128 v[144:147], v166
	ds_read_b128 v[148:151], v166 offset:1024
	ds_read_b128 v[152:155], v166 offset:2048
	ds_read_b128 v[166:169], v166 offset:3072
	s_add_u32 s28, s28, s6
	s_addc_u32 s29, s29, s7
	s_mov_b32 m0, s37
	v_lshl_add_u64 v[238:239], s[28:29], 0, v[160:161]
	ds_read_b128 v[170:173], v206 offset:32768
	ds_read_b128 v[174:177], v206 offset:33792
	ds_read_b128 v[194:197], v206 offset:34816
	ds_read_b128 v[208:211], v206 offset:35840
	ds_read_b128 v[212:215], v206 offset:36864
	ds_read_b128 v[220:223], v206 offset:37888
	ds_read_b128 v[224:227], v206 offset:38912
	ds_read_b128 v[228:231], v206 offset:39936
	global_load_lds_dwordx4 v[238:239], off
	v_lshl_add_u64 v[238:239], s[28:29], 0, v[158:159]
	s_mov_b32 m0, s38
	s_nop 0
	global_load_lds_dwordx4 v[238:239], off
	s_waitcnt vmcnt(8)
	s_waitcnt lgkmcnt(0)
	s_barrier
	s_waitcnt lgkmcnt(0)
	v_mfma_f32_16x16x32_bf16 v[120:123], v[128:131], v[170:173], v[120:123]
	v_mfma_f32_16x16x32_bf16 v[124:127], v[136:139], v[170:173], v[124:127]
	v_lshl_add_u64 v[178:179], v[178:179], 0, s[12:13]
	v_mfma_f32_16x16x32_bf16 v[108:111], v[128:131], v[194:197], v[108:111]
	v_lshl_add_u64 v[202:203], v[202:203], 0, s[12:13]
	v_mfma_f32_16x16x32_bf16 v[104:107], v[136:139], v[194:197], v[104:107]
	v_lshl_add_u64 v[216:217], v[216:217], 0, s[12:13]
	v_mfma_f32_16x16x32_bf16 v[92:95], v[128:131], v[212:215], v[92:95]
	v_lshl_add_u64 v[232:233], v[232:233], 0, s[12:13]
	v_mfma_f32_16x16x32_bf16 v[88:91], v[136:139], v[212:215], v[88:91]
	v_lshl_add_u64 v[234:235], v[234:235], 0, s[12:13]
	v_mfma_f32_16x16x32_bf16 v[76:79], v[128:131], v[224:227], v[76:79]
	v_lshl_add_u64 v[236:237], v[236:237], 0, s[12:13]
	v_mfma_f32_16x16x32_bf16 v[72:75], v[136:139], v[224:227], v[72:75]
	v_mfma_f32_16x16x32_bf16 v[120:123], v[132:135], v[174:177], v[120:123]
	v_mfma_f32_16x16x32_bf16 v[124:127], v[140:143], v[174:177], v[124:127]
	v_mfma_f32_16x16x32_bf16 v[108:111], v[132:135], v[208:211], v[108:111]
	v_mfma_f32_16x16x32_bf16 v[104:107], v[140:143], v[208:211], v[104:107]
	v_mfma_f32_16x16x32_bf16 v[92:95], v[132:135], v[220:223], v[92:95]
	v_mfma_f32_16x16x32_bf16 v[88:91], v[140:143], v[220:223], v[88:91]
	v_mfma_f32_16x16x32_bf16 v[76:79], v[132:135], v[228:231], v[76:79]
	v_mfma_f32_16x16x32_bf16 v[72:75], v[140:143], v[228:231], v[72:75]
	v_mfma_f32_16x16x32_bf16 v[116:119], v[144:147], v[170:173], v[116:119]
	v_mfma_f32_16x16x32_bf16 v[112:115], v[152:155], v[170:173], v[112:115]
	v_mfma_f32_16x16x32_bf16 v[100:103], v[144:147], v[194:197], v[100:103]
	v_mfma_f32_16x16x32_bf16 v[96:99], v[152:155], v[194:197], v[96:99]
	v_mfma_f32_16x16x32_bf16 v[84:87], v[144:147], v[212:215], v[84:87]
	v_mfma_f32_16x16x32_bf16 v[80:83], v[152:155], v[212:215], v[80:83]
	v_mfma_f32_16x16x32_bf16 v[68:71], v[144:147], v[224:227], v[68:71]
	v_mfma_f32_16x16x32_bf16 v[64:67], v[152:155], v[224:227], v[64:67]
	v_mfma_f32_16x16x32_bf16 v[116:119], v[148:151], v[174:177], v[116:119]
	v_mfma_f32_16x16x32_bf16 v[112:115], v[166:169], v[174:177], v[112:115]
	v_mfma_f32_16x16x32_bf16 v[100:103], v[148:151], v[208:211], v[100:103]
	v_mfma_f32_16x16x32_bf16 v[96:99], v[166:169], v[208:211], v[96:99]
	v_mfma_f32_16x16x32_bf16 v[84:87], v[148:151], v[220:223], v[84:87]
	v_mfma_f32_16x16x32_bf16 v[80:83], v[166:169], v[220:223], v[80:83]
	v_mfma_f32_16x16x32_bf16 v[68:71], v[148:151], v[228:231], v[68:71]
	v_mfma_f32_16x16x32_bf16 v[64:67], v[166:169], v[228:231], v[64:67]
	s_barrier
	s_add_i32 s28, s45, s34
	s_mov_b32 m0, s28
	ds_read_b128 v[170:173], v206 offset:49152
	ds_read_b128 v[174:177], v206 offset:50176
	ds_read_b128 v[194:197], v206 offset:51200
	ds_read_b128 v[208:211], v206 offset:52224
	ds_read_b128 v[212:215], v206 offset:53248
	ds_read_b128 v[220:223], v206 offset:54272
	ds_read_b128 v[224:227], v206 offset:55296
	ds_read_b128 v[228:231], v206 offset:56320
	global_load_lds_dwordx4 v[178:179], off
	s_add_i32 m0, s28, 0x2000
	s_add_i32 s28, s60, s34
	global_load_lds_dwordx4 v[202:203], off
	s_mov_b32 m0, s28
	s_nop 0
	global_load_lds_dwordx4 v[216:217], off
	s_add_i32 m0, s28, 0x2000
	s_nop 0
	global_load_lds_dwordx4 v[232:233], off
	s_mov_b32 m0, s47
	s_nop 0
	global_load_lds_dwordx4 v[234:235], off
	s_mov_b32 m0, s48
	s_nop 0
	global_load_lds_dwordx4 v[236:237], off
	s_waitcnt vmcnt(8)
	s_waitcnt lgkmcnt(0)
	s_barrier
	s_waitcnt lgkmcnt(0)
	v_mfma_f32_16x16x32_bf16 v[60:63], v[128:131], v[170:173], v[60:63]
	s_add_u32 s26, s26, 0x100
	v_mfma_f32_16x16x32_bf16 v[56:59], v[136:139], v[170:173], v[56:59]
	s_addc_u32 s27, s27, 0
	v_mfma_f32_16x16x32_bf16 v[44:47], v[128:131], v[194:197], v[44:47]
	s_add_u32 s10, s10, 0x100
	v_mfma_f32_16x16x32_bf16 v[40:43], v[136:139], v[194:197], v[40:43]
	s_addc_u32 s11, s11, 0
	v_mfma_f32_16x16x32_bf16 v[28:31], v[128:131], v[212:215], v[28:31]
	s_mov_b32 s28, s44
	v_mfma_f32_16x16x32_bf16 v[24:27], v[136:139], v[212:215], v[24:27]
	s_cmp_ge_i32 s44, s46
	v_mfma_f32_16x16x32_bf16 v[12:15], v[128:131], v[224:227], v[12:15]
	s_cselect_b32 s99, 1, 0
	v_mfma_f32_16x16x32_bf16 v[8:11], v[136:139], v[224:227], v[8:11]
	s_add_i32 s44, s28, 2
	v_mfma_f32_16x16x32_bf16 v[60:63], v[132:135], v[174:177], v[60:63]
	s_add_u32 s45, s26, 0x80
	v_mfma_f32_16x16x32_bf16 v[56:59], v[140:143], v[174:177], v[56:59]
	s_addc_u32 s29, s27, 0
	v_mfma_f32_16x16x32_bf16 v[44:47], v[132:135], v[208:211], v[44:47]
	s_add_i32 s62, 0, 0x10000
	v_mfma_f32_16x16x32_bf16 v[40:43], v[140:143], v[208:211], v[40:43]
	s_cmp_eq_u32 s49, s28
	v_mfma_f32_16x16x32_bf16 v[28:31], v[132:135], v[220:223], v[28:31]
	s_cselect_b32 s29, s23, s29
	v_mfma_f32_16x16x32_bf16 v[24:27], v[140:143], v[220:223], v[24:27]
	s_cselect_b32 s28, s22, s45
	v_mfma_f32_16x16x32_bf16 v[12:15], v[132:135], v[228:231], v[12:15]
	s_cselect_b32 s61, s25, s11
	v_mfma_f32_16x16x32_bf16 v[8:11], v[140:143], v[228:231], v[8:11]
	s_cselect_b32 s60, s24, s10
	v_mfma_f32_16x16x32_bf16 v[52:55], v[144:147], v[170:173], v[52:55]
	s_add_i32 s45, 0, 0x14000
	v_mfma_f32_16x16x32_bf16 v[48:51], v[152:155], v[170:173], v[48:51]
	v_mfma_f32_16x16x32_bf16 v[36:39], v[144:147], v[194:197], v[36:39]
	v_mfma_f32_16x16x32_bf16 v[32:35], v[152:155], v[194:197], v[32:35]
	v_mfma_f32_16x16x32_bf16 v[20:23], v[144:147], v[212:215], v[20:23]
	v_mfma_f32_16x16x32_bf16 v[16:19], v[152:155], v[212:215], v[16:19]
	v_mfma_f32_16x16x32_bf16 v[4:7], v[144:147], v[224:227], v[4:7]
	v_mfma_f32_16x16x32_bf16 v[0:3], v[152:155], v[224:227], v[0:3]
	v_mfma_f32_16x16x32_bf16 v[52:55], v[148:151], v[174:177], v[52:55]
	v_mfma_f32_16x16x32_bf16 v[48:51], v[166:169], v[174:177], v[48:51]
	v_mfma_f32_16x16x32_bf16 v[36:39], v[148:151], v[208:211], v[36:39]
	v_mfma_f32_16x16x32_bf16 v[32:35], v[166:169], v[208:211], v[32:35]
	v_mfma_f32_16x16x32_bf16 v[20:23], v[148:151], v[220:223], v[20:23]
	v_mfma_f32_16x16x32_bf16 v[16:19], v[166:169], v[220:223], v[16:19]
	v_mfma_f32_16x16x32_bf16 v[4:7], v[148:151], v[228:231], v[4:7]
	v_mfma_f32_16x16x32_bf16 v[0:3], v[166:169], v[228:231], v[0:3]
	s_barrier
	s_cmp_lg_u32 s99, 0
	s_cbranch_scc1 .Lpeelx_15
.LBB0_1224:
	v_add_u32_e32 v140, s62, v199
	v_add_u32_e32 v166, s45, v199
	ds_read_b128 v[128:131], v140
	ds_read_b128 v[132:135], v140 offset:1024
	ds_read_b128 v[136:139], v140 offset:2048
	ds_read_b128 v[140:143], v140 offset:3072
	ds_read_b128 v[144:147], v166
	ds_read_b128 v[148:151], v166 offset:1024
	ds_read_b128 v[152:155], v166 offset:2048
	ds_read_b128 v[166:169], v166 offset:3072
	v_lshl_add_u64 v[178:179], s[26:27], 0, v[162:163]
	s_add_i32 m0, s35, 0xc000
	ds_read_b128 v[170:173], v206
	ds_read_b128 v[174:177], v206 offset:1024
	ds_read_b128 v[194:197], v206 offset:2048
	ds_read_b128 v[208:211], v206 offset:3072
	ds_read_b128 v[212:215], v206 offset:4096
	ds_read_b128 v[220:223], v206 offset:5120
	ds_read_b128 v[224:227], v206 offset:6144
	ds_read_b128 v[228:231], v206 offset:7168
	global_load_lds_dwordx4 v[178:179], off
	v_lshl_add_u64 v[178:179], s[26:27], 0, v[164:165]
	s_add_i32 m0, s35, 0xe000
	s_nop 0
	global_load_lds_dwordx4 v[178:179], off
	s_waitcnt vmcnt(8)
	s_waitcnt lgkmcnt(0)
	s_barrier
	s_waitcnt lgkmcnt(0)
	v_mfma_f32_16x16x32_bf16 v[120:123], v[128:131], v[170:173], v[120:123]
	v_mfma_f32_16x16x32_bf16 v[124:127], v[136:139], v[170:173], v[124:127]
	v_lshl_add_u64 v[178:179], s[60:61], 0, v[180:181]
	v_mfma_f32_16x16x32_bf16 v[108:111], v[128:131], v[194:197], v[108:111]
	v_lshl_add_u64 v[202:203], s[60:61], 0, v[156:157]
	v_mfma_f32_16x16x32_bf16 v[104:107], v[136:139], v[194:197], v[104:107]
	s_add_u32 s60, s60, s6
	v_mfma_f32_16x16x32_bf16 v[92:95], v[128:131], v[212:215], v[92:95]
	s_addc_u32 s61, s61, s7
	v_mfma_f32_16x16x32_bf16 v[88:91], v[136:139], v[212:215], v[88:91]
	v_lshl_add_u64 v[216:217], s[60:61], 0, v[180:181]
	v_mfma_f32_16x16x32_bf16 v[76:79], v[128:131], v[224:227], v[76:79]
	v_lshl_add_u64 v[232:233], s[60:61], 0, v[156:157]
	v_mfma_f32_16x16x32_bf16 v[72:75], v[136:139], v[224:227], v[72:75]
	v_lshl_add_u64 v[234:235], s[28:29], 0, v[160:161]
	v_mfma_f32_16x16x32_bf16 v[120:123], v[132:135], v[174:177], v[120:123]
	v_lshl_add_u64 v[236:237], s[28:29], 0, v[158:159]
	v_mfma_f32_16x16x32_bf16 v[124:127], v[140:143], v[174:177], v[124:127]
	v_mfma_f32_16x16x32_bf16 v[108:111], v[132:135], v[208:211], v[108:111]
	v_mfma_f32_16x16x32_bf16 v[104:107], v[140:143], v[208:211], v[104:107]
	v_mfma_f32_16x16x32_bf16 v[92:95], v[132:135], v[220:223], v[92:95]
	v_mfma_f32_16x16x32_bf16 v[88:91], v[140:143], v[220:223], v[88:91]
	v_mfma_f32_16x16x32_bf16 v[76:79], v[132:135], v[228:231], v[76:79]
	v_mfma_f32_16x16x32_bf16 v[72:75], v[140:143], v[228:231], v[72:75]
	v_mfma_f32_16x16x32_bf16 v[116:119], v[144:147], v[170:173], v[116:119]
	v_mfma_f32_16x16x32_bf16 v[112:115], v[152:155], v[170:173], v[112:115]
	v_mfma_f32_16x16x32_bf16 v[100:103], v[144:147], v[194:197], v[100:103]
	v_mfma_f32_16x16x32_bf16 v[96:99], v[152:155], v[194:197], v[96:99]
	v_mfma_f32_16x16x32_bf16 v[84:87], v[144:147], v[212:215], v[84:87]
	v_mfma_f32_16x16x32_bf16 v[80:83], v[152:155], v[212:215], v[80:83]
	v_mfma_f32_16x16x32_bf16 v[68:71], v[144:147], v[224:227], v[68:71]
	v_mfma_f32_16x16x32_bf16 v[64:67], v[152:155], v[224:227], v[64:67]
	v_mfma_f32_16x16x32_bf16 v[116:119], v[148:151], v[174:177], v[116:119]
	v_mfma_f32_16x16x32_bf16 v[112:115], v[166:169], v[174:177], v[112:115]
	v_mfma_f32_16x16x32_bf16 v[100:103], v[148:151], v[208:211], v[100:103]
	v_mfma_f32_16x16x32_bf16 v[96:99], v[166:169], v[208:211], v[96:99]
	v_mfma_f32_16x16x32_bf16 v[84:87], v[148:151], v[220:223], v[84:87]
	v_mfma_f32_16x16x32_bf16 v[80:83], v[166:169], v[220:223], v[80:83]
	v_mfma_f32_16x16x32_bf16 v[68:71], v[148:151], v[228:231], v[68:71]
	v_mfma_f32_16x16x32_bf16 v[64:67], v[166:169], v[228:231], v[64:67]
	s_barrier
	s_add_i32 s62, s62, s34
	s_mov_b32 m0, s62
	ds_read_b128 v[170:173], v206 offset:16384
	ds_read_b128 v[174:177], v206 offset:17408
	ds_read_b128 v[194:197], v206 offset:18432
	ds_read_b128 v[208:211], v206 offset:19456
	ds_read_b128 v[212:215], v206 offset:20480
	ds_read_b128 v[220:223], v206 offset:21504
	ds_read_b128 v[224:227], v206 offset:22528
	ds_read_b128 v[228:231], v206 offset:23552
	global_load_lds_dwordx4 v[178:179], off
	s_add_i32 m0, s62, 0x2000
	s_add_i32 s45, s45, s34
	global_load_lds_dwordx4 v[202:203], off
	s_mov_b32 m0, s45
	s_nop 0
	global_load_lds_dwordx4 v[216:217], off
	s_add_i32 m0, s45, 0x2000
	s_nop 0
	global_load_lds_dwordx4 v[232:233], off
	s_mov_b32 m0, s35
	s_nop 0
	global_load_lds_dwordx4 v[234:235], off
	s_mov_b32 m0, s36
	s_nop 0
	global_load_lds_dwordx4 v[236:237], off
	s_waitcnt vmcnt(8)
	s_waitcnt lgkmcnt(0)
	s_barrier
	s_waitcnt lgkmcnt(0)
	v_mfma_f32_16x16x32_bf16 v[60:63], v[128:131], v[170:173], v[60:63]
	v_mfma_f32_16x16x32_bf16 v[56:59], v[136:139], v[170:173], v[56:59]
	v_mfma_f32_16x16x32_bf16 v[44:47], v[128:131], v[194:197], v[44:47]
	v_mfma_f32_16x16x32_bf16 v[40:43], v[136:139], v[194:197], v[40:43]
	v_mfma_f32_16x16x32_bf16 v[28:31], v[128:131], v[212:215], v[28:31]
	v_mfma_f32_16x16x32_bf16 v[24:27], v[136:139], v[212:215], v[24:27]
	v_mfma_f32_16x16x32_bf16 v[12:15], v[128:131], v[224:227], v[12:15]
	v_mfma_f32_16x16x32_bf16 v[8:11], v[136:139], v[224:227], v[8:11]
	v_mfma_f32_16x16x32_bf16 v[60:63], v[132:135], v[174:177], v[60:63]
	v_mfma_f32_16x16x32_bf16 v[56:59], v[140:143], v[174:177], v[56:59]
	v_mfma_f32_16x16x32_bf16 v[44:47], v[132:135], v[208:211], v[44:47]
	v_mfma_f32_16x16x32_bf16 v[40:43], v[140:143], v[208:211], v[40:43]
	v_mfma_f32_16x16x32_bf16 v[28:31], v[132:135], v[220:223], v[28:31]
	v_mfma_f32_16x16x32_bf16 v[24:27], v[140:143], v[220:223], v[24:27]
	v_mfma_f32_16x16x32_bf16 v[12:15], v[132:135], v[228:231], v[12:15]
	v_mfma_f32_16x16x32_bf16 v[8:11], v[140:143], v[228:231], v[8:11]
	v_mfma_f32_16x16x32_bf16 v[52:55], v[144:147], v[170:173], v[52:55]
	v_mfma_f32_16x16x32_bf16 v[48:51], v[152:155], v[170:173], v[48:51]
	v_mfma_f32_16x16x32_bf16 v[36:39], v[144:147], v[194:197], v[36:39]
	v_mfma_f32_16x16x32_bf16 v[32:35], v[152:155], v[194:197], v[32:35]
	v_mfma_f32_16x16x32_bf16 v[20:23], v[144:147], v[212:215], v[20:23]
	v_mfma_f32_16x16x32_bf16 v[16:19], v[152:155], v[212:215], v[16:19]
	v_mfma_f32_16x16x32_bf16 v[4:7], v[144:147], v[224:227], v[4:7]
	v_mfma_f32_16x16x32_bf16 v[0:3], v[152:155], v[224:227], v[0:3]
	v_mfma_f32_16x16x32_bf16 v[52:55], v[148:151], v[174:177], v[52:55]
	v_mfma_f32_16x16x32_bf16 v[48:51], v[166:169], v[174:177], v[48:51]
	v_mfma_f32_16x16x32_bf16 v[36:39], v[148:151], v[208:211], v[36:39]
	v_mfma_f32_16x16x32_bf16 v[32:35], v[166:169], v[208:211], v[32:35]
	v_mfma_f32_16x16x32_bf16 v[20:23], v[148:151], v[220:223], v[20:23]
	v_mfma_f32_16x16x32_bf16 v[16:19], v[166:169], v[220:223], v[16:19]
	v_mfma_f32_16x16x32_bf16 v[4:7], v[148:151], v[228:231], v[4:7]
	v_mfma_f32_16x16x32_bf16 v[0:3], v[166:169], v[228:231], v[0:3]
	s_barrier
	s_add_i32 s45, 0, 0x18000
	s_add_i32 s60, 0, 0x1c000
	v_add_u32_e32 v140, s45, v199
	v_add_u32_e32 v166, s60, v199
	ds_read_b128 v[128:131], v140
	ds_read_b128 v[132:135], v140 offset:1024
	ds_read_b128 v[136:139], v140 offset:2048
	ds_read_b128 v[140:143], v140 offset:3072
	ds_read_b128 v[144:147], v166
	ds_read_b128 v[148:151], v166 offset:1024
	ds_read_b128 v[152:155], v166 offset:2048
	ds_read_b128 v[166:169], v166 offset:3072
	s_add_u32 s28, s28, s6
	s_addc_u32 s29, s29, s7
	s_mov_b32 m0, s37
	v_lshl_add_u64 v[238:239], s[28:29], 0, v[160:161]
	ds_read_b128 v[170:173], v206 offset:32768
	ds_read_b128 v[174:177], v206 offset:33792
	ds_read_b128 v[194:197], v206 offset:34816
	ds_read_b128 v[208:211], v206 offset:35840
	ds_read_b128 v[212:215], v206 offset:36864
	ds_read_b128 v[220:223], v206 offset:37888
	ds_read_b128 v[224:227], v206 offset:38912
	ds_read_b128 v[228:231], v206 offset:39936
	global_load_lds_dwordx4 v[238:239], off
	v_lshl_add_u64 v[238:239], s[28:29], 0, v[158:159]
	s_mov_b32 m0, s38
	s_nop 0
	global_load_lds_dwordx4 v[238:239], off
	s_waitcnt vmcnt(8)
	s_waitcnt lgkmcnt(0)
	s_barrier
	s_waitcnt lgkmcnt(0)
	v_mfma_f32_16x16x32_bf16 v[120:123], v[128:131], v[170:173], v[120:123]
	v_mfma_f32_16x16x32_bf16 v[124:127], v[136:139], v[170:173], v[124:127]
	v_lshl_add_u64 v[178:179], v[178:179], 0, s[12:13]
	v_mfma_f32_16x16x32_bf16 v[108:111], v[128:131], v[194:197], v[108:111]
	v_lshl_add_u64 v[202:203], v[202:203], 0, s[12:13]
	v_mfma_f32_16x16x32_bf16 v[104:107], v[136:139], v[194:197], v[104:107]
	v_lshl_add_u64 v[216:217], v[216:217], 0, s[12:13]
	v_mfma_f32_16x16x32_bf16 v[92:95], v[128:131], v[212:215], v[92:95]
	v_lshl_add_u64 v[232:233], v[232:233], 0, s[12:13]
	v_mfma_f32_16x16x32_bf16 v[88:91], v[136:139], v[212:215], v[88:91]
	v_lshl_add_u64 v[234:235], v[234:235], 0, s[12:13]
	v_mfma_f32_16x16x32_bf16 v[76:79], v[128:131], v[224:227], v[76:79]
	v_lshl_add_u64 v[236:237], v[236:237], 0, s[12:13]
	v_mfma_f32_16x16x32_bf16 v[72:75], v[136:139], v[224:227], v[72:75]
	v_mfma_f32_16x16x32_bf16 v[120:123], v[132:135], v[174:177], v[120:123]
	v_mfma_f32_16x16x32_bf16 v[124:127], v[140:143], v[174:177], v[124:127]
	v_mfma_f32_16x16x32_bf16 v[108:111], v[132:135], v[208:211], v[108:111]
	v_mfma_f32_16x16x32_bf16 v[104:107], v[140:143], v[208:211], v[104:107]
	v_mfma_f32_16x16x32_bf16 v[92:95], v[132:135], v[220:223], v[92:95]
	v_mfma_f32_16x16x32_bf16 v[88:91], v[140:143], v[220:223], v[88:91]
	v_mfma_f32_16x16x32_bf16 v[76:79], v[132:135], v[228:231], v[76:79]
	v_mfma_f32_16x16x32_bf16 v[72:75], v[140:143], v[228:231], v[72:75]
	v_mfma_f32_16x16x32_bf16 v[116:119], v[144:147], v[170:173], v[116:119]
	v_mfma_f32_16x16x32_bf16 v[112:115], v[152:155], v[170:173], v[112:115]
	v_mfma_f32_16x16x32_bf16 v[100:103], v[144:147], v[194:197], v[100:103]
	v_mfma_f32_16x16x32_bf16 v[96:99], v[152:155], v[194:197], v[96:99]
	v_mfma_f32_16x16x32_bf16 v[84:87], v[144:147], v[212:215], v[84:87]
	v_mfma_f32_16x16x32_bf16 v[80:83], v[152:155], v[212:215], v[80:83]
	v_mfma_f32_16x16x32_bf16 v[68:71], v[144:147], v[224:227], v[68:71]
	v_mfma_f32_16x16x32_bf16 v[64:67], v[152:155], v[224:227], v[64:67]
	v_mfma_f32_16x16x32_bf16 v[116:119], v[148:151], v[174:177], v[116:119]
	v_mfma_f32_16x16x32_bf16 v[112:115], v[166:169], v[174:177], v[112:115]
	v_mfma_f32_16x16x32_bf16 v[100:103], v[148:151], v[208:211], v[100:103]
	v_mfma_f32_16x16x32_bf16 v[96:99], v[166:169], v[208:211], v[96:99]
	v_mfma_f32_16x16x32_bf16 v[84:87], v[148:151], v[220:223], v[84:87]
	v_mfma_f32_16x16x32_bf16 v[80:83], v[166:169], v[220:223], v[80:83]
	v_mfma_f32_16x16x32_bf16 v[68:71], v[148:151], v[228:231], v[68:71]
	v_mfma_f32_16x16x32_bf16 v[64:67], v[166:169], v[228:231], v[64:67]
	s_barrier
	s_add_i32 s28, s45, s34
	s_mov_b32 m0, s28
	ds_read_b128 v[170:173], v206 offset:49152
	ds_read_b128 v[174:177], v206 offset:50176
	ds_read_b128 v[194:197], v206 offset:51200
	ds_read_b128 v[208:211], v206 offset:52224
	ds_read_b128 v[212:215], v206 offset:53248
	ds_read_b128 v[220:223], v206 offset:54272
	ds_read_b128 v[224:227], v206 offset:55296
	ds_read_b128 v[228:231], v206 offset:56320
	global_load_lds_dwordx4 v[178:179], off
	s_add_i32 m0, s28, 0x2000
	s_add_i32 s28, s60, s34
	global_load_lds_dwordx4 v[202:203], off
	s_mov_b32 m0, s28
	s_nop 0
	global_load_lds_dwordx4 v[216:217], off
	s_add_i32 m0, s28, 0x2000
	s_nop 0
	global_load_lds_dwordx4 v[232:233], off
	s_mov_b32 m0, s47
	s_nop 0
	global_load_lds_dwordx4 v[234:235], off
	s_mov_b32 m0, s48
	s_nop 0
	global_load_lds_dwordx4 v[236:237], off
	s_waitcnt vmcnt(8)
	s_waitcnt lgkmcnt(0)
	s_barrier
	s_waitcnt lgkmcnt(0)
	v_mfma_f32_16x16x32_bf16 v[60:63], v[128:131], v[170:173], v[60:63]
	s_add_u32 s26, s26, 0x100
	v_mfma_f32_16x16x32_bf16 v[56:59], v[136:139], v[170:173], v[56:59]
	s_addc_u32 s27, s27, 0
	v_mfma_f32_16x16x32_bf16 v[44:47], v[128:131], v[194:197], v[44:47]
	s_add_u32 s10, s10, 0x100
	v_mfma_f32_16x16x32_bf16 v[40:43], v[136:139], v[194:197], v[40:43]
	s_addc_u32 s11, s11, 0
	v_mfma_f32_16x16x32_bf16 v[28:31], v[128:131], v[212:215], v[28:31]
	s_mov_b32 s28, s44
	v_mfma_f32_16x16x32_bf16 v[24:27], v[136:139], v[212:215], v[24:27]
	s_cmp_ge_i32 s44, s46
	v_mfma_f32_16x16x32_bf16 v[12:15], v[128:131], v[224:227], v[12:15]
	s_cselect_b32 s99, 1, 0
	v_mfma_f32_16x16x32_bf16 v[8:11], v[136:139], v[224:227], v[8:11]
	s_add_i32 s44, s28, 2
	v_mfma_f32_16x16x32_bf16 v[60:63], v[132:135], v[174:177], v[60:63]
	s_add_u32 s45, s26, 0x80
	v_mfma_f32_16x16x32_bf16 v[56:59], v[140:143], v[174:177], v[56:59]
	s_addc_u32 s29, s27, 0
	v_mfma_f32_16x16x32_bf16 v[44:47], v[132:135], v[208:211], v[44:47]
	s_add_i32 s62, 0, 0x10000
	v_mfma_f32_16x16x32_bf16 v[40:43], v[140:143], v[208:211], v[40:43]
	s_cmp_eq_u32 s49, s28
	v_mfma_f32_16x16x32_bf16 v[28:31], v[132:135], v[220:223], v[28:31]
	s_cselect_b32 s29, s23, s29
	v_mfma_f32_16x16x32_bf16 v[24:27], v[140:143], v[220:223], v[24:27]
	s_cselect_b32 s28, s22, s45
	v_mfma_f32_16x16x32_bf16 v[12:15], v[132:135], v[228:231], v[12:15]
	s_cselect_b32 s61, s25, s11
	v_mfma_f32_16x16x32_bf16 v[8:11], v[140:143], v[228:231], v[8:11]
	s_cselect_b32 s60, s24, s10
	v_mfma_f32_16x16x32_bf16 v[52:55], v[144:147], v[170:173], v[52:55]
	s_add_i32 s45, 0, 0x14000
	v_mfma_f32_16x16x32_bf16 v[48:51], v[152:155], v[170:173], v[48:51]
	v_mfma_f32_16x16x32_bf16 v[36:39], v[144:147], v[194:197], v[36:39]
	v_mfma_f32_16x16x32_bf16 v[32:35], v[152:155], v[194:197], v[32:35]
	v_mfma_f32_16x16x32_bf16 v[20:23], v[144:147], v[212:215], v[20:23]
	v_mfma_f32_16x16x32_bf16 v[16:19], v[152:155], v[212:215], v[16:19]
	v_mfma_f32_16x16x32_bf16 v[4:7], v[144:147], v[224:227], v[4:7]
	v_mfma_f32_16x16x32_bf16 v[0:3], v[152:155], v[224:227], v[0:3]
	v_mfma_f32_16x16x32_bf16 v[52:55], v[148:151], v[174:177], v[52:55]
	v_mfma_f32_16x16x32_bf16 v[48:51], v[166:169], v[174:177], v[48:51]
	v_mfma_f32_16x16x32_bf16 v[36:39], v[148:151], v[208:211], v[36:39]
	v_mfma_f32_16x16x32_bf16 v[32:35], v[166:169], v[208:211], v[32:35]
	v_mfma_f32_16x16x32_bf16 v[20:23], v[148:151], v[220:223], v[20:23]
	v_mfma_f32_16x16x32_bf16 v[16:19], v[166:169], v[220:223], v[16:19]
	v_mfma_f32_16x16x32_bf16 v[4:7], v[148:151], v[228:231], v[4:7]
	v_mfma_f32_16x16x32_bf16 v[0:3], v[166:169], v[228:231], v[0:3]
	s_barrier
	s_cmp_lg_u32 s99, 0
	s_cbranch_scc0 .LBB0_1224
